# v44 without the per-segment s_setprio flips in the K-loops (loader segments are VALU-free now)
# speedup vs baseline: 1.0072x; 1.0072x over previous
; #define PG8_STAGE(bufoff, gbase, voff) do { _Pragma("unroll") for (int _i = 0; _i < 2; ++_i) \
;         __builtin_amdgcn_global_load_lds((const unsigned*)((const char*)(gbase) + (voff)[_i]), (PG8_LAS unsigned*)(lds + (bufoff) + ldsw + _i * 8192), 16, 0, 0); } while (0)
; #define PG8_LDA(dst, b, h) do { _Pragma("unroll") for (int m = 0; m < 4; ++m) _Pragma("unroll") for (int k = 0; k < 2; ++k) dst[m][k] = *(const PG8_LAS bf16x8*)(lds + PG8_SA(b, h) + aoff + m * 2048 + k * 1024); } while (0)
; #define PG8_LDB(dst, b, h) do { _Pragma("unroll") for (int n = 0; n < 2; ++n) _Pragma("unroll") for (int k = 0; k < 2; ++k) dst[n][k] = *(const PG8_LAS bf16x8*)(lds + PG8_SB(b, h) + boff + n * 2048 + k * 1024); } while (0)
; #define PG8_SCHED __builtin_amdgcn_sched_barrier(0)
; template <class Epi, class Sched, bool ALIGN_EPI = false, bool SP2 = false>
; __device__ __forceinline__ void gemm_phase(PG8_LAS unsigned char* lds, const Gemm g, const Sched& S, const Epi& E) {
;     ...
;         const char* nA = has_next ? (const char*)g.A + (size_t)nxt.pm * tstep : cA; const char* nB = has_next ? (const char*)g.Bt + (size_t)nxt.pn * tstep : cB;
;         for (int t = 0; t < nt; t += 2) {
;             const bool last = (t == nt - 2);
;             const char* a1 = cA + (size_t)(t + 1) * kstep;
;             const char* a2 = last ? nA : cA + (size_t)(t + 2) * kstep; const char* b2 = last ? nB : cB + (size_t)(t + 2) * kstep;
;             const char* a3 = a2 + kstep; const char* b3 = b2 + kstep;
;             if (last && has_next) S.a_ready(nxt);
;             if constexpr (SP2) {
;             PG8_LDB(B0, 0, 0); PG8_LDB(B1, 0, 1); PG8_SCHED; PG8_LDA(At, 0, 0); PG8_STAGE(PG8_SA(1, 1), a1 + hstep, voffA);
.LBB0_66:
	ds_read_b128 v[152:155], v149
	ds_read_b128 v[156:159], v149 offset:1024
	ds_read_b128 v[160:163], v149 offset:2048
	ds_read_b128 v[164:167], v149 offset:3072
	ds_read_b128 v[168:171], v150
	ds_read_b128 v[172:175], v150 offset:1024
	ds_read_b128 v[176:179], v150 offset:2048
	ds_read_b128 v[180:183], v150 offset:3072
	s_add_u32 s42, s40, 0xfff80080
	s_addc_u32 s43, s41, -1
	s_cmp_eq_u32 s68, 28
	s_cselect_b32 s45, s35, s43
	s_cselect_b32 s44, s63, s42
	s_cselect_b32 s43, s31, s67
	s_cselect_b32 s42, s64, s65

; #define PG8_STAGE(bufoff, gbase, voff) do { _Pragma("unroll") for (int _i = 0; _i < 2; ++_i) \
;         __builtin_amdgcn_global_load_lds((const unsigned*)((const char*)(gbase) + (voff)[_i]), (PG8_LAS unsigned*)(lds + (bufoff) + ldsw + _i * 8192), 16, 0, 0); } while (0)
; #define PG8_LDA(dst, b, h) do { _Pragma("unroll") for (int m = 0; m < 4; ++m) _Pragma("unroll") for (int k = 0; k < 2; ++k) dst[m][k] = *(const PG8_LAS bf16x8*)(lds + PG8_SA(b, h) + aoff + m * 2048 + k * 1024); } while (0)
; #define PG8_LDB(dst, b, h) do { _Pragma("unroll") for (int n = 0; n < 2; ++n) _Pragma("unroll") for (int k = 0; k < 2; ++k) dst[n][k] = *(const PG8_LAS bf16x8*)(lds + PG8_SB(b, h) + boff + n * 2048 + k * 1024); } while (0)
; #define PG8_SCHED __builtin_amdgcn_sched_barrier(0)
; template <class Epi, class Sched, bool ALIGN_EPI = false, bool SP2 = false>
; __device__ __forceinline__ void gemm_phase(PG8_LAS unsigned char* lds, const Gemm g, const Sched& S, const Epi& E) {
;     ...
;             PG8_LDB(B0, 0, 0); PG8_LDB(B1, 0, 1); PG8_SCHED; PG8_LDA(At, 0, 0); PG8_STAGE(PG8_SA(1, 1), a1 + hstep, voffA);
	s_add_i32 m0, s29, 0xc000
	ds_read_b128 v[184:187], v151
	ds_read_b128 v[188:191], v151 offset:1024
	ds_read_b128 v[192:195], v151 offset:2048
	ds_read_b128 v[196:199], v151 offset:3072
	ds_read_b128 v[200:203], v151 offset:4096
	ds_read_b128 v[204:207], v151 offset:5120
	ds_read_b128 v[208:211], v151 offset:6144
	ds_read_b128 v[212:215], v151 offset:7168
	global_load_lds_dwordx4 v136, s[40:41]

; #define PG8_STAGE(bufoff, gbase, voff) do { _Pragma("unroll") for (int _i = 0; _i < 2; ++_i) \
;         __builtin_amdgcn_global_load_lds((const unsigned*)((const char*)(gbase) + (voff)[_i]), (PG8_LAS unsigned*)(lds + (bufoff) + ldsw + _i * 8192), 16, 0, 0); } while (0)
; #define PG8_LDA(dst, b, h) do { _Pragma("unroll") for (int m = 0; m < 4; ++m) _Pragma("unroll") for (int k = 0; k < 2; ++k) dst[m][k] = *(const PG8_LAS bf16x8*)(lds + PG8_SA(b, h) + aoff + m * 2048 + k * 1024); } while (0)
; #define PG8_LDB(dst, b, h) do { _Pragma("unroll") for (int n = 0; n < 2; ++n) _Pragma("unroll") for (int k = 0; k < 2; ++k) dst[n][k] = *(const PG8_LAS bf16x8*)(lds + PG8_SB(b, h) + boff + n * 2048 + k * 1024); } while (0)
; #define PG8_MMA(ai, bj, At, Bt) do { __builtin_amdgcn_s_setprio(1); _Pragma("unroll") for (int m = 0; m < 4; ++m) _Pragma("unroll") for (int n = 0; n < 2; ++n) _Pragma("unroll") for (int k = 0; k < 2; ++k) \
;         acc[ai][bj][m][n] = __builtin_amdgcn_mfma_f32_16x16x32_bf16(Bt[n][k], At[m][k], acc[ai][bj][m][n], 0, 0, 0); __builtin_amdgcn_s_setprio(0); } while (0)
; #define PG8_WAIT_V(n) asm volatile("s_waitcnt vmcnt(" #n ")" ::: "memory")
; #define PG8_WAIT_L(n) asm volatile("s_waitcnt lgkmcnt(" #n ")" ::: "memory")
; #define PG8_BAR __builtin_amdgcn_s_barrier()
; #define PG8_SCHED __builtin_amdgcn_sched_barrier(0)
; template <class Epi, class Sched, bool ALIGN_EPI = false, bool SP2 = false>
; __device__ __forceinline__ void gemm_phase(PG8_LAS unsigned char* lds, const Gemm g, const Sched& S, const Epi& E) {
;     ...
;             PG8_LDB(B0, 0, 0); PG8_LDB(B1, 0, 1); PG8_SCHED; PG8_LDA(At, 0, 0); PG8_STAGE(PG8_SA(1, 1), a1 + hstep, voffA);
;             PG8_WAIT_V(8); PG8_WAIT_L(0); PG8_BAR; PG8_MMA(0, 0, At, B0); PG8_MMA(0, 1, At, B1); PG8_BAR; PG8_SCHED;
	s_add_i32 m0, s29, 0xe000
	s_nop 0
	global_load_lds_dwordx4 v138, s[40:41]
	s_waitcnt vmcnt(8)
	s_waitcnt lgkmcnt(0)

; #define PG8_MMA(ai, bj, At, Bt) do { __builtin_amdgcn_s_setprio(1); _Pragma("unroll") for (int m = 0; m < 4; ++m) _Pragma("unroll") for (int n = 0; n < 2; ++n) _Pragma("unroll") for (int k = 0; k < 2; ++k) \
;         acc[ai][bj][m][n] = __builtin_amdgcn_mfma_f32_16x16x32_bf16(Bt[n][k], At[m][k], acc[ai][bj][m][n], 0, 0, 0); __builtin_amdgcn_s_setprio(0); } while (0)
; #define PG8_WAIT_V(n) asm volatile("s_waitcnt vmcnt(" #n ")" ::: "memory")
; #define PG8_WAIT_L(n) asm volatile("s_waitcnt lgkmcnt(" #n ")" ::: "memory")
; #define PG8_BAR __builtin_amdgcn_s_barrier()
; #define PG8_SCHED __builtin_amdgcn_sched_barrier(0)
; template <class Epi, class Sched, bool ALIGN_EPI = false, bool SP2 = false>
; __device__ __forceinline__ void gemm_phase(PG8_LAS unsigned char* lds, const Gemm g, const Sched& S, const Epi& E) {
;     ...
;             PG8_WAIT_V(8); PG8_WAIT_L(0); PG8_BAR; PG8_MMA(0, 0, At, B0); PG8_MMA(0, 1, At, B1); PG8_BAR; PG8_SCHED;
	s_barrier

; #define PG8_MMA(ai, bj, At, Bt) do { __builtin_amdgcn_s_setprio(1); _Pragma("unroll") for (int m = 0; m < 4; ++m) _Pragma("unroll") for (int n = 0; n < 2; ++n) _Pragma("unroll") for (int k = 0; k < 2; ++k) \
;         acc[ai][bj][m][n] = __builtin_amdgcn_mfma_f32_16x16x32_bf16(Bt[n][k], At[m][k], acc[ai][bj][m][n], 0, 0, 0); __builtin_amdgcn_s_setprio(0); } while (0)
; #define PG8_WAIT_V(n) asm volatile("s_waitcnt vmcnt(" #n ")" ::: "memory")
; #define PG8_WAIT_L(n) asm volatile("s_waitcnt lgkmcnt(" #n ")" ::: "memory")
; #define PG8_BAR __builtin_amdgcn_s_barrier()
; #define PG8_SCHED __builtin_amdgcn_sched_barrier(0)
; template <class Epi, class Sched, bool ALIGN_EPI = false, bool SP2 = false>
; __device__ __forceinline__ void gemm_phase(PG8_LAS unsigned char* lds, const Gemm g, const Sched& S, const Epi& E) {
;     ...
;             PG8_WAIT_V(8); PG8_WAIT_L(0); PG8_BAR; PG8_MMA(0, 0, At, B0); PG8_MMA(0, 1, At, B1); PG8_BAR; PG8_SCHED;
	v_mfma_f32_16x16x32_bf16 v[124:127], v[152:155], v[184:187], v[124:127]
	v_mfma_f32_16x16x32_bf16 v[120:123], v[160:163], v[184:187], v[120:123]
	v_mfma_f32_16x16x32_bf16 v[116:119], v[152:155], v[192:195], v[116:119]
	v_mfma_f32_16x16x32_bf16 v[112:115], v[160:163], v[192:195], v[112:115]
	v_mfma_f32_16x16x32_bf16 v[100:103], v[152:155], v[200:203], v[100:103]
	v_mfma_f32_16x16x32_bf16 v[96:99], v[160:163], v[200:203], v[96:99]
	v_mfma_f32_16x16x32_bf16 v[84:87], v[152:155], v[208:211], v[84:87]
	v_mfma_f32_16x16x32_bf16 v[80:83], v[160:163], v[208:211], v[80:83]
	v_mfma_f32_16x16x32_bf16 v[124:127], v[156:159], v[188:191], v[124:127]
	v_mfma_f32_16x16x32_bf16 v[120:123], v[164:167], v[188:191], v[120:123]
	v_mfma_f32_16x16x32_bf16 v[116:119], v[156:159], v[196:199], v[116:119]
	v_mfma_f32_16x16x32_bf16 v[112:115], v[164:167], v[196:199], v[112:115]
	v_mfma_f32_16x16x32_bf16 v[100:103], v[156:159], v[204:207], v[100:103]
	v_mfma_f32_16x16x32_bf16 v[96:99], v[164:167], v[204:207], v[96:99]
	v_mfma_f32_16x16x32_bf16 v[84:87], v[156:159], v[212:215], v[84:87]
	v_mfma_f32_16x16x32_bf16 v[80:83], v[164:167], v[212:215], v[80:83]


; #define PG8_MMA(ai, bj, At, Bt) do { __builtin_amdgcn_s_setprio(1); _Pragma("unroll") for (int m = 0; m < 4; ++m) _Pragma("unroll") for (int n = 0; n < 2; ++n) _Pragma("unroll") for (int k = 0; k < 2; ++k) \
;         acc[ai][bj][m][n] = __builtin_amdgcn_mfma_f32_16x16x32_bf16(Bt[n][k], At[m][k], acc[ai][bj][m][n], 0, 0, 0); __builtin_amdgcn_s_setprio(0); } while (0)
; #define PG8_WAIT_V(n) asm volatile("s_waitcnt vmcnt(" #n ")" ::: "memory")
; #define PG8_WAIT_L(n) asm volatile("s_waitcnt lgkmcnt(" #n ")" ::: "memory")
; #define PG8_BAR __builtin_amdgcn_s_barrier()
; #define PG8_SCHED __builtin_amdgcn_sched_barrier(0)
; template <class Epi, class Sched, bool ALIGN_EPI = false, bool SP2 = false>
; __device__ __forceinline__ void gemm_phase(PG8_LAS unsigned char* lds, const Gemm g, const Sched& S, const Epi& E) {
;     ...
;             PG8_WAIT_V(8); PG8_WAIT_L(0); PG8_BAR; PG8_MMA(0, 0, At, B0); PG8_MMA(0, 1, At, B1); PG8_BAR; PG8_SCHED;
	v_mfma_f32_16x16x32_bf16 v[108:111], v[168:171], v[184:187], v[108:111]
	v_mfma_f32_16x16x32_bf16 v[104:107], v[176:179], v[184:187], v[104:107]
	v_mfma_f32_16x16x32_bf16 v[92:95], v[168:171], v[192:195], v[92:95]
	v_mfma_f32_16x16x32_bf16 v[88:91], v[176:179], v[192:195], v[88:91]
	v_mfma_f32_16x16x32_bf16 v[76:79], v[168:171], v[200:203], v[76:79]
	v_mfma_f32_16x16x32_bf16 v[72:75], v[176:179], v[200:203], v[72:75]
	v_mfma_f32_16x16x32_bf16 v[68:71], v[168:171], v[208:211], v[68:71]
	v_mfma_f32_16x16x32_bf16 v[64:67], v[176:179], v[208:211], v[64:67]
	v_mfma_f32_16x16x32_bf16 v[108:111], v[172:175], v[188:191], v[108:111]
	v_mfma_f32_16x16x32_bf16 v[104:107], v[180:183], v[188:191], v[104:107]
	v_mfma_f32_16x16x32_bf16 v[92:95], v[172:175], v[196:199], v[92:95]
	v_mfma_f32_16x16x32_bf16 v[88:91], v[180:183], v[196:199], v[88:91]
	v_mfma_f32_16x16x32_bf16 v[76:79], v[172:175], v[204:207], v[76:79]
	v_mfma_f32_16x16x32_bf16 v[72:75], v[180:183], v[204:207], v[72:75]
	v_mfma_f32_16x16x32_bf16 v[68:71], v[172:175], v[212:215], v[68:71]
	v_mfma_f32_16x16x32_bf16 v[64:67], v[180:183], v[212:215], v[64:67]

; #define PG8_STAGE(bufoff, gbase, voff) do { _Pragma("unroll") for (int _i = 0; _i < 2; ++_i) \
;         __builtin_amdgcn_global_load_lds((const unsigned*)((const char*)(gbase) + (voff)[_i]), (PG8_LAS unsigned*)(lds + (bufoff) + ldsw + _i * 8192), 16, 0, 0); } while (0)
; #define PG8_LDA(dst, b, h) do { _Pragma("unroll") for (int m = 0; m < 4; ++m) _Pragma("unroll") for (int k = 0; k < 2; ++k) dst[m][k] = *(const PG8_LAS bf16x8*)(lds + PG8_SA(b, h) + aoff + m * 2048 + k * 1024); } while (0)
; #define PG8_MMA(ai, bj, At, Bt) do { __builtin_amdgcn_s_setprio(1); _Pragma("unroll") for (int m = 0; m < 4; ++m) _Pragma("unroll") for (int n = 0; n < 2; ++n) _Pragma("unroll") for (int k = 0; k < 2; ++k) \
;         acc[ai][bj][m][n] = __builtin_amdgcn_mfma_f32_16x16x32_bf16(Bt[n][k], At[m][k], acc[ai][bj][m][n], 0, 0, 0); __builtin_amdgcn_s_setprio(0); } while (0)
; #define PG8_WAIT_V(n) asm volatile("s_waitcnt vmcnt(" #n ")" ::: "memory")
; #define PG8_WAIT_L(n) asm volatile("s_waitcnt lgkmcnt(" #n ")" ::: "memory")
; #define PG8_BAR __builtin_amdgcn_s_barrier()
; #define PG8_SCHED __builtin_amdgcn_sched_barrier(0)
; template <class Epi, class Sched, bool ALIGN_EPI = false, bool SP2 = false>
; __device__ __forceinline__ void gemm_phase(PG8_LAS unsigned char* lds, const Gemm g, const Sched& S, const Epi& E) {
;     ...
;             PG8_WAIT_V(8); PG8_WAIT_L(0); PG8_BAR; PG8_MMA(0, 0, At, B0); PG8_MMA(0, 1, At, B1); PG8_BAR; PG8_SCHED;
;             PG8_LDA(At, 0, 1); PG8_STAGE(PG8_SB(0, 0), b2, voffB); PG8_STAGE(PG8_SB(0, 1), b2 + hstep, voffB); PG8_STAGE(PG8_SA(0, 0), a2, voffA);
	s_barrier
	s_add_i32 s69, s59, s48
	s_mov_b64 s[96:97], s[42:43]

; #define PG8_STAGE(bufoff, gbase, voff) do { _Pragma("unroll") for (int _i = 0; _i < 2; ++_i) \
;         __builtin_amdgcn_global_load_lds((const unsigned*)((const char*)(gbase) + (voff)[_i]), (PG8_LAS unsigned*)(lds + (bufoff) + ldsw + _i * 8192), 16, 0, 0); } while (0)
; #define PG8_LDA(dst, b, h) do { _Pragma("unroll") for (int m = 0; m < 4; ++m) _Pragma("unroll") for (int k = 0; k < 2; ++k) dst[m][k] = *(const PG8_LAS bf16x8*)(lds + PG8_SA(b, h) + aoff + m * 2048 + k * 1024); } while (0)
; template <class Epi, class Sched, bool ALIGN_EPI = false, bool SP2 = false>
; __device__ __forceinline__ void gemm_phase(PG8_LAS unsigned char* lds, const Gemm g, const Sched& S, const Epi& E) {
;     ...
;             PG8_LDA(At, 0, 1); PG8_STAGE(PG8_SB(0, 0), b2, voffB); PG8_STAGE(PG8_SB(0, 1), b2 + hstep, voffB); PG8_STAGE(PG8_SA(0, 0), a2, voffA);
	s_mov_b32 m0, s69
	ds_read_b128 v[184:187], v151 offset:16384
	ds_read_b128 v[188:191], v151 offset:17408
	ds_read_b128 v[192:195], v151 offset:18432
	ds_read_b128 v[196:199], v151 offset:19456
	ds_read_b128 v[200:203], v151 offset:20480
	ds_read_b128 v[204:207], v151 offset:21504
	ds_read_b128 v[208:211], v151 offset:22528
	ds_read_b128 v[212:215], v151 offset:23552
	global_load_lds_dwordx4 v132, s[42:43]
	s_add_i32 m0, s69, 0x2000
	s_add_u32 s70, s42, 0x80000

; #define PG8_STAGE(bufoff, gbase, voff) do { _Pragma("unroll") for (int _i = 0; _i < 2; ++_i) \
;         __builtin_amdgcn_global_load_lds((const unsigned*)((const char*)(gbase) + (voff)[_i]), (PG8_LAS unsigned*)(lds + (bufoff) + ldsw + _i * 8192), 16, 0, 0); } while (0)
; #define PG8_LDA(dst, b, h) do { _Pragma("unroll") for (int m = 0; m < 4; ++m) _Pragma("unroll") for (int k = 0; k < 2; ++k) dst[m][k] = *(const PG8_LAS bf16x8*)(lds + PG8_SA(b, h) + aoff + m * 2048 + k * 1024); } while (0)
; template <class Epi, class Sched, bool ALIGN_EPI = false, bool SP2 = false>
; __device__ __forceinline__ void gemm_phase(PG8_LAS unsigned char* lds, const Gemm g, const Sched& S, const Epi& E) {
;     ...
;             PG8_LDA(At, 0, 1); PG8_STAGE(PG8_SB(0, 0), b2, voffB); PG8_STAGE(PG8_SB(0, 1), b2 + hstep, voffB); PG8_STAGE(PG8_SA(0, 0), a2, voffA);
	s_addc_u32 s71, s43, 0
	s_add_i32 s69, s60, s48
	global_load_lds_dwordx4 v128, s[42:43]

; #define PG8_STAGE(bufoff, gbase, voff) do { _Pragma("unroll") for (int _i = 0; _i < 2; ++_i) \
;         __builtin_amdgcn_global_load_lds((const unsigned*)((const char*)(gbase) + (voff)[_i]), (PG8_LAS unsigned*)(lds + (bufoff) + ldsw + _i * 8192), 16, 0, 0); } while (0)
; #define PG8_LDA(dst, b, h) do { _Pragma("unroll") for (int m = 0; m < 4; ++m) _Pragma("unroll") for (int k = 0; k < 2; ++k) dst[m][k] = *(const PG8_LAS bf16x8*)(lds + PG8_SA(b, h) + aoff + m * 2048 + k * 1024); } while (0)
; template <class Epi, class Sched, bool ALIGN_EPI = false, bool SP2 = false>
; __device__ __forceinline__ void gemm_phase(PG8_LAS unsigned char* lds, const Gemm g, const Sched& S, const Epi& E) {
;     ...
;             PG8_LDA(At, 0, 1); PG8_STAGE(PG8_SB(0, 0), b2, voffB); PG8_STAGE(PG8_SB(0, 1), b2 + hstep, voffB); PG8_STAGE(PG8_SA(0, 0), a2, voffA);
	s_mov_b32 m0, s69
	s_nop 0
	global_load_lds_dwordx4 v132, s[70:71]

; #define PG8_STAGE(bufoff, gbase, voff) do { _Pragma("unroll") for (int _i = 0; _i < 2; ++_i) \
;         __builtin_amdgcn_global_load_lds((const unsigned*)((const char*)(gbase) + (voff)[_i]), (PG8_LAS unsigned*)(lds + (bufoff) + ldsw + _i * 8192), 16, 0, 0); } while (0)
; #define PG8_LDA(dst, b, h) do { _Pragma("unroll") for (int m = 0; m < 4; ++m) _Pragma("unroll") for (int k = 0; k < 2; ++k) dst[m][k] = *(const PG8_LAS bf16x8*)(lds + PG8_SA(b, h) + aoff + m * 2048 + k * 1024); } while (0)
; template <class Epi, class Sched, bool ALIGN_EPI = false, bool SP2 = false>
; __device__ __forceinline__ void gemm_phase(PG8_LAS unsigned char* lds, const Gemm g, const Sched& S, const Epi& E) {
;     ...
;             PG8_LDA(At, 0, 1); PG8_STAGE(PG8_SB(0, 0), b2, voffB); PG8_STAGE(PG8_SB(0, 1), b2 + hstep, voffB); PG8_STAGE(PG8_SA(0, 0), a2, voffA);
	s_add_i32 m0, s69, 0x2000
	s_nop 0
	global_load_lds_dwordx4 v128, s[70:71]
	s_mov_b64 s[98:99], s[44:45]

; #define PG8_STAGE(bufoff, gbase, voff) do { _Pragma("unroll") for (int _i = 0; _i < 2; ++_i) \
;         __builtin_amdgcn_global_load_lds((const unsigned*)((const char*)(gbase) + (voff)[_i]), (PG8_LAS unsigned*)(lds + (bufoff) + ldsw + _i * 8192), 16, 0, 0); } while (0)
; #define PG8_LDA(dst, b, h) do { _Pragma("unroll") for (int m = 0; m < 4; ++m) _Pragma("unroll") for (int k = 0; k < 2; ++k) dst[m][k] = *(const PG8_LAS bf16x8*)(lds + PG8_SA(b, h) + aoff + m * 2048 + k * 1024); } while (0)
; #define PG8_MMA(ai, bj, At, Bt) do { __builtin_amdgcn_s_setprio(1); _Pragma("unroll") for (int m = 0; m < 4; ++m) _Pragma("unroll") for (int n = 0; n < 2; ++n) _Pragma("unroll") for (int k = 0; k < 2; ++k) \
;         acc[ai][bj][m][n] = __builtin_amdgcn_mfma_f32_16x16x32_bf16(Bt[n][k], At[m][k], acc[ai][bj][m][n], 0, 0, 0); __builtin_amdgcn_s_setprio(0); } while (0)
; #define PG8_WAIT_V(n) asm volatile("s_waitcnt vmcnt(" #n ")" ::: "memory")
; #define PG8_WAIT_L(n) asm volatile("s_waitcnt lgkmcnt(" #n ")" ::: "memory")
; #define PG8_BAR __builtin_amdgcn_s_barrier()
; #define PG8_SCHED __builtin_amdgcn_sched_barrier(0)
; template <class Epi, class Sched, bool ALIGN_EPI = false, bool SP2 = false>
; __device__ __forceinline__ void gemm_phase(PG8_LAS unsigned char* lds, const Gemm g, const Sched& S, const Epi& E) {
;     ...
;             PG8_LDA(At, 0, 1); PG8_STAGE(PG8_SB(0, 0), b2, voffB); PG8_STAGE(PG8_SB(0, 1), b2 + hstep, voffB); PG8_STAGE(PG8_SA(0, 0), a2, voffA);
;             PG8_WAIT_V(8); PG8_WAIT_L(0); PG8_BAR; PG8_MMA(1, 0, At, B0); PG8_MMA(1, 1, At, B1); PG8_BAR; PG8_SCHED;
	s_mov_b32 m0, s29
	s_nop 0
	global_load_lds_dwordx4 v134, s[44:45]
	s_mov_b32 m0, s51
	s_nop 0
	global_load_lds_dwordx4 v130, s[44:45]
	s_waitcnt vmcnt(8)
	s_waitcnt lgkmcnt(0)

; #define PG8_MMA(ai, bj, At, Bt) do { __builtin_amdgcn_s_setprio(1); _Pragma("unroll") for (int m = 0; m < 4; ++m) _Pragma("unroll") for (int n = 0; n < 2; ++n) _Pragma("unroll") for (int k = 0; k < 2; ++k) \
;         acc[ai][bj][m][n] = __builtin_amdgcn_mfma_f32_16x16x32_bf16(Bt[n][k], At[m][k], acc[ai][bj][m][n], 0, 0, 0); __builtin_amdgcn_s_setprio(0); } while (0)
; #define PG8_WAIT_V(n) asm volatile("s_waitcnt vmcnt(" #n ")" ::: "memory")
; #define PG8_WAIT_L(n) asm volatile("s_waitcnt lgkmcnt(" #n ")" ::: "memory")
; #define PG8_BAR __builtin_amdgcn_s_barrier()
; #define PG8_SCHED __builtin_amdgcn_sched_barrier(0)
; template <class Epi, class Sched, bool ALIGN_EPI = false, bool SP2 = false>
; __device__ __forceinline__ void gemm_phase(PG8_LAS unsigned char* lds, const Gemm g, const Sched& S, const Epi& E) {
;     ...
;             PG8_WAIT_V(8); PG8_WAIT_L(0); PG8_BAR; PG8_MMA(1, 0, At, B0); PG8_MMA(1, 1, At, B1); PG8_BAR; PG8_SCHED;
	s_barrier

; #define PG8_MMA(ai, bj, At, Bt) do { __builtin_amdgcn_s_setprio(1); _Pragma("unroll") for (int m = 0; m < 4; ++m) _Pragma("unroll") for (int n = 0; n < 2; ++n) _Pragma("unroll") for (int k = 0; k < 2; ++k) \
;         acc[ai][bj][m][n] = __builtin_amdgcn_mfma_f32_16x16x32_bf16(Bt[n][k], At[m][k], acc[ai][bj][m][n], 0, 0, 0); __builtin_amdgcn_s_setprio(0); } while (0)
; #define PG8_WAIT_V(n) asm volatile("s_waitcnt vmcnt(" #n ")" ::: "memory")
; #define PG8_WAIT_L(n) asm volatile("s_waitcnt lgkmcnt(" #n ")" ::: "memory")
; #define PG8_BAR __builtin_amdgcn_s_barrier()
; #define PG8_SCHED __builtin_amdgcn_sched_barrier(0)
; template <class Epi, class Sched, bool ALIGN_EPI = false, bool SP2 = false>
; __device__ __forceinline__ void gemm_phase(PG8_LAS unsigned char* lds, const Gemm g, const Sched& S, const Epi& E) {
;     ...
;             PG8_WAIT_V(8); PG8_WAIT_L(0); PG8_BAR; PG8_MMA(1, 0, At, B0); PG8_MMA(1, 1, At, B1); PG8_BAR; PG8_SCHED;
	v_mfma_f32_16x16x32_bf16 v[60:63], v[152:155], v[184:187], v[60:63]
	v_mfma_f32_16x16x32_bf16 v[56:59], v[160:163], v[184:187], v[56:59]
	v_mfma_f32_16x16x32_bf16 v[52:55], v[152:155], v[192:195], v[52:55]
	v_mfma_f32_16x16x32_bf16 v[48:51], v[160:163], v[192:195], v[48:51]
	v_mfma_f32_16x16x32_bf16 v[36:39], v[152:155], v[200:203], v[36:39]
	v_mfma_f32_16x16x32_bf16 v[32:35], v[160:163], v[200:203], v[32:35]
	v_mfma_f32_16x16x32_bf16 v[20:23], v[152:155], v[208:211], v[20:23]
	v_mfma_f32_16x16x32_bf16 v[16:19], v[160:163], v[208:211], v[16:19]
	v_mfma_f32_16x16x32_bf16 v[60:63], v[156:159], v[188:191], v[60:63]
	v_mfma_f32_16x16x32_bf16 v[56:59], v[164:167], v[188:191], v[56:59]
	v_mfma_f32_16x16x32_bf16 v[52:55], v[156:159], v[196:199], v[52:55]
	v_mfma_f32_16x16x32_bf16 v[48:51], v[164:167], v[196:199], v[48:51]
	v_mfma_f32_16x16x32_bf16 v[36:39], v[156:159], v[204:207], v[36:39]
	v_mfma_f32_16x16x32_bf16 v[32:35], v[164:167], v[204:207], v[32:35]
	v_mfma_f32_16x16x32_bf16 v[20:23], v[156:159], v[212:215], v[20:23]
	v_mfma_f32_16x16x32_bf16 v[16:19], v[164:167], v[212:215], v[16:19]


; #define PG8_MMA(ai, bj, At, Bt) do { __builtin_amdgcn_s_setprio(1); _Pragma("unroll") for (int m = 0; m < 4; ++m) _Pragma("unroll") for (int n = 0; n < 2; ++n) _Pragma("unroll") for (int k = 0; k < 2; ++k) \
;         acc[ai][bj][m][n] = __builtin_amdgcn_mfma_f32_16x16x32_bf16(Bt[n][k], At[m][k], acc[ai][bj][m][n], 0, 0, 0); __builtin_amdgcn_s_setprio(0); } while (0)
; #define PG8_WAIT_V(n) asm volatile("s_waitcnt vmcnt(" #n ")" ::: "memory")
; #define PG8_WAIT_L(n) asm volatile("s_waitcnt lgkmcnt(" #n ")" ::: "memory")
; #define PG8_BAR __builtin_amdgcn_s_barrier()
; #define PG8_SCHED __builtin_amdgcn_sched_barrier(0)
; template <class Epi, class Sched, bool ALIGN_EPI = false, bool SP2 = false>
; __device__ __forceinline__ void gemm_phase(PG8_LAS unsigned char* lds, const Gemm g, const Sched& S, const Epi& E) {
;     ...
;             PG8_WAIT_V(8); PG8_WAIT_L(0); PG8_BAR; PG8_MMA(1, 0, At, B0); PG8_MMA(1, 1, At, B1); PG8_BAR; PG8_SCHED;
	v_mfma_f32_16x16x32_bf16 v[44:47], v[168:171], v[184:187], v[44:47]
	v_mfma_f32_16x16x32_bf16 v[40:43], v[176:179], v[184:187], v[40:43]
	v_mfma_f32_16x16x32_bf16 v[28:31], v[168:171], v[192:195], v[28:31]
	v_mfma_f32_16x16x32_bf16 v[24:27], v[176:179], v[192:195], v[24:27]
	v_mfma_f32_16x16x32_bf16 v[12:15], v[168:171], v[200:203], v[12:15]
	v_mfma_f32_16x16x32_bf16 v[8:11], v[176:179], v[200:203], v[8:11]
	v_mfma_f32_16x16x32_bf16 v[4:7], v[168:171], v[208:211], v[4:7]
	v_mfma_f32_16x16x32_bf16 v[0:3], v[176:179], v[208:211], v[0:3]
	v_mfma_f32_16x16x32_bf16 v[44:47], v[172:175], v[188:191], v[44:47]
	v_mfma_f32_16x16x32_bf16 v[40:43], v[180:183], v[188:191], v[40:43]
	v_mfma_f32_16x16x32_bf16 v[28:31], v[172:175], v[196:199], v[28:31]
	v_mfma_f32_16x16x32_bf16 v[24:27], v[180:183], v[196:199], v[24:27]
	v_mfma_f32_16x16x32_bf16 v[12:15], v[172:175], v[204:207], v[12:15]
	v_mfma_f32_16x16x32_bf16 v[8:11], v[180:183], v[204:207], v[8:11]
	v_mfma_f32_16x16x32_bf16 v[4:7], v[172:175], v[212:215], v[4:7]
	v_mfma_f32_16x16x32_bf16 v[0:3], v[180:183], v[212:215], v[0:3]

; #define PG8_STAGE(bufoff, gbase, voff) do { _Pragma("unroll") for (int _i = 0; _i < 2; ++_i) \
;         __builtin_amdgcn_global_load_lds((const unsigned*)((const char*)(gbase) + (voff)[_i]), (PG8_LAS unsigned*)(lds + (bufoff) + ldsw + _i * 8192), 16, 0, 0); } while (0)
; #define PG8_LDA(dst, b, h) do { _Pragma("unroll") for (int m = 0; m < 4; ++m) _Pragma("unroll") for (int k = 0; k < 2; ++k) dst[m][k] = *(const PG8_LAS bf16x8*)(lds + PG8_SA(b, h) + aoff + m * 2048 + k * 1024); } while (0)
; #define PG8_LDB(dst, b, h) do { _Pragma("unroll") for (int n = 0; n < 2; ++n) _Pragma("unroll") for (int k = 0; k < 2; ++k) dst[n][k] = *(const PG8_LAS bf16x8*)(lds + PG8_SB(b, h) + boff + n * 2048 + k * 1024); } while (0)
; #define PG8_MMA(ai, bj, At, Bt) do { __builtin_amdgcn_s_setprio(1); _Pragma("unroll") for (int m = 0; m < 4; ++m) _Pragma("unroll") for (int n = 0; n < 2; ++n) _Pragma("unroll") for (int k = 0; k < 2; ++k) \
;         acc[ai][bj][m][n] = __builtin_amdgcn_mfma_f32_16x16x32_bf16(Bt[n][k], At[m][k], acc[ai][bj][m][n], 0, 0, 0); __builtin_amdgcn_s_setprio(0); } while (0)
; #define PG8_WAIT_V(n) asm volatile("s_waitcnt vmcnt(" #n ")" ::: "memory")
; #define PG8_WAIT_L(n) asm volatile("s_waitcnt lgkmcnt(" #n ")" ::: "memory")
; #define PG8_BAR __builtin_amdgcn_s_barrier()
; #define PG8_SCHED __builtin_amdgcn_sched_barrier(0)
; template <class Epi, class Sched, bool ALIGN_EPI = false, bool SP2 = false>
; __device__ __forceinline__ void gemm_phase(PG8_LAS unsigned char* lds, const Gemm g, const Sched& S, const Epi& E) {
;     ...
;             PG8_WAIT_V(8); PG8_WAIT_L(0); PG8_BAR; PG8_MMA(1, 0, At, B0); PG8_MMA(1, 1, At, B1); PG8_BAR; PG8_SCHED;
;             PG8_LDB(B0, 1, 0); PG8_LDB(B1, 1, 1); PG8_SCHED; PG8_LDA(At, 1, 0); PG8_STAGE(PG8_SA(0, 1), a2 + hstep, voffA);
	s_barrier
	s_add_i32 s69, 0, 0x18000
	s_add_i32 s70, 0, 0x1c000


; #define PG8_STAGE(bufoff, gbase, voff) do { _Pragma("unroll") for (int _i = 0; _i < 2; ++_i) \
;         __builtin_amdgcn_global_load_lds((const unsigned*)((const char*)(gbase) + (voff)[_i]), (PG8_LAS unsigned*)(lds + (bufoff) + ldsw + _i * 8192), 16, 0, 0); } while (0)
; #define PG8_LDA(dst, b, h) do { _Pragma("unroll") for (int m = 0; m < 4; ++m) _Pragma("unroll") for (int k = 0; k < 2; ++k) dst[m][k] = *(const PG8_LAS bf16x8*)(lds + PG8_SA(b, h) + aoff + m * 2048 + k * 1024); } while (0)
; #define PG8_LDB(dst, b, h) do { _Pragma("unroll") for (int n = 0; n < 2; ++n) _Pragma("unroll") for (int k = 0; k < 2; ++k) dst[n][k] = *(const PG8_LAS bf16x8*)(lds + PG8_SB(b, h) + boff + n * 2048 + k * 1024); } while (0)
; #define PG8_SCHED __builtin_amdgcn_sched_barrier(0)
; template <class Epi, class Sched, bool ALIGN_EPI = false, bool SP2 = false>
; __device__ __forceinline__ void gemm_phase(PG8_LAS unsigned char* lds, const Gemm g, const Sched& S, const Epi& E) {
;     ...
;             PG8_LDB(B0, 1, 0); PG8_LDB(B1, 1, 1); PG8_SCHED; PG8_LDA(At, 1, 0); PG8_STAGE(PG8_SA(0, 1), a2 + hstep, voffA);
	ds_read_b128 v[152:155], v254
	ds_read_b128 v[156:159], v254 offset:1024
	ds_read_b128 v[160:163], v254 offset:2048
	ds_read_b128 v[164:167], v254 offset:3072
	ds_read_b128 v[168:171], v255
	ds_read_b128 v[172:175], v255 offset:1024
	ds_read_b128 v[176:179], v255 offset:2048
	ds_read_b128 v[180:183], v255 offset:3072
	s_add_u32 s44, s44, 0x80000
	s_addc_u32 s45, s45, 0
	s_mov_b32 m0, s52

; #define PG8_STAGE(bufoff, gbase, voff) do { _Pragma("unroll") for (int _i = 0; _i < 2; ++_i) \
;         __builtin_amdgcn_global_load_lds((const unsigned*)((const char*)(gbase) + (voff)[_i]), (PG8_LAS unsigned*)(lds + (bufoff) + ldsw + _i * 8192), 16, 0, 0); } while (0)
; #define PG8_LDA(dst, b, h) do { _Pragma("unroll") for (int m = 0; m < 4; ++m) _Pragma("unroll") for (int k = 0; k < 2; ++k) dst[m][k] = *(const PG8_LAS bf16x8*)(lds + PG8_SA(b, h) + aoff + m * 2048 + k * 1024); } while (0)
; #define PG8_LDB(dst, b, h) do { _Pragma("unroll") for (int n = 0; n < 2; ++n) _Pragma("unroll") for (int k = 0; k < 2; ++k) dst[n][k] = *(const PG8_LAS bf16x8*)(lds + PG8_SB(b, h) + boff + n * 2048 + k * 1024); } while (0)
; #define PG8_SCHED __builtin_amdgcn_sched_barrier(0)
; template <class Epi, class Sched, bool ALIGN_EPI = false, bool SP2 = false>
; __device__ __forceinline__ void gemm_phase(PG8_LAS unsigned char* lds, const Gemm g, const Sched& S, const Epi& E) {
;     ...
;             PG8_LDB(B0, 1, 0); PG8_LDB(B1, 1, 1); PG8_SCHED; PG8_LDA(At, 1, 0); PG8_STAGE(PG8_SA(0, 1), a2 + hstep, voffA);
	ds_read_b128 v[184:187], v151 offset:32768
	ds_read_b128 v[188:191], v151 offset:33792
	ds_read_b128 v[192:195], v151 offset:34816
	ds_read_b128 v[196:199], v151 offset:35840
	ds_read_b128 v[200:203], v151 offset:36864
	ds_read_b128 v[204:207], v151 offset:37888
	ds_read_b128 v[208:211], v151 offset:38912
	ds_read_b128 v[212:215], v151 offset:39936
	global_load_lds_dwordx4 v134, s[44:45]

; #define PG8_STAGE(bufoff, gbase, voff) do { _Pragma("unroll") for (int _i = 0; _i < 2; ++_i) \
;         __builtin_amdgcn_global_load_lds((const unsigned*)((const char*)(gbase) + (voff)[_i]), (PG8_LAS unsigned*)(lds + (bufoff) + ldsw + _i * 8192), 16, 0, 0); } while (0)
; #define PG8_LDA(dst, b, h) do { _Pragma("unroll") for (int m = 0; m < 4; ++m) _Pragma("unroll") for (int k = 0; k < 2; ++k) dst[m][k] = *(const PG8_LAS bf16x8*)(lds + PG8_SA(b, h) + aoff + m * 2048 + k * 1024); } while (0)
; #define PG8_LDB(dst, b, h) do { _Pragma("unroll") for (int n = 0; n < 2; ++n) _Pragma("unroll") for (int k = 0; k < 2; ++k) dst[n][k] = *(const PG8_LAS bf16x8*)(lds + PG8_SB(b, h) + boff + n * 2048 + k * 1024); } while (0)
; #define PG8_MMA(ai, bj, At, Bt) do { __builtin_amdgcn_s_setprio(1); _Pragma("unroll") for (int m = 0; m < 4; ++m) _Pragma("unroll") for (int n = 0; n < 2; ++n) _Pragma("unroll") for (int k = 0; k < 2; ++k) \
;         acc[ai][bj][m][n] = __builtin_amdgcn_mfma_f32_16x16x32_bf16(Bt[n][k], At[m][k], acc[ai][bj][m][n], 0, 0, 0); __builtin_amdgcn_s_setprio(0); } while (0)
; #define PG8_WAIT_V(n) asm volatile("s_waitcnt vmcnt(" #n ")" ::: "memory")
; #define PG8_WAIT_L(n) asm volatile("s_waitcnt lgkmcnt(" #n ")" ::: "memory")
; #define PG8_BAR __builtin_amdgcn_s_barrier()
; #define PG8_SCHED __builtin_amdgcn_sched_barrier(0)
; template <class Epi, class Sched, bool ALIGN_EPI = false, bool SP2 = false>
; __device__ __forceinline__ void gemm_phase(PG8_LAS unsigned char* lds, const Gemm g, const Sched& S, const Epi& E) {
;     ...
;             PG8_LDB(B0, 1, 0); PG8_LDB(B1, 1, 1); PG8_SCHED; PG8_LDA(At, 1, 0); PG8_STAGE(PG8_SA(0, 1), a2 + hstep, voffA);
;             PG8_WAIT_V(8); PG8_WAIT_L(0); PG8_BAR; PG8_MMA(0, 0, At, B0); PG8_MMA(0, 1, At, B1); PG8_BAR; PG8_SCHED;
	s_mov_b32 m0, s53
	s_nop 0
	global_load_lds_dwordx4 v130, s[44:45]
	s_waitcnt vmcnt(8)
	s_waitcnt lgkmcnt(0)

; #define PG8_MMA(ai, bj, At, Bt) do { __builtin_amdgcn_s_setprio(1); _Pragma("unroll") for (int m = 0; m < 4; ++m) _Pragma("unroll") for (int n = 0; n < 2; ++n) _Pragma("unroll") for (int k = 0; k < 2; ++k) \
;         acc[ai][bj][m][n] = __builtin_amdgcn_mfma_f32_16x16x32_bf16(Bt[n][k], At[m][k], acc[ai][bj][m][n], 0, 0, 0); __builtin_amdgcn_s_setprio(0); } while (0)
; #define PG8_WAIT_V(n) asm volatile("s_waitcnt vmcnt(" #n ")" ::: "memory")
; #define PG8_WAIT_L(n) asm volatile("s_waitcnt lgkmcnt(" #n ")" ::: "memory")
; #define PG8_BAR __builtin_amdgcn_s_barrier()
; #define PG8_SCHED __builtin_amdgcn_sched_barrier(0)
; template <class Epi, class Sched, bool ALIGN_EPI = false, bool SP2 = false>
; __device__ __forceinline__ void gemm_phase(PG8_LAS unsigned char* lds, const Gemm g, const Sched& S, const Epi& E) {
;     ...
;             PG8_WAIT_V(8); PG8_WAIT_L(0); PG8_BAR; PG8_MMA(0, 0, At, B0); PG8_MMA(0, 1, At, B1); PG8_BAR; PG8_SCHED;
	s_barrier

; #define PG8_MMA(ai, bj, At, Bt) do { __builtin_amdgcn_s_setprio(1); _Pragma("unroll") for (int m = 0; m < 4; ++m) _Pragma("unroll") for (int n = 0; n < 2; ++n) _Pragma("unroll") for (int k = 0; k < 2; ++k) \
;         acc[ai][bj][m][n] = __builtin_amdgcn_mfma_f32_16x16x32_bf16(Bt[n][k], At[m][k], acc[ai][bj][m][n], 0, 0, 0); __builtin_amdgcn_s_setprio(0); } while (0)
; #define PG8_WAIT_V(n) asm volatile("s_waitcnt vmcnt(" #n ")" ::: "memory")
; #define PG8_WAIT_L(n) asm volatile("s_waitcnt lgkmcnt(" #n ")" ::: "memory")
; #define PG8_BAR __builtin_amdgcn_s_barrier()
; #define PG8_SCHED __builtin_amdgcn_sched_barrier(0)
; template <class Epi, class Sched, bool ALIGN_EPI = false, bool SP2 = false>
; __device__ __forceinline__ void gemm_phase(PG8_LAS unsigned char* lds, const Gemm g, const Sched& S, const Epi& E) {
;     ...
;             PG8_WAIT_V(8); PG8_WAIT_L(0); PG8_BAR; PG8_MMA(0, 0, At, B0); PG8_MMA(0, 1, At, B1); PG8_BAR; PG8_SCHED;
	v_mfma_f32_16x16x32_bf16 v[124:127], v[152:155], v[184:187], v[124:127]
	v_mfma_f32_16x16x32_bf16 v[120:123], v[160:163], v[184:187], v[120:123]
	v_mfma_f32_16x16x32_bf16 v[116:119], v[152:155], v[192:195], v[116:119]
	v_mfma_f32_16x16x32_bf16 v[112:115], v[160:163], v[192:195], v[112:115]
	v_mfma_f32_16x16x32_bf16 v[100:103], v[152:155], v[200:203], v[100:103]
	v_mfma_f32_16x16x32_bf16 v[96:99], v[160:163], v[200:203], v[96:99]
	v_mfma_f32_16x16x32_bf16 v[84:87], v[152:155], v[208:211], v[84:87]
	v_mfma_f32_16x16x32_bf16 v[80:83], v[160:163], v[208:211], v[80:83]
	v_mfma_f32_16x16x32_bf16 v[124:127], v[156:159], v[188:191], v[124:127]
	v_mfma_f32_16x16x32_bf16 v[120:123], v[164:167], v[188:191], v[120:123]
	v_mfma_f32_16x16x32_bf16 v[116:119], v[156:159], v[196:199], v[116:119]
	v_mfma_f32_16x16x32_bf16 v[112:115], v[164:167], v[196:199], v[112:115]
	v_mfma_f32_16x16x32_bf16 v[100:103], v[156:159], v[204:207], v[100:103]
	v_mfma_f32_16x16x32_bf16 v[96:99], v[164:167], v[204:207], v[96:99]
	v_mfma_f32_16x16x32_bf16 v[84:87], v[156:159], v[212:215], v[84:87]
	v_mfma_f32_16x16x32_bf16 v[80:83], v[164:167], v[212:215], v[80:83]


; #define PG8_MMA(ai, bj, At, Bt) do { __builtin_amdgcn_s_setprio(1); _Pragma("unroll") for (int m = 0; m < 4; ++m) _Pragma("unroll") for (int n = 0; n < 2; ++n) _Pragma("unroll") for (int k = 0; k < 2; ++k) \
;         acc[ai][bj][m][n] = __builtin_amdgcn_mfma_f32_16x16x32_bf16(Bt[n][k], At[m][k], acc[ai][bj][m][n], 0, 0, 0); __builtin_amdgcn_s_setprio(0); } while (0)
; #define PG8_WAIT_V(n) asm volatile("s_waitcnt vmcnt(" #n ")" ::: "memory")
; #define PG8_WAIT_L(n) asm volatile("s_waitcnt lgkmcnt(" #n ")" ::: "memory")
; #define PG8_BAR __builtin_amdgcn_s_barrier()
; #define PG8_SCHED __builtin_amdgcn_sched_barrier(0)
; template <class Epi, class Sched, bool ALIGN_EPI = false, bool SP2 = false>
; __device__ __forceinline__ void gemm_phase(PG8_LAS unsigned char* lds, const Gemm g, const Sched& S, const Epi& E) {
;     ...
;             PG8_WAIT_V(8); PG8_WAIT_L(0); PG8_BAR; PG8_MMA(0, 0, At, B0); PG8_MMA(0, 1, At, B1); PG8_BAR; PG8_SCHED;
	v_mfma_f32_16x16x32_bf16 v[108:111], v[168:171], v[184:187], v[108:111]
	v_mfma_f32_16x16x32_bf16 v[104:107], v[176:179], v[184:187], v[104:107]
	v_mfma_f32_16x16x32_bf16 v[92:95], v[168:171], v[192:195], v[92:95]
	v_mfma_f32_16x16x32_bf16 v[88:91], v[176:179], v[192:195], v[88:91]
	v_mfma_f32_16x16x32_bf16 v[76:79], v[168:171], v[200:203], v[76:79]
	v_mfma_f32_16x16x32_bf16 v[72:75], v[176:179], v[200:203], v[72:75]
	v_mfma_f32_16x16x32_bf16 v[68:71], v[168:171], v[208:211], v[68:71]
	v_mfma_f32_16x16x32_bf16 v[64:67], v[176:179], v[208:211], v[64:67]
	v_mfma_f32_16x16x32_bf16 v[108:111], v[172:175], v[188:191], v[108:111]
	v_mfma_f32_16x16x32_bf16 v[104:107], v[180:183], v[188:191], v[104:107]
	v_mfma_f32_16x16x32_bf16 v[92:95], v[172:175], v[196:199], v[92:95]
	v_mfma_f32_16x16x32_bf16 v[88:91], v[180:183], v[196:199], v[88:91]
	v_mfma_f32_16x16x32_bf16 v[76:79], v[172:175], v[204:207], v[76:79]
	v_mfma_f32_16x16x32_bf16 v[72:75], v[180:183], v[204:207], v[72:75]
	v_mfma_f32_16x16x32_bf16 v[68:71], v[172:175], v[212:215], v[68:71]
	v_mfma_f32_16x16x32_bf16 v[64:67], v[180:183], v[212:215], v[64:67]

; #define PG8_STAGE(bufoff, gbase, voff) do { _Pragma("unroll") for (int _i = 0; _i < 2; ++_i) \
;         __builtin_amdgcn_global_load_lds((const unsigned*)((const char*)(gbase) + (voff)[_i]), (PG8_LAS unsigned*)(lds + (bufoff) + ldsw + _i * 8192), 16, 0, 0); } while (0)
; #define PG8_LDA(dst, b, h) do { _Pragma("unroll") for (int m = 0; m < 4; ++m) _Pragma("unroll") for (int k = 0; k < 2; ++k) dst[m][k] = *(const PG8_LAS bf16x8*)(lds + PG8_SA(b, h) + aoff + m * 2048 + k * 1024); } while (0)
; #define PG8_MMA(ai, bj, At, Bt) do { __builtin_amdgcn_s_setprio(1); _Pragma("unroll") for (int m = 0; m < 4; ++m) _Pragma("unroll") for (int n = 0; n < 2; ++n) _Pragma("unroll") for (int k = 0; k < 2; ++k) \
;         acc[ai][bj][m][n] = __builtin_amdgcn_mfma_f32_16x16x32_bf16(Bt[n][k], At[m][k], acc[ai][bj][m][n], 0, 0, 0); __builtin_amdgcn_s_setprio(0); } while (0)
; #define PG8_WAIT_V(n) asm volatile("s_waitcnt vmcnt(" #n ")" ::: "memory")
; #define PG8_WAIT_L(n) asm volatile("s_waitcnt lgkmcnt(" #n ")" ::: "memory")
; #define PG8_BAR __builtin_amdgcn_s_barrier()
; #define PG8_SCHED __builtin_amdgcn_sched_barrier(0)
; template <class Epi, class Sched, bool ALIGN_EPI = false, bool SP2 = false>
; __device__ __forceinline__ void gemm_phase(PG8_LAS unsigned char* lds, const Gemm g, const Sched& S, const Epi& E) {
;     ...
;             PG8_WAIT_V(8); PG8_WAIT_L(0); PG8_BAR; PG8_MMA(0, 0, At, B0); PG8_MMA(0, 1, At, B1); PG8_BAR; PG8_SCHED;
;             PG8_LDA(At, 1, 1); PG8_STAGE(PG8_SB(1, 0), b3, voffB); PG8_STAGE(PG8_SB(1, 1), b3 + hstep, voffB); PG8_STAGE(PG8_SA(1, 0), a3, voffA);
	s_barrier
	s_add_i32 s44, s69, s48

; #define PG8_STAGE(bufoff, gbase, voff) do { _Pragma("unroll") for (int _i = 0; _i < 2; ++_i) \
;         __builtin_amdgcn_global_load_lds((const unsigned*)((const char*)(gbase) + (voff)[_i]), (PG8_LAS unsigned*)(lds + (bufoff) + ldsw + _i * 8192), 16, 0, 0); } while (0)
; #define PG8_LDA(dst, b, h) do { _Pragma("unroll") for (int m = 0; m < 4; ++m) _Pragma("unroll") for (int k = 0; k < 2; ++k) dst[m][k] = *(const PG8_LAS bf16x8*)(lds + PG8_SA(b, h) + aoff + m * 2048 + k * 1024); } while (0)
; template <class Epi, class Sched, bool ALIGN_EPI = false, bool SP2 = false>
; __device__ __forceinline__ void gemm_phase(PG8_LAS unsigned char* lds, const Gemm g, const Sched& S, const Epi& E) {
;     ...
;             PG8_LDA(At, 1, 1); PG8_STAGE(PG8_SB(1, 0), b3, voffB); PG8_STAGE(PG8_SB(1, 1), b3 + hstep, voffB); PG8_STAGE(PG8_SA(1, 0), a3, voffA);
	s_mov_b32 m0, s44
	ds_read_b128 v[184:187], v151 offset:49152
	ds_read_b128 v[188:191], v151 offset:50176
	ds_read_b128 v[192:195], v151 offset:51200
	ds_read_b128 v[196:199], v151 offset:52224
	ds_read_b128 v[200:203], v151 offset:53248
	ds_read_b128 v[204:207], v151 offset:54272
	ds_read_b128 v[208:211], v151 offset:55296
	ds_read_b128 v[212:215], v151 offset:56320
	global_load_lds_dwordx4 v250, s[96:97]
	s_add_i32 m0, s44, 0x2000
	s_add_u32 s42, s42, 0x80080

; #define PG8_STAGE(bufoff, gbase, voff) do { _Pragma("unroll") for (int _i = 0; _i < 2; ++_i) \
;         __builtin_amdgcn_global_load_lds((const unsigned*)((const char*)(gbase) + (voff)[_i]), (PG8_LAS unsigned*)(lds + (bufoff) + ldsw + _i * 8192), 16, 0, 0); } while (0)
; #define PG8_LDA(dst, b, h) do { _Pragma("unroll") for (int m = 0; m < 4; ++m) _Pragma("unroll") for (int k = 0; k < 2; ++k) dst[m][k] = *(const PG8_LAS bf16x8*)(lds + PG8_SA(b, h) + aoff + m * 2048 + k * 1024); } while (0)
; template <class Epi, class Sched, bool ALIGN_EPI = false, bool SP2 = false>
; __device__ __forceinline__ void gemm_phase(PG8_LAS unsigned char* lds, const Gemm g, const Sched& S, const Epi& E) {
;     ...
;             PG8_LDA(At, 1, 1); PG8_STAGE(PG8_SB(1, 0), b3, voffB); PG8_STAGE(PG8_SB(1, 1), b3 + hstep, voffB); PG8_STAGE(PG8_SA(1, 0), a3, voffA);
	s_addc_u32 s43, s43, 0
	s_add_i32 s44, s70, s48
	global_load_lds_dwordx4 v251, s[96:97]

; #define PG8_STAGE(bufoff, gbase, voff) do { _Pragma("unroll") for (int _i = 0; _i < 2; ++_i) \
;         __builtin_amdgcn_global_load_lds((const unsigned*)((const char*)(gbase) + (voff)[_i]), (PG8_LAS unsigned*)(lds + (bufoff) + ldsw + _i * 8192), 16, 0, 0); } while (0)
; #define PG8_LDA(dst, b, h) do { _Pragma("unroll") for (int m = 0; m < 4; ++m) _Pragma("unroll") for (int k = 0; k < 2; ++k) dst[m][k] = *(const PG8_LAS bf16x8*)(lds + PG8_SA(b, h) + aoff + m * 2048 + k * 1024); } while (0)
; template <class Epi, class Sched, bool ALIGN_EPI = false, bool SP2 = false>
; __device__ __forceinline__ void gemm_phase(PG8_LAS unsigned char* lds, const Gemm g, const Sched& S, const Epi& E) {
;     ...
;             PG8_LDA(At, 1, 1); PG8_STAGE(PG8_SB(1, 0), b3, voffB); PG8_STAGE(PG8_SB(1, 1), b3 + hstep, voffB); PG8_STAGE(PG8_SA(1, 0), a3, voffA);
	s_mov_b32 m0, s44
	s_nop 0
	global_load_lds_dwordx4 v132, s[42:43]

; #define PG8_STAGE(bufoff, gbase, voff) do { _Pragma("unroll") for (int _i = 0; _i < 2; ++_i) \
;         __builtin_amdgcn_global_load_lds((const unsigned*)((const char*)(gbase) + (voff)[_i]), (PG8_LAS unsigned*)(lds + (bufoff) + ldsw + _i * 8192), 16, 0, 0); } while (0)
; #define PG8_LDA(dst, b, h) do { _Pragma("unroll") for (int m = 0; m < 4; ++m) _Pragma("unroll") for (int k = 0; k < 2; ++k) dst[m][k] = *(const PG8_LAS bf16x8*)(lds + PG8_SA(b, h) + aoff + m * 2048 + k * 1024); } while (0)
; template <class Epi, class Sched, bool ALIGN_EPI = false, bool SP2 = false>
; __device__ __forceinline__ void gemm_phase(PG8_LAS unsigned char* lds, const Gemm g, const Sched& S, const Epi& E) {
;     ...
;             PG8_LDA(At, 1, 1); PG8_STAGE(PG8_SB(1, 0), b3, voffB); PG8_STAGE(PG8_SB(1, 1), b3 + hstep, voffB); PG8_STAGE(PG8_SA(1, 0), a3, voffA);
	s_add_i32 m0, s44, 0x2000
	s_nop 0
	global_load_lds_dwordx4 v128, s[42:43]

; #define PG8_STAGE(bufoff, gbase, voff) do { _Pragma("unroll") for (int _i = 0; _i < 2; ++_i) \
;         __builtin_amdgcn_global_load_lds((const unsigned*)((const char*)(gbase) + (voff)[_i]), (PG8_LAS unsigned*)(lds + (bufoff) + ldsw + _i * 8192), 16, 0, 0); } while (0)
; #define PG8_LDA(dst, b, h) do { _Pragma("unroll") for (int m = 0; m < 4; ++m) _Pragma("unroll") for (int k = 0; k < 2; ++k) dst[m][k] = *(const PG8_LAS bf16x8*)(lds + PG8_SA(b, h) + aoff + m * 2048 + k * 1024); } while (0)
; template <class Epi, class Sched, bool ALIGN_EPI = false, bool SP2 = false>
; __device__ __forceinline__ void gemm_phase(PG8_LAS unsigned char* lds, const Gemm g, const Sched& S, const Epi& E) {
;     ...
;             PG8_LDA(At, 1, 1); PG8_STAGE(PG8_SB(1, 0), b3, voffB); PG8_STAGE(PG8_SB(1, 1), b3 + hstep, voffB); PG8_STAGE(PG8_SA(1, 0), a3, voffA);
	s_mov_b32 m0, s55
	s_nop 0
	global_load_lds_dwordx4 v252, s[98:99]

; #define PG8_STAGE(bufoff, gbase, voff) do { _Pragma("unroll") for (int _i = 0; _i < 2; ++_i) \
;         __builtin_amdgcn_global_load_lds((const unsigned*)((const char*)(gbase) + (voff)[_i]), (PG8_LAS unsigned*)(lds + (bufoff) + ldsw + _i * 8192), 16, 0, 0); } while (0)
; #define PG8_LDA(dst, b, h) do { _Pragma("unroll") for (int m = 0; m < 4; ++m) _Pragma("unroll") for (int k = 0; k < 2; ++k) dst[m][k] = *(const PG8_LAS bf16x8*)(lds + PG8_SA(b, h) + aoff + m * 2048 + k * 1024); } while (0)
; #define PG8_MMA(ai, bj, At, Bt) do { __builtin_amdgcn_s_setprio(1); _Pragma("unroll") for (int m = 0; m < 4; ++m) _Pragma("unroll") for (int n = 0; n < 2; ++n) _Pragma("unroll") for (int k = 0; k < 2; ++k) \
;         acc[ai][bj][m][n] = __builtin_amdgcn_mfma_f32_16x16x32_bf16(Bt[n][k], At[m][k], acc[ai][bj][m][n], 0, 0, 0); __builtin_amdgcn_s_setprio(0); } while (0)
; #define PG8_WAIT_V(n) asm volatile("s_waitcnt vmcnt(" #n ")" ::: "memory")
; #define PG8_WAIT_L(n) asm volatile("s_waitcnt lgkmcnt(" #n ")" ::: "memory")
; #define PG8_BAR __builtin_amdgcn_s_barrier()
; #define PG8_SCHED __builtin_amdgcn_sched_barrier(0)
; template <class Epi, class Sched, bool ALIGN_EPI = false, bool SP2 = false>
; __device__ __forceinline__ void gemm_phase(PG8_LAS unsigned char* lds, const Gemm g, const Sched& S, const Epi& E) {
;     ...
;             PG8_LDA(At, 1, 1); PG8_STAGE(PG8_SB(1, 0), b3, voffB); PG8_STAGE(PG8_SB(1, 1), b3 + hstep, voffB); PG8_STAGE(PG8_SA(1, 0), a3, voffA);
;             PG8_WAIT_V(8); PG8_WAIT_L(0); PG8_BAR; PG8_MMA(1, 0, At, B0); PG8_MMA(1, 1, At, B1); PG8_BAR; PG8_SCHED;
	s_mov_b32 m0, s56
	s_nop 0
	global_load_lds_dwordx4 v253, s[98:99]
	s_waitcnt vmcnt(8)
	s_waitcnt lgkmcnt(0)

; #define PG8_MMA(ai, bj, At, Bt) do { __builtin_amdgcn_s_setprio(1); _Pragma("unroll") for (int m = 0; m < 4; ++m) _Pragma("unroll") for (int n = 0; n < 2; ++n) _Pragma("unroll") for (int k = 0; k < 2; ++k) \
;         acc[ai][bj][m][n] = __builtin_amdgcn_mfma_f32_16x16x32_bf16(Bt[n][k], At[m][k], acc[ai][bj][m][n], 0, 0, 0); __builtin_amdgcn_s_setprio(0); } while (0)
; #define PG8_WAIT_V(n) asm volatile("s_waitcnt vmcnt(" #n ")" ::: "memory")
; #define PG8_WAIT_L(n) asm volatile("s_waitcnt lgkmcnt(" #n ")" ::: "memory")
; #define PG8_BAR __builtin_amdgcn_s_barrier()
; #define PG8_SCHED __builtin_amdgcn_sched_barrier(0)
; template <class Epi, class Sched, bool ALIGN_EPI = false, bool SP2 = false>
; __device__ __forceinline__ void gemm_phase(PG8_LAS unsigned char* lds, const Gemm g, const Sched& S, const Epi& E) {
;     ...
;             PG8_WAIT_V(8); PG8_WAIT_L(0); PG8_BAR; PG8_MMA(1, 0, At, B0); PG8_MMA(1, 1, At, B1); PG8_BAR; PG8_SCHED;
	s_barrier

; #define PG8_MMA(ai, bj, At, Bt) do { __builtin_amdgcn_s_setprio(1); _Pragma("unroll") for (int m = 0; m < 4; ++m) _Pragma("unroll") for (int n = 0; n < 2; ++n) _Pragma("unroll") for (int k = 0; k < 2; ++k) \
;         acc[ai][bj][m][n] = __builtin_amdgcn_mfma_f32_16x16x32_bf16(Bt[n][k], At[m][k], acc[ai][bj][m][n], 0, 0, 0); __builtin_amdgcn_s_setprio(0); } while (0)
; #define PG8_WAIT_V(n) asm volatile("s_waitcnt vmcnt(" #n ")" ::: "memory")
; #define PG8_WAIT_L(n) asm volatile("s_waitcnt lgkmcnt(" #n ")" ::: "memory")
; #define PG8_BAR __builtin_amdgcn_s_barrier()
; #define PG8_SCHED __builtin_amdgcn_sched_barrier(0)
; template <class Epi, class Sched, bool ALIGN_EPI = false, bool SP2 = false>
; __device__ __forceinline__ void gemm_phase(PG8_LAS unsigned char* lds, const Gemm g, const Sched& S, const Epi& E) {
;     ...
;             PG8_WAIT_V(8); PG8_WAIT_L(0); PG8_BAR; PG8_MMA(1, 0, At, B0); PG8_MMA(1, 1, At, B1); PG8_BAR; PG8_SCHED;
	v_mfma_f32_16x16x32_bf16 v[60:63], v[152:155], v[184:187], v[60:63]
	v_mfma_f32_16x16x32_bf16 v[56:59], v[160:163], v[184:187], v[56:59]
	v_mfma_f32_16x16x32_bf16 v[52:55], v[152:155], v[192:195], v[52:55]
	v_mfma_f32_16x16x32_bf16 v[48:51], v[160:163], v[192:195], v[48:51]
	v_mfma_f32_16x16x32_bf16 v[36:39], v[152:155], v[200:203], v[36:39]
	v_mfma_f32_16x16x32_bf16 v[32:35], v[160:163], v[200:203], v[32:35]
	v_mfma_f32_16x16x32_bf16 v[20:23], v[152:155], v[208:211], v[20:23]
	v_mfma_f32_16x16x32_bf16 v[16:19], v[160:163], v[208:211], v[16:19]
	v_mfma_f32_16x16x32_bf16 v[60:63], v[156:159], v[188:191], v[60:63]
	v_mfma_f32_16x16x32_bf16 v[56:59], v[164:167], v[188:191], v[56:59]
	v_mfma_f32_16x16x32_bf16 v[52:55], v[156:159], v[196:199], v[52:55]
	v_mfma_f32_16x16x32_bf16 v[48:51], v[164:167], v[196:199], v[48:51]
	v_mfma_f32_16x16x32_bf16 v[36:39], v[156:159], v[204:207], v[36:39]
	v_mfma_f32_16x16x32_bf16 v[32:35], v[164:167], v[204:207], v[32:35]
	v_mfma_f32_16x16x32_bf16 v[20:23], v[156:159], v[212:215], v[20:23]
	v_mfma_f32_16x16x32_bf16 v[16:19], v[164:167], v[212:215], v[16:19]


; #define PG8_MMA(ai, bj, At, Bt) do { __builtin_amdgcn_s_setprio(1); _Pragma("unroll") for (int m = 0; m < 4; ++m) _Pragma("unroll") for (int n = 0; n < 2; ++n) _Pragma("unroll") for (int k = 0; k < 2; ++k) \
;         acc[ai][bj][m][n] = __builtin_amdgcn_mfma_f32_16x16x32_bf16(Bt[n][k], At[m][k], acc[ai][bj][m][n], 0, 0, 0); __builtin_amdgcn_s_setprio(0); } while (0)
; #define PG8_WAIT_V(n) asm volatile("s_waitcnt vmcnt(" #n ")" ::: "memory")
; #define PG8_WAIT_L(n) asm volatile("s_waitcnt lgkmcnt(" #n ")" ::: "memory")
; #define PG8_BAR __builtin_amdgcn_s_barrier()
; #define PG8_SCHED __builtin_amdgcn_sched_barrier(0)
; template <class Epi, class Sched, bool ALIGN_EPI = false, bool SP2 = false>
; __device__ __forceinline__ void gemm_phase(PG8_LAS unsigned char* lds, const Gemm g, const Sched& S, const Epi& E) {
;     ...
;             PG8_WAIT_V(8); PG8_WAIT_L(0); PG8_BAR; PG8_MMA(1, 0, At, B0); PG8_MMA(1, 1, At, B1); PG8_BAR; PG8_SCHED;
	v_mfma_f32_16x16x32_bf16 v[44:47], v[168:171], v[184:187], v[44:47]
	v_mfma_f32_16x16x32_bf16 v[40:43], v[176:179], v[184:187], v[40:43]
	v_mfma_f32_16x16x32_bf16 v[28:31], v[168:171], v[192:195], v[28:31]
	v_mfma_f32_16x16x32_bf16 v[24:27], v[176:179], v[192:195], v[24:27]
	v_mfma_f32_16x16x32_bf16 v[12:15], v[168:171], v[200:203], v[12:15]
	v_mfma_f32_16x16x32_bf16 v[8:11], v[176:179], v[200:203], v[8:11]
	v_mfma_f32_16x16x32_bf16 v[4:7], v[168:171], v[208:211], v[4:7]
	v_mfma_f32_16x16x32_bf16 v[0:3], v[176:179], v[208:211], v[0:3]
	v_mfma_f32_16x16x32_bf16 v[44:47], v[172:175], v[188:191], v[44:47]
	v_mfma_f32_16x16x32_bf16 v[40:43], v[180:183], v[188:191], v[40:43]
	v_mfma_f32_16x16x32_bf16 v[28:31], v[172:175], v[196:199], v[28:31]
	v_mfma_f32_16x16x32_bf16 v[24:27], v[180:183], v[196:199], v[24:27]
	v_mfma_f32_16x16x32_bf16 v[12:15], v[172:175], v[204:207], v[12:15]
	v_mfma_f32_16x16x32_bf16 v[8:11], v[180:183], v[204:207], v[8:11]
	v_mfma_f32_16x16x32_bf16 v[4:7], v[172:175], v[212:215], v[4:7]
	v_mfma_f32_16x16x32_bf16 v[0:3], v[180:183], v[212:215], v[0:3]

; #define PG8_STAGE(bufoff, gbase, voff) do { _Pragma("unroll") for (int _i = 0; _i < 2; ++_i) \
;         __builtin_amdgcn_global_load_lds((const unsigned*)((const char*)(gbase) + (voff)[_i]), (PG8_LAS unsigned*)(lds + (bufoff) + ldsw + _i * 8192), 16, 0, 0); } while (0)
; #define PG8_LDA(dst, b, h) do { _Pragma("unroll") for (int m = 0; m < 4; ++m) _Pragma("unroll") for (int k = 0; k < 2; ++k) dst[m][k] = *(const PG8_LAS bf16x8*)(lds + PG8_SA(b, h) + aoff + m * 2048 + k * 1024); } while (0)
; #define PG8_WAIT_V(n) asm volatile("s_waitcnt vmcnt(" #n ")" ::: "memory")
; #define PG8_WAIT_L(n) asm volatile("s_waitcnt lgkmcnt(" #n ")" ::: "memory")
; template <class Epi, class Sched, bool ALIGN_EPI = false, bool SP2 = false>
; __device__ __forceinline__ void gemm_phase(PG8_LAS unsigned char* lds, const Gemm g, const Sched& S, const Epi& E) {
;     ...
;         for (int t = 0; t < nt; t += 2) {
;             const bool last = (t == nt - 2);
;             const char* a1 = cA + (size_t)(t + 1) * kstep;
;             const char* a2 = last ? nA : cA + (size_t)(t + 2) * kstep; const char* b2 = last ? nB : cB + (size_t)(t + 2) * kstep;
;             const char* a3 = a2 + kstep; const char* b3 = b2 + kstep;
;             if (last && has_next) S.a_ready(nxt);
;             if constexpr (SP2) {
;             PG8_LDB(B0, 0, 0); PG8_LDB(B1, 0, 1); PG8_SCHED; PG8_LDA(At, 0, 0); PG8_STAGE(PG8_SA(1, 1), a1 + hstep, voffA);
;             PG8_WAIT_V(8); PG8_WAIT_L(0); PG8_BAR; PG8_MMA(0, 0, At, B0); PG8_MMA(0, 1, At, B1); PG8_BAR; PG8_SCHED;
;             PG8_LDA(At, 0, 1); PG8_STAGE(PG8_SB(0, 0), b2, voffB); PG8_STAGE(PG8_SB(0, 1), b2 + hstep, voffB); PG8_STAGE(PG8_SA(0, 0), a2, voffA);
;             PG8_WAIT_V(8); PG8_WAIT_L(0); PG8_BAR; PG8_MMA(1, 0, At, B0); PG8_MMA(1, 1, At, B1); PG8_BAR; PG8_SCHED;
;             PG8_LDB(B0, 1, 0); PG8_LDB(B1, 1, 1); PG8_SCHED; PG8_LDA(At, 1, 0); PG8_STAGE(PG8_SA(0, 1), a2 + hstep, voffA);
;             PG8_WAIT_V(8); PG8_WAIT_L(0); PG8_BAR; PG8_MMA(0, 0, At, B0); PG8_MMA(0, 1, At, B1); PG8_BAR; PG8_SCHED;
;             PG8_LDA(At, 1, 1); PG8_STAGE(PG8_SB(1, 0), b3, voffB); PG8_STAGE(PG8_SB(1, 1), b3 + hstep, voffB); PG8_STAGE(PG8_SA(1, 0), a3, voffA);
;             PG8_WAIT_V(8); PG8_WAIT_L(0); PG8_BAR; PG8_MMA(1, 0, At, B0); PG8_MMA(1, 1, At, B1); PG8_BAR; PG8_SCHED;
;     ...
;         if constexpr (ALIGN_EPI) { if (wr == 0) PG8_BAR; }
	s_barrier
	s_add_i32 s68, s68, 2
	s_add_u32 s40, s40, 0x100
	s_addc_u32 s41, s41, 0
	s_add_u32 s65, s65, 0x100
	s_addc_u32 s67, s67, 0
	s_cmp_gt_u32 s68, 29
	s_cbranch_scc0 .LBB0_66
	s_and_b64 vcc, exec, s[26:27]
	s_cbranch_vccz .LBB0_69
	s_barrier

; #define PG8_STAGE(bufoff, gbase, voff) do { _Pragma("unroll") for (int _i = 0; _i < 2; ++_i) \
;         __builtin_amdgcn_global_load_lds((const unsigned*)((const char*)(gbase) + (voff)[_i]), (PG8_LAS unsigned*)(lds + (bufoff) + ldsw + _i * 8192), 16, 0, 0); } while (0)
; #define PG8_LDA(dst, b, h) do { _Pragma("unroll") for (int m = 0; m < 4; ++m) _Pragma("unroll") for (int k = 0; k < 2; ++k) dst[m][k] = *(const PG8_LAS bf16x8*)(lds + PG8_SA(b, h) + aoff + m * 2048 + k * 1024); } while (0)
; #define PG8_LDB(dst, b, h) do { _Pragma("unroll") for (int n = 0; n < 2; ++n) _Pragma("unroll") for (int k = 0; k < 2; ++k) dst[n][k] = *(const PG8_LAS bf16x8*)(lds + PG8_SB(b, h) + boff + n * 2048 + k * 1024); } while (0)
; #define PG8_SCHED __builtin_amdgcn_sched_barrier(0)
; template <class Epi, class Sched, bool ALIGN_EPI = false, bool SP2 = false>
; __device__ __forceinline__ void gemm_phase(PG8_LAS unsigned char* lds, const Gemm g, const Sched& S, const Epi& E) {
;     ...
;         const char* nA = has_next ? (const char*)g.A + (size_t)nxt.pm * tstep : cA; const char* nB = has_next ? (const char*)g.Bt + (size_t)nxt.pn * tstep : cB;
;         for (int t = 0; t < nt; t += 2) {
;             const bool last = (t == nt - 2);
;             const char* a1 = cA + (size_t)(t + 1) * kstep;
;             const char* a2 = last ? nA : cA + (size_t)(t + 2) * kstep; const char* b2 = last ? nB : cB + (size_t)(t + 2) * kstep;
;             const char* a3 = a2 + kstep; const char* b3 = b2 + kstep;
;             if (last && has_next) S.a_ready(nxt);
;             if constexpr (SP2) {
;             PG8_LDB(B0, 0, 0); PG8_LDB(B1, 0, 1); PG8_SCHED; PG8_LDA(At, 0, 0); PG8_STAGE(PG8_SA(1, 1), a1 + hstep, voffA);
.LBB0_333:
	ds_read_b128 v[64:67], v211
	ds_read_b128 v[68:71], v211 offset:1024
	ds_read_b128 v[72:75], v211 offset:2048
	ds_read_b128 v[76:79], v211 offset:3072
	ds_read_b128 v[144:147], v212
	ds_read_b128 v[148:151], v212 offset:1024
	ds_read_b128 v[152:155], v212 offset:2048
	ds_read_b128 v[156:159], v212 offset:3072
	s_add_u32 s60, s58, 0xfff80080
	s_addc_u32 s61, s59, -1
	s_cmp_eq_u32 s81, 28
	s_cselect_b32 s63, s11, s61
	s_cselect_b32 s62, s51, s60
	s_cselect_b32 s61, s49, s80
	s_cselect_b32 s60, s78, s79

; #define PG8_STAGE(bufoff, gbase, voff) do { _Pragma("unroll") for (int _i = 0; _i < 2; ++_i) \
;         __builtin_amdgcn_global_load_lds((const unsigned*)((const char*)(gbase) + (voff)[_i]), (PG8_LAS unsigned*)(lds + (bufoff) + ldsw + _i * 8192), 16, 0, 0); } while (0)
; #define PG8_LDA(dst, b, h) do { _Pragma("unroll") for (int m = 0; m < 4; ++m) _Pragma("unroll") for (int k = 0; k < 2; ++k) dst[m][k] = *(const PG8_LAS bf16x8*)(lds + PG8_SA(b, h) + aoff + m * 2048 + k * 1024); } while (0)
; #define PG8_LDB(dst, b, h) do { _Pragma("unroll") for (int n = 0; n < 2; ++n) _Pragma("unroll") for (int k = 0; k < 2; ++k) dst[n][k] = *(const PG8_LAS bf16x8*)(lds + PG8_SB(b, h) + boff + n * 2048 + k * 1024); } while (0)
; #define PG8_SCHED __builtin_amdgcn_sched_barrier(0)
; template <class Epi, class Sched, bool ALIGN_EPI = false, bool SP2 = false>
; __device__ __forceinline__ void gemm_phase(PG8_LAS unsigned char* lds, const Gemm g, const Sched& S, const Epi& E) {
;     ...
;             PG8_LDB(B0, 0, 0); PG8_LDB(B1, 0, 1); PG8_SCHED; PG8_LDA(At, 0, 0); PG8_STAGE(PG8_SA(1, 1), a1 + hstep, voffA);
	s_add_i32 m0, s57, 0xc000
	ds_read_b128 v[176:179], v213
	ds_read_b128 v[180:183], v213 offset:1024
	ds_read_b128 v[184:187], v213 offset:2048
	ds_read_b128 v[188:191], v213 offset:3072
	ds_read_b128 v[192:195], v213 offset:4096
	ds_read_b128 v[196:199], v213 offset:5120
	ds_read_b128 v[200:203], v213 offset:6144
	ds_read_b128 v[204:207], v213 offset:7168
	global_load_lds_dwordx4 v168, s[58:59]

; #define PG8_STAGE(bufoff, gbase, voff) do { _Pragma("unroll") for (int _i = 0; _i < 2; ++_i) \
;         __builtin_amdgcn_global_load_lds((const unsigned*)((const char*)(gbase) + (voff)[_i]), (PG8_LAS unsigned*)(lds + (bufoff) + ldsw + _i * 8192), 16, 0, 0); } while (0)
; #define PG8_LDA(dst, b, h) do { _Pragma("unroll") for (int m = 0; m < 4; ++m) _Pragma("unroll") for (int k = 0; k < 2; ++k) dst[m][k] = *(const PG8_LAS bf16x8*)(lds + PG8_SA(b, h) + aoff + m * 2048 + k * 1024); } while (0)
; #define PG8_LDB(dst, b, h) do { _Pragma("unroll") for (int n = 0; n < 2; ++n) _Pragma("unroll") for (int k = 0; k < 2; ++k) dst[n][k] = *(const PG8_LAS bf16x8*)(lds + PG8_SB(b, h) + boff + n * 2048 + k * 1024); } while (0)
; #define PG8_MMA(ai, bj, At, Bt) do { __builtin_amdgcn_s_setprio(1); _Pragma("unroll") for (int m = 0; m < 4; ++m) _Pragma("unroll") for (int n = 0; n < 2; ++n) _Pragma("unroll") for (int k = 0; k < 2; ++k) \
;         acc[ai][bj][m][n] = __builtin_amdgcn_mfma_f32_16x16x32_bf16(Bt[n][k], At[m][k], acc[ai][bj][m][n], 0, 0, 0); __builtin_amdgcn_s_setprio(0); } while (0)
; #define PG8_WAIT_V(n) asm volatile("s_waitcnt vmcnt(" #n ")" ::: "memory")
; #define PG8_WAIT_L(n) asm volatile("s_waitcnt lgkmcnt(" #n ")" ::: "memory")
; #define PG8_BAR __builtin_amdgcn_s_barrier()
; #define PG8_SCHED __builtin_amdgcn_sched_barrier(0)
; template <class Epi, class Sched, bool ALIGN_EPI = false, bool SP2 = false>
; __device__ __forceinline__ void gemm_phase(PG8_LAS unsigned char* lds, const Gemm g, const Sched& S, const Epi& E) {
;     ...
;             PG8_LDB(B0, 0, 0); PG8_LDB(B1, 0, 1); PG8_SCHED; PG8_LDA(At, 0, 0); PG8_STAGE(PG8_SA(1, 1), a1 + hstep, voffA);
;             PG8_WAIT_V(8); PG8_WAIT_L(0); PG8_BAR; PG8_MMA(0, 0, At, B0); PG8_MMA(0, 1, At, B1); PG8_BAR; PG8_SCHED;
	s_add_i32 m0, s57, 0xe000
	s_nop 0
	global_load_lds_dwordx4 v170, s[58:59]
	s_waitcnt vmcnt(8)
	s_waitcnt lgkmcnt(0)

; #define PG8_MMA(ai, bj, At, Bt) do { __builtin_amdgcn_s_setprio(1); _Pragma("unroll") for (int m = 0; m < 4; ++m) _Pragma("unroll") for (int n = 0; n < 2; ++n) _Pragma("unroll") for (int k = 0; k < 2; ++k) \
;         acc[ai][bj][m][n] = __builtin_amdgcn_mfma_f32_16x16x32_bf16(Bt[n][k], At[m][k], acc[ai][bj][m][n], 0, 0, 0); __builtin_amdgcn_s_setprio(0); } while (0)
; #define PG8_WAIT_V(n) asm volatile("s_waitcnt vmcnt(" #n ")" ::: "memory")
; #define PG8_WAIT_L(n) asm volatile("s_waitcnt lgkmcnt(" #n ")" ::: "memory")
; #define PG8_BAR __builtin_amdgcn_s_barrier()
; #define PG8_SCHED __builtin_amdgcn_sched_barrier(0)
; template <class Epi, class Sched, bool ALIGN_EPI = false, bool SP2 = false>
; __device__ __forceinline__ void gemm_phase(PG8_LAS unsigned char* lds, const Gemm g, const Sched& S, const Epi& E) {
;     ...
;             PG8_WAIT_V(8); PG8_WAIT_L(0); PG8_BAR; PG8_MMA(0, 0, At, B0); PG8_MMA(0, 1, At, B1); PG8_BAR; PG8_SCHED;
	s_barrier

; #define PG8_MMA(ai, bj, At, Bt) do { __builtin_amdgcn_s_setprio(1); _Pragma("unroll") for (int m = 0; m < 4; ++m) _Pragma("unroll") for (int n = 0; n < 2; ++n) _Pragma("unroll") for (int k = 0; k < 2; ++k) \
;         acc[ai][bj][m][n] = __builtin_amdgcn_mfma_f32_16x16x32_bf16(Bt[n][k], At[m][k], acc[ai][bj][m][n], 0, 0, 0); __builtin_amdgcn_s_setprio(0); } while (0)
; #define PG8_WAIT_V(n) asm volatile("s_waitcnt vmcnt(" #n ")" ::: "memory")
; #define PG8_WAIT_L(n) asm volatile("s_waitcnt lgkmcnt(" #n ")" ::: "memory")
; #define PG8_BAR __builtin_amdgcn_s_barrier()
; #define PG8_SCHED __builtin_amdgcn_sched_barrier(0)
; template <class Epi, class Sched, bool ALIGN_EPI = false, bool SP2 = false>
; __device__ __forceinline__ void gemm_phase(PG8_LAS unsigned char* lds, const Gemm g, const Sched& S, const Epi& E) {
;     ...
;             PG8_WAIT_V(8); PG8_WAIT_L(0); PG8_BAR; PG8_MMA(0, 0, At, B0); PG8_MMA(0, 1, At, B1); PG8_BAR; PG8_SCHED;
	v_mfma_f32_16x16x32_bf16 v[140:143], v[64:67], v[176:179], v[140:143]
	v_mfma_f32_16x16x32_bf16 v[136:139], v[72:75], v[176:179], v[136:139]
	v_mfma_f32_16x16x32_bf16 v[124:127], v[64:67], v[184:187], v[124:127]
	v_mfma_f32_16x16x32_bf16 v[120:123], v[72:75], v[184:187], v[120:123]
	v_mfma_f32_16x16x32_bf16 v[108:111], v[64:67], v[192:195], v[108:111]
	v_mfma_f32_16x16x32_bf16 v[104:107], v[72:75], v[192:195], v[104:107]
	v_mfma_f32_16x16x32_bf16 v[92:95], v[64:67], v[200:203], v[92:95]
	v_mfma_f32_16x16x32_bf16 v[88:91], v[72:75], v[200:203], v[88:91]
	v_mfma_f32_16x16x32_bf16 v[140:143], v[68:71], v[180:183], v[140:143]
	v_mfma_f32_16x16x32_bf16 v[136:139], v[76:79], v[180:183], v[136:139]
	v_mfma_f32_16x16x32_bf16 v[124:127], v[68:71], v[188:191], v[124:127]
	v_mfma_f32_16x16x32_bf16 v[120:123], v[76:79], v[188:191], v[120:123]
	v_mfma_f32_16x16x32_bf16 v[108:111], v[68:71], v[196:199], v[108:111]
	v_mfma_f32_16x16x32_bf16 v[104:107], v[76:79], v[196:199], v[104:107]
	v_mfma_f32_16x16x32_bf16 v[92:95], v[68:71], v[204:207], v[92:95]
	v_mfma_f32_16x16x32_bf16 v[88:91], v[76:79], v[204:207], v[88:91]


; #define PG8_MMA(ai, bj, At, Bt) do { __builtin_amdgcn_s_setprio(1); _Pragma("unroll") for (int m = 0; m < 4; ++m) _Pragma("unroll") for (int n = 0; n < 2; ++n) _Pragma("unroll") for (int k = 0; k < 2; ++k) \
;         acc[ai][bj][m][n] = __builtin_amdgcn_mfma_f32_16x16x32_bf16(Bt[n][k], At[m][k], acc[ai][bj][m][n], 0, 0, 0); __builtin_amdgcn_s_setprio(0); } while (0)
; #define PG8_WAIT_V(n) asm volatile("s_waitcnt vmcnt(" #n ")" ::: "memory")
; #define PG8_WAIT_L(n) asm volatile("s_waitcnt lgkmcnt(" #n ")" ::: "memory")
; #define PG8_BAR __builtin_amdgcn_s_barrier()
; #define PG8_SCHED __builtin_amdgcn_sched_barrier(0)
; template <class Epi, class Sched, bool ALIGN_EPI = false, bool SP2 = false>
; __device__ __forceinline__ void gemm_phase(PG8_LAS unsigned char* lds, const Gemm g, const Sched& S, const Epi& E) {
;     ...
;             PG8_WAIT_V(8); PG8_WAIT_L(0); PG8_BAR; PG8_MMA(0, 0, At, B0); PG8_MMA(0, 1, At, B1); PG8_BAR; PG8_SCHED;
	v_mfma_f32_16x16x32_bf16 v[132:135], v[144:147], v[176:179], v[132:135]
	v_mfma_f32_16x16x32_bf16 v[128:131], v[152:155], v[176:179], v[128:131]
	v_mfma_f32_16x16x32_bf16 v[116:119], v[144:147], v[184:187], v[116:119]
	v_mfma_f32_16x16x32_bf16 v[112:115], v[152:155], v[184:187], v[112:115]
	v_mfma_f32_16x16x32_bf16 v[100:103], v[144:147], v[192:195], v[100:103]
	v_mfma_f32_16x16x32_bf16 v[96:99], v[152:155], v[192:195], v[96:99]
	v_mfma_f32_16x16x32_bf16 v[84:87], v[144:147], v[200:203], v[84:87]
	v_mfma_f32_16x16x32_bf16 v[80:83], v[152:155], v[200:203], v[80:83]
	v_mfma_f32_16x16x32_bf16 v[132:135], v[148:151], v[180:183], v[132:135]
	v_mfma_f32_16x16x32_bf16 v[128:131], v[156:159], v[180:183], v[128:131]
	v_mfma_f32_16x16x32_bf16 v[116:119], v[148:151], v[188:191], v[116:119]
	v_mfma_f32_16x16x32_bf16 v[112:115], v[156:159], v[188:191], v[112:115]
	v_mfma_f32_16x16x32_bf16 v[100:103], v[148:151], v[196:199], v[100:103]
	v_mfma_f32_16x16x32_bf16 v[96:99], v[156:159], v[196:199], v[96:99]
	v_mfma_f32_16x16x32_bf16 v[84:87], v[148:151], v[204:207], v[84:87]
	v_mfma_f32_16x16x32_bf16 v[80:83], v[156:159], v[204:207], v[80:83]

; #define PG8_STAGE(bufoff, gbase, voff) do { _Pragma("unroll") for (int _i = 0; _i < 2; ++_i) \
;         __builtin_amdgcn_global_load_lds((const unsigned*)((const char*)(gbase) + (voff)[_i]), (PG8_LAS unsigned*)(lds + (bufoff) + ldsw + _i * 8192), 16, 0, 0); } while (0)
; #define PG8_LDA(dst, b, h) do { _Pragma("unroll") for (int m = 0; m < 4; ++m) _Pragma("unroll") for (int k = 0; k < 2; ++k) dst[m][k] = *(const PG8_LAS bf16x8*)(lds + PG8_SA(b, h) + aoff + m * 2048 + k * 1024); } while (0)
; #define PG8_MMA(ai, bj, At, Bt) do { __builtin_amdgcn_s_setprio(1); _Pragma("unroll") for (int m = 0; m < 4; ++m) _Pragma("unroll") for (int n = 0; n < 2; ++n) _Pragma("unroll") for (int k = 0; k < 2; ++k) \
;         acc[ai][bj][m][n] = __builtin_amdgcn_mfma_f32_16x16x32_bf16(Bt[n][k], At[m][k], acc[ai][bj][m][n], 0, 0, 0); __builtin_amdgcn_s_setprio(0); } while (0)
; #define PG8_WAIT_V(n) asm volatile("s_waitcnt vmcnt(" #n ")" ::: "memory")
; #define PG8_WAIT_L(n) asm volatile("s_waitcnt lgkmcnt(" #n ")" ::: "memory")
; #define PG8_BAR __builtin_amdgcn_s_barrier()
; #define PG8_SCHED __builtin_amdgcn_sched_barrier(0)
; template <class Epi, class Sched, bool ALIGN_EPI = false, bool SP2 = false>
; __device__ __forceinline__ void gemm_phase(PG8_LAS unsigned char* lds, const Gemm g, const Sched& S, const Epi& E) {
;     ...
;             PG8_WAIT_V(8); PG8_WAIT_L(0); PG8_BAR; PG8_MMA(0, 0, At, B0); PG8_MMA(0, 1, At, B1); PG8_BAR; PG8_SCHED;
;             PG8_LDA(At, 0, 1); PG8_STAGE(PG8_SB(0, 0), b2, voffB); PG8_STAGE(PG8_SB(0, 1), b2 + hstep, voffB); PG8_STAGE(PG8_SA(0, 0), a2, voffA);
	s_barrier
	s_add_i32 s82, s75, s64
	s_mov_b64 s[96:97], s[60:61]

; #define PG8_STAGE(bufoff, gbase, voff) do { _Pragma("unroll") for (int _i = 0; _i < 2; ++_i) \
;         __builtin_amdgcn_global_load_lds((const unsigned*)((const char*)(gbase) + (voff)[_i]), (PG8_LAS unsigned*)(lds + (bufoff) + ldsw + _i * 8192), 16, 0, 0); } while (0)
; #define PG8_LDA(dst, b, h) do { _Pragma("unroll") for (int m = 0; m < 4; ++m) _Pragma("unroll") for (int k = 0; k < 2; ++k) dst[m][k] = *(const PG8_LAS bf16x8*)(lds + PG8_SA(b, h) + aoff + m * 2048 + k * 1024); } while (0)
; template <class Epi, class Sched, bool ALIGN_EPI = false, bool SP2 = false>
; __device__ __forceinline__ void gemm_phase(PG8_LAS unsigned char* lds, const Gemm g, const Sched& S, const Epi& E) {
;     ...
;             PG8_LDA(At, 0, 1); PG8_STAGE(PG8_SB(0, 0), b2, voffB); PG8_STAGE(PG8_SB(0, 1), b2 + hstep, voffB); PG8_STAGE(PG8_SA(0, 0), a2, voffA);
	s_mov_b32 m0, s82
	ds_read_b128 v[176:179], v213 offset:16384
	ds_read_b128 v[180:183], v213 offset:17408
	ds_read_b128 v[184:187], v213 offset:18432
	ds_read_b128 v[188:191], v213 offset:19456
	ds_read_b128 v[192:195], v213 offset:20480
	ds_read_b128 v[196:199], v213 offset:21504
	ds_read_b128 v[200:203], v213 offset:22528
	ds_read_b128 v[204:207], v213 offset:23552
	global_load_lds_dwordx4 v162, s[60:61]
	s_add_i32 m0, s82, 0x2000
	s_add_u32 s82, s60, 0x80000

; #define PG8_STAGE(bufoff, gbase, voff) do { _Pragma("unroll") for (int _i = 0; _i < 2; ++_i) \
;         __builtin_amdgcn_global_load_lds((const unsigned*)((const char*)(gbase) + (voff)[_i]), (PG8_LAS unsigned*)(lds + (bufoff) + ldsw + _i * 8192), 16, 0, 0); } while (0)
; #define PG8_LDA(dst, b, h) do { _Pragma("unroll") for (int m = 0; m < 4; ++m) _Pragma("unroll") for (int k = 0; k < 2; ++k) dst[m][k] = *(const PG8_LAS bf16x8*)(lds + PG8_SA(b, h) + aoff + m * 2048 + k * 1024); } while (0)
; template <class Epi, class Sched, bool ALIGN_EPI = false, bool SP2 = false>
; __device__ __forceinline__ void gemm_phase(PG8_LAS unsigned char* lds, const Gemm g, const Sched& S, const Epi& E) {
;     ...
;             PG8_LDA(At, 0, 1); PG8_STAGE(PG8_SB(0, 0), b2, voffB); PG8_STAGE(PG8_SB(0, 1), b2 + hstep, voffB); PG8_STAGE(PG8_SA(0, 0), a2, voffA);
	s_addc_u32 s83, s61, 0
	s_add_i32 s84, s76, s64
	global_load_lds_dwordx4 v166, s[60:61]

; #define PG8_STAGE(bufoff, gbase, voff) do { _Pragma("unroll") for (int _i = 0; _i < 2; ++_i) \
;         __builtin_amdgcn_global_load_lds((const unsigned*)((const char*)(gbase) + (voff)[_i]), (PG8_LAS unsigned*)(lds + (bufoff) + ldsw + _i * 8192), 16, 0, 0); } while (0)
; #define PG8_LDA(dst, b, h) do { _Pragma("unroll") for (int m = 0; m < 4; ++m) _Pragma("unroll") for (int k = 0; k < 2; ++k) dst[m][k] = *(const PG8_LAS bf16x8*)(lds + PG8_SA(b, h) + aoff + m * 2048 + k * 1024); } while (0)
; template <class Epi, class Sched, bool ALIGN_EPI = false, bool SP2 = false>
; __device__ __forceinline__ void gemm_phase(PG8_LAS unsigned char* lds, const Gemm g, const Sched& S, const Epi& E) {
;     ...
;             PG8_LDA(At, 0, 1); PG8_STAGE(PG8_SB(0, 0), b2, voffB); PG8_STAGE(PG8_SB(0, 1), b2 + hstep, voffB); PG8_STAGE(PG8_SA(0, 0), a2, voffA);
	s_mov_b32 m0, s84
	s_nop 0
	global_load_lds_dwordx4 v162, s[82:83]

; #define PG8_STAGE(bufoff, gbase, voff) do { _Pragma("unroll") for (int _i = 0; _i < 2; ++_i) \
;         __builtin_amdgcn_global_load_lds((const unsigned*)((const char*)(gbase) + (voff)[_i]), (PG8_LAS unsigned*)(lds + (bufoff) + ldsw + _i * 8192), 16, 0, 0); } while (0)
; #define PG8_LDA(dst, b, h) do { _Pragma("unroll") for (int m = 0; m < 4; ++m) _Pragma("unroll") for (int k = 0; k < 2; ++k) dst[m][k] = *(const PG8_LAS bf16x8*)(lds + PG8_SA(b, h) + aoff + m * 2048 + k * 1024); } while (0)
; template <class Epi, class Sched, bool ALIGN_EPI = false, bool SP2 = false>
; __device__ __forceinline__ void gemm_phase(PG8_LAS unsigned char* lds, const Gemm g, const Sched& S, const Epi& E) {
;     ...
;             PG8_LDA(At, 0, 1); PG8_STAGE(PG8_SB(0, 0), b2, voffB); PG8_STAGE(PG8_SB(0, 1), b2 + hstep, voffB); PG8_STAGE(PG8_SA(0, 0), a2, voffA);
	s_add_i32 m0, s84, 0x2000
	s_nop 0
	global_load_lds_dwordx4 v166, s[82:83]
	s_mov_b64 s[98:99], s[62:63]

; #define PG8_STAGE(bufoff, gbase, voff) do { _Pragma("unroll") for (int _i = 0; _i < 2; ++_i) \
;         __builtin_amdgcn_global_load_lds((const unsigned*)((const char*)(gbase) + (voff)[_i]), (PG8_LAS unsigned*)(lds + (bufoff) + ldsw + _i * 8192), 16, 0, 0); } while (0)
; #define PG8_LDA(dst, b, h) do { _Pragma("unroll") for (int m = 0; m < 4; ++m) _Pragma("unroll") for (int k = 0; k < 2; ++k) dst[m][k] = *(const PG8_LAS bf16x8*)(lds + PG8_SA(b, h) + aoff + m * 2048 + k * 1024); } while (0)
; #define PG8_MMA(ai, bj, At, Bt) do { __builtin_amdgcn_s_setprio(1); _Pragma("unroll") for (int m = 0; m < 4; ++m) _Pragma("unroll") for (int n = 0; n < 2; ++n) _Pragma("unroll") for (int k = 0; k < 2; ++k) \
;         acc[ai][bj][m][n] = __builtin_amdgcn_mfma_f32_16x16x32_bf16(Bt[n][k], At[m][k], acc[ai][bj][m][n], 0, 0, 0); __builtin_amdgcn_s_setprio(0); } while (0)
; #define PG8_WAIT_V(n) asm volatile("s_waitcnt vmcnt(" #n ")" ::: "memory")
; #define PG8_WAIT_L(n) asm volatile("s_waitcnt lgkmcnt(" #n ")" ::: "memory")
; #define PG8_BAR __builtin_amdgcn_s_barrier()
; #define PG8_SCHED __builtin_amdgcn_sched_barrier(0)
; template <class Epi, class Sched, bool ALIGN_EPI = false, bool SP2 = false>
; __device__ __forceinline__ void gemm_phase(PG8_LAS unsigned char* lds, const Gemm g, const Sched& S, const Epi& E) {
;     ...
;             PG8_LDA(At, 0, 1); PG8_STAGE(PG8_SB(0, 0), b2, voffB); PG8_STAGE(PG8_SB(0, 1), b2 + hstep, voffB); PG8_STAGE(PG8_SA(0, 0), a2, voffA);
;             PG8_WAIT_V(8); PG8_WAIT_L(0); PG8_BAR; PG8_MMA(1, 0, At, B0); PG8_MMA(1, 1, At, B1); PG8_BAR; PG8_SCHED;
	s_mov_b32 m0, s57
	s_nop 0
	global_load_lds_dwordx4 v160, s[62:63]
	s_mov_b32 m0, s65
	s_nop 0
	global_load_lds_dwordx4 v164, s[62:63]
	s_waitcnt vmcnt(8)
	s_waitcnt lgkmcnt(0)

; #define PG8_MMA(ai, bj, At, Bt) do { __builtin_amdgcn_s_setprio(1); _Pragma("unroll") for (int m = 0; m < 4; ++m) _Pragma("unroll") for (int n = 0; n < 2; ++n) _Pragma("unroll") for (int k = 0; k < 2; ++k) \
;         acc[ai][bj][m][n] = __builtin_amdgcn_mfma_f32_16x16x32_bf16(Bt[n][k], At[m][k], acc[ai][bj][m][n], 0, 0, 0); __builtin_amdgcn_s_setprio(0); } while (0)
; #define PG8_WAIT_V(n) asm volatile("s_waitcnt vmcnt(" #n ")" ::: "memory")
; #define PG8_WAIT_L(n) asm volatile("s_waitcnt lgkmcnt(" #n ")" ::: "memory")
; #define PG8_BAR __builtin_amdgcn_s_barrier()
; #define PG8_SCHED __builtin_amdgcn_sched_barrier(0)
; template <class Epi, class Sched, bool ALIGN_EPI = false, bool SP2 = false>
; __device__ __forceinline__ void gemm_phase(PG8_LAS unsigned char* lds, const Gemm g, const Sched& S, const Epi& E) {
;     ...
;             PG8_WAIT_V(8); PG8_WAIT_L(0); PG8_BAR; PG8_MMA(1, 0, At, B0); PG8_MMA(1, 1, At, B1); PG8_BAR; PG8_SCHED;
	s_barrier

; #define PG8_MMA(ai, bj, At, Bt) do { __builtin_amdgcn_s_setprio(1); _Pragma("unroll") for (int m = 0; m < 4; ++m) _Pragma("unroll") for (int n = 0; n < 2; ++n) _Pragma("unroll") for (int k = 0; k < 2; ++k) \
;         acc[ai][bj][m][n] = __builtin_amdgcn_mfma_f32_16x16x32_bf16(Bt[n][k], At[m][k], acc[ai][bj][m][n], 0, 0, 0); __builtin_amdgcn_s_setprio(0); } while (0)
; #define PG8_WAIT_V(n) asm volatile("s_waitcnt vmcnt(" #n ")" ::: "memory")
; #define PG8_WAIT_L(n) asm volatile("s_waitcnt lgkmcnt(" #n ")" ::: "memory")
; #define PG8_BAR __builtin_amdgcn_s_barrier()
; #define PG8_SCHED __builtin_amdgcn_sched_barrier(0)
; template <class Epi, class Sched, bool ALIGN_EPI = false, bool SP2 = false>
; __device__ __forceinline__ void gemm_phase(PG8_LAS unsigned char* lds, const Gemm g, const Sched& S, const Epi& E) {
;     ...
;             PG8_WAIT_V(8); PG8_WAIT_L(0); PG8_BAR; PG8_MMA(1, 0, At, B0); PG8_MMA(1, 1, At, B1); PG8_BAR; PG8_SCHED;
	v_mfma_f32_16x16x32_bf16 v[60:63], v[64:67], v[176:179], v[60:63]
	v_mfma_f32_16x16x32_bf16 v[56:59], v[72:75], v[176:179], v[56:59]
	v_mfma_f32_16x16x32_bf16 v[44:47], v[64:67], v[184:187], v[44:47]
	v_mfma_f32_16x16x32_bf16 v[40:43], v[72:75], v[184:187], v[40:43]
	v_mfma_f32_16x16x32_bf16 v[28:31], v[64:67], v[192:195], v[28:31]
	v_mfma_f32_16x16x32_bf16 v[24:27], v[72:75], v[192:195], v[24:27]
	v_mfma_f32_16x16x32_bf16 v[12:15], v[64:67], v[200:203], v[12:15]
	v_mfma_f32_16x16x32_bf16 v[8:11], v[72:75], v[200:203], v[8:11]
	v_mfma_f32_16x16x32_bf16 v[60:63], v[68:71], v[180:183], v[60:63]
	v_mfma_f32_16x16x32_bf16 v[56:59], v[76:79], v[180:183], v[56:59]
	v_mfma_f32_16x16x32_bf16 v[44:47], v[68:71], v[188:191], v[44:47]
	v_mfma_f32_16x16x32_bf16 v[40:43], v[76:79], v[188:191], v[40:43]
	v_mfma_f32_16x16x32_bf16 v[28:31], v[68:71], v[196:199], v[28:31]
	v_mfma_f32_16x16x32_bf16 v[24:27], v[76:79], v[196:199], v[24:27]
	v_mfma_f32_16x16x32_bf16 v[12:15], v[68:71], v[204:207], v[12:15]
	v_mfma_f32_16x16x32_bf16 v[8:11], v[76:79], v[204:207], v[8:11]


; #define PG8_MMA(ai, bj, At, Bt) do { __builtin_amdgcn_s_setprio(1); _Pragma("unroll") for (int m = 0; m < 4; ++m) _Pragma("unroll") for (int n = 0; n < 2; ++n) _Pragma("unroll") for (int k = 0; k < 2; ++k) \
;         acc[ai][bj][m][n] = __builtin_amdgcn_mfma_f32_16x16x32_bf16(Bt[n][k], At[m][k], acc[ai][bj][m][n], 0, 0, 0); __builtin_amdgcn_s_setprio(0); } while (0)
; #define PG8_WAIT_V(n) asm volatile("s_waitcnt vmcnt(" #n ")" ::: "memory")
; #define PG8_WAIT_L(n) asm volatile("s_waitcnt lgkmcnt(" #n ")" ::: "memory")
; #define PG8_BAR __builtin_amdgcn_s_barrier()
; #define PG8_SCHED __builtin_amdgcn_sched_barrier(0)
; template <class Epi, class Sched, bool ALIGN_EPI = false, bool SP2 = false>
; __device__ __forceinline__ void gemm_phase(PG8_LAS unsigned char* lds, const Gemm g, const Sched& S, const Epi& E) {
;     ...
;             PG8_WAIT_V(8); PG8_WAIT_L(0); PG8_BAR; PG8_MMA(1, 0, At, B0); PG8_MMA(1, 1, At, B1); PG8_BAR; PG8_SCHED;
	v_mfma_f32_16x16x32_bf16 v[52:55], v[144:147], v[176:179], v[52:55]
	v_mfma_f32_16x16x32_bf16 v[48:51], v[152:155], v[176:179], v[48:51]
	v_mfma_f32_16x16x32_bf16 v[36:39], v[144:147], v[184:187], v[36:39]
	v_mfma_f32_16x16x32_bf16 v[32:35], v[152:155], v[184:187], v[32:35]
	v_mfma_f32_16x16x32_bf16 v[20:23], v[144:147], v[192:195], v[20:23]
	v_mfma_f32_16x16x32_bf16 v[16:19], v[152:155], v[192:195], v[16:19]
	v_mfma_f32_16x16x32_bf16 v[4:7], v[144:147], v[200:203], v[4:7]
	v_mfma_f32_16x16x32_bf16 v[0:3], v[152:155], v[200:203], v[0:3]
	v_mfma_f32_16x16x32_bf16 v[52:55], v[148:151], v[180:183], v[52:55]
	v_mfma_f32_16x16x32_bf16 v[48:51], v[156:159], v[180:183], v[48:51]
	v_mfma_f32_16x16x32_bf16 v[36:39], v[148:151], v[188:191], v[36:39]
	v_mfma_f32_16x16x32_bf16 v[32:35], v[156:159], v[188:191], v[32:35]
	v_mfma_f32_16x16x32_bf16 v[20:23], v[148:151], v[196:199], v[20:23]
	v_mfma_f32_16x16x32_bf16 v[16:19], v[156:159], v[196:199], v[16:19]
	v_mfma_f32_16x16x32_bf16 v[4:7], v[148:151], v[204:207], v[4:7]
	v_mfma_f32_16x16x32_bf16 v[0:3], v[156:159], v[204:207], v[0:3]

; #define PG8_STAGE(bufoff, gbase, voff) do { _Pragma("unroll") for (int _i = 0; _i < 2; ++_i) \
;         __builtin_amdgcn_global_load_lds((const unsigned*)((const char*)(gbase) + (voff)[_i]), (PG8_LAS unsigned*)(lds + (bufoff) + ldsw + _i * 8192), 16, 0, 0); } while (0)
; #define PG8_LDA(dst, b, h) do { _Pragma("unroll") for (int m = 0; m < 4; ++m) _Pragma("unroll") for (int k = 0; k < 2; ++k) dst[m][k] = *(const PG8_LAS bf16x8*)(lds + PG8_SA(b, h) + aoff + m * 2048 + k * 1024); } while (0)
; #define PG8_LDB(dst, b, h) do { _Pragma("unroll") for (int n = 0; n < 2; ++n) _Pragma("unroll") for (int k = 0; k < 2; ++k) dst[n][k] = *(const PG8_LAS bf16x8*)(lds + PG8_SB(b, h) + boff + n * 2048 + k * 1024); } while (0)
; #define PG8_MMA(ai, bj, At, Bt) do { __builtin_amdgcn_s_setprio(1); _Pragma("unroll") for (int m = 0; m < 4; ++m) _Pragma("unroll") for (int n = 0; n < 2; ++n) _Pragma("unroll") for (int k = 0; k < 2; ++k) \
;         acc[ai][bj][m][n] = __builtin_amdgcn_mfma_f32_16x16x32_bf16(Bt[n][k], At[m][k], acc[ai][bj][m][n], 0, 0, 0); __builtin_amdgcn_s_setprio(0); } while (0)
; #define PG8_WAIT_V(n) asm volatile("s_waitcnt vmcnt(" #n ")" ::: "memory")
; #define PG8_WAIT_L(n) asm volatile("s_waitcnt lgkmcnt(" #n ")" ::: "memory")
; #define PG8_BAR __builtin_amdgcn_s_barrier()
; #define PG8_SCHED __builtin_amdgcn_sched_barrier(0)
; template <class Epi, class Sched, bool ALIGN_EPI = false, bool SP2 = false>
; __device__ __forceinline__ void gemm_phase(PG8_LAS unsigned char* lds, const Gemm g, const Sched& S, const Epi& E) {
;     ...
;             PG8_WAIT_V(8); PG8_WAIT_L(0); PG8_BAR; PG8_MMA(1, 0, At, B0); PG8_MMA(1, 1, At, B1); PG8_BAR; PG8_SCHED;
;             PG8_LDB(B0, 1, 0); PG8_LDB(B1, 1, 1); PG8_SCHED; PG8_LDA(At, 1, 0); PG8_STAGE(PG8_SA(0, 1), a2 + hstep, voffA);
	s_barrier
	s_add_i32 s82, 0, 0x18000
	s_add_i32 s83, 0, 0x1c000


; #define PG8_STAGE(bufoff, gbase, voff) do { _Pragma("unroll") for (int _i = 0; _i < 2; ++_i) \
;         __builtin_amdgcn_global_load_lds((const unsigned*)((const char*)(gbase) + (voff)[_i]), (PG8_LAS unsigned*)(lds + (bufoff) + ldsw + _i * 8192), 16, 0, 0); } while (0)
; #define PG8_LDA(dst, b, h) do { _Pragma("unroll") for (int m = 0; m < 4; ++m) _Pragma("unroll") for (int k = 0; k < 2; ++k) dst[m][k] = *(const PG8_LAS bf16x8*)(lds + PG8_SA(b, h) + aoff + m * 2048 + k * 1024); } while (0)
; #define PG8_LDB(dst, b, h) do { _Pragma("unroll") for (int n = 0; n < 2; ++n) _Pragma("unroll") for (int k = 0; k < 2; ++k) dst[n][k] = *(const PG8_LAS bf16x8*)(lds + PG8_SB(b, h) + boff + n * 2048 + k * 1024); } while (0)
; #define PG8_SCHED __builtin_amdgcn_sched_barrier(0)
; template <class Epi, class Sched, bool ALIGN_EPI = false, bool SP2 = false>
; __device__ __forceinline__ void gemm_phase(PG8_LAS unsigned char* lds, const Gemm g, const Sched& S, const Epi& E) {
;     ...
;             PG8_LDB(B0, 1, 0); PG8_LDB(B1, 1, 1); PG8_SCHED; PG8_LDA(At, 1, 0); PG8_STAGE(PG8_SA(0, 1), a2 + hstep, voffA);
	ds_read_b128 v[64:67], v254
	ds_read_b128 v[68:71], v254 offset:1024
	ds_read_b128 v[72:75], v254 offset:2048
	ds_read_b128 v[76:79], v254 offset:3072
	ds_read_b128 v[144:147], v255
	ds_read_b128 v[148:151], v255 offset:1024
	ds_read_b128 v[152:155], v255 offset:2048
	ds_read_b128 v[156:159], v255 offset:3072
	s_add_u32 s62, s62, 0x80000
	s_addc_u32 s63, s63, 0
	s_mov_b32 m0, s67

; #define PG8_STAGE(bufoff, gbase, voff) do { _Pragma("unroll") for (int _i = 0; _i < 2; ++_i) \
;         __builtin_amdgcn_global_load_lds((const unsigned*)((const char*)(gbase) + (voff)[_i]), (PG8_LAS unsigned*)(lds + (bufoff) + ldsw + _i * 8192), 16, 0, 0); } while (0)
; #define PG8_LDA(dst, b, h) do { _Pragma("unroll") for (int m = 0; m < 4; ++m) _Pragma("unroll") for (int k = 0; k < 2; ++k) dst[m][k] = *(const PG8_LAS bf16x8*)(lds + PG8_SA(b, h) + aoff + m * 2048 + k * 1024); } while (0)
; #define PG8_LDB(dst, b, h) do { _Pragma("unroll") for (int n = 0; n < 2; ++n) _Pragma("unroll") for (int k = 0; k < 2; ++k) dst[n][k] = *(const PG8_LAS bf16x8*)(lds + PG8_SB(b, h) + boff + n * 2048 + k * 1024); } while (0)
; #define PG8_SCHED __builtin_amdgcn_sched_barrier(0)
; template <class Epi, class Sched, bool ALIGN_EPI = false, bool SP2 = false>
; __device__ __forceinline__ void gemm_phase(PG8_LAS unsigned char* lds, const Gemm g, const Sched& S, const Epi& E) {
;     ...
;             PG8_LDB(B0, 1, 0); PG8_LDB(B1, 1, 1); PG8_SCHED; PG8_LDA(At, 1, 0); PG8_STAGE(PG8_SA(0, 1), a2 + hstep, voffA);
	ds_read_b128 v[176:179], v213 offset:32768
	ds_read_b128 v[180:183], v213 offset:33792
	ds_read_b128 v[184:187], v213 offset:34816
	ds_read_b128 v[188:191], v213 offset:35840
	ds_read_b128 v[192:195], v213 offset:36864
	ds_read_b128 v[196:199], v213 offset:37888
	ds_read_b128 v[200:203], v213 offset:38912
	ds_read_b128 v[204:207], v213 offset:39936
	global_load_lds_dwordx4 v160, s[62:63]

; #define PG8_STAGE(bufoff, gbase, voff) do { _Pragma("unroll") for (int _i = 0; _i < 2; ++_i) \
;         __builtin_amdgcn_global_load_lds((const unsigned*)((const char*)(gbase) + (voff)[_i]), (PG8_LAS unsigned*)(lds + (bufoff) + ldsw + _i * 8192), 16, 0, 0); } while (0)
; #define PG8_LDA(dst, b, h) do { _Pragma("unroll") for (int m = 0; m < 4; ++m) _Pragma("unroll") for (int k = 0; k < 2; ++k) dst[m][k] = *(const PG8_LAS bf16x8*)(lds + PG8_SA(b, h) + aoff + m * 2048 + k * 1024); } while (0)
; #define PG8_LDB(dst, b, h) do { _Pragma("unroll") for (int n = 0; n < 2; ++n) _Pragma("unroll") for (int k = 0; k < 2; ++k) dst[n][k] = *(const PG8_LAS bf16x8*)(lds + PG8_SB(b, h) + boff + n * 2048 + k * 1024); } while (0)
; #define PG8_MMA(ai, bj, At, Bt) do { __builtin_amdgcn_s_setprio(1); _Pragma("unroll") for (int m = 0; m < 4; ++m) _Pragma("unroll") for (int n = 0; n < 2; ++n) _Pragma("unroll") for (int k = 0; k < 2; ++k) \
;         acc[ai][bj][m][n] = __builtin_amdgcn_mfma_f32_16x16x32_bf16(Bt[n][k], At[m][k], acc[ai][bj][m][n], 0, 0, 0); __builtin_amdgcn_s_setprio(0); } while (0)
; #define PG8_WAIT_V(n) asm volatile("s_waitcnt vmcnt(" #n ")" ::: "memory")
; #define PG8_WAIT_L(n) asm volatile("s_waitcnt lgkmcnt(" #n ")" ::: "memory")
; #define PG8_BAR __builtin_amdgcn_s_barrier()
; #define PG8_SCHED __builtin_amdgcn_sched_barrier(0)
; template <class Epi, class Sched, bool ALIGN_EPI = false, bool SP2 = false>
; __device__ __forceinline__ void gemm_phase(PG8_LAS unsigned char* lds, const Gemm g, const Sched& S, const Epi& E) {
;     ...
;             PG8_LDB(B0, 1, 0); PG8_LDB(B1, 1, 1); PG8_SCHED; PG8_LDA(At, 1, 0); PG8_STAGE(PG8_SA(0, 1), a2 + hstep, voffA);
;             PG8_WAIT_V(8); PG8_WAIT_L(0); PG8_BAR; PG8_MMA(0, 0, At, B0); PG8_MMA(0, 1, At, B1); PG8_BAR; PG8_SCHED;
	s_mov_b32 m0, s68
	s_nop 0
	global_load_lds_dwordx4 v164, s[62:63]
	s_waitcnt vmcnt(8)
	s_waitcnt lgkmcnt(0)

; #define PG8_MMA(ai, bj, At, Bt) do { __builtin_amdgcn_s_setprio(1); _Pragma("unroll") for (int m = 0; m < 4; ++m) _Pragma("unroll") for (int n = 0; n < 2; ++n) _Pragma("unroll") for (int k = 0; k < 2; ++k) \
;         acc[ai][bj][m][n] = __builtin_amdgcn_mfma_f32_16x16x32_bf16(Bt[n][k], At[m][k], acc[ai][bj][m][n], 0, 0, 0); __builtin_amdgcn_s_setprio(0); } while (0)
; #define PG8_WAIT_V(n) asm volatile("s_waitcnt vmcnt(" #n ")" ::: "memory")
; #define PG8_WAIT_L(n) asm volatile("s_waitcnt lgkmcnt(" #n ")" ::: "memory")
; #define PG8_BAR __builtin_amdgcn_s_barrier()
; #define PG8_SCHED __builtin_amdgcn_sched_barrier(0)
; template <class Epi, class Sched, bool ALIGN_EPI = false, bool SP2 = false>
; __device__ __forceinline__ void gemm_phase(PG8_LAS unsigned char* lds, const Gemm g, const Sched& S, const Epi& E) {
;     ...
;             PG8_WAIT_V(8); PG8_WAIT_L(0); PG8_BAR; PG8_MMA(0, 0, At, B0); PG8_MMA(0, 1, At, B1); PG8_BAR; PG8_SCHED;
	s_barrier

; #define PG8_MMA(ai, bj, At, Bt) do { __builtin_amdgcn_s_setprio(1); _Pragma("unroll") for (int m = 0; m < 4; ++m) _Pragma("unroll") for (int n = 0; n < 2; ++n) _Pragma("unroll") for (int k = 0; k < 2; ++k) \
;         acc[ai][bj][m][n] = __builtin_amdgcn_mfma_f32_16x16x32_bf16(Bt[n][k], At[m][k], acc[ai][bj][m][n], 0, 0, 0); __builtin_amdgcn_s_setprio(0); } while (0)
; #define PG8_WAIT_V(n) asm volatile("s_waitcnt vmcnt(" #n ")" ::: "memory")
; #define PG8_WAIT_L(n) asm volatile("s_waitcnt lgkmcnt(" #n ")" ::: "memory")
; #define PG8_BAR __builtin_amdgcn_s_barrier()
; #define PG8_SCHED __builtin_amdgcn_sched_barrier(0)
; template <class Epi, class Sched, bool ALIGN_EPI = false, bool SP2 = false>
; __device__ __forceinline__ void gemm_phase(PG8_LAS unsigned char* lds, const Gemm g, const Sched& S, const Epi& E) {
;     ...
;             PG8_WAIT_V(8); PG8_WAIT_L(0); PG8_BAR; PG8_MMA(0, 0, At, B0); PG8_MMA(0, 1, At, B1); PG8_BAR; PG8_SCHED;
	v_mfma_f32_16x16x32_bf16 v[140:143], v[64:67], v[176:179], v[140:143]
	v_mfma_f32_16x16x32_bf16 v[136:139], v[72:75], v[176:179], v[136:139]
	v_mfma_f32_16x16x32_bf16 v[124:127], v[64:67], v[184:187], v[124:127]
	v_mfma_f32_16x16x32_bf16 v[120:123], v[72:75], v[184:187], v[120:123]
	v_mfma_f32_16x16x32_bf16 v[108:111], v[64:67], v[192:195], v[108:111]
	v_mfma_f32_16x16x32_bf16 v[104:107], v[72:75], v[192:195], v[104:107]
	v_mfma_f32_16x16x32_bf16 v[92:95], v[64:67], v[200:203], v[92:95]
	v_mfma_f32_16x16x32_bf16 v[88:91], v[72:75], v[200:203], v[88:91]
	v_mfma_f32_16x16x32_bf16 v[140:143], v[68:71], v[180:183], v[140:143]
	v_mfma_f32_16x16x32_bf16 v[136:139], v[76:79], v[180:183], v[136:139]
	v_mfma_f32_16x16x32_bf16 v[124:127], v[68:71], v[188:191], v[124:127]
	v_mfma_f32_16x16x32_bf16 v[120:123], v[76:79], v[188:191], v[120:123]
	v_mfma_f32_16x16x32_bf16 v[108:111], v[68:71], v[196:199], v[108:111]
	v_mfma_f32_16x16x32_bf16 v[104:107], v[76:79], v[196:199], v[104:107]
	v_mfma_f32_16x16x32_bf16 v[92:95], v[68:71], v[204:207], v[92:95]
	v_mfma_f32_16x16x32_bf16 v[88:91], v[76:79], v[204:207], v[88:91]


; #define PG8_MMA(ai, bj, At, Bt) do { __builtin_amdgcn_s_setprio(1); _Pragma("unroll") for (int m = 0; m < 4; ++m) _Pragma("unroll") for (int n = 0; n < 2; ++n) _Pragma("unroll") for (int k = 0; k < 2; ++k) \
;         acc[ai][bj][m][n] = __builtin_amdgcn_mfma_f32_16x16x32_bf16(Bt[n][k], At[m][k], acc[ai][bj][m][n], 0, 0, 0); __builtin_amdgcn_s_setprio(0); } while (0)
; #define PG8_WAIT_V(n) asm volatile("s_waitcnt vmcnt(" #n ")" ::: "memory")
; #define PG8_WAIT_L(n) asm volatile("s_waitcnt lgkmcnt(" #n ")" ::: "memory")
; #define PG8_BAR __builtin_amdgcn_s_barrier()
; #define PG8_SCHED __builtin_amdgcn_sched_barrier(0)
; template <class Epi, class Sched, bool ALIGN_EPI = false, bool SP2 = false>
; __device__ __forceinline__ void gemm_phase(PG8_LAS unsigned char* lds, const Gemm g, const Sched& S, const Epi& E) {
;     ...
;             PG8_WAIT_V(8); PG8_WAIT_L(0); PG8_BAR; PG8_MMA(0, 0, At, B0); PG8_MMA(0, 1, At, B1); PG8_BAR; PG8_SCHED;
	v_mfma_f32_16x16x32_bf16 v[132:135], v[144:147], v[176:179], v[132:135]
	v_mfma_f32_16x16x32_bf16 v[128:131], v[152:155], v[176:179], v[128:131]
	v_mfma_f32_16x16x32_bf16 v[116:119], v[144:147], v[184:187], v[116:119]
	v_mfma_f32_16x16x32_bf16 v[112:115], v[152:155], v[184:187], v[112:115]
	v_mfma_f32_16x16x32_bf16 v[100:103], v[144:147], v[192:195], v[100:103]
	v_mfma_f32_16x16x32_bf16 v[96:99], v[152:155], v[192:195], v[96:99]
	v_mfma_f32_16x16x32_bf16 v[84:87], v[144:147], v[200:203], v[84:87]
	v_mfma_f32_16x16x32_bf16 v[80:83], v[152:155], v[200:203], v[80:83]
	v_mfma_f32_16x16x32_bf16 v[132:135], v[148:151], v[180:183], v[132:135]
	v_mfma_f32_16x16x32_bf16 v[128:131], v[156:159], v[180:183], v[128:131]
	v_mfma_f32_16x16x32_bf16 v[116:119], v[148:151], v[188:191], v[116:119]
	v_mfma_f32_16x16x32_bf16 v[112:115], v[156:159], v[188:191], v[112:115]
	v_mfma_f32_16x16x32_bf16 v[100:103], v[148:151], v[196:199], v[100:103]
	v_mfma_f32_16x16x32_bf16 v[96:99], v[156:159], v[196:199], v[96:99]
	v_mfma_f32_16x16x32_bf16 v[84:87], v[148:151], v[204:207], v[84:87]
	v_mfma_f32_16x16x32_bf16 v[80:83], v[156:159], v[204:207], v[80:83]

; #define PG8_STAGE(bufoff, gbase, voff) do { _Pragma("unroll") for (int _i = 0; _i < 2; ++_i) \
;         __builtin_amdgcn_global_load_lds((const unsigned*)((const char*)(gbase) + (voff)[_i]), (PG8_LAS unsigned*)(lds + (bufoff) + ldsw + _i * 8192), 16, 0, 0); } while (0)
; #define PG8_LDA(dst, b, h) do { _Pragma("unroll") for (int m = 0; m < 4; ++m) _Pragma("unroll") for (int k = 0; k < 2; ++k) dst[m][k] = *(const PG8_LAS bf16x8*)(lds + PG8_SA(b, h) + aoff + m * 2048 + k * 1024); } while (0)
; #define PG8_MMA(ai, bj, At, Bt) do { __builtin_amdgcn_s_setprio(1); _Pragma("unroll") for (int m = 0; m < 4; ++m) _Pragma("unroll") for (int n = 0; n < 2; ++n) _Pragma("unroll") for (int k = 0; k < 2; ++k) \
;         acc[ai][bj][m][n] = __builtin_amdgcn_mfma_f32_16x16x32_bf16(Bt[n][k], At[m][k], acc[ai][bj][m][n], 0, 0, 0); __builtin_amdgcn_s_setprio(0); } while (0)
; #define PG8_WAIT_V(n) asm volatile("s_waitcnt vmcnt(" #n ")" ::: "memory")
; #define PG8_WAIT_L(n) asm volatile("s_waitcnt lgkmcnt(" #n ")" ::: "memory")
; #define PG8_BAR __builtin_amdgcn_s_barrier()
; #define PG8_SCHED __builtin_amdgcn_sched_barrier(0)
; template <class Epi, class Sched, bool ALIGN_EPI = false, bool SP2 = false>
; __device__ __forceinline__ void gemm_phase(PG8_LAS unsigned char* lds, const Gemm g, const Sched& S, const Epi& E) {
;     ...
;             PG8_WAIT_V(8); PG8_WAIT_L(0); PG8_BAR; PG8_MMA(0, 0, At, B0); PG8_MMA(0, 1, At, B1); PG8_BAR; PG8_SCHED;
;             PG8_LDA(At, 1, 1); PG8_STAGE(PG8_SB(1, 0), b3, voffB); PG8_STAGE(PG8_SB(1, 1), b3 + hstep, voffB); PG8_STAGE(PG8_SA(1, 0), a3, voffA);
	s_barrier
	s_add_i32 s62, s82, s64

; #define PG8_STAGE(bufoff, gbase, voff) do { _Pragma("unroll") for (int _i = 0; _i < 2; ++_i) \
;         __builtin_amdgcn_global_load_lds((const unsigned*)((const char*)(gbase) + (voff)[_i]), (PG8_LAS unsigned*)(lds + (bufoff) + ldsw + _i * 8192), 16, 0, 0); } while (0)
; #define PG8_LDA(dst, b, h) do { _Pragma("unroll") for (int m = 0; m < 4; ++m) _Pragma("unroll") for (int k = 0; k < 2; ++k) dst[m][k] = *(const PG8_LAS bf16x8*)(lds + PG8_SA(b, h) + aoff + m * 2048 + k * 1024); } while (0)
; template <class Epi, class Sched, bool ALIGN_EPI = false, bool SP2 = false>
; __device__ __forceinline__ void gemm_phase(PG8_LAS unsigned char* lds, const Gemm g, const Sched& S, const Epi& E) {
;     ...
;             PG8_LDA(At, 1, 1); PG8_STAGE(PG8_SB(1, 0), b3, voffB); PG8_STAGE(PG8_SB(1, 1), b3 + hstep, voffB); PG8_STAGE(PG8_SA(1, 0), a3, voffA);
	s_mov_b32 m0, s62
	ds_read_b128 v[176:179], v213 offset:49152
	ds_read_b128 v[180:183], v213 offset:50176
	ds_read_b128 v[184:187], v213 offset:51200
	ds_read_b128 v[188:191], v213 offset:52224
	ds_read_b128 v[192:195], v213 offset:53248
	ds_read_b128 v[196:199], v213 offset:54272
	ds_read_b128 v[200:203], v213 offset:55296
	ds_read_b128 v[204:207], v213 offset:56320
	global_load_lds_dwordx4 v250, s[96:97]
	s_add_i32 m0, s62, 0x2000
	s_add_u32 s60, s60, 0x80080

; #define PG8_STAGE(bufoff, gbase, voff) do { _Pragma("unroll") for (int _i = 0; _i < 2; ++_i) \
;         __builtin_amdgcn_global_load_lds((const unsigned*)((const char*)(gbase) + (voff)[_i]), (PG8_LAS unsigned*)(lds + (bufoff) + ldsw + _i * 8192), 16, 0, 0); } while (0)
; #define PG8_LDA(dst, b, h) do { _Pragma("unroll") for (int m = 0; m < 4; ++m) _Pragma("unroll") for (int k = 0; k < 2; ++k) dst[m][k] = *(const PG8_LAS bf16x8*)(lds + PG8_SA(b, h) + aoff + m * 2048 + k * 1024); } while (0)
; template <class Epi, class Sched, bool ALIGN_EPI = false, bool SP2 = false>
; __device__ __forceinline__ void gemm_phase(PG8_LAS unsigned char* lds, const Gemm g, const Sched& S, const Epi& E) {
;     ...
;             PG8_LDA(At, 1, 1); PG8_STAGE(PG8_SB(1, 0), b3, voffB); PG8_STAGE(PG8_SB(1, 1), b3 + hstep, voffB); PG8_STAGE(PG8_SA(1, 0), a3, voffA);
	s_addc_u32 s61, s61, 0
	s_add_i32 s62, s83, s64
	global_load_lds_dwordx4 v251, s[96:97]

; #define PG8_STAGE(bufoff, gbase, voff) do { _Pragma("unroll") for (int _i = 0; _i < 2; ++_i) \
;         __builtin_amdgcn_global_load_lds((const unsigned*)((const char*)(gbase) + (voff)[_i]), (PG8_LAS unsigned*)(lds + (bufoff) + ldsw + _i * 8192), 16, 0, 0); } while (0)
; #define PG8_LDA(dst, b, h) do { _Pragma("unroll") for (int m = 0; m < 4; ++m) _Pragma("unroll") for (int k = 0; k < 2; ++k) dst[m][k] = *(const PG8_LAS bf16x8*)(lds + PG8_SA(b, h) + aoff + m * 2048 + k * 1024); } while (0)
; template <class Epi, class Sched, bool ALIGN_EPI = false, bool SP2 = false>
; __device__ __forceinline__ void gemm_phase(PG8_LAS unsigned char* lds, const Gemm g, const Sched& S, const Epi& E) {
;     ...
;             PG8_LDA(At, 1, 1); PG8_STAGE(PG8_SB(1, 0), b3, voffB); PG8_STAGE(PG8_SB(1, 1), b3 + hstep, voffB); PG8_STAGE(PG8_SA(1, 0), a3, voffA);
	s_mov_b32 m0, s62
	s_nop 0
	global_load_lds_dwordx4 v162, s[60:61]

; #define PG8_STAGE(bufoff, gbase, voff) do { _Pragma("unroll") for (int _i = 0; _i < 2; ++_i) \
;         __builtin_amdgcn_global_load_lds((const unsigned*)((const char*)(gbase) + (voff)[_i]), (PG8_LAS unsigned*)(lds + (bufoff) + ldsw + _i * 8192), 16, 0, 0); } while (0)
; #define PG8_LDA(dst, b, h) do { _Pragma("unroll") for (int m = 0; m < 4; ++m) _Pragma("unroll") for (int k = 0; k < 2; ++k) dst[m][k] = *(const PG8_LAS bf16x8*)(lds + PG8_SA(b, h) + aoff + m * 2048 + k * 1024); } while (0)
; template <class Epi, class Sched, bool ALIGN_EPI = false, bool SP2 = false>
; __device__ __forceinline__ void gemm_phase(PG8_LAS unsigned char* lds, const Gemm g, const Sched& S, const Epi& E) {
;     ...
;             PG8_LDA(At, 1, 1); PG8_STAGE(PG8_SB(1, 0), b3, voffB); PG8_STAGE(PG8_SB(1, 1), b3 + hstep, voffB); PG8_STAGE(PG8_SA(1, 0), a3, voffA);
	s_add_i32 m0, s62, 0x2000
	s_nop 0
	global_load_lds_dwordx4 v166, s[60:61]

; #define PG8_STAGE(bufoff, gbase, voff) do { _Pragma("unroll") for (int _i = 0; _i < 2; ++_i) \
;         __builtin_amdgcn_global_load_lds((const unsigned*)((const char*)(gbase) + (voff)[_i]), (PG8_LAS unsigned*)(lds + (bufoff) + ldsw + _i * 8192), 16, 0, 0); } while (0)
; #define PG8_LDA(dst, b, h) do { _Pragma("unroll") for (int m = 0; m < 4; ++m) _Pragma("unroll") for (int k = 0; k < 2; ++k) dst[m][k] = *(const PG8_LAS bf16x8*)(lds + PG8_SA(b, h) + aoff + m * 2048 + k * 1024); } while (0)
; template <class Epi, class Sched, bool ALIGN_EPI = false, bool SP2 = false>
; __device__ __forceinline__ void gemm_phase(PG8_LAS unsigned char* lds, const Gemm g, const Sched& S, const Epi& E) {
;     ...
;             PG8_LDA(At, 1, 1); PG8_STAGE(PG8_SB(1, 0), b3, voffB); PG8_STAGE(PG8_SB(1, 1), b3 + hstep, voffB); PG8_STAGE(PG8_SA(1, 0), a3, voffA);
	s_mov_b32 m0, s70
	s_nop 0
	global_load_lds_dwordx4 v252, s[98:99]

; #define PG8_STAGE(bufoff, gbase, voff) do { _Pragma("unroll") for (int _i = 0; _i < 2; ++_i) \
;         __builtin_amdgcn_global_load_lds((const unsigned*)((const char*)(gbase) + (voff)[_i]), (PG8_LAS unsigned*)(lds + (bufoff) + ldsw + _i * 8192), 16, 0, 0); } while (0)
; #define PG8_LDA(dst, b, h) do { _Pragma("unroll") for (int m = 0; m < 4; ++m) _Pragma("unroll") for (int k = 0; k < 2; ++k) dst[m][k] = *(const PG8_LAS bf16x8*)(lds + PG8_SA(b, h) + aoff + m * 2048 + k * 1024); } while (0)
; #define PG8_MMA(ai, bj, At, Bt) do { __builtin_amdgcn_s_setprio(1); _Pragma("unroll") for (int m = 0; m < 4; ++m) _Pragma("unroll") for (int n = 0; n < 2; ++n) _Pragma("unroll") for (int k = 0; k < 2; ++k) \
;         acc[ai][bj][m][n] = __builtin_amdgcn_mfma_f32_16x16x32_bf16(Bt[n][k], At[m][k], acc[ai][bj][m][n], 0, 0, 0); __builtin_amdgcn_s_setprio(0); } while (0)
; #define PG8_WAIT_V(n) asm volatile("s_waitcnt vmcnt(" #n ")" ::: "memory")
; #define PG8_WAIT_L(n) asm volatile("s_waitcnt lgkmcnt(" #n ")" ::: "memory")
; #define PG8_BAR __builtin_amdgcn_s_barrier()
; #define PG8_SCHED __builtin_amdgcn_sched_barrier(0)
; template <class Epi, class Sched, bool ALIGN_EPI = false, bool SP2 = false>
; __device__ __forceinline__ void gemm_phase(PG8_LAS unsigned char* lds, const Gemm g, const Sched& S, const Epi& E) {
;     ...
;             PG8_LDA(At, 1, 1); PG8_STAGE(PG8_SB(1, 0), b3, voffB); PG8_STAGE(PG8_SB(1, 1), b3 + hstep, voffB); PG8_STAGE(PG8_SA(1, 0), a3, voffA);
;             PG8_WAIT_V(8); PG8_WAIT_L(0); PG8_BAR; PG8_MMA(1, 0, At, B0); PG8_MMA(1, 1, At, B1); PG8_BAR; PG8_SCHED;
	s_mov_b32 m0, s71
	s_nop 0
	global_load_lds_dwordx4 v253, s[98:99]
	s_waitcnt vmcnt(8)
	s_waitcnt lgkmcnt(0)

; #define PG8_MMA(ai, bj, At, Bt) do { __builtin_amdgcn_s_setprio(1); _Pragma("unroll") for (int m = 0; m < 4; ++m) _Pragma("unroll") for (int n = 0; n < 2; ++n) _Pragma("unroll") for (int k = 0; k < 2; ++k) \
;         acc[ai][bj][m][n] = __builtin_amdgcn_mfma_f32_16x16x32_bf16(Bt[n][k], At[m][k], acc[ai][bj][m][n], 0, 0, 0); __builtin_amdgcn_s_setprio(0); } while (0)
; #define PG8_WAIT_V(n) asm volatile("s_waitcnt vmcnt(" #n ")" ::: "memory")
; #define PG8_WAIT_L(n) asm volatile("s_waitcnt lgkmcnt(" #n ")" ::: "memory")
; #define PG8_BAR __builtin_amdgcn_s_barrier()
; #define PG8_SCHED __builtin_amdgcn_sched_barrier(0)
; template <class Epi, class Sched, bool ALIGN_EPI = false, bool SP2 = false>
; __device__ __forceinline__ void gemm_phase(PG8_LAS unsigned char* lds, const Gemm g, const Sched& S, const Epi& E) {
;     ...
;             PG8_WAIT_V(8); PG8_WAIT_L(0); PG8_BAR; PG8_MMA(1, 0, At, B0); PG8_MMA(1, 1, At, B1); PG8_BAR; PG8_SCHED;
	s_barrier

; #define PG8_MMA(ai, bj, At, Bt) do { __builtin_amdgcn_s_setprio(1); _Pragma("unroll") for (int m = 0; m < 4; ++m) _Pragma("unroll") for (int n = 0; n < 2; ++n) _Pragma("unroll") for (int k = 0; k < 2; ++k) \
;         acc[ai][bj][m][n] = __builtin_amdgcn_mfma_f32_16x16x32_bf16(Bt[n][k], At[m][k], acc[ai][bj][m][n], 0, 0, 0); __builtin_amdgcn_s_setprio(0); } while (0)
; #define PG8_WAIT_V(n) asm volatile("s_waitcnt vmcnt(" #n ")" ::: "memory")
; #define PG8_WAIT_L(n) asm volatile("s_waitcnt lgkmcnt(" #n ")" ::: "memory")
; #define PG8_BAR __builtin_amdgcn_s_barrier()
; #define PG8_SCHED __builtin_amdgcn_sched_barrier(0)
; template <class Epi, class Sched, bool ALIGN_EPI = false, bool SP2 = false>
; __device__ __forceinline__ void gemm_phase(PG8_LAS unsigned char* lds, const Gemm g, const Sched& S, const Epi& E) {
;     ...
;             PG8_WAIT_V(8); PG8_WAIT_L(0); PG8_BAR; PG8_MMA(1, 0, At, B0); PG8_MMA(1, 1, At, B1); PG8_BAR; PG8_SCHED;
	v_mfma_f32_16x16x32_bf16 v[60:63], v[64:67], v[176:179], v[60:63]
	v_mfma_f32_16x16x32_bf16 v[56:59], v[72:75], v[176:179], v[56:59]
	v_mfma_f32_16x16x32_bf16 v[44:47], v[64:67], v[184:187], v[44:47]
	v_mfma_f32_16x16x32_bf16 v[40:43], v[72:75], v[184:187], v[40:43]
	v_mfma_f32_16x16x32_bf16 v[28:31], v[64:67], v[192:195], v[28:31]
	v_mfma_f32_16x16x32_bf16 v[24:27], v[72:75], v[192:195], v[24:27]
	v_mfma_f32_16x16x32_bf16 v[12:15], v[64:67], v[200:203], v[12:15]
	v_mfma_f32_16x16x32_bf16 v[8:11], v[72:75], v[200:203], v[8:11]
	v_mfma_f32_16x16x32_bf16 v[60:63], v[68:71], v[180:183], v[60:63]
	v_mfma_f32_16x16x32_bf16 v[56:59], v[76:79], v[180:183], v[56:59]
	v_mfma_f32_16x16x32_bf16 v[44:47], v[68:71], v[188:191], v[44:47]
	v_mfma_f32_16x16x32_bf16 v[40:43], v[76:79], v[188:191], v[40:43]
	v_mfma_f32_16x16x32_bf16 v[28:31], v[68:71], v[196:199], v[28:31]
	v_mfma_f32_16x16x32_bf16 v[24:27], v[76:79], v[196:199], v[24:27]
	v_mfma_f32_16x16x32_bf16 v[12:15], v[68:71], v[204:207], v[12:15]
	v_mfma_f32_16x16x32_bf16 v[8:11], v[76:79], v[204:207], v[8:11]


; #define PG8_MMA(ai, bj, At, Bt) do { __builtin_amdgcn_s_setprio(1); _Pragma("unroll") for (int m = 0; m < 4; ++m) _Pragma("unroll") for (int n = 0; n < 2; ++n) _Pragma("unroll") for (int k = 0; k < 2; ++k) \
;         acc[ai][bj][m][n] = __builtin_amdgcn_mfma_f32_16x16x32_bf16(Bt[n][k], At[m][k], acc[ai][bj][m][n], 0, 0, 0); __builtin_amdgcn_s_setprio(0); } while (0)
; #define PG8_WAIT_V(n) asm volatile("s_waitcnt vmcnt(" #n ")" ::: "memory")
; #define PG8_WAIT_L(n) asm volatile("s_waitcnt lgkmcnt(" #n ")" ::: "memory")
; #define PG8_BAR __builtin_amdgcn_s_barrier()
; #define PG8_SCHED __builtin_amdgcn_sched_barrier(0)
; template <class Epi, class Sched, bool ALIGN_EPI = false, bool SP2 = false>
; __device__ __forceinline__ void gemm_phase(PG8_LAS unsigned char* lds, const Gemm g, const Sched& S, const Epi& E) {
;     ...
;             PG8_WAIT_V(8); PG8_WAIT_L(0); PG8_BAR; PG8_MMA(1, 0, At, B0); PG8_MMA(1, 1, At, B1); PG8_BAR; PG8_SCHED;
	v_mfma_f32_16x16x32_bf16 v[52:55], v[144:147], v[176:179], v[52:55]
	v_mfma_f32_16x16x32_bf16 v[48:51], v[152:155], v[176:179], v[48:51]
	v_mfma_f32_16x16x32_bf16 v[36:39], v[144:147], v[184:187], v[36:39]
	v_mfma_f32_16x16x32_bf16 v[32:35], v[152:155], v[184:187], v[32:35]
	v_mfma_f32_16x16x32_bf16 v[20:23], v[144:147], v[192:195], v[20:23]
	v_mfma_f32_16x16x32_bf16 v[16:19], v[152:155], v[192:195], v[16:19]
	v_mfma_f32_16x16x32_bf16 v[4:7], v[144:147], v[200:203], v[4:7]
	v_mfma_f32_16x16x32_bf16 v[0:3], v[152:155], v[200:203], v[0:3]
	v_mfma_f32_16x16x32_bf16 v[52:55], v[148:151], v[180:183], v[52:55]
	v_mfma_f32_16x16x32_bf16 v[48:51], v[156:159], v[180:183], v[48:51]
	v_mfma_f32_16x16x32_bf16 v[36:39], v[148:151], v[188:191], v[36:39]
	v_mfma_f32_16x16x32_bf16 v[32:35], v[156:159], v[188:191], v[32:35]
	v_mfma_f32_16x16x32_bf16 v[20:23], v[148:151], v[196:199], v[20:23]
	v_mfma_f32_16x16x32_bf16 v[16:19], v[156:159], v[196:199], v[16:19]
	v_mfma_f32_16x16x32_bf16 v[4:7], v[148:151], v[204:207], v[4:7]
	v_mfma_f32_16x16x32_bf16 v[0:3], v[156:159], v[204:207], v[0:3]

; #define PG8_STAGE(bufoff, gbase, voff) do { _Pragma("unroll") for (int _i = 0; _i < 2; ++_i) \
;         __builtin_amdgcn_global_load_lds((const unsigned*)((const char*)(gbase) + (voff)[_i]), (PG8_LAS unsigned*)(lds + (bufoff) + ldsw + _i * 8192), 16, 0, 0); } while (0)
; #define PG8_LDA(dst, b, h) do { _Pragma("unroll") for (int m = 0; m < 4; ++m) _Pragma("unroll") for (int k = 0; k < 2; ++k) dst[m][k] = *(const PG8_LAS bf16x8*)(lds + PG8_SA(b, h) + aoff + m * 2048 + k * 1024); } while (0)
; #define PG8_WAIT_V(n) asm volatile("s_waitcnt vmcnt(" #n ")" ::: "memory")
; #define PG8_WAIT_L(n) asm volatile("s_waitcnt lgkmcnt(" #n ")" ::: "memory")
; template <class Epi, class Sched, bool ALIGN_EPI = false, bool SP2 = false>
; __device__ __forceinline__ void gemm_phase(PG8_LAS unsigned char* lds, const Gemm g, const Sched& S, const Epi& E) {
;     ...
;         for (int t = 0; t < nt; t += 2) {
;             const bool last = (t == nt - 2);
;             const char* a1 = cA + (size_t)(t + 1) * kstep;
;             const char* a2 = last ? nA : cA + (size_t)(t + 2) * kstep; const char* b2 = last ? nB : cB + (size_t)(t + 2) * kstep;
;             const char* a3 = a2 + kstep; const char* b3 = b2 + kstep;
;             if (last && has_next) S.a_ready(nxt);
;             if constexpr (SP2) {
;             PG8_LDB(B0, 0, 0); PG8_LDB(B1, 0, 1); PG8_SCHED; PG8_LDA(At, 0, 0); PG8_STAGE(PG8_SA(1, 1), a1 + hstep, voffA);
;             PG8_WAIT_V(8); PG8_WAIT_L(0); PG8_BAR; PG8_MMA(0, 0, At, B0); PG8_MMA(0, 1, At, B1); PG8_BAR; PG8_SCHED;
;             PG8_LDA(At, 0, 1); PG8_STAGE(PG8_SB(0, 0), b2, voffB); PG8_STAGE(PG8_SB(0, 1), b2 + hstep, voffB); PG8_STAGE(PG8_SA(0, 0), a2, voffA);
;             PG8_WAIT_V(8); PG8_WAIT_L(0); PG8_BAR; PG8_MMA(1, 0, At, B0); PG8_MMA(1, 1, At, B1); PG8_BAR; PG8_SCHED;
;             PG8_LDB(B0, 1, 0); PG8_LDB(B1, 1, 1); PG8_SCHED; PG8_LDA(At, 1, 0); PG8_STAGE(PG8_SA(0, 1), a2 + hstep, voffA);
;             PG8_WAIT_V(8); PG8_WAIT_L(0); PG8_BAR; PG8_MMA(0, 0, At, B0); PG8_MMA(0, 1, At, B1); PG8_BAR; PG8_SCHED;
;             PG8_LDA(At, 1, 1); PG8_STAGE(PG8_SB(1, 0), b3, voffB); PG8_STAGE(PG8_SB(1, 1), b3 + hstep, voffB); PG8_STAGE(PG8_SA(1, 0), a3, voffA);
;             PG8_WAIT_V(8); PG8_WAIT_L(0); PG8_BAR; PG8_MMA(1, 0, At, B0); PG8_MMA(1, 1, At, B1); PG8_BAR; PG8_SCHED;
;     ...
;         if constexpr (ALIGN_EPI) { if (wr == 0) PG8_BAR; }
	s_barrier
	s_add_i32 s81, s81, 2
	s_add_u32 s58, s58, 0x100
	s_addc_u32 s59, s59, 0
	s_add_u32 s79, s79, 0x100
	s_addc_u32 s80, s80, 0
	s_cmp_gt_u32 s81, 29
	s_cbranch_scc0 .LBB0_333
	s_and_b64 vcc, exec, s[42:43]
	s_cbranch_vccz .LBB0_336
	s_barrier

; #define PG8_STAGE(bufoff, gbase, voff) do { _Pragma("unroll") for (int _i = 0; _i < 2; ++_i) \
;         __builtin_amdgcn_global_load_lds((const unsigned*)((const char*)(gbase) + (voff)[_i]), (PG8_LAS unsigned*)(lds + (bufoff) + ldsw + _i * 8192), 16, 0, 0); } while (0)
; #define PG8_LDA(dst, b, h) do { _Pragma("unroll") for (int m = 0; m < 4; ++m) _Pragma("unroll") for (int k = 0; k < 2; ++k) dst[m][k] = *(const PG8_LAS bf16x8*)(lds + PG8_SA(b, h) + aoff + m * 2048 + k * 1024); } while (0)
; #define PG8_LDB(dst, b, h) do { _Pragma("unroll") for (int n = 0; n < 2; ++n) _Pragma("unroll") for (int k = 0; k < 2; ++k) dst[n][k] = *(const PG8_LAS bf16x8*)(lds + PG8_SB(b, h) + boff + n * 2048 + k * 1024); } while (0)
; #define PG8_SCHED __builtin_amdgcn_sched_barrier(0)
; template <class Epi, class Sched, bool ALIGN_EPI = false, bool SP2 = false>
; __device__ __forceinline__ void gemm_phase(PG8_LAS unsigned char* lds, const Gemm g, const Sched& S, const Epi& E) {
;     ...
;             const bool last = (t == nt - 2);
;             const char* a1 = cA + (size_t)(t + 1) * kstep;
;             const char* a2 = last ? nA : cA + (size_t)(t + 2) * kstep; const char* b2 = last ? nB : cB + (size_t)(t + 2) * kstep;
;             const char* a3 = a2 + kstep; const char* b3 = b2 + kstep;
;             if (last && has_next) S.a_ready(nxt);
;             if constexpr (SP2) {
;             PG8_LDB(B0, 0, 0); PG8_LDB(B1, 0, 1); PG8_SCHED; PG8_LDA(At, 0, 0); PG8_STAGE(PG8_SA(1, 1), a1 + hstep, voffA);
.LBB0_428:
	ds_read_b128 v[128:131], v201
	ds_read_b128 v[132:135], v201 offset:1024
	ds_read_b128 v[136:139], v201 offset:2048
	ds_read_b128 v[140:143], v201 offset:3072
	ds_read_b128 v[144:147], v205
	ds_read_b128 v[148:151], v205 offset:1024
	ds_read_b128 v[152:155], v205 offset:2048
	ds_read_b128 v[156:159], v205 offset:3072
	s_add_u32 s12, s10, 0xfff80080
	s_addc_u32 s13, s11, -1
	s_cmp_eq_u32 s85, 28
	s_cselect_b32 s61, s55, s13
	s_cselect_b32 s60, s81, s12
	s_cselect_b32 s13, s53, s84
	s_cselect_b32 s12, s82, s83

; #define PG8_STAGE(bufoff, gbase, voff) do { _Pragma("unroll") for (int _i = 0; _i < 2; ++_i) \
;         __builtin_amdgcn_global_load_lds((const unsigned*)((const char*)(gbase) + (voff)[_i]), (PG8_LAS unsigned*)(lds + (bufoff) + ldsw + _i * 8192), 16, 0, 0); } while (0)
; #define PG8_LDA(dst, b, h) do { _Pragma("unroll") for (int m = 0; m < 4; ++m) _Pragma("unroll") for (int k = 0; k < 2; ++k) dst[m][k] = *(const PG8_LAS bf16x8*)(lds + PG8_SA(b, h) + aoff + m * 2048 + k * 1024); } while (0)
; #define PG8_LDB(dst, b, h) do { _Pragma("unroll") for (int n = 0; n < 2; ++n) _Pragma("unroll") for (int k = 0; k < 2; ++k) dst[n][k] = *(const PG8_LAS bf16x8*)(lds + PG8_SB(b, h) + boff + n * 2048 + k * 1024); } while (0)
; #define PG8_SCHED __builtin_amdgcn_sched_barrier(0)
; template <class Epi, class Sched, bool ALIGN_EPI = false, bool SP2 = false>
; __device__ __forceinline__ void gemm_phase(PG8_LAS unsigned char* lds, const Gemm g, const Sched& S, const Epi& E) {
;     ...
;             PG8_LDB(B0, 0, 0); PG8_LDB(B1, 0, 1); PG8_SCHED; PG8_LDA(At, 0, 0); PG8_STAGE(PG8_SA(1, 1), a1 + hstep, voffA);
	s_add_i32 m0, s65, 0xc000
	ds_read_b128 v[176:179], v207
	ds_read_b128 v[184:187], v207 offset:1024
	ds_read_b128 v[190:193], v207 offset:2048
	ds_read_b128 v[210:213], v207 offset:3072
	ds_read_b128 v[214:217], v207 offset:4096
	ds_read_b128 v[218:221], v207 offset:5120
	ds_read_b128 v[222:225], v207 offset:6144
	ds_read_b128 v[226:229], v207 offset:7168
	global_load_lds_dwordx4 v168, s[10:11]

; #define PG8_STAGE(bufoff, gbase, voff) do { _Pragma("unroll") for (int _i = 0; _i < 2; ++_i) \
;         __builtin_amdgcn_global_load_lds((const unsigned*)((const char*)(gbase) + (voff)[_i]), (PG8_LAS unsigned*)(lds + (bufoff) + ldsw + _i * 8192), 16, 0, 0); } while (0)
; #define PG8_LDA(dst, b, h) do { _Pragma("unroll") for (int m = 0; m < 4; ++m) _Pragma("unroll") for (int k = 0; k < 2; ++k) dst[m][k] = *(const PG8_LAS bf16x8*)(lds + PG8_SA(b, h) + aoff + m * 2048 + k * 1024); } while (0)
; #define PG8_LDB(dst, b, h) do { _Pragma("unroll") for (int n = 0; n < 2; ++n) _Pragma("unroll") for (int k = 0; k < 2; ++k) dst[n][k] = *(const PG8_LAS bf16x8*)(lds + PG8_SB(b, h) + boff + n * 2048 + k * 1024); } while (0)
; #define PG8_MMA(ai, bj, At, Bt) do { __builtin_amdgcn_s_setprio(1); _Pragma("unroll") for (int m = 0; m < 4; ++m) _Pragma("unroll") for (int n = 0; n < 2; ++n) _Pragma("unroll") for (int k = 0; k < 2; ++k) \
;         acc[ai][bj][m][n] = __builtin_amdgcn_mfma_f32_16x16x32_bf16(Bt[n][k], At[m][k], acc[ai][bj][m][n], 0, 0, 0); __builtin_amdgcn_s_setprio(0); } while (0)
; #define PG8_WAIT_V(n) asm volatile("s_waitcnt vmcnt(" #n ")" ::: "memory")
; #define PG8_WAIT_L(n) asm volatile("s_waitcnt lgkmcnt(" #n ")" ::: "memory")
; #define PG8_BAR __builtin_amdgcn_s_barrier()
; #define PG8_SCHED __builtin_amdgcn_sched_barrier(0)
; template <class Epi, class Sched, bool ALIGN_EPI = false, bool SP2 = false>
; __device__ __forceinline__ void gemm_phase(PG8_LAS unsigned char* lds, const Gemm g, const Sched& S, const Epi& E) {
;     ...
;             PG8_LDB(B0, 0, 0); PG8_LDB(B1, 0, 1); PG8_SCHED; PG8_LDA(At, 0, 0); PG8_STAGE(PG8_SA(1, 1), a1 + hstep, voffA);
;             PG8_WAIT_V(8); PG8_WAIT_L(0); PG8_BAR; PG8_MMA(0, 0, At, B0); PG8_MMA(0, 1, At, B1); PG8_BAR; PG8_SCHED;
	s_add_i32 m0, s65, 0xe000
	s_nop 0
	global_load_lds_dwordx4 v170, s[10:11]
	s_waitcnt vmcnt(8)
	s_waitcnt lgkmcnt(0)

; #define PG8_MMA(ai, bj, At, Bt) do { __builtin_amdgcn_s_setprio(1); _Pragma("unroll") for (int m = 0; m < 4; ++m) _Pragma("unroll") for (int n = 0; n < 2; ++n) _Pragma("unroll") for (int k = 0; k < 2; ++k) \
;         acc[ai][bj][m][n] = __builtin_amdgcn_mfma_f32_16x16x32_bf16(Bt[n][k], At[m][k], acc[ai][bj][m][n], 0, 0, 0); __builtin_amdgcn_s_setprio(0); } while (0)
; #define PG8_WAIT_V(n) asm volatile("s_waitcnt vmcnt(" #n ")" ::: "memory")
; #define PG8_WAIT_L(n) asm volatile("s_waitcnt lgkmcnt(" #n ")" ::: "memory")
; #define PG8_BAR __builtin_amdgcn_s_barrier()
; #define PG8_SCHED __builtin_amdgcn_sched_barrier(0)
; template <class Epi, class Sched, bool ALIGN_EPI = false, bool SP2 = false>
; __device__ __forceinline__ void gemm_phase(PG8_LAS unsigned char* lds, const Gemm g, const Sched& S, const Epi& E) {
;     ...
;             PG8_WAIT_V(8); PG8_WAIT_L(0); PG8_BAR; PG8_MMA(0, 0, At, B0); PG8_MMA(0, 1, At, B1); PG8_BAR; PG8_SCHED;
	s_barrier

; #define PG8_MMA(ai, bj, At, Bt) do { __builtin_amdgcn_s_setprio(1); _Pragma("unroll") for (int m = 0; m < 4; ++m) _Pragma("unroll") for (int n = 0; n < 2; ++n) _Pragma("unroll") for (int k = 0; k < 2; ++k) \
;         acc[ai][bj][m][n] = __builtin_amdgcn_mfma_f32_16x16x32_bf16(Bt[n][k], At[m][k], acc[ai][bj][m][n], 0, 0, 0); __builtin_amdgcn_s_setprio(0); } while (0)
; #define PG8_WAIT_V(n) asm volatile("s_waitcnt vmcnt(" #n ")" ::: "memory")
; #define PG8_WAIT_L(n) asm volatile("s_waitcnt lgkmcnt(" #n ")" ::: "memory")
; #define PG8_BAR __builtin_amdgcn_s_barrier()
; #define PG8_SCHED __builtin_amdgcn_sched_barrier(0)
; template <class Epi, class Sched, bool ALIGN_EPI = false, bool SP2 = false>
; __device__ __forceinline__ void gemm_phase(PG8_LAS unsigned char* lds, const Gemm g, const Sched& S, const Epi& E) {
;     ...
;             PG8_WAIT_V(8); PG8_WAIT_L(0); PG8_BAR; PG8_MMA(0, 0, At, B0); PG8_MMA(0, 1, At, B1); PG8_BAR; PG8_SCHED;
	v_mfma_f32_16x16x32_bf16 v[124:127], v[128:131], v[176:179], v[124:127]
	v_mfma_f32_16x16x32_bf16 v[120:123], v[136:139], v[176:179], v[120:123]
	v_mfma_f32_16x16x32_bf16 v[108:111], v[128:131], v[190:193], v[108:111]
	v_mfma_f32_16x16x32_bf16 v[104:107], v[136:139], v[190:193], v[104:107]
	v_mfma_f32_16x16x32_bf16 v[92:95], v[128:131], v[214:217], v[92:95]
	v_mfma_f32_16x16x32_bf16 v[88:91], v[136:139], v[214:217], v[88:91]
	v_mfma_f32_16x16x32_bf16 v[76:79], v[128:131], v[222:225], v[76:79]
	v_mfma_f32_16x16x32_bf16 v[72:75], v[136:139], v[222:225], v[72:75]
	v_mfma_f32_16x16x32_bf16 v[124:127], v[132:135], v[184:187], v[124:127]
	v_mfma_f32_16x16x32_bf16 v[120:123], v[140:143], v[184:187], v[120:123]
	v_mfma_f32_16x16x32_bf16 v[108:111], v[132:135], v[210:213], v[108:111]
	v_mfma_f32_16x16x32_bf16 v[104:107], v[140:143], v[210:213], v[104:107]
	v_mfma_f32_16x16x32_bf16 v[92:95], v[132:135], v[218:221], v[92:95]
	v_mfma_f32_16x16x32_bf16 v[88:91], v[140:143], v[218:221], v[88:91]
	v_mfma_f32_16x16x32_bf16 v[76:79], v[132:135], v[226:229], v[76:79]
	v_mfma_f32_16x16x32_bf16 v[72:75], v[140:143], v[226:229], v[72:75]


; #define PG8_MMA(ai, bj, At, Bt) do { __builtin_amdgcn_s_setprio(1); _Pragma("unroll") for (int m = 0; m < 4; ++m) _Pragma("unroll") for (int n = 0; n < 2; ++n) _Pragma("unroll") for (int k = 0; k < 2; ++k) \
;         acc[ai][bj][m][n] = __builtin_amdgcn_mfma_f32_16x16x32_bf16(Bt[n][k], At[m][k], acc[ai][bj][m][n], 0, 0, 0); __builtin_amdgcn_s_setprio(0); } while (0)
; #define PG8_WAIT_V(n) asm volatile("s_waitcnt vmcnt(" #n ")" ::: "memory")
; #define PG8_WAIT_L(n) asm volatile("s_waitcnt lgkmcnt(" #n ")" ::: "memory")
; #define PG8_BAR __builtin_amdgcn_s_barrier()
; #define PG8_SCHED __builtin_amdgcn_sched_barrier(0)
; template <class Epi, class Sched, bool ALIGN_EPI = false, bool SP2 = false>
; __device__ __forceinline__ void gemm_phase(PG8_LAS unsigned char* lds, const Gemm g, const Sched& S, const Epi& E) {
;     ...
;             PG8_WAIT_V(8); PG8_WAIT_L(0); PG8_BAR; PG8_MMA(0, 0, At, B0); PG8_MMA(0, 1, At, B1); PG8_BAR; PG8_SCHED;
	v_mfma_f32_16x16x32_bf16 v[116:119], v[144:147], v[176:179], v[116:119]
	v_mfma_f32_16x16x32_bf16 v[112:115], v[152:155], v[176:179], v[112:115]
	v_mfma_f32_16x16x32_bf16 v[100:103], v[144:147], v[190:193], v[100:103]
	v_mfma_f32_16x16x32_bf16 v[96:99], v[152:155], v[190:193], v[96:99]
	v_mfma_f32_16x16x32_bf16 v[84:87], v[144:147], v[214:217], v[84:87]
	v_mfma_f32_16x16x32_bf16 v[80:83], v[152:155], v[214:217], v[80:83]
	v_mfma_f32_16x16x32_bf16 v[68:71], v[144:147], v[222:225], v[68:71]
	v_mfma_f32_16x16x32_bf16 v[64:67], v[152:155], v[222:225], v[64:67]
	v_mfma_f32_16x16x32_bf16 v[116:119], v[148:151], v[184:187], v[116:119]
	v_mfma_f32_16x16x32_bf16 v[112:115], v[156:159], v[184:187], v[112:115]
	v_mfma_f32_16x16x32_bf16 v[100:103], v[148:151], v[210:213], v[100:103]
	v_mfma_f32_16x16x32_bf16 v[96:99], v[156:159], v[210:213], v[96:99]
	v_mfma_f32_16x16x32_bf16 v[84:87], v[148:151], v[218:221], v[84:87]
	v_mfma_f32_16x16x32_bf16 v[80:83], v[156:159], v[218:221], v[80:83]
	v_mfma_f32_16x16x32_bf16 v[68:71], v[148:151], v[226:229], v[68:71]
	v_mfma_f32_16x16x32_bf16 v[64:67], v[156:159], v[226:229], v[64:67]

; #define PG8_STAGE(bufoff, gbase, voff) do { _Pragma("unroll") for (int _i = 0; _i < 2; ++_i) \
;         __builtin_amdgcn_global_load_lds((const unsigned*)((const char*)(gbase) + (voff)[_i]), (PG8_LAS unsigned*)(lds + (bufoff) + ldsw + _i * 8192), 16, 0, 0); } while (0)
; #define PG8_LDA(dst, b, h) do { _Pragma("unroll") for (int m = 0; m < 4; ++m) _Pragma("unroll") for (int k = 0; k < 2; ++k) dst[m][k] = *(const PG8_LAS bf16x8*)(lds + PG8_SA(b, h) + aoff + m * 2048 + k * 1024); } while (0)
; #define PG8_MMA(ai, bj, At, Bt) do { __builtin_amdgcn_s_setprio(1); _Pragma("unroll") for (int m = 0; m < 4; ++m) _Pragma("unroll") for (int n = 0; n < 2; ++n) _Pragma("unroll") for (int k = 0; k < 2; ++k) \
;         acc[ai][bj][m][n] = __builtin_amdgcn_mfma_f32_16x16x32_bf16(Bt[n][k], At[m][k], acc[ai][bj][m][n], 0, 0, 0); __builtin_amdgcn_s_setprio(0); } while (0)
; #define PG8_WAIT_V(n) asm volatile("s_waitcnt vmcnt(" #n ")" ::: "memory")
; #define PG8_WAIT_L(n) asm volatile("s_waitcnt lgkmcnt(" #n ")" ::: "memory")
; #define PG8_BAR __builtin_amdgcn_s_barrier()
; #define PG8_SCHED __builtin_amdgcn_sched_barrier(0)
; template <class Epi, class Sched, bool ALIGN_EPI = false, bool SP2 = false>
; __device__ __forceinline__ void gemm_phase(PG8_LAS unsigned char* lds, const Gemm g, const Sched& S, const Epi& E) {
;     ...
;             PG8_WAIT_V(8); PG8_WAIT_L(0); PG8_BAR; PG8_MMA(0, 0, At, B0); PG8_MMA(0, 1, At, B1); PG8_BAR; PG8_SCHED;
;             PG8_LDA(At, 0, 1); PG8_STAGE(PG8_SB(0, 0), b2, voffB); PG8_STAGE(PG8_SB(0, 1), b2 + hstep, voffB); PG8_STAGE(PG8_SA(0, 0), a2, voffA);
	s_barrier
	s_add_i32 s86, s75, s64
	s_mov_b64 s[96:97], s[12:13]

; #define PG8_STAGE(bufoff, gbase, voff) do { _Pragma("unroll") for (int _i = 0; _i < 2; ++_i) \
;         __builtin_amdgcn_global_load_lds((const unsigned*)((const char*)(gbase) + (voff)[_i]), (PG8_LAS unsigned*)(lds + (bufoff) + ldsw + _i * 8192), 16, 0, 0); } while (0)
; #define PG8_LDA(dst, b, h) do { _Pragma("unroll") for (int m = 0; m < 4; ++m) _Pragma("unroll") for (int k = 0; k < 2; ++k) dst[m][k] = *(const PG8_LAS bf16x8*)(lds + PG8_SA(b, h) + aoff + m * 2048 + k * 1024); } while (0)
; template <class Epi, class Sched, bool ALIGN_EPI = false, bool SP2 = false>
; __device__ __forceinline__ void gemm_phase(PG8_LAS unsigned char* lds, const Gemm g, const Sched& S, const Epi& E) {
;     ...
;             PG8_LDA(At, 0, 1); PG8_STAGE(PG8_SB(0, 0), b2, voffB); PG8_STAGE(PG8_SB(0, 1), b2 + hstep, voffB); PG8_STAGE(PG8_SA(0, 0), a2, voffA);
	s_mov_b32 m0, s86
	ds_read_b128 v[176:179], v207 offset:16384
	ds_read_b128 v[184:187], v207 offset:17408
	ds_read_b128 v[190:193], v207 offset:18432
	ds_read_b128 v[210:213], v207 offset:19456
	ds_read_b128 v[214:217], v207 offset:20480
	ds_read_b128 v[218:221], v207 offset:21504
	ds_read_b128 v[222:225], v207 offset:22528
	ds_read_b128 v[226:229], v207 offset:23552
	global_load_lds_dwordx4 v162, s[12:13]
	s_add_i32 m0, s86, 0x2000
	s_add_u32 s86, s12, 0x80000

; #define PG8_STAGE(bufoff, gbase, voff) do { _Pragma("unroll") for (int _i = 0; _i < 2; ++_i) \
;         __builtin_amdgcn_global_load_lds((const unsigned*)((const char*)(gbase) + (voff)[_i]), (PG8_LAS unsigned*)(lds + (bufoff) + ldsw + _i * 8192), 16, 0, 0); } while (0)
; #define PG8_LDA(dst, b, h) do { _Pragma("unroll") for (int m = 0; m < 4; ++m) _Pragma("unroll") for (int k = 0; k < 2; ++k) dst[m][k] = *(const PG8_LAS bf16x8*)(lds + PG8_SA(b, h) + aoff + m * 2048 + k * 1024); } while (0)
; template <class Epi, class Sched, bool ALIGN_EPI = false, bool SP2 = false>
; __device__ __forceinline__ void gemm_phase(PG8_LAS unsigned char* lds, const Gemm g, const Sched& S, const Epi& E) {
;     ...
;             PG8_LDA(At, 0, 1); PG8_STAGE(PG8_SB(0, 0), b2, voffB); PG8_STAGE(PG8_SB(0, 1), b2 + hstep, voffB); PG8_STAGE(PG8_SA(0, 0), a2, voffA);
	s_addc_u32 s87, s13, 0
	s_add_i32 s88, s76, s64
	global_load_lds_dwordx4 v166, s[12:13]

; #define PG8_STAGE(bufoff, gbase, voff) do { _Pragma("unroll") for (int _i = 0; _i < 2; ++_i) \
;         __builtin_amdgcn_global_load_lds((const unsigned*)((const char*)(gbase) + (voff)[_i]), (PG8_LAS unsigned*)(lds + (bufoff) + ldsw + _i * 8192), 16, 0, 0); } while (0)
; #define PG8_LDA(dst, b, h) do { _Pragma("unroll") for (int m = 0; m < 4; ++m) _Pragma("unroll") for (int k = 0; k < 2; ++k) dst[m][k] = *(const PG8_LAS bf16x8*)(lds + PG8_SA(b, h) + aoff + m * 2048 + k * 1024); } while (0)
; template <class Epi, class Sched, bool ALIGN_EPI = false, bool SP2 = false>
; __device__ __forceinline__ void gemm_phase(PG8_LAS unsigned char* lds, const Gemm g, const Sched& S, const Epi& E) {
;     ...
;             PG8_LDA(At, 0, 1); PG8_STAGE(PG8_SB(0, 0), b2, voffB); PG8_STAGE(PG8_SB(0, 1), b2 + hstep, voffB); PG8_STAGE(PG8_SA(0, 0), a2, voffA);
	s_mov_b32 m0, s88
	s_nop 0
	global_load_lds_dwordx4 v162, s[86:87]

; #define PG8_STAGE(bufoff, gbase, voff) do { _Pragma("unroll") for (int _i = 0; _i < 2; ++_i) \
;         __builtin_amdgcn_global_load_lds((const unsigned*)((const char*)(gbase) + (voff)[_i]), (PG8_LAS unsigned*)(lds + (bufoff) + ldsw + _i * 8192), 16, 0, 0); } while (0)
; #define PG8_LDA(dst, b, h) do { _Pragma("unroll") for (int m = 0; m < 4; ++m) _Pragma("unroll") for (int k = 0; k < 2; ++k) dst[m][k] = *(const PG8_LAS bf16x8*)(lds + PG8_SA(b, h) + aoff + m * 2048 + k * 1024); } while (0)
; template <class Epi, class Sched, bool ALIGN_EPI = false, bool SP2 = false>
; __device__ __forceinline__ void gemm_phase(PG8_LAS unsigned char* lds, const Gemm g, const Sched& S, const Epi& E) {
;     ...
;             PG8_LDA(At, 0, 1); PG8_STAGE(PG8_SB(0, 0), b2, voffB); PG8_STAGE(PG8_SB(0, 1), b2 + hstep, voffB); PG8_STAGE(PG8_SA(0, 0), a2, voffA);
	s_add_i32 m0, s88, 0x2000
	s_nop 0
	global_load_lds_dwordx4 v166, s[86:87]
	s_mov_b64 s[98:99], s[60:61]

; #define PG8_STAGE(bufoff, gbase, voff) do { _Pragma("unroll") for (int _i = 0; _i < 2; ++_i) \
;         __builtin_amdgcn_global_load_lds((const unsigned*)((const char*)(gbase) + (voff)[_i]), (PG8_LAS unsigned*)(lds + (bufoff) + ldsw + _i * 8192), 16, 0, 0); } while (0)
; #define PG8_LDA(dst, b, h) do { _Pragma("unroll") for (int m = 0; m < 4; ++m) _Pragma("unroll") for (int k = 0; k < 2; ++k) dst[m][k] = *(const PG8_LAS bf16x8*)(lds + PG8_SA(b, h) + aoff + m * 2048 + k * 1024); } while (0)
; #define PG8_MMA(ai, bj, At, Bt) do { __builtin_amdgcn_s_setprio(1); _Pragma("unroll") for (int m = 0; m < 4; ++m) _Pragma("unroll") for (int n = 0; n < 2; ++n) _Pragma("unroll") for (int k = 0; k < 2; ++k) \
;         acc[ai][bj][m][n] = __builtin_amdgcn_mfma_f32_16x16x32_bf16(Bt[n][k], At[m][k], acc[ai][bj][m][n], 0, 0, 0); __builtin_amdgcn_s_setprio(0); } while (0)
; #define PG8_WAIT_V(n) asm volatile("s_waitcnt vmcnt(" #n ")" ::: "memory")
; #define PG8_WAIT_L(n) asm volatile("s_waitcnt lgkmcnt(" #n ")" ::: "memory")
; #define PG8_BAR __builtin_amdgcn_s_barrier()
; #define PG8_SCHED __builtin_amdgcn_sched_barrier(0)
; template <class Epi, class Sched, bool ALIGN_EPI = false, bool SP2 = false>
; __device__ __forceinline__ void gemm_phase(PG8_LAS unsigned char* lds, const Gemm g, const Sched& S, const Epi& E) {
;     ...
;             PG8_LDA(At, 0, 1); PG8_STAGE(PG8_SB(0, 0), b2, voffB); PG8_STAGE(PG8_SB(0, 1), b2 + hstep, voffB); PG8_STAGE(PG8_SA(0, 0), a2, voffA);
;             PG8_WAIT_V(8); PG8_WAIT_L(0); PG8_BAR; PG8_MMA(1, 0, At, B0); PG8_MMA(1, 1, At, B1); PG8_BAR; PG8_SCHED;
	s_mov_b32 m0, s65
	s_nop 0
	global_load_lds_dwordx4 v160, s[60:61]
	s_mov_b32 m0, s67
	s_nop 0
	global_load_lds_dwordx4 v164, s[60:61]
	s_waitcnt vmcnt(8)
	s_waitcnt lgkmcnt(0)

; #define PG8_MMA(ai, bj, At, Bt) do { __builtin_amdgcn_s_setprio(1); _Pragma("unroll") for (int m = 0; m < 4; ++m) _Pragma("unroll") for (int n = 0; n < 2; ++n) _Pragma("unroll") for (int k = 0; k < 2; ++k) \
;         acc[ai][bj][m][n] = __builtin_amdgcn_mfma_f32_16x16x32_bf16(Bt[n][k], At[m][k], acc[ai][bj][m][n], 0, 0, 0); __builtin_amdgcn_s_setprio(0); } while (0)
; #define PG8_WAIT_V(n) asm volatile("s_waitcnt vmcnt(" #n ")" ::: "memory")
; #define PG8_WAIT_L(n) asm volatile("s_waitcnt lgkmcnt(" #n ")" ::: "memory")
; #define PG8_BAR __builtin_amdgcn_s_barrier()
; #define PG8_SCHED __builtin_amdgcn_sched_barrier(0)
; template <class Epi, class Sched, bool ALIGN_EPI = false, bool SP2 = false>
; __device__ __forceinline__ void gemm_phase(PG8_LAS unsigned char* lds, const Gemm g, const Sched& S, const Epi& E) {
;     ...
;             PG8_WAIT_V(8); PG8_WAIT_L(0); PG8_BAR; PG8_MMA(1, 0, At, B0); PG8_MMA(1, 1, At, B1); PG8_BAR; PG8_SCHED;
	s_barrier

; #define PG8_MMA(ai, bj, At, Bt) do { __builtin_amdgcn_s_setprio(1); _Pragma("unroll") for (int m = 0; m < 4; ++m) _Pragma("unroll") for (int n = 0; n < 2; ++n) _Pragma("unroll") for (int k = 0; k < 2; ++k) \
;         acc[ai][bj][m][n] = __builtin_amdgcn_mfma_f32_16x16x32_bf16(Bt[n][k], At[m][k], acc[ai][bj][m][n], 0, 0, 0); __builtin_amdgcn_s_setprio(0); } while (0)
; #define PG8_WAIT_V(n) asm volatile("s_waitcnt vmcnt(" #n ")" ::: "memory")
; #define PG8_WAIT_L(n) asm volatile("s_waitcnt lgkmcnt(" #n ")" ::: "memory")
; #define PG8_BAR __builtin_amdgcn_s_barrier()
; #define PG8_SCHED __builtin_amdgcn_sched_barrier(0)
; template <class Epi, class Sched, bool ALIGN_EPI = false, bool SP2 = false>
; __device__ __forceinline__ void gemm_phase(PG8_LAS unsigned char* lds, const Gemm g, const Sched& S, const Epi& E) {
;     ...
;             PG8_WAIT_V(8); PG8_WAIT_L(0); PG8_BAR; PG8_MMA(1, 0, At, B0); PG8_MMA(1, 1, At, B1); PG8_BAR; PG8_SCHED;
	v_mfma_f32_16x16x32_bf16 v[60:63], v[128:131], v[176:179], v[60:63]
	v_mfma_f32_16x16x32_bf16 v[56:59], v[136:139], v[176:179], v[56:59]
	v_mfma_f32_16x16x32_bf16 v[44:47], v[128:131], v[190:193], v[44:47]
	v_mfma_f32_16x16x32_bf16 v[40:43], v[136:139], v[190:193], v[40:43]
	v_mfma_f32_16x16x32_bf16 v[28:31], v[128:131], v[214:217], v[28:31]
	v_mfma_f32_16x16x32_bf16 v[24:27], v[136:139], v[214:217], v[24:27]
	v_mfma_f32_16x16x32_bf16 v[12:15], v[128:131], v[222:225], v[12:15]
	v_mfma_f32_16x16x32_bf16 v[8:11], v[136:139], v[222:225], v[8:11]
	v_mfma_f32_16x16x32_bf16 v[60:63], v[132:135], v[184:187], v[60:63]
	v_mfma_f32_16x16x32_bf16 v[56:59], v[140:143], v[184:187], v[56:59]
	v_mfma_f32_16x16x32_bf16 v[44:47], v[132:135], v[210:213], v[44:47]
	v_mfma_f32_16x16x32_bf16 v[40:43], v[140:143], v[210:213], v[40:43]
	v_mfma_f32_16x16x32_bf16 v[28:31], v[132:135], v[218:221], v[28:31]
	v_mfma_f32_16x16x32_bf16 v[24:27], v[140:143], v[218:221], v[24:27]
	v_mfma_f32_16x16x32_bf16 v[12:15], v[132:135], v[226:229], v[12:15]
	v_mfma_f32_16x16x32_bf16 v[8:11], v[140:143], v[226:229], v[8:11]


; #define PG8_MMA(ai, bj, At, Bt) do { __builtin_amdgcn_s_setprio(1); _Pragma("unroll") for (int m = 0; m < 4; ++m) _Pragma("unroll") for (int n = 0; n < 2; ++n) _Pragma("unroll") for (int k = 0; k < 2; ++k) \
;         acc[ai][bj][m][n] = __builtin_amdgcn_mfma_f32_16x16x32_bf16(Bt[n][k], At[m][k], acc[ai][bj][m][n], 0, 0, 0); __builtin_amdgcn_s_setprio(0); } while (0)
; #define PG8_WAIT_V(n) asm volatile("s_waitcnt vmcnt(" #n ")" ::: "memory")
; #define PG8_WAIT_L(n) asm volatile("s_waitcnt lgkmcnt(" #n ")" ::: "memory")
; #define PG8_BAR __builtin_amdgcn_s_barrier()
; #define PG8_SCHED __builtin_amdgcn_sched_barrier(0)
; template <class Epi, class Sched, bool ALIGN_EPI = false, bool SP2 = false>
; __device__ __forceinline__ void gemm_phase(PG8_LAS unsigned char* lds, const Gemm g, const Sched& S, const Epi& E) {
;     ...
;             PG8_WAIT_V(8); PG8_WAIT_L(0); PG8_BAR; PG8_MMA(1, 0, At, B0); PG8_MMA(1, 1, At, B1); PG8_BAR; PG8_SCHED;
	v_mfma_f32_16x16x32_bf16 v[52:55], v[144:147], v[176:179], v[52:55]
	v_mfma_f32_16x16x32_bf16 v[48:51], v[152:155], v[176:179], v[48:51]
	v_mfma_f32_16x16x32_bf16 v[36:39], v[144:147], v[190:193], v[36:39]
	v_mfma_f32_16x16x32_bf16 v[32:35], v[152:155], v[190:193], v[32:35]
	v_mfma_f32_16x16x32_bf16 v[20:23], v[144:147], v[214:217], v[20:23]
	v_mfma_f32_16x16x32_bf16 v[16:19], v[152:155], v[214:217], v[16:19]
	v_mfma_f32_16x16x32_bf16 v[4:7], v[144:147], v[222:225], v[4:7]
	v_mfma_f32_16x16x32_bf16 v[0:3], v[152:155], v[222:225], v[0:3]
	v_mfma_f32_16x16x32_bf16 v[52:55], v[148:151], v[184:187], v[52:55]
	v_mfma_f32_16x16x32_bf16 v[48:51], v[156:159], v[184:187], v[48:51]
	v_mfma_f32_16x16x32_bf16 v[36:39], v[148:151], v[210:213], v[36:39]
	v_mfma_f32_16x16x32_bf16 v[32:35], v[156:159], v[210:213], v[32:35]
	v_mfma_f32_16x16x32_bf16 v[20:23], v[148:151], v[218:221], v[20:23]
	v_mfma_f32_16x16x32_bf16 v[16:19], v[156:159], v[218:221], v[16:19]
	v_mfma_f32_16x16x32_bf16 v[4:7], v[148:151], v[226:229], v[4:7]
	v_mfma_f32_16x16x32_bf16 v[0:3], v[156:159], v[226:229], v[0:3]

; #define PG8_STAGE(bufoff, gbase, voff) do { _Pragma("unroll") for (int _i = 0; _i < 2; ++_i) \
;         __builtin_amdgcn_global_load_lds((const unsigned*)((const char*)(gbase) + (voff)[_i]), (PG8_LAS unsigned*)(lds + (bufoff) + ldsw + _i * 8192), 16, 0, 0); } while (0)
; #define PG8_LDA(dst, b, h) do { _Pragma("unroll") for (int m = 0; m < 4; ++m) _Pragma("unroll") for (int k = 0; k < 2; ++k) dst[m][k] = *(const PG8_LAS bf16x8*)(lds + PG8_SA(b, h) + aoff + m * 2048 + k * 1024); } while (0)
; #define PG8_LDB(dst, b, h) do { _Pragma("unroll") for (int n = 0; n < 2; ++n) _Pragma("unroll") for (int k = 0; k < 2; ++k) dst[n][k] = *(const PG8_LAS bf16x8*)(lds + PG8_SB(b, h) + boff + n * 2048 + k * 1024); } while (0)
; #define PG8_MMA(ai, bj, At, Bt) do { __builtin_amdgcn_s_setprio(1); _Pragma("unroll") for (int m = 0; m < 4; ++m) _Pragma("unroll") for (int n = 0; n < 2; ++n) _Pragma("unroll") for (int k = 0; k < 2; ++k) \
;         acc[ai][bj][m][n] = __builtin_amdgcn_mfma_f32_16x16x32_bf16(Bt[n][k], At[m][k], acc[ai][bj][m][n], 0, 0, 0); __builtin_amdgcn_s_setprio(0); } while (0)
; #define PG8_WAIT_V(n) asm volatile("s_waitcnt vmcnt(" #n ")" ::: "memory")
; #define PG8_WAIT_L(n) asm volatile("s_waitcnt lgkmcnt(" #n ")" ::: "memory")
; #define PG8_BAR __builtin_amdgcn_s_barrier()
; #define PG8_SCHED __builtin_amdgcn_sched_barrier(0)
; template <class Epi, class Sched, bool ALIGN_EPI = false, bool SP2 = false>
; __device__ __forceinline__ void gemm_phase(PG8_LAS unsigned char* lds, const Gemm g, const Sched& S, const Epi& E) {
;     ...
;             PG8_WAIT_V(8); PG8_WAIT_L(0); PG8_BAR; PG8_MMA(1, 0, At, B0); PG8_MMA(1, 1, At, B1); PG8_BAR; PG8_SCHED;
;             PG8_LDB(B0, 1, 0); PG8_LDB(B1, 1, 1); PG8_SCHED; PG8_LDA(At, 1, 0); PG8_STAGE(PG8_SA(0, 1), a2 + hstep, voffA);
	s_barrier
	s_add_i32 s86, 0, 0x18000
	s_add_i32 s87, 0, 0x1c000


; #define PG8_STAGE(bufoff, gbase, voff) do { _Pragma("unroll") for (int _i = 0; _i < 2; ++_i) \
;         __builtin_amdgcn_global_load_lds((const unsigned*)((const char*)(gbase) + (voff)[_i]), (PG8_LAS unsigned*)(lds + (bufoff) + ldsw + _i * 8192), 16, 0, 0); } while (0)
; #define PG8_LDA(dst, b, h) do { _Pragma("unroll") for (int m = 0; m < 4; ++m) _Pragma("unroll") for (int k = 0; k < 2; ++k) dst[m][k] = *(const PG8_LAS bf16x8*)(lds + PG8_SA(b, h) + aoff + m * 2048 + k * 1024); } while (0)
; #define PG8_LDB(dst, b, h) do { _Pragma("unroll") for (int n = 0; n < 2; ++n) _Pragma("unroll") for (int k = 0; k < 2; ++k) dst[n][k] = *(const PG8_LAS bf16x8*)(lds + PG8_SB(b, h) + boff + n * 2048 + k * 1024); } while (0)
; #define PG8_SCHED __builtin_amdgcn_sched_barrier(0)
; template <class Epi, class Sched, bool ALIGN_EPI = false, bool SP2 = false>
; __device__ __forceinline__ void gemm_phase(PG8_LAS unsigned char* lds, const Gemm g, const Sched& S, const Epi& E) {
;     ...
;             PG8_LDB(B0, 1, 0); PG8_LDB(B1, 1, 1); PG8_SCHED; PG8_LDA(At, 1, 0); PG8_STAGE(PG8_SA(0, 1), a2 + hstep, voffA);
	ds_read_b128 v[128:131], v254
	ds_read_b128 v[132:135], v254 offset:1024
	ds_read_b128 v[136:139], v254 offset:2048
	ds_read_b128 v[140:143], v254 offset:3072
	ds_read_b128 v[144:147], v255
	ds_read_b128 v[148:151], v255 offset:1024
	ds_read_b128 v[152:155], v255 offset:2048
	ds_read_b128 v[156:159], v255 offset:3072
	s_add_u32 s60, s60, 0x80000
	s_addc_u32 s61, s61, 0
	s_mov_b32 m0, s68

; #define PG8_STAGE(bufoff, gbase, voff) do { _Pragma("unroll") for (int _i = 0; _i < 2; ++_i) \
;         __builtin_amdgcn_global_load_lds((const unsigned*)((const char*)(gbase) + (voff)[_i]), (PG8_LAS unsigned*)(lds + (bufoff) + ldsw + _i * 8192), 16, 0, 0); } while (0)
; #define PG8_LDA(dst, b, h) do { _Pragma("unroll") for (int m = 0; m < 4; ++m) _Pragma("unroll") for (int k = 0; k < 2; ++k) dst[m][k] = *(const PG8_LAS bf16x8*)(lds + PG8_SA(b, h) + aoff + m * 2048 + k * 1024); } while (0)
; #define PG8_LDB(dst, b, h) do { _Pragma("unroll") for (int n = 0; n < 2; ++n) _Pragma("unroll") for (int k = 0; k < 2; ++k) dst[n][k] = *(const PG8_LAS bf16x8*)(lds + PG8_SB(b, h) + boff + n * 2048 + k * 1024); } while (0)
; #define PG8_SCHED __builtin_amdgcn_sched_barrier(0)
; template <class Epi, class Sched, bool ALIGN_EPI = false, bool SP2 = false>
; __device__ __forceinline__ void gemm_phase(PG8_LAS unsigned char* lds, const Gemm g, const Sched& S, const Epi& E) {
;     ...
;             PG8_LDB(B0, 1, 0); PG8_LDB(B1, 1, 1); PG8_SCHED; PG8_LDA(At, 1, 0); PG8_STAGE(PG8_SA(0, 1), a2 + hstep, voffA);
	ds_read_b128 v[176:179], v207 offset:32768
	ds_read_b128 v[184:187], v207 offset:33792
	ds_read_b128 v[190:193], v207 offset:34816
	ds_read_b128 v[210:213], v207 offset:35840
	ds_read_b128 v[214:217], v207 offset:36864
	ds_read_b128 v[218:221], v207 offset:37888
	ds_read_b128 v[222:225], v207 offset:38912
	ds_read_b128 v[226:229], v207 offset:39936
	global_load_lds_dwordx4 v160, s[60:61]

; #define PG8_STAGE(bufoff, gbase, voff) do { _Pragma("unroll") for (int _i = 0; _i < 2; ++_i) \
;         __builtin_amdgcn_global_load_lds((const unsigned*)((const char*)(gbase) + (voff)[_i]), (PG8_LAS unsigned*)(lds + (bufoff) + ldsw + _i * 8192), 16, 0, 0); } while (0)
; #define PG8_LDA(dst, b, h) do { _Pragma("unroll") for (int m = 0; m < 4; ++m) _Pragma("unroll") for (int k = 0; k < 2; ++k) dst[m][k] = *(const PG8_LAS bf16x8*)(lds + PG8_SA(b, h) + aoff + m * 2048 + k * 1024); } while (0)
; #define PG8_LDB(dst, b, h) do { _Pragma("unroll") for (int n = 0; n < 2; ++n) _Pragma("unroll") for (int k = 0; k < 2; ++k) dst[n][k] = *(const PG8_LAS bf16x8*)(lds + PG8_SB(b, h) + boff + n * 2048 + k * 1024); } while (0)
; #define PG8_MMA(ai, bj, At, Bt) do { __builtin_amdgcn_s_setprio(1); _Pragma("unroll") for (int m = 0; m < 4; ++m) _Pragma("unroll") for (int n = 0; n < 2; ++n) _Pragma("unroll") for (int k = 0; k < 2; ++k) \
;         acc[ai][bj][m][n] = __builtin_amdgcn_mfma_f32_16x16x32_bf16(Bt[n][k], At[m][k], acc[ai][bj][m][n], 0, 0, 0); __builtin_amdgcn_s_setprio(0); } while (0)
; #define PG8_WAIT_V(n) asm volatile("s_waitcnt vmcnt(" #n ")" ::: "memory")
; #define PG8_WAIT_L(n) asm volatile("s_waitcnt lgkmcnt(" #n ")" ::: "memory")
; #define PG8_BAR __builtin_amdgcn_s_barrier()
; #define PG8_SCHED __builtin_amdgcn_sched_barrier(0)
; template <class Epi, class Sched, bool ALIGN_EPI = false, bool SP2 = false>
; __device__ __forceinline__ void gemm_phase(PG8_LAS unsigned char* lds, const Gemm g, const Sched& S, const Epi& E) {
;     ...
;             PG8_LDB(B0, 1, 0); PG8_LDB(B1, 1, 1); PG8_SCHED; PG8_LDA(At, 1, 0); PG8_STAGE(PG8_SA(0, 1), a2 + hstep, voffA);
;             PG8_WAIT_V(8); PG8_WAIT_L(0); PG8_BAR; PG8_MMA(0, 0, At, B0); PG8_MMA(0, 1, At, B1); PG8_BAR; PG8_SCHED;
	s_mov_b32 m0, s69
	s_nop 0
	global_load_lds_dwordx4 v164, s[60:61]
	s_waitcnt vmcnt(8)
	s_waitcnt lgkmcnt(0)

; #define PG8_MMA(ai, bj, At, Bt) do { __builtin_amdgcn_s_setprio(1); _Pragma("unroll") for (int m = 0; m < 4; ++m) _Pragma("unroll") for (int n = 0; n < 2; ++n) _Pragma("unroll") for (int k = 0; k < 2; ++k) \
;         acc[ai][bj][m][n] = __builtin_amdgcn_mfma_f32_16x16x32_bf16(Bt[n][k], At[m][k], acc[ai][bj][m][n], 0, 0, 0); __builtin_amdgcn_s_setprio(0); } while (0)
; #define PG8_WAIT_V(n) asm volatile("s_waitcnt vmcnt(" #n ")" ::: "memory")
; #define PG8_WAIT_L(n) asm volatile("s_waitcnt lgkmcnt(" #n ")" ::: "memory")
; #define PG8_BAR __builtin_amdgcn_s_barrier()
; #define PG8_SCHED __builtin_amdgcn_sched_barrier(0)
; template <class Epi, class Sched, bool ALIGN_EPI = false, bool SP2 = false>
; __device__ __forceinline__ void gemm_phase(PG8_LAS unsigned char* lds, const Gemm g, const Sched& S, const Epi& E) {
;     ...
;             PG8_WAIT_V(8); PG8_WAIT_L(0); PG8_BAR; PG8_MMA(0, 0, At, B0); PG8_MMA(0, 1, At, B1); PG8_BAR; PG8_SCHED;
	s_barrier

; #define PG8_MMA(ai, bj, At, Bt) do { __builtin_amdgcn_s_setprio(1); _Pragma("unroll") for (int m = 0; m < 4; ++m) _Pragma("unroll") for (int n = 0; n < 2; ++n) _Pragma("unroll") for (int k = 0; k < 2; ++k) \
;         acc[ai][bj][m][n] = __builtin_amdgcn_mfma_f32_16x16x32_bf16(Bt[n][k], At[m][k], acc[ai][bj][m][n], 0, 0, 0); __builtin_amdgcn_s_setprio(0); } while (0)
; #define PG8_WAIT_V(n) asm volatile("s_waitcnt vmcnt(" #n ")" ::: "memory")
; #define PG8_WAIT_L(n) asm volatile("s_waitcnt lgkmcnt(" #n ")" ::: "memory")
; #define PG8_BAR __builtin_amdgcn_s_barrier()
; #define PG8_SCHED __builtin_amdgcn_sched_barrier(0)
; template <class Epi, class Sched, bool ALIGN_EPI = false, bool SP2 = false>
; __device__ __forceinline__ void gemm_phase(PG8_LAS unsigned char* lds, const Gemm g, const Sched& S, const Epi& E) {
;     ...
;             PG8_WAIT_V(8); PG8_WAIT_L(0); PG8_BAR; PG8_MMA(0, 0, At, B0); PG8_MMA(0, 1, At, B1); PG8_BAR; PG8_SCHED;
	v_mfma_f32_16x16x32_bf16 v[124:127], v[128:131], v[176:179], v[124:127]
	v_mfma_f32_16x16x32_bf16 v[120:123], v[136:139], v[176:179], v[120:123]
	v_mfma_f32_16x16x32_bf16 v[108:111], v[128:131], v[190:193], v[108:111]
	v_mfma_f32_16x16x32_bf16 v[104:107], v[136:139], v[190:193], v[104:107]
	v_mfma_f32_16x16x32_bf16 v[92:95], v[128:131], v[214:217], v[92:95]
	v_mfma_f32_16x16x32_bf16 v[88:91], v[136:139], v[214:217], v[88:91]
	v_mfma_f32_16x16x32_bf16 v[76:79], v[128:131], v[222:225], v[76:79]
	v_mfma_f32_16x16x32_bf16 v[72:75], v[136:139], v[222:225], v[72:75]
	v_mfma_f32_16x16x32_bf16 v[124:127], v[132:135], v[184:187], v[124:127]
	v_mfma_f32_16x16x32_bf16 v[120:123], v[140:143], v[184:187], v[120:123]
	v_mfma_f32_16x16x32_bf16 v[108:111], v[132:135], v[210:213], v[108:111]
	v_mfma_f32_16x16x32_bf16 v[104:107], v[140:143], v[210:213], v[104:107]
	v_mfma_f32_16x16x32_bf16 v[92:95], v[132:135], v[218:221], v[92:95]
	v_mfma_f32_16x16x32_bf16 v[88:91], v[140:143], v[218:221], v[88:91]
	v_mfma_f32_16x16x32_bf16 v[76:79], v[132:135], v[226:229], v[76:79]
	v_mfma_f32_16x16x32_bf16 v[72:75], v[140:143], v[226:229], v[72:75]


; #define PG8_MMA(ai, bj, At, Bt) do { __builtin_amdgcn_s_setprio(1); _Pragma("unroll") for (int m = 0; m < 4; ++m) _Pragma("unroll") for (int n = 0; n < 2; ++n) _Pragma("unroll") for (int k = 0; k < 2; ++k) \
;         acc[ai][bj][m][n] = __builtin_amdgcn_mfma_f32_16x16x32_bf16(Bt[n][k], At[m][k], acc[ai][bj][m][n], 0, 0, 0); __builtin_amdgcn_s_setprio(0); } while (0)
; #define PG8_WAIT_V(n) asm volatile("s_waitcnt vmcnt(" #n ")" ::: "memory")
; #define PG8_WAIT_L(n) asm volatile("s_waitcnt lgkmcnt(" #n ")" ::: "memory")
; #define PG8_BAR __builtin_amdgcn_s_barrier()
; #define PG8_SCHED __builtin_amdgcn_sched_barrier(0)
; template <class Epi, class Sched, bool ALIGN_EPI = false, bool SP2 = false>
; __device__ __forceinline__ void gemm_phase(PG8_LAS unsigned char* lds, const Gemm g, const Sched& S, const Epi& E) {
;     ...
;             PG8_WAIT_V(8); PG8_WAIT_L(0); PG8_BAR; PG8_MMA(0, 0, At, B0); PG8_MMA(0, 1, At, B1); PG8_BAR; PG8_SCHED;
	v_mfma_f32_16x16x32_bf16 v[116:119], v[144:147], v[176:179], v[116:119]
	v_mfma_f32_16x16x32_bf16 v[112:115], v[152:155], v[176:179], v[112:115]
	v_mfma_f32_16x16x32_bf16 v[100:103], v[144:147], v[190:193], v[100:103]
	v_mfma_f32_16x16x32_bf16 v[96:99], v[152:155], v[190:193], v[96:99]
	v_mfma_f32_16x16x32_bf16 v[84:87], v[144:147], v[214:217], v[84:87]
	v_mfma_f32_16x16x32_bf16 v[80:83], v[152:155], v[214:217], v[80:83]
	v_mfma_f32_16x16x32_bf16 v[68:71], v[144:147], v[222:225], v[68:71]
	v_mfma_f32_16x16x32_bf16 v[64:67], v[152:155], v[222:225], v[64:67]
	v_mfma_f32_16x16x32_bf16 v[116:119], v[148:151], v[184:187], v[116:119]
	v_mfma_f32_16x16x32_bf16 v[112:115], v[156:159], v[184:187], v[112:115]
	v_mfma_f32_16x16x32_bf16 v[100:103], v[148:151], v[210:213], v[100:103]
	v_mfma_f32_16x16x32_bf16 v[96:99], v[156:159], v[210:213], v[96:99]
	v_mfma_f32_16x16x32_bf16 v[84:87], v[148:151], v[218:221], v[84:87]
	v_mfma_f32_16x16x32_bf16 v[80:83], v[156:159], v[218:221], v[80:83]
	v_mfma_f32_16x16x32_bf16 v[68:71], v[148:151], v[226:229], v[68:71]
	v_mfma_f32_16x16x32_bf16 v[64:67], v[156:159], v[226:229], v[64:67]

; #define PG8_STAGE(bufoff, gbase, voff) do { _Pragma("unroll") for (int _i = 0; _i < 2; ++_i) \
;         __builtin_amdgcn_global_load_lds((const unsigned*)((const char*)(gbase) + (voff)[_i]), (PG8_LAS unsigned*)(lds + (bufoff) + ldsw + _i * 8192), 16, 0, 0); } while (0)
; #define PG8_LDA(dst, b, h) do { _Pragma("unroll") for (int m = 0; m < 4; ++m) _Pragma("unroll") for (int k = 0; k < 2; ++k) dst[m][k] = *(const PG8_LAS bf16x8*)(lds + PG8_SA(b, h) + aoff + m * 2048 + k * 1024); } while (0)
; #define PG8_MMA(ai, bj, At, Bt) do { __builtin_amdgcn_s_setprio(1); _Pragma("unroll") for (int m = 0; m < 4; ++m) _Pragma("unroll") for (int n = 0; n < 2; ++n) _Pragma("unroll") for (int k = 0; k < 2; ++k) \
;         acc[ai][bj][m][n] = __builtin_amdgcn_mfma_f32_16x16x32_bf16(Bt[n][k], At[m][k], acc[ai][bj][m][n], 0, 0, 0); __builtin_amdgcn_s_setprio(0); } while (0)
; #define PG8_WAIT_V(n) asm volatile("s_waitcnt vmcnt(" #n ")" ::: "memory")
; #define PG8_WAIT_L(n) asm volatile("s_waitcnt lgkmcnt(" #n ")" ::: "memory")
; #define PG8_BAR __builtin_amdgcn_s_barrier()
; #define PG8_SCHED __builtin_amdgcn_sched_barrier(0)
; template <class Epi, class Sched, bool ALIGN_EPI = false, bool SP2 = false>
; __device__ __forceinline__ void gemm_phase(PG8_LAS unsigned char* lds, const Gemm g, const Sched& S, const Epi& E) {
;     ...
;             PG8_WAIT_V(8); PG8_WAIT_L(0); PG8_BAR; PG8_MMA(0, 0, At, B0); PG8_MMA(0, 1, At, B1); PG8_BAR; PG8_SCHED;
;             PG8_LDA(At, 1, 1); PG8_STAGE(PG8_SB(1, 0), b3, voffB); PG8_STAGE(PG8_SB(1, 1), b3 + hstep, voffB); PG8_STAGE(PG8_SA(1, 0), a3, voffA);
	s_barrier
	s_add_i32 s60, s86, s64

; #define PG8_STAGE(bufoff, gbase, voff) do { _Pragma("unroll") for (int _i = 0; _i < 2; ++_i) \
;         __builtin_amdgcn_global_load_lds((const unsigned*)((const char*)(gbase) + (voff)[_i]), (PG8_LAS unsigned*)(lds + (bufoff) + ldsw + _i * 8192), 16, 0, 0); } while (0)
; #define PG8_LDA(dst, b, h) do { _Pragma("unroll") for (int m = 0; m < 4; ++m) _Pragma("unroll") for (int k = 0; k < 2; ++k) dst[m][k] = *(const PG8_LAS bf16x8*)(lds + PG8_SA(b, h) + aoff + m * 2048 + k * 1024); } while (0)
; template <class Epi, class Sched, bool ALIGN_EPI = false, bool SP2 = false>
; __device__ __forceinline__ void gemm_phase(PG8_LAS unsigned char* lds, const Gemm g, const Sched& S, const Epi& E) {
;     ...
;             PG8_LDA(At, 1, 1); PG8_STAGE(PG8_SB(1, 0), b3, voffB); PG8_STAGE(PG8_SB(1, 1), b3 + hstep, voffB); PG8_STAGE(PG8_SA(1, 0), a3, voffA);
	s_mov_b32 m0, s60
	ds_read_b128 v[176:179], v207 offset:49152
	ds_read_b128 v[184:187], v207 offset:50176
	ds_read_b128 v[190:193], v207 offset:51200
	ds_read_b128 v[210:213], v207 offset:52224
	ds_read_b128 v[214:217], v207 offset:53248
	ds_read_b128 v[218:221], v207 offset:54272
	ds_read_b128 v[222:225], v207 offset:55296
	ds_read_b128 v[226:229], v207 offset:56320
	global_load_lds_dwordx4 v250, s[96:97]
	s_add_i32 m0, s60, 0x2000
	s_add_u32 s12, s12, 0x80080

; #define PG8_STAGE(bufoff, gbase, voff) do { _Pragma("unroll") for (int _i = 0; _i < 2; ++_i) \
;         __builtin_amdgcn_global_load_lds((const unsigned*)((const char*)(gbase) + (voff)[_i]), (PG8_LAS unsigned*)(lds + (bufoff) + ldsw + _i * 8192), 16, 0, 0); } while (0)
; #define PG8_LDA(dst, b, h) do { _Pragma("unroll") for (int m = 0; m < 4; ++m) _Pragma("unroll") for (int k = 0; k < 2; ++k) dst[m][k] = *(const PG8_LAS bf16x8*)(lds + PG8_SA(b, h) + aoff + m * 2048 + k * 1024); } while (0)
; template <class Epi, class Sched, bool ALIGN_EPI = false, bool SP2 = false>
; __device__ __forceinline__ void gemm_phase(PG8_LAS unsigned char* lds, const Gemm g, const Sched& S, const Epi& E) {
;     ...
;             PG8_LDA(At, 1, 1); PG8_STAGE(PG8_SB(1, 0), b3, voffB); PG8_STAGE(PG8_SB(1, 1), b3 + hstep, voffB); PG8_STAGE(PG8_SA(1, 0), a3, voffA);
	s_addc_u32 s13, s13, 0
	s_add_i32 s60, s87, s64
	global_load_lds_dwordx4 v251, s[96:97]

; #define PG8_STAGE(bufoff, gbase, voff) do { _Pragma("unroll") for (int _i = 0; _i < 2; ++_i) \
;         __builtin_amdgcn_global_load_lds((const unsigned*)((const char*)(gbase) + (voff)[_i]), (PG8_LAS unsigned*)(lds + (bufoff) + ldsw + _i * 8192), 16, 0, 0); } while (0)
; #define PG8_LDA(dst, b, h) do { _Pragma("unroll") for (int m = 0; m < 4; ++m) _Pragma("unroll") for (int k = 0; k < 2; ++k) dst[m][k] = *(const PG8_LAS bf16x8*)(lds + PG8_SA(b, h) + aoff + m * 2048 + k * 1024); } while (0)
; template <class Epi, class Sched, bool ALIGN_EPI = false, bool SP2 = false>
; __device__ __forceinline__ void gemm_phase(PG8_LAS unsigned char* lds, const Gemm g, const Sched& S, const Epi& E) {
;     ...
;             PG8_LDA(At, 1, 1); PG8_STAGE(PG8_SB(1, 0), b3, voffB); PG8_STAGE(PG8_SB(1, 1), b3 + hstep, voffB); PG8_STAGE(PG8_SA(1, 0), a3, voffA);
	s_mov_b32 m0, s60
	s_nop 0
	global_load_lds_dwordx4 v162, s[12:13]

; #define PG8_STAGE(bufoff, gbase, voff) do { _Pragma("unroll") for (int _i = 0; _i < 2; ++_i) \
;         __builtin_amdgcn_global_load_lds((const unsigned*)((const char*)(gbase) + (voff)[_i]), (PG8_LAS unsigned*)(lds + (bufoff) + ldsw + _i * 8192), 16, 0, 0); } while (0)
; #define PG8_LDA(dst, b, h) do { _Pragma("unroll") for (int m = 0; m < 4; ++m) _Pragma("unroll") for (int k = 0; k < 2; ++k) dst[m][k] = *(const PG8_LAS bf16x8*)(lds + PG8_SA(b, h) + aoff + m * 2048 + k * 1024); } while (0)
; template <class Epi, class Sched, bool ALIGN_EPI = false, bool SP2 = false>
; __device__ __forceinline__ void gemm_phase(PG8_LAS unsigned char* lds, const Gemm g, const Sched& S, const Epi& E) {
;     ...
;             PG8_LDA(At, 1, 1); PG8_STAGE(PG8_SB(1, 0), b3, voffB); PG8_STAGE(PG8_SB(1, 1), b3 + hstep, voffB); PG8_STAGE(PG8_SA(1, 0), a3, voffA);
	s_add_i32 m0, s60, 0x2000
	s_nop 0
	global_load_lds_dwordx4 v166, s[12:13]

; #define PG8_STAGE(bufoff, gbase, voff) do { _Pragma("unroll") for (int _i = 0; _i < 2; ++_i) \
;         __builtin_amdgcn_global_load_lds((const unsigned*)((const char*)(gbase) + (voff)[_i]), (PG8_LAS unsigned*)(lds + (bufoff) + ldsw + _i * 8192), 16, 0, 0); } while (0)
; #define PG8_LDA(dst, b, h) do { _Pragma("unroll") for (int m = 0; m < 4; ++m) _Pragma("unroll") for (int k = 0; k < 2; ++k) dst[m][k] = *(const PG8_LAS bf16x8*)(lds + PG8_SA(b, h) + aoff + m * 2048 + k * 1024); } while (0)
; template <class Epi, class Sched, bool ALIGN_EPI = false, bool SP2 = false>
; __device__ __forceinline__ void gemm_phase(PG8_LAS unsigned char* lds, const Gemm g, const Sched& S, const Epi& E) {
;     ...
;             PG8_LDA(At, 1, 1); PG8_STAGE(PG8_SB(1, 0), b3, voffB); PG8_STAGE(PG8_SB(1, 1), b3 + hstep, voffB); PG8_STAGE(PG8_SA(1, 0), a3, voffA);
	s_mov_b32 m0, s71
	s_nop 0
	global_load_lds_dwordx4 v252, s[98:99]

; #define PG8_STAGE(bufoff, gbase, voff) do { _Pragma("unroll") for (int _i = 0; _i < 2; ++_i) \
;         __builtin_amdgcn_global_load_lds((const unsigned*)((const char*)(gbase) + (voff)[_i]), (PG8_LAS unsigned*)(lds + (bufoff) + ldsw + _i * 8192), 16, 0, 0); } while (0)
; #define PG8_LDA(dst, b, h) do { _Pragma("unroll") for (int m = 0; m < 4; ++m) _Pragma("unroll") for (int k = 0; k < 2; ++k) dst[m][k] = *(const PG8_LAS bf16x8*)(lds + PG8_SA(b, h) + aoff + m * 2048 + k * 1024); } while (0)
; #define PG8_MMA(ai, bj, At, Bt) do { __builtin_amdgcn_s_setprio(1); _Pragma("unroll") for (int m = 0; m < 4; ++m) _Pragma("unroll") for (int n = 0; n < 2; ++n) _Pragma("unroll") for (int k = 0; k < 2; ++k) \
;         acc[ai][bj][m][n] = __builtin_amdgcn_mfma_f32_16x16x32_bf16(Bt[n][k], At[m][k], acc[ai][bj][m][n], 0, 0, 0); __builtin_amdgcn_s_setprio(0); } while (0)
; #define PG8_WAIT_V(n) asm volatile("s_waitcnt vmcnt(" #n ")" ::: "memory")
; #define PG8_WAIT_L(n) asm volatile("s_waitcnt lgkmcnt(" #n ")" ::: "memory")
; #define PG8_BAR __builtin_amdgcn_s_barrier()
; #define PG8_SCHED __builtin_amdgcn_sched_barrier(0)
; template <class Epi, class Sched, bool ALIGN_EPI = false, bool SP2 = false>
; __device__ __forceinline__ void gemm_phase(PG8_LAS unsigned char* lds, const Gemm g, const Sched& S, const Epi& E) {
;     ...
;             PG8_LDA(At, 1, 1); PG8_STAGE(PG8_SB(1, 0), b3, voffB); PG8_STAGE(PG8_SB(1, 1), b3 + hstep, voffB); PG8_STAGE(PG8_SA(1, 0), a3, voffA);
;             PG8_WAIT_V(8); PG8_WAIT_L(0); PG8_BAR; PG8_MMA(1, 0, At, B0); PG8_MMA(1, 1, At, B1); PG8_BAR; PG8_SCHED;
	s_mov_b32 m0, s72
	s_nop 0
	global_load_lds_dwordx4 v253, s[98:99]
	s_waitcnt vmcnt(8)
	s_waitcnt lgkmcnt(0)

; #define PG8_MMA(ai, bj, At, Bt) do { __builtin_amdgcn_s_setprio(1); _Pragma("unroll") for (int m = 0; m < 4; ++m) _Pragma("unroll") for (int n = 0; n < 2; ++n) _Pragma("unroll") for (int k = 0; k < 2; ++k) \
;         acc[ai][bj][m][n] = __builtin_amdgcn_mfma_f32_16x16x32_bf16(Bt[n][k], At[m][k], acc[ai][bj][m][n], 0, 0, 0); __builtin_amdgcn_s_setprio(0); } while (0)
; #define PG8_WAIT_V(n) asm volatile("s_waitcnt vmcnt(" #n ")" ::: "memory")
; #define PG8_WAIT_L(n) asm volatile("s_waitcnt lgkmcnt(" #n ")" ::: "memory")
; #define PG8_BAR __builtin_amdgcn_s_barrier()
; #define PG8_SCHED __builtin_amdgcn_sched_barrier(0)
; template <class Epi, class Sched, bool ALIGN_EPI = false, bool SP2 = false>
; __device__ __forceinline__ void gemm_phase(PG8_LAS unsigned char* lds, const Gemm g, const Sched& S, const Epi& E) {
;     ...
;             PG8_WAIT_V(8); PG8_WAIT_L(0); PG8_BAR; PG8_MMA(1, 0, At, B0); PG8_MMA(1, 1, At, B1); PG8_BAR; PG8_SCHED;
	s_barrier

; #define PG8_MMA(ai, bj, At, Bt) do { __builtin_amdgcn_s_setprio(1); _Pragma("unroll") for (int m = 0; m < 4; ++m) _Pragma("unroll") for (int n = 0; n < 2; ++n) _Pragma("unroll") for (int k = 0; k < 2; ++k) \
;         acc[ai][bj][m][n] = __builtin_amdgcn_mfma_f32_16x16x32_bf16(Bt[n][k], At[m][k], acc[ai][bj][m][n], 0, 0, 0); __builtin_amdgcn_s_setprio(0); } while (0)
; #define PG8_WAIT_V(n) asm volatile("s_waitcnt vmcnt(" #n ")" ::: "memory")
; #define PG8_WAIT_L(n) asm volatile("s_waitcnt lgkmcnt(" #n ")" ::: "memory")
; #define PG8_BAR __builtin_amdgcn_s_barrier()
; #define PG8_SCHED __builtin_amdgcn_sched_barrier(0)
; template <class Epi, class Sched, bool ALIGN_EPI = false, bool SP2 = false>
; __device__ __forceinline__ void gemm_phase(PG8_LAS unsigned char* lds, const Gemm g, const Sched& S, const Epi& E) {
;     ...
;             PG8_WAIT_V(8); PG8_WAIT_L(0); PG8_BAR; PG8_MMA(1, 0, At, B0); PG8_MMA(1, 1, At, B1); PG8_BAR; PG8_SCHED;
	v_mfma_f32_16x16x32_bf16 v[60:63], v[128:131], v[176:179], v[60:63]
	v_mfma_f32_16x16x32_bf16 v[56:59], v[136:139], v[176:179], v[56:59]
	v_mfma_f32_16x16x32_bf16 v[44:47], v[128:131], v[190:193], v[44:47]
	v_mfma_f32_16x16x32_bf16 v[40:43], v[136:139], v[190:193], v[40:43]
	v_mfma_f32_16x16x32_bf16 v[28:31], v[128:131], v[214:217], v[28:31]
	v_mfma_f32_16x16x32_bf16 v[24:27], v[136:139], v[214:217], v[24:27]
	v_mfma_f32_16x16x32_bf16 v[12:15], v[128:131], v[222:225], v[12:15]
	v_mfma_f32_16x16x32_bf16 v[8:11], v[136:139], v[222:225], v[8:11]
	v_mfma_f32_16x16x32_bf16 v[60:63], v[132:135], v[184:187], v[60:63]
	v_mfma_f32_16x16x32_bf16 v[56:59], v[140:143], v[184:187], v[56:59]
	v_mfma_f32_16x16x32_bf16 v[44:47], v[132:135], v[210:213], v[44:47]
	v_mfma_f32_16x16x32_bf16 v[40:43], v[140:143], v[210:213], v[40:43]
	v_mfma_f32_16x16x32_bf16 v[28:31], v[132:135], v[218:221], v[28:31]
	v_mfma_f32_16x16x32_bf16 v[24:27], v[140:143], v[218:221], v[24:27]
	v_mfma_f32_16x16x32_bf16 v[12:15], v[132:135], v[226:229], v[12:15]
	v_mfma_f32_16x16x32_bf16 v[8:11], v[140:143], v[226:229], v[8:11]


; #define PG8_MMA(ai, bj, At, Bt) do { __builtin_amdgcn_s_setprio(1); _Pragma("unroll") for (int m = 0; m < 4; ++m) _Pragma("unroll") for (int n = 0; n < 2; ++n) _Pragma("unroll") for (int k = 0; k < 2; ++k) \
;         acc[ai][bj][m][n] = __builtin_amdgcn_mfma_f32_16x16x32_bf16(Bt[n][k], At[m][k], acc[ai][bj][m][n], 0, 0, 0); __builtin_amdgcn_s_setprio(0); } while (0)
; #define PG8_WAIT_V(n) asm volatile("s_waitcnt vmcnt(" #n ")" ::: "memory")
; #define PG8_WAIT_L(n) asm volatile("s_waitcnt lgkmcnt(" #n ")" ::: "memory")
; #define PG8_BAR __builtin_amdgcn_s_barrier()
; #define PG8_SCHED __builtin_amdgcn_sched_barrier(0)
; template <class Epi, class Sched, bool ALIGN_EPI = false, bool SP2 = false>
; __device__ __forceinline__ void gemm_phase(PG8_LAS unsigned char* lds, const Gemm g, const Sched& S, const Epi& E) {
;     ...
;             PG8_WAIT_V(8); PG8_WAIT_L(0); PG8_BAR; PG8_MMA(1, 0, At, B0); PG8_MMA(1, 1, At, B1); PG8_BAR; PG8_SCHED;
	v_mfma_f32_16x16x32_bf16 v[52:55], v[144:147], v[176:179], v[52:55]
	v_mfma_f32_16x16x32_bf16 v[48:51], v[152:155], v[176:179], v[48:51]
	v_mfma_f32_16x16x32_bf16 v[36:39], v[144:147], v[190:193], v[36:39]
	v_mfma_f32_16x16x32_bf16 v[32:35], v[152:155], v[190:193], v[32:35]
	v_mfma_f32_16x16x32_bf16 v[20:23], v[144:147], v[214:217], v[20:23]
	v_mfma_f32_16x16x32_bf16 v[16:19], v[152:155], v[214:217], v[16:19]
	v_mfma_f32_16x16x32_bf16 v[4:7], v[144:147], v[222:225], v[4:7]
	v_mfma_f32_16x16x32_bf16 v[0:3], v[152:155], v[222:225], v[0:3]
	v_mfma_f32_16x16x32_bf16 v[52:55], v[148:151], v[184:187], v[52:55]
	v_mfma_f32_16x16x32_bf16 v[48:51], v[156:159], v[184:187], v[48:51]
	v_mfma_f32_16x16x32_bf16 v[36:39], v[148:151], v[210:213], v[36:39]
	v_mfma_f32_16x16x32_bf16 v[32:35], v[156:159], v[210:213], v[32:35]
	v_mfma_f32_16x16x32_bf16 v[20:23], v[148:151], v[218:221], v[20:23]
	v_mfma_f32_16x16x32_bf16 v[16:19], v[156:159], v[218:221], v[16:19]
	v_mfma_f32_16x16x32_bf16 v[4:7], v[148:151], v[226:229], v[4:7]
	v_mfma_f32_16x16x32_bf16 v[0:3], v[156:159], v[226:229], v[0:3]

; #define PG8_STAGE(bufoff, gbase, voff) do { _Pragma("unroll") for (int _i = 0; _i < 2; ++_i) \
;         __builtin_amdgcn_global_load_lds((const unsigned*)((const char*)(gbase) + (voff)[_i]), (PG8_LAS unsigned*)(lds + (bufoff) + ldsw + _i * 8192), 16, 0, 0); } while (0)
; #define PG8_LDA(dst, b, h) do { _Pragma("unroll") for (int m = 0; m < 4; ++m) _Pragma("unroll") for (int k = 0; k < 2; ++k) dst[m][k] = *(const PG8_LAS bf16x8*)(lds + PG8_SA(b, h) + aoff + m * 2048 + k * 1024); } while (0)
; #define PG8_WAIT_V(n) asm volatile("s_waitcnt vmcnt(" #n ")" ::: "memory")
; #define PG8_WAIT_L(n) asm volatile("s_waitcnt lgkmcnt(" #n ")" ::: "memory")
; template <class Epi, class Sched, bool ALIGN_EPI = false, bool SP2 = false>
; __device__ __forceinline__ void gemm_phase(PG8_LAS unsigned char* lds, const Gemm g, const Sched& S, const Epi& E) {
;     ...
;         for (int t = 0; t < nt; t += 2) {
;             const bool last = (t == nt - 2);
;             const char* a1 = cA + (size_t)(t + 1) * kstep;
;             const char* a2 = last ? nA : cA + (size_t)(t + 2) * kstep; const char* b2 = last ? nB : cB + (size_t)(t + 2) * kstep;
;             const char* a3 = a2 + kstep; const char* b3 = b2 + kstep;
;             if (last && has_next) S.a_ready(nxt);
;             if constexpr (SP2) {
;             PG8_LDB(B0, 0, 0); PG8_LDB(B1, 0, 1); PG8_SCHED; PG8_LDA(At, 0, 0); PG8_STAGE(PG8_SA(1, 1), a1 + hstep, voffA);
;             PG8_WAIT_V(8); PG8_WAIT_L(0); PG8_BAR; PG8_MMA(0, 0, At, B0); PG8_MMA(0, 1, At, B1); PG8_BAR; PG8_SCHED;
;             PG8_LDA(At, 0, 1); PG8_STAGE(PG8_SB(0, 0), b2, voffB); PG8_STAGE(PG8_SB(0, 1), b2 + hstep, voffB); PG8_STAGE(PG8_SA(0, 0), a2, voffA);
;             PG8_WAIT_V(8); PG8_WAIT_L(0); PG8_BAR; PG8_MMA(1, 0, At, B0); PG8_MMA(1, 1, At, B1); PG8_BAR; PG8_SCHED;
;             PG8_LDB(B0, 1, 0); PG8_LDB(B1, 1, 1); PG8_SCHED; PG8_LDA(At, 1, 0); PG8_STAGE(PG8_SA(0, 1), a2 + hstep, voffA);
;             PG8_WAIT_V(8); PG8_WAIT_L(0); PG8_BAR; PG8_MMA(0, 0, At, B0); PG8_MMA(0, 1, At, B1); PG8_BAR; PG8_SCHED;
;             PG8_LDA(At, 1, 1); PG8_STAGE(PG8_SB(1, 0), b3, voffB); PG8_STAGE(PG8_SB(1, 1), b3 + hstep, voffB); PG8_STAGE(PG8_SA(1, 0), a3, voffA);
;             PG8_WAIT_V(8); PG8_WAIT_L(0); PG8_BAR; PG8_MMA(1, 0, At, B0); PG8_MMA(1, 1, At, B1); PG8_BAR; PG8_SCHED;
;     ...
;         if constexpr (ALIGN_EPI) { if (wr == 0) PG8_BAR; }
	s_barrier
	s_add_i32 s85, s85, 2
	s_add_u32 s10, s10, 0x100
	s_addc_u32 s11, s11, 0
	s_add_u32 s83, s83, 0x100
	s_addc_u32 s84, s84, 0
	s_cmp_gt_u32 s85, 29
	s_cbranch_scc0 .LBB0_428
	s_and_b64 vcc, exec, s[42:43]
	s_cbranch_vccz .LBB0_431
	s_barrier

; #define PG8_STAGE(bufoff, gbase, voff) do { _Pragma("unroll") for (int _i = 0; _i < 2; ++_i) \
;         __builtin_amdgcn_global_load_lds((const unsigned*)((const char*)(gbase) + (voff)[_i]), (PG8_LAS unsigned*)(lds + (bufoff) + ldsw + _i * 8192), 16, 0, 0); } while (0)
; #define PG8_LDA(dst, b, h) do { _Pragma("unroll") for (int m = 0; m < 4; ++m) _Pragma("unroll") for (int k = 0; k < 2; ++k) dst[m][k] = *(const PG8_LAS bf16x8*)(lds + PG8_SA(b, h) + aoff + m * 2048 + k * 1024); } while (0)
; #define PG8_LDB(dst, b, h) do { _Pragma("unroll") for (int n = 0; n < 2; ++n) _Pragma("unroll") for (int k = 0; k < 2; ++k) dst[n][k] = *(const PG8_LAS bf16x8*)(lds + PG8_SB(b, h) + boff + n * 2048 + k * 1024); } while (0)
; #define PG8_SCHED __builtin_amdgcn_sched_barrier(0)
; template <class Epi, class Sched, bool ALIGN_EPI = false, bool SP2 = false>
; __device__ __forceinline__ void gemm_phase(PG8_LAS unsigned char* lds, const Gemm g, const Sched& S, const Epi& E) {
;     ...
;             const bool last = (t == nt - 2);
;             const char* a1 = cA + (size_t)(t + 1) * kstep;
;             const char* a2 = last ? nA : cA + (size_t)(t + 2) * kstep; const char* b2 = last ? nB : cB + (size_t)(t + 2) * kstep;
;             const char* a3 = a2 + kstep; const char* b3 = b2 + kstep;
;             if (last && has_next) S.a_ready(nxt);
;             if constexpr (SP2) {
;             PG8_LDB(B0, 0, 0); PG8_LDB(B1, 0, 1); PG8_SCHED; PG8_LDA(At, 0, 0); PG8_STAGE(PG8_SA(1, 1), a1 + hstep, voffA);
.LBB0_509:
	ds_read_b128 v[64:67], v213
	ds_read_b128 v[68:71], v213 offset:1024
	ds_read_b128 v[72:75], v213 offset:2048
	ds_read_b128 v[76:79], v213 offset:3072
	ds_read_b128 v[144:147], v214
	ds_read_b128 v[148:151], v214 offset:1024
	ds_read_b128 v[152:155], v214 offset:2048
	ds_read_b128 v[156:159], v214 offset:3072
	s_add_u32 s60, s58, 0xffe00080
	s_addc_u32 s61, s59, -1
	s_cmpk_eq_i32 s81, 0x7c
	s_cselect_b32 s63, s11, s61
	s_cselect_b32 s62, s51, s60
	s_cselect_b32 s61, s49, s80
	s_cselect_b32 s60, s78, s79

; #define PG8_STAGE(bufoff, gbase, voff) do { _Pragma("unroll") for (int _i = 0; _i < 2; ++_i) \
;         __builtin_amdgcn_global_load_lds((const unsigned*)((const char*)(gbase) + (voff)[_i]), (PG8_LAS unsigned*)(lds + (bufoff) + ldsw + _i * 8192), 16, 0, 0); } while (0)
; #define PG8_LDA(dst, b, h) do { _Pragma("unroll") for (int m = 0; m < 4; ++m) _Pragma("unroll") for (int k = 0; k < 2; ++k) dst[m][k] = *(const PG8_LAS bf16x8*)(lds + PG8_SA(b, h) + aoff + m * 2048 + k * 1024); } while (0)
; #define PG8_LDB(dst, b, h) do { _Pragma("unroll") for (int n = 0; n < 2; ++n) _Pragma("unroll") for (int k = 0; k < 2; ++k) dst[n][k] = *(const PG8_LAS bf16x8*)(lds + PG8_SB(b, h) + boff + n * 2048 + k * 1024); } while (0)
; #define PG8_SCHED __builtin_amdgcn_sched_barrier(0)
; template <class Epi, class Sched, bool ALIGN_EPI = false, bool SP2 = false>
; __device__ __forceinline__ void gemm_phase(PG8_LAS unsigned char* lds, const Gemm g, const Sched& S, const Epi& E) {
;     ...
;             PG8_LDB(B0, 0, 0); PG8_LDB(B1, 0, 1); PG8_SCHED; PG8_LDA(At, 0, 0); PG8_STAGE(PG8_SA(1, 1), a1 + hstep, voffA);
	s_add_i32 m0, s57, 0xc000
	ds_read_b128 v[176:179], v215
	ds_read_b128 v[180:183], v215 offset:1024
	ds_read_b128 v[184:187], v215 offset:2048
	ds_read_b128 v[188:191], v215 offset:3072
	ds_read_b128 v[192:195], v215 offset:4096
	ds_read_b128 v[196:199], v215 offset:5120
	ds_read_b128 v[200:203], v215 offset:6144
	ds_read_b128 v[204:207], v215 offset:7168
	global_load_lds_dwordx4 v168, s[58:59]

; #define PG8_STAGE(bufoff, gbase, voff) do { _Pragma("unroll") for (int _i = 0; _i < 2; ++_i) \
;         __builtin_amdgcn_global_load_lds((const unsigned*)((const char*)(gbase) + (voff)[_i]), (PG8_LAS unsigned*)(lds + (bufoff) + ldsw + _i * 8192), 16, 0, 0); } while (0)
; #define PG8_LDA(dst, b, h) do { _Pragma("unroll") for (int m = 0; m < 4; ++m) _Pragma("unroll") for (int k = 0; k < 2; ++k) dst[m][k] = *(const PG8_LAS bf16x8*)(lds + PG8_SA(b, h) + aoff + m * 2048 + k * 1024); } while (0)
; #define PG8_LDB(dst, b, h) do { _Pragma("unroll") for (int n = 0; n < 2; ++n) _Pragma("unroll") for (int k = 0; k < 2; ++k) dst[n][k] = *(const PG8_LAS bf16x8*)(lds + PG8_SB(b, h) + boff + n * 2048 + k * 1024); } while (0)
; #define PG8_MMA(ai, bj, At, Bt) do { __builtin_amdgcn_s_setprio(1); _Pragma("unroll") for (int m = 0; m < 4; ++m) _Pragma("unroll") for (int n = 0; n < 2; ++n) _Pragma("unroll") for (int k = 0; k < 2; ++k) \
;         acc[ai][bj][m][n] = __builtin_amdgcn_mfma_f32_16x16x32_bf16(Bt[n][k], At[m][k], acc[ai][bj][m][n], 0, 0, 0); __builtin_amdgcn_s_setprio(0); } while (0)
; #define PG8_WAIT_V(n) asm volatile("s_waitcnt vmcnt(" #n ")" ::: "memory")
; #define PG8_WAIT_L(n) asm volatile("s_waitcnt lgkmcnt(" #n ")" ::: "memory")
; #define PG8_BAR __builtin_amdgcn_s_barrier()
; #define PG8_SCHED __builtin_amdgcn_sched_barrier(0)
; template <class Epi, class Sched, bool ALIGN_EPI = false, bool SP2 = false>
; __device__ __forceinline__ void gemm_phase(PG8_LAS unsigned char* lds, const Gemm g, const Sched& S, const Epi& E) {
;     ...
;             PG8_LDB(B0, 0, 0); PG8_LDB(B1, 0, 1); PG8_SCHED; PG8_LDA(At, 0, 0); PG8_STAGE(PG8_SA(1, 1), a1 + hstep, voffA);
;             PG8_WAIT_V(8); PG8_WAIT_L(0); PG8_BAR; PG8_MMA(0, 0, At, B0); PG8_MMA(0, 1, At, B1); PG8_BAR; PG8_SCHED;
	s_add_i32 m0, s57, 0xe000
	s_nop 0
	global_load_lds_dwordx4 v170, s[58:59]
	s_waitcnt vmcnt(8)
	s_waitcnt lgkmcnt(0)

; #define PG8_MMA(ai, bj, At, Bt) do { __builtin_amdgcn_s_setprio(1); _Pragma("unroll") for (int m = 0; m < 4; ++m) _Pragma("unroll") for (int n = 0; n < 2; ++n) _Pragma("unroll") for (int k = 0; k < 2; ++k) \
;         acc[ai][bj][m][n] = __builtin_amdgcn_mfma_f32_16x16x32_bf16(Bt[n][k], At[m][k], acc[ai][bj][m][n], 0, 0, 0); __builtin_amdgcn_s_setprio(0); } while (0)
; #define PG8_WAIT_V(n) asm volatile("s_waitcnt vmcnt(" #n ")" ::: "memory")
; #define PG8_WAIT_L(n) asm volatile("s_waitcnt lgkmcnt(" #n ")" ::: "memory")
; #define PG8_BAR __builtin_amdgcn_s_barrier()
; #define PG8_SCHED __builtin_amdgcn_sched_barrier(0)
; template <class Epi, class Sched, bool ALIGN_EPI = false, bool SP2 = false>
; __device__ __forceinline__ void gemm_phase(PG8_LAS unsigned char* lds, const Gemm g, const Sched& S, const Epi& E) {
;     ...
;             PG8_WAIT_V(8); PG8_WAIT_L(0); PG8_BAR; PG8_MMA(0, 0, At, B0); PG8_MMA(0, 1, At, B1); PG8_BAR; PG8_SCHED;
	s_barrier

; #define PG8_MMA(ai, bj, At, Bt) do { __builtin_amdgcn_s_setprio(1); _Pragma("unroll") for (int m = 0; m < 4; ++m) _Pragma("unroll") for (int n = 0; n < 2; ++n) _Pragma("unroll") for (int k = 0; k < 2; ++k) \
;         acc[ai][bj][m][n] = __builtin_amdgcn_mfma_f32_16x16x32_bf16(Bt[n][k], At[m][k], acc[ai][bj][m][n], 0, 0, 0); __builtin_amdgcn_s_setprio(0); } while (0)
; #define PG8_WAIT_V(n) asm volatile("s_waitcnt vmcnt(" #n ")" ::: "memory")
; #define PG8_WAIT_L(n) asm volatile("s_waitcnt lgkmcnt(" #n ")" ::: "memory")
; #define PG8_BAR __builtin_amdgcn_s_barrier()
; #define PG8_SCHED __builtin_amdgcn_sched_barrier(0)
; template <class Epi, class Sched, bool ALIGN_EPI = false, bool SP2 = false>
; __device__ __forceinline__ void gemm_phase(PG8_LAS unsigned char* lds, const Gemm g, const Sched& S, const Epi& E) {
;     ...
;             PG8_WAIT_V(8); PG8_WAIT_L(0); PG8_BAR; PG8_MMA(0, 0, At, B0); PG8_MMA(0, 1, At, B1); PG8_BAR; PG8_SCHED;
	v_mfma_f32_16x16x32_bf16 v[140:143], v[64:67], v[176:179], v[140:143]
	v_mfma_f32_16x16x32_bf16 v[136:139], v[72:75], v[176:179], v[136:139]
	v_mfma_f32_16x16x32_bf16 v[124:127], v[64:67], v[184:187], v[124:127]
	v_mfma_f32_16x16x32_bf16 v[120:123], v[72:75], v[184:187], v[120:123]
	v_mfma_f32_16x16x32_bf16 v[108:111], v[64:67], v[192:195], v[108:111]
	v_mfma_f32_16x16x32_bf16 v[104:107], v[72:75], v[192:195], v[104:107]
	v_mfma_f32_16x16x32_bf16 v[92:95], v[64:67], v[200:203], v[92:95]
	v_mfma_f32_16x16x32_bf16 v[88:91], v[72:75], v[200:203], v[88:91]
	v_mfma_f32_16x16x32_bf16 v[140:143], v[68:71], v[180:183], v[140:143]
	v_mfma_f32_16x16x32_bf16 v[136:139], v[76:79], v[180:183], v[136:139]
	v_mfma_f32_16x16x32_bf16 v[124:127], v[68:71], v[188:191], v[124:127]
	v_mfma_f32_16x16x32_bf16 v[120:123], v[76:79], v[188:191], v[120:123]
	v_mfma_f32_16x16x32_bf16 v[108:111], v[68:71], v[196:199], v[108:111]
	v_mfma_f32_16x16x32_bf16 v[104:107], v[76:79], v[196:199], v[104:107]
	v_mfma_f32_16x16x32_bf16 v[92:95], v[68:71], v[204:207], v[92:95]
	v_mfma_f32_16x16x32_bf16 v[88:91], v[76:79], v[204:207], v[88:91]


; #define PG8_MMA(ai, bj, At, Bt) do { __builtin_amdgcn_s_setprio(1); _Pragma("unroll") for (int m = 0; m < 4; ++m) _Pragma("unroll") for (int n = 0; n < 2; ++n) _Pragma("unroll") for (int k = 0; k < 2; ++k) \
;         acc[ai][bj][m][n] = __builtin_amdgcn_mfma_f32_16x16x32_bf16(Bt[n][k], At[m][k], acc[ai][bj][m][n], 0, 0, 0); __builtin_amdgcn_s_setprio(0); } while (0)
; #define PG8_WAIT_V(n) asm volatile("s_waitcnt vmcnt(" #n ")" ::: "memory")
; #define PG8_WAIT_L(n) asm volatile("s_waitcnt lgkmcnt(" #n ")" ::: "memory")
; #define PG8_BAR __builtin_amdgcn_s_barrier()
; #define PG8_SCHED __builtin_amdgcn_sched_barrier(0)
; template <class Epi, class Sched, bool ALIGN_EPI = false, bool SP2 = false>
; __device__ __forceinline__ void gemm_phase(PG8_LAS unsigned char* lds, const Gemm g, const Sched& S, const Epi& E) {
;     ...
;             PG8_WAIT_V(8); PG8_WAIT_L(0); PG8_BAR; PG8_MMA(0, 0, At, B0); PG8_MMA(0, 1, At, B1); PG8_BAR; PG8_SCHED;
	v_mfma_f32_16x16x32_bf16 v[132:135], v[144:147], v[176:179], v[132:135]
	v_mfma_f32_16x16x32_bf16 v[128:131], v[152:155], v[176:179], v[128:131]
	v_mfma_f32_16x16x32_bf16 v[116:119], v[144:147], v[184:187], v[116:119]
	v_mfma_f32_16x16x32_bf16 v[112:115], v[152:155], v[184:187], v[112:115]
	v_mfma_f32_16x16x32_bf16 v[100:103], v[144:147], v[192:195], v[100:103]
	v_mfma_f32_16x16x32_bf16 v[96:99], v[152:155], v[192:195], v[96:99]
	v_mfma_f32_16x16x32_bf16 v[84:87], v[144:147], v[200:203], v[84:87]
	v_mfma_f32_16x16x32_bf16 v[80:83], v[152:155], v[200:203], v[80:83]
	v_mfma_f32_16x16x32_bf16 v[132:135], v[148:151], v[180:183], v[132:135]
	v_mfma_f32_16x16x32_bf16 v[128:131], v[156:159], v[180:183], v[128:131]
	v_mfma_f32_16x16x32_bf16 v[116:119], v[148:151], v[188:191], v[116:119]
	v_mfma_f32_16x16x32_bf16 v[112:115], v[156:159], v[188:191], v[112:115]
	v_mfma_f32_16x16x32_bf16 v[100:103], v[148:151], v[196:199], v[100:103]
	v_mfma_f32_16x16x32_bf16 v[96:99], v[156:159], v[196:199], v[96:99]
	v_mfma_f32_16x16x32_bf16 v[84:87], v[148:151], v[204:207], v[84:87]
	v_mfma_f32_16x16x32_bf16 v[80:83], v[156:159], v[204:207], v[80:83]

; #define PG8_STAGE(bufoff, gbase, voff) do { _Pragma("unroll") for (int _i = 0; _i < 2; ++_i) \
;         __builtin_amdgcn_global_load_lds((const unsigned*)((const char*)(gbase) + (voff)[_i]), (PG8_LAS unsigned*)(lds + (bufoff) + ldsw + _i * 8192), 16, 0, 0); } while (0)
; #define PG8_LDA(dst, b, h) do { _Pragma("unroll") for (int m = 0; m < 4; ++m) _Pragma("unroll") for (int k = 0; k < 2; ++k) dst[m][k] = *(const PG8_LAS bf16x8*)(lds + PG8_SA(b, h) + aoff + m * 2048 + k * 1024); } while (0)
; #define PG8_MMA(ai, bj, At, Bt) do { __builtin_amdgcn_s_setprio(1); _Pragma("unroll") for (int m = 0; m < 4; ++m) _Pragma("unroll") for (int n = 0; n < 2; ++n) _Pragma("unroll") for (int k = 0; k < 2; ++k) \
;         acc[ai][bj][m][n] = __builtin_amdgcn_mfma_f32_16x16x32_bf16(Bt[n][k], At[m][k], acc[ai][bj][m][n], 0, 0, 0); __builtin_amdgcn_s_setprio(0); } while (0)
; #define PG8_WAIT_V(n) asm volatile("s_waitcnt vmcnt(" #n ")" ::: "memory")
; #define PG8_WAIT_L(n) asm volatile("s_waitcnt lgkmcnt(" #n ")" ::: "memory")
; #define PG8_BAR __builtin_amdgcn_s_barrier()
; #define PG8_SCHED __builtin_amdgcn_sched_barrier(0)
; template <class Epi, class Sched, bool ALIGN_EPI = false, bool SP2 = false>
; __device__ __forceinline__ void gemm_phase(PG8_LAS unsigned char* lds, const Gemm g, const Sched& S, const Epi& E) {
;     ...
;             PG8_WAIT_V(8); PG8_WAIT_L(0); PG8_BAR; PG8_MMA(0, 0, At, B0); PG8_MMA(0, 1, At, B1); PG8_BAR; PG8_SCHED;
;             PG8_LDA(At, 0, 1); PG8_STAGE(PG8_SB(0, 0), b2, voffB); PG8_STAGE(PG8_SB(0, 1), b2 + hstep, voffB); PG8_STAGE(PG8_SA(0, 0), a2, voffA);
	s_barrier
	s_add_i32 s82, s75, s64
	s_mov_b64 s[96:97], s[60:61]

; #define PG8_STAGE(bufoff, gbase, voff) do { _Pragma("unroll") for (int _i = 0; _i < 2; ++_i) \
;         __builtin_amdgcn_global_load_lds((const unsigned*)((const char*)(gbase) + (voff)[_i]), (PG8_LAS unsigned*)(lds + (bufoff) + ldsw + _i * 8192), 16, 0, 0); } while (0)
; #define PG8_LDA(dst, b, h) do { _Pragma("unroll") for (int m = 0; m < 4; ++m) _Pragma("unroll") for (int k = 0; k < 2; ++k) dst[m][k] = *(const PG8_LAS bf16x8*)(lds + PG8_SA(b, h) + aoff + m * 2048 + k * 1024); } while (0)
; template <class Epi, class Sched, bool ALIGN_EPI = false, bool SP2 = false>
; __device__ __forceinline__ void gemm_phase(PG8_LAS unsigned char* lds, const Gemm g, const Sched& S, const Epi& E) {
;     ...
;             PG8_LDA(At, 0, 1); PG8_STAGE(PG8_SB(0, 0), b2, voffB); PG8_STAGE(PG8_SB(0, 1), b2 + hstep, voffB); PG8_STAGE(PG8_SA(0, 0), a2, voffA);
	s_mov_b32 m0, s82
	ds_read_b128 v[176:179], v215 offset:16384
	ds_read_b128 v[180:183], v215 offset:17408
	ds_read_b128 v[184:187], v215 offset:18432
	ds_read_b128 v[188:191], v215 offset:19456
	ds_read_b128 v[192:195], v215 offset:20480
	ds_read_b128 v[196:199], v215 offset:21504
	ds_read_b128 v[200:203], v215 offset:22528
	ds_read_b128 v[204:207], v215 offset:23552
	global_load_lds_dwordx4 v162, s[60:61]
	s_add_i32 m0, s82, 0x2000
	s_add_u32 s82, s60, 0x200000

; #define PG8_STAGE(bufoff, gbase, voff) do { _Pragma("unroll") for (int _i = 0; _i < 2; ++_i) \
;         __builtin_amdgcn_global_load_lds((const unsigned*)((const char*)(gbase) + (voff)[_i]), (PG8_LAS unsigned*)(lds + (bufoff) + ldsw + _i * 8192), 16, 0, 0); } while (0)
; #define PG8_LDA(dst, b, h) do { _Pragma("unroll") for (int m = 0; m < 4; ++m) _Pragma("unroll") for (int k = 0; k < 2; ++k) dst[m][k] = *(const PG8_LAS bf16x8*)(lds + PG8_SA(b, h) + aoff + m * 2048 + k * 1024); } while (0)
; template <class Epi, class Sched, bool ALIGN_EPI = false, bool SP2 = false>
; __device__ __forceinline__ void gemm_phase(PG8_LAS unsigned char* lds, const Gemm g, const Sched& S, const Epi& E) {
;     ...
;             PG8_LDA(At, 0, 1); PG8_STAGE(PG8_SB(0, 0), b2, voffB); PG8_STAGE(PG8_SB(0, 1), b2 + hstep, voffB); PG8_STAGE(PG8_SA(0, 0), a2, voffA);
	s_addc_u32 s83, s61, 0
	s_add_i32 s84, s76, s64
	global_load_lds_dwordx4 v166, s[60:61]

; #define PG8_STAGE(bufoff, gbase, voff) do { _Pragma("unroll") for (int _i = 0; _i < 2; ++_i) \
;         __builtin_amdgcn_global_load_lds((const unsigned*)((const char*)(gbase) + (voff)[_i]), (PG8_LAS unsigned*)(lds + (bufoff) + ldsw + _i * 8192), 16, 0, 0); } while (0)
; #define PG8_LDA(dst, b, h) do { _Pragma("unroll") for (int m = 0; m < 4; ++m) _Pragma("unroll") for (int k = 0; k < 2; ++k) dst[m][k] = *(const PG8_LAS bf16x8*)(lds + PG8_SA(b, h) + aoff + m * 2048 + k * 1024); } while (0)
; template <class Epi, class Sched, bool ALIGN_EPI = false, bool SP2 = false>
; __device__ __forceinline__ void gemm_phase(PG8_LAS unsigned char* lds, const Gemm g, const Sched& S, const Epi& E) {
;     ...
;             PG8_LDA(At, 0, 1); PG8_STAGE(PG8_SB(0, 0), b2, voffB); PG8_STAGE(PG8_SB(0, 1), b2 + hstep, voffB); PG8_STAGE(PG8_SA(0, 0), a2, voffA);
	s_mov_b32 m0, s84
	s_nop 0
	global_load_lds_dwordx4 v162, s[82:83]

; #define PG8_STAGE(bufoff, gbase, voff) do { _Pragma("unroll") for (int _i = 0; _i < 2; ++_i) \
;         __builtin_amdgcn_global_load_lds((const unsigned*)((const char*)(gbase) + (voff)[_i]), (PG8_LAS unsigned*)(lds + (bufoff) + ldsw + _i * 8192), 16, 0, 0); } while (0)
; #define PG8_LDA(dst, b, h) do { _Pragma("unroll") for (int m = 0; m < 4; ++m) _Pragma("unroll") for (int k = 0; k < 2; ++k) dst[m][k] = *(const PG8_LAS bf16x8*)(lds + PG8_SA(b, h) + aoff + m * 2048 + k * 1024); } while (0)
; template <class Epi, class Sched, bool ALIGN_EPI = false, bool SP2 = false>
; __device__ __forceinline__ void gemm_phase(PG8_LAS unsigned char* lds, const Gemm g, const Sched& S, const Epi& E) {
;     ...
;             PG8_LDA(At, 0, 1); PG8_STAGE(PG8_SB(0, 0), b2, voffB); PG8_STAGE(PG8_SB(0, 1), b2 + hstep, voffB); PG8_STAGE(PG8_SA(0, 0), a2, voffA);
	s_add_i32 m0, s84, 0x2000
	s_nop 0
	global_load_lds_dwordx4 v166, s[82:83]
	s_mov_b64 s[98:99], s[62:63]

; #define PG8_STAGE(bufoff, gbase, voff) do { _Pragma("unroll") for (int _i = 0; _i < 2; ++_i) \
;         __builtin_amdgcn_global_load_lds((const unsigned*)((const char*)(gbase) + (voff)[_i]), (PG8_LAS unsigned*)(lds + (bufoff) + ldsw + _i * 8192), 16, 0, 0); } while (0)
; #define PG8_LDA(dst, b, h) do { _Pragma("unroll") for (int m = 0; m < 4; ++m) _Pragma("unroll") for (int k = 0; k < 2; ++k) dst[m][k] = *(const PG8_LAS bf16x8*)(lds + PG8_SA(b, h) + aoff + m * 2048 + k * 1024); } while (0)
; #define PG8_MMA(ai, bj, At, Bt) do { __builtin_amdgcn_s_setprio(1); _Pragma("unroll") for (int m = 0; m < 4; ++m) _Pragma("unroll") for (int n = 0; n < 2; ++n) _Pragma("unroll") for (int k = 0; k < 2; ++k) \
;         acc[ai][bj][m][n] = __builtin_amdgcn_mfma_f32_16x16x32_bf16(Bt[n][k], At[m][k], acc[ai][bj][m][n], 0, 0, 0); __builtin_amdgcn_s_setprio(0); } while (0)
; #define PG8_WAIT_V(n) asm volatile("s_waitcnt vmcnt(" #n ")" ::: "memory")
; #define PG8_WAIT_L(n) asm volatile("s_waitcnt lgkmcnt(" #n ")" ::: "memory")
; #define PG8_BAR __builtin_amdgcn_s_barrier()
; #define PG8_SCHED __builtin_amdgcn_sched_barrier(0)
; template <class Epi, class Sched, bool ALIGN_EPI = false, bool SP2 = false>
; __device__ __forceinline__ void gemm_phase(PG8_LAS unsigned char* lds, const Gemm g, const Sched& S, const Epi& E) {
;     ...
;             PG8_LDA(At, 0, 1); PG8_STAGE(PG8_SB(0, 0), b2, voffB); PG8_STAGE(PG8_SB(0, 1), b2 + hstep, voffB); PG8_STAGE(PG8_SA(0, 0), a2, voffA);
;             PG8_WAIT_V(8); PG8_WAIT_L(0); PG8_BAR; PG8_MMA(1, 0, At, B0); PG8_MMA(1, 1, At, B1); PG8_BAR; PG8_SCHED;
	s_mov_b32 m0, s57
	s_nop 0
	global_load_lds_dwordx4 v160, s[62:63]
	s_mov_b32 m0, s65
	s_nop 0
	global_load_lds_dwordx4 v164, s[62:63]
	s_waitcnt vmcnt(8)
	s_waitcnt lgkmcnt(0)

; #define PG8_MMA(ai, bj, At, Bt) do { __builtin_amdgcn_s_setprio(1); _Pragma("unroll") for (int m = 0; m < 4; ++m) _Pragma("unroll") for (int n = 0; n < 2; ++n) _Pragma("unroll") for (int k = 0; k < 2; ++k) \
;         acc[ai][bj][m][n] = __builtin_amdgcn_mfma_f32_16x16x32_bf16(Bt[n][k], At[m][k], acc[ai][bj][m][n], 0, 0, 0); __builtin_amdgcn_s_setprio(0); } while (0)
; #define PG8_WAIT_V(n) asm volatile("s_waitcnt vmcnt(" #n ")" ::: "memory")
; #define PG8_WAIT_L(n) asm volatile("s_waitcnt lgkmcnt(" #n ")" ::: "memory")
; #define PG8_BAR __builtin_amdgcn_s_barrier()
; #define PG8_SCHED __builtin_amdgcn_sched_barrier(0)
; template <class Epi, class Sched, bool ALIGN_EPI = false, bool SP2 = false>
; __device__ __forceinline__ void gemm_phase(PG8_LAS unsigned char* lds, const Gemm g, const Sched& S, const Epi& E) {
;     ...
;             PG8_WAIT_V(8); PG8_WAIT_L(0); PG8_BAR; PG8_MMA(1, 0, At, B0); PG8_MMA(1, 1, At, B1); PG8_BAR; PG8_SCHED;
	s_barrier

; #define PG8_MMA(ai, bj, At, Bt) do { __builtin_amdgcn_s_setprio(1); _Pragma("unroll") for (int m = 0; m < 4; ++m) _Pragma("unroll") for (int n = 0; n < 2; ++n) _Pragma("unroll") for (int k = 0; k < 2; ++k) \
;         acc[ai][bj][m][n] = __builtin_amdgcn_mfma_f32_16x16x32_bf16(Bt[n][k], At[m][k], acc[ai][bj][m][n], 0, 0, 0); __builtin_amdgcn_s_setprio(0); } while (0)
; #define PG8_WAIT_V(n) asm volatile("s_waitcnt vmcnt(" #n ")" ::: "memory")
; #define PG8_WAIT_L(n) asm volatile("s_waitcnt lgkmcnt(" #n ")" ::: "memory")
; #define PG8_BAR __builtin_amdgcn_s_barrier()
; #define PG8_SCHED __builtin_amdgcn_sched_barrier(0)
; template <class Epi, class Sched, bool ALIGN_EPI = false, bool SP2 = false>
; __device__ __forceinline__ void gemm_phase(PG8_LAS unsigned char* lds, const Gemm g, const Sched& S, const Epi& E) {
;     ...
;             PG8_WAIT_V(8); PG8_WAIT_L(0); PG8_BAR; PG8_MMA(1, 0, At, B0); PG8_MMA(1, 1, At, B1); PG8_BAR; PG8_SCHED;
	v_mfma_f32_16x16x32_bf16 v[60:63], v[64:67], v[176:179], v[60:63]
	v_mfma_f32_16x16x32_bf16 v[56:59], v[72:75], v[176:179], v[56:59]
	v_mfma_f32_16x16x32_bf16 v[44:47], v[64:67], v[184:187], v[44:47]
	v_mfma_f32_16x16x32_bf16 v[40:43], v[72:75], v[184:187], v[40:43]
	v_mfma_f32_16x16x32_bf16 v[28:31], v[64:67], v[192:195], v[28:31]
	v_mfma_f32_16x16x32_bf16 v[24:27], v[72:75], v[192:195], v[24:27]
	v_mfma_f32_16x16x32_bf16 v[12:15], v[64:67], v[200:203], v[12:15]
	v_mfma_f32_16x16x32_bf16 v[8:11], v[72:75], v[200:203], v[8:11]
	v_mfma_f32_16x16x32_bf16 v[60:63], v[68:71], v[180:183], v[60:63]
	v_mfma_f32_16x16x32_bf16 v[56:59], v[76:79], v[180:183], v[56:59]
	v_mfma_f32_16x16x32_bf16 v[44:47], v[68:71], v[188:191], v[44:47]
	v_mfma_f32_16x16x32_bf16 v[40:43], v[76:79], v[188:191], v[40:43]
	v_mfma_f32_16x16x32_bf16 v[28:31], v[68:71], v[196:199], v[28:31]
	v_mfma_f32_16x16x32_bf16 v[24:27], v[76:79], v[196:199], v[24:27]
	v_mfma_f32_16x16x32_bf16 v[12:15], v[68:71], v[204:207], v[12:15]
	v_mfma_f32_16x16x32_bf16 v[8:11], v[76:79], v[204:207], v[8:11]


; #define PG8_MMA(ai, bj, At, Bt) do { __builtin_amdgcn_s_setprio(1); _Pragma("unroll") for (int m = 0; m < 4; ++m) _Pragma("unroll") for (int n = 0; n < 2; ++n) _Pragma("unroll") for (int k = 0; k < 2; ++k) \
;         acc[ai][bj][m][n] = __builtin_amdgcn_mfma_f32_16x16x32_bf16(Bt[n][k], At[m][k], acc[ai][bj][m][n], 0, 0, 0); __builtin_amdgcn_s_setprio(0); } while (0)
; #define PG8_WAIT_V(n) asm volatile("s_waitcnt vmcnt(" #n ")" ::: "memory")
; #define PG8_WAIT_L(n) asm volatile("s_waitcnt lgkmcnt(" #n ")" ::: "memory")
; #define PG8_BAR __builtin_amdgcn_s_barrier()
; #define PG8_SCHED __builtin_amdgcn_sched_barrier(0)
; template <class Epi, class Sched, bool ALIGN_EPI = false, bool SP2 = false>
; __device__ __forceinline__ void gemm_phase(PG8_LAS unsigned char* lds, const Gemm g, const Sched& S, const Epi& E) {
;     ...
;             PG8_WAIT_V(8); PG8_WAIT_L(0); PG8_BAR; PG8_MMA(1, 0, At, B0); PG8_MMA(1, 1, At, B1); PG8_BAR; PG8_SCHED;
	v_mfma_f32_16x16x32_bf16 v[52:55], v[144:147], v[176:179], v[52:55]
	v_mfma_f32_16x16x32_bf16 v[48:51], v[152:155], v[176:179], v[48:51]
	v_mfma_f32_16x16x32_bf16 v[36:39], v[144:147], v[184:187], v[36:39]
	v_mfma_f32_16x16x32_bf16 v[32:35], v[152:155], v[184:187], v[32:35]
	v_mfma_f32_16x16x32_bf16 v[20:23], v[144:147], v[192:195], v[20:23]
	v_mfma_f32_16x16x32_bf16 v[16:19], v[152:155], v[192:195], v[16:19]
	v_mfma_f32_16x16x32_bf16 v[4:7], v[144:147], v[200:203], v[4:7]
	v_mfma_f32_16x16x32_bf16 v[0:3], v[152:155], v[200:203], v[0:3]
	v_mfma_f32_16x16x32_bf16 v[52:55], v[148:151], v[180:183], v[52:55]
	v_mfma_f32_16x16x32_bf16 v[48:51], v[156:159], v[180:183], v[48:51]
	v_mfma_f32_16x16x32_bf16 v[36:39], v[148:151], v[188:191], v[36:39]
	v_mfma_f32_16x16x32_bf16 v[32:35], v[156:159], v[188:191], v[32:35]
	v_mfma_f32_16x16x32_bf16 v[20:23], v[148:151], v[196:199], v[20:23]
	v_mfma_f32_16x16x32_bf16 v[16:19], v[156:159], v[196:199], v[16:19]
	v_mfma_f32_16x16x32_bf16 v[4:7], v[148:151], v[204:207], v[4:7]
	v_mfma_f32_16x16x32_bf16 v[0:3], v[156:159], v[204:207], v[0:3]

; #define PG8_STAGE(bufoff, gbase, voff) do { _Pragma("unroll") for (int _i = 0; _i < 2; ++_i) \
;         __builtin_amdgcn_global_load_lds((const unsigned*)((const char*)(gbase) + (voff)[_i]), (PG8_LAS unsigned*)(lds + (bufoff) + ldsw + _i * 8192), 16, 0, 0); } while (0)
; #define PG8_LDA(dst, b, h) do { _Pragma("unroll") for (int m = 0; m < 4; ++m) _Pragma("unroll") for (int k = 0; k < 2; ++k) dst[m][k] = *(const PG8_LAS bf16x8*)(lds + PG8_SA(b, h) + aoff + m * 2048 + k * 1024); } while (0)
; #define PG8_LDB(dst, b, h) do { _Pragma("unroll") for (int n = 0; n < 2; ++n) _Pragma("unroll") for (int k = 0; k < 2; ++k) dst[n][k] = *(const PG8_LAS bf16x8*)(lds + PG8_SB(b, h) + boff + n * 2048 + k * 1024); } while (0)
; #define PG8_MMA(ai, bj, At, Bt) do { __builtin_amdgcn_s_setprio(1); _Pragma("unroll") for (int m = 0; m < 4; ++m) _Pragma("unroll") for (int n = 0; n < 2; ++n) _Pragma("unroll") for (int k = 0; k < 2; ++k) \
;         acc[ai][bj][m][n] = __builtin_amdgcn_mfma_f32_16x16x32_bf16(Bt[n][k], At[m][k], acc[ai][bj][m][n], 0, 0, 0); __builtin_amdgcn_s_setprio(0); } while (0)
; #define PG8_WAIT_V(n) asm volatile("s_waitcnt vmcnt(" #n ")" ::: "memory")
; #define PG8_WAIT_L(n) asm volatile("s_waitcnt lgkmcnt(" #n ")" ::: "memory")
; #define PG8_BAR __builtin_amdgcn_s_barrier()
; #define PG8_SCHED __builtin_amdgcn_sched_barrier(0)
; template <class Epi, class Sched, bool ALIGN_EPI = false, bool SP2 = false>
; __device__ __forceinline__ void gemm_phase(PG8_LAS unsigned char* lds, const Gemm g, const Sched& S, const Epi& E) {
;     ...
;             PG8_WAIT_V(8); PG8_WAIT_L(0); PG8_BAR; PG8_MMA(1, 0, At, B0); PG8_MMA(1, 1, At, B1); PG8_BAR; PG8_SCHED;
;             PG8_LDB(B0, 1, 0); PG8_LDB(B1, 1, 1); PG8_SCHED; PG8_LDA(At, 1, 0); PG8_STAGE(PG8_SA(0, 1), a2 + hstep, voffA);
	s_barrier
	s_add_i32 s82, 0, 0x18000
	s_add_i32 s83, 0, 0x1c000


; #define PG8_STAGE(bufoff, gbase, voff) do { _Pragma("unroll") for (int _i = 0; _i < 2; ++_i) \
;         __builtin_amdgcn_global_load_lds((const unsigned*)((const char*)(gbase) + (voff)[_i]), (PG8_LAS unsigned*)(lds + (bufoff) + ldsw + _i * 8192), 16, 0, 0); } while (0)
; #define PG8_LDA(dst, b, h) do { _Pragma("unroll") for (int m = 0; m < 4; ++m) _Pragma("unroll") for (int k = 0; k < 2; ++k) dst[m][k] = *(const PG8_LAS bf16x8*)(lds + PG8_SA(b, h) + aoff + m * 2048 + k * 1024); } while (0)
; #define PG8_LDB(dst, b, h) do { _Pragma("unroll") for (int n = 0; n < 2; ++n) _Pragma("unroll") for (int k = 0; k < 2; ++k) dst[n][k] = *(const PG8_LAS bf16x8*)(lds + PG8_SB(b, h) + boff + n * 2048 + k * 1024); } while (0)
; #define PG8_SCHED __builtin_amdgcn_sched_barrier(0)
; template <class Epi, class Sched, bool ALIGN_EPI = false, bool SP2 = false>
; __device__ __forceinline__ void gemm_phase(PG8_LAS unsigned char* lds, const Gemm g, const Sched& S, const Epi& E) {
;     ...
;             PG8_LDB(B0, 1, 0); PG8_LDB(B1, 1, 1); PG8_SCHED; PG8_LDA(At, 1, 0); PG8_STAGE(PG8_SA(0, 1), a2 + hstep, voffA);
	ds_read_b128 v[64:67], v254
	ds_read_b128 v[68:71], v254 offset:1024
	ds_read_b128 v[72:75], v254 offset:2048
	ds_read_b128 v[76:79], v254 offset:3072
	ds_read_b128 v[144:147], v255
	ds_read_b128 v[148:151], v255 offset:1024
	ds_read_b128 v[152:155], v255 offset:2048
	ds_read_b128 v[156:159], v255 offset:3072
	s_add_u32 s62, s62, 0x200000
	s_addc_u32 s63, s63, 0
	s_mov_b32 m0, s67

; #define PG8_STAGE(bufoff, gbase, voff) do { _Pragma("unroll") for (int _i = 0; _i < 2; ++_i) \
;         __builtin_amdgcn_global_load_lds((const unsigned*)((const char*)(gbase) + (voff)[_i]), (PG8_LAS unsigned*)(lds + (bufoff) + ldsw + _i * 8192), 16, 0, 0); } while (0)
; #define PG8_LDA(dst, b, h) do { _Pragma("unroll") for (int m = 0; m < 4; ++m) _Pragma("unroll") for (int k = 0; k < 2; ++k) dst[m][k] = *(const PG8_LAS bf16x8*)(lds + PG8_SA(b, h) + aoff + m * 2048 + k * 1024); } while (0)
; #define PG8_LDB(dst, b, h) do { _Pragma("unroll") for (int n = 0; n < 2; ++n) _Pragma("unroll") for (int k = 0; k < 2; ++k) dst[n][k] = *(const PG8_LAS bf16x8*)(lds + PG8_SB(b, h) + boff + n * 2048 + k * 1024); } while (0)
; #define PG8_SCHED __builtin_amdgcn_sched_barrier(0)
; template <class Epi, class Sched, bool ALIGN_EPI = false, bool SP2 = false>
; __device__ __forceinline__ void gemm_phase(PG8_LAS unsigned char* lds, const Gemm g, const Sched& S, const Epi& E) {
;     ...
;             PG8_LDB(B0, 1, 0); PG8_LDB(B1, 1, 1); PG8_SCHED; PG8_LDA(At, 1, 0); PG8_STAGE(PG8_SA(0, 1), a2 + hstep, voffA);
	ds_read_b128 v[176:179], v215 offset:32768
	ds_read_b128 v[180:183], v215 offset:33792
	ds_read_b128 v[184:187], v215 offset:34816
	ds_read_b128 v[188:191], v215 offset:35840
	ds_read_b128 v[192:195], v215 offset:36864
	ds_read_b128 v[196:199], v215 offset:37888
	ds_read_b128 v[200:203], v215 offset:38912
	ds_read_b128 v[204:207], v215 offset:39936
	global_load_lds_dwordx4 v160, s[62:63]

; #define PG8_STAGE(bufoff, gbase, voff) do { _Pragma("unroll") for (int _i = 0; _i < 2; ++_i) \
;         __builtin_amdgcn_global_load_lds((const unsigned*)((const char*)(gbase) + (voff)[_i]), (PG8_LAS unsigned*)(lds + (bufoff) + ldsw + _i * 8192), 16, 0, 0); } while (0)
; #define PG8_LDA(dst, b, h) do { _Pragma("unroll") for (int m = 0; m < 4; ++m) _Pragma("unroll") for (int k = 0; k < 2; ++k) dst[m][k] = *(const PG8_LAS bf16x8*)(lds + PG8_SA(b, h) + aoff + m * 2048 + k * 1024); } while (0)
; #define PG8_LDB(dst, b, h) do { _Pragma("unroll") for (int n = 0; n < 2; ++n) _Pragma("unroll") for (int k = 0; k < 2; ++k) dst[n][k] = *(const PG8_LAS bf16x8*)(lds + PG8_SB(b, h) + boff + n * 2048 + k * 1024); } while (0)
; #define PG8_MMA(ai, bj, At, Bt) do { __builtin_amdgcn_s_setprio(1); _Pragma("unroll") for (int m = 0; m < 4; ++m) _Pragma("unroll") for (int n = 0; n < 2; ++n) _Pragma("unroll") for (int k = 0; k < 2; ++k) \
;         acc[ai][bj][m][n] = __builtin_amdgcn_mfma_f32_16x16x32_bf16(Bt[n][k], At[m][k], acc[ai][bj][m][n], 0, 0, 0); __builtin_amdgcn_s_setprio(0); } while (0)
; #define PG8_WAIT_V(n) asm volatile("s_waitcnt vmcnt(" #n ")" ::: "memory")
; #define PG8_WAIT_L(n) asm volatile("s_waitcnt lgkmcnt(" #n ")" ::: "memory")
; #define PG8_BAR __builtin_amdgcn_s_barrier()
; #define PG8_SCHED __builtin_amdgcn_sched_barrier(0)
; template <class Epi, class Sched, bool ALIGN_EPI = false, bool SP2 = false>
; __device__ __forceinline__ void gemm_phase(PG8_LAS unsigned char* lds, const Gemm g, const Sched& S, const Epi& E) {
;     ...
;             PG8_LDB(B0, 1, 0); PG8_LDB(B1, 1, 1); PG8_SCHED; PG8_LDA(At, 1, 0); PG8_STAGE(PG8_SA(0, 1), a2 + hstep, voffA);
;             PG8_WAIT_V(8); PG8_WAIT_L(0); PG8_BAR; PG8_MMA(0, 0, At, B0); PG8_MMA(0, 1, At, B1); PG8_BAR; PG8_SCHED;
	s_mov_b32 m0, s68
	s_nop 0
	global_load_lds_dwordx4 v164, s[62:63]
	s_waitcnt vmcnt(8)
	s_waitcnt lgkmcnt(0)

; #define PG8_MMA(ai, bj, At, Bt) do { __builtin_amdgcn_s_setprio(1); _Pragma("unroll") for (int m = 0; m < 4; ++m) _Pragma("unroll") for (int n = 0; n < 2; ++n) _Pragma("unroll") for (int k = 0; k < 2; ++k) \
;         acc[ai][bj][m][n] = __builtin_amdgcn_mfma_f32_16x16x32_bf16(Bt[n][k], At[m][k], acc[ai][bj][m][n], 0, 0, 0); __builtin_amdgcn_s_setprio(0); } while (0)
; #define PG8_WAIT_V(n) asm volatile("s_waitcnt vmcnt(" #n ")" ::: "memory")
; #define PG8_WAIT_L(n) asm volatile("s_waitcnt lgkmcnt(" #n ")" ::: "memory")
; #define PG8_BAR __builtin_amdgcn_s_barrier()
; #define PG8_SCHED __builtin_amdgcn_sched_barrier(0)
; template <class Epi, class Sched, bool ALIGN_EPI = false, bool SP2 = false>
; __device__ __forceinline__ void gemm_phase(PG8_LAS unsigned char* lds, const Gemm g, const Sched& S, const Epi& E) {
;     ...
;             PG8_WAIT_V(8); PG8_WAIT_L(0); PG8_BAR; PG8_MMA(0, 0, At, B0); PG8_MMA(0, 1, At, B1); PG8_BAR; PG8_SCHED;
	s_barrier

; #define PG8_MMA(ai, bj, At, Bt) do { __builtin_amdgcn_s_setprio(1); _Pragma("unroll") for (int m = 0; m < 4; ++m) _Pragma("unroll") for (int n = 0; n < 2; ++n) _Pragma("unroll") for (int k = 0; k < 2; ++k) \
;         acc[ai][bj][m][n] = __builtin_amdgcn_mfma_f32_16x16x32_bf16(Bt[n][k], At[m][k], acc[ai][bj][m][n], 0, 0, 0); __builtin_amdgcn_s_setprio(0); } while (0)
; #define PG8_WAIT_V(n) asm volatile("s_waitcnt vmcnt(" #n ")" ::: "memory")
; #define PG8_WAIT_L(n) asm volatile("s_waitcnt lgkmcnt(" #n ")" ::: "memory")
; #define PG8_BAR __builtin_amdgcn_s_barrier()
; #define PG8_SCHED __builtin_amdgcn_sched_barrier(0)
; template <class Epi, class Sched, bool ALIGN_EPI = false, bool SP2 = false>
; __device__ __forceinline__ void gemm_phase(PG8_LAS unsigned char* lds, const Gemm g, const Sched& S, const Epi& E) {
;     ...
;             PG8_WAIT_V(8); PG8_WAIT_L(0); PG8_BAR; PG8_MMA(0, 0, At, B0); PG8_MMA(0, 1, At, B1); PG8_BAR; PG8_SCHED;
	v_mfma_f32_16x16x32_bf16 v[140:143], v[64:67], v[176:179], v[140:143]
	v_mfma_f32_16x16x32_bf16 v[136:139], v[72:75], v[176:179], v[136:139]
	v_mfma_f32_16x16x32_bf16 v[124:127], v[64:67], v[184:187], v[124:127]
	v_mfma_f32_16x16x32_bf16 v[120:123], v[72:75], v[184:187], v[120:123]
	v_mfma_f32_16x16x32_bf16 v[108:111], v[64:67], v[192:195], v[108:111]
	v_mfma_f32_16x16x32_bf16 v[104:107], v[72:75], v[192:195], v[104:107]
	v_mfma_f32_16x16x32_bf16 v[92:95], v[64:67], v[200:203], v[92:95]
	v_mfma_f32_16x16x32_bf16 v[88:91], v[72:75], v[200:203], v[88:91]
	v_mfma_f32_16x16x32_bf16 v[140:143], v[68:71], v[180:183], v[140:143]
	v_mfma_f32_16x16x32_bf16 v[136:139], v[76:79], v[180:183], v[136:139]
	v_mfma_f32_16x16x32_bf16 v[124:127], v[68:71], v[188:191], v[124:127]
	v_mfma_f32_16x16x32_bf16 v[120:123], v[76:79], v[188:191], v[120:123]
	v_mfma_f32_16x16x32_bf16 v[108:111], v[68:71], v[196:199], v[108:111]
	v_mfma_f32_16x16x32_bf16 v[104:107], v[76:79], v[196:199], v[104:107]
	v_mfma_f32_16x16x32_bf16 v[92:95], v[68:71], v[204:207], v[92:95]
	v_mfma_f32_16x16x32_bf16 v[88:91], v[76:79], v[204:207], v[88:91]


; #define PG8_MMA(ai, bj, At, Bt) do { __builtin_amdgcn_s_setprio(1); _Pragma("unroll") for (int m = 0; m < 4; ++m) _Pragma("unroll") for (int n = 0; n < 2; ++n) _Pragma("unroll") for (int k = 0; k < 2; ++k) \
;         acc[ai][bj][m][n] = __builtin_amdgcn_mfma_f32_16x16x32_bf16(Bt[n][k], At[m][k], acc[ai][bj][m][n], 0, 0, 0); __builtin_amdgcn_s_setprio(0); } while (0)
; #define PG8_WAIT_V(n) asm volatile("s_waitcnt vmcnt(" #n ")" ::: "memory")
; #define PG8_WAIT_L(n) asm volatile("s_waitcnt lgkmcnt(" #n ")" ::: "memory")
; #define PG8_BAR __builtin_amdgcn_s_barrier()
; #define PG8_SCHED __builtin_amdgcn_sched_barrier(0)
; template <class Epi, class Sched, bool ALIGN_EPI = false, bool SP2 = false>
; __device__ __forceinline__ void gemm_phase(PG8_LAS unsigned char* lds, const Gemm g, const Sched& S, const Epi& E) {
;     ...
;             PG8_WAIT_V(8); PG8_WAIT_L(0); PG8_BAR; PG8_MMA(0, 0, At, B0); PG8_MMA(0, 1, At, B1); PG8_BAR; PG8_SCHED;
	v_mfma_f32_16x16x32_bf16 v[132:135], v[144:147], v[176:179], v[132:135]
	v_mfma_f32_16x16x32_bf16 v[128:131], v[152:155], v[176:179], v[128:131]
	v_mfma_f32_16x16x32_bf16 v[116:119], v[144:147], v[184:187], v[116:119]
	v_mfma_f32_16x16x32_bf16 v[112:115], v[152:155], v[184:187], v[112:115]
	v_mfma_f32_16x16x32_bf16 v[100:103], v[144:147], v[192:195], v[100:103]
	v_mfma_f32_16x16x32_bf16 v[96:99], v[152:155], v[192:195], v[96:99]
	v_mfma_f32_16x16x32_bf16 v[84:87], v[144:147], v[200:203], v[84:87]
	v_mfma_f32_16x16x32_bf16 v[80:83], v[152:155], v[200:203], v[80:83]
	v_mfma_f32_16x16x32_bf16 v[132:135], v[148:151], v[180:183], v[132:135]
	v_mfma_f32_16x16x32_bf16 v[128:131], v[156:159], v[180:183], v[128:131]
	v_mfma_f32_16x16x32_bf16 v[116:119], v[148:151], v[188:191], v[116:119]
	v_mfma_f32_16x16x32_bf16 v[112:115], v[156:159], v[188:191], v[112:115]
	v_mfma_f32_16x16x32_bf16 v[100:103], v[148:151], v[196:199], v[100:103]
	v_mfma_f32_16x16x32_bf16 v[96:99], v[156:159], v[196:199], v[96:99]
	v_mfma_f32_16x16x32_bf16 v[84:87], v[148:151], v[204:207], v[84:87]
	v_mfma_f32_16x16x32_bf16 v[80:83], v[156:159], v[204:207], v[80:83]

; #define PG8_STAGE(bufoff, gbase, voff) do { _Pragma("unroll") for (int _i = 0; _i < 2; ++_i) \
;         __builtin_amdgcn_global_load_lds((const unsigned*)((const char*)(gbase) + (voff)[_i]), (PG8_LAS unsigned*)(lds + (bufoff) + ldsw + _i * 8192), 16, 0, 0); } while (0)
; #define PG8_LDA(dst, b, h) do { _Pragma("unroll") for (int m = 0; m < 4; ++m) _Pragma("unroll") for (int k = 0; k < 2; ++k) dst[m][k] = *(const PG8_LAS bf16x8*)(lds + PG8_SA(b, h) + aoff + m * 2048 + k * 1024); } while (0)
; #define PG8_MMA(ai, bj, At, Bt) do { __builtin_amdgcn_s_setprio(1); _Pragma("unroll") for (int m = 0; m < 4; ++m) _Pragma("unroll") for (int n = 0; n < 2; ++n) _Pragma("unroll") for (int k = 0; k < 2; ++k) \
;         acc[ai][bj][m][n] = __builtin_amdgcn_mfma_f32_16x16x32_bf16(Bt[n][k], At[m][k], acc[ai][bj][m][n], 0, 0, 0); __builtin_amdgcn_s_setprio(0); } while (0)
; #define PG8_WAIT_V(n) asm volatile("s_waitcnt vmcnt(" #n ")" ::: "memory")
; #define PG8_WAIT_L(n) asm volatile("s_waitcnt lgkmcnt(" #n ")" ::: "memory")
; #define PG8_BAR __builtin_amdgcn_s_barrier()
; #define PG8_SCHED __builtin_amdgcn_sched_barrier(0)
; template <class Epi, class Sched, bool ALIGN_EPI = false, bool SP2 = false>
; __device__ __forceinline__ void gemm_phase(PG8_LAS unsigned char* lds, const Gemm g, const Sched& S, const Epi& E) {
;     ...
;             PG8_WAIT_V(8); PG8_WAIT_L(0); PG8_BAR; PG8_MMA(0, 0, At, B0); PG8_MMA(0, 1, At, B1); PG8_BAR; PG8_SCHED;
;             PG8_LDA(At, 1, 1); PG8_STAGE(PG8_SB(1, 0), b3, voffB); PG8_STAGE(PG8_SB(1, 1), b3 + hstep, voffB); PG8_STAGE(PG8_SA(1, 0), a3, voffA);
	s_barrier
	s_add_i32 s62, s82, s64

; #define PG8_STAGE(bufoff, gbase, voff) do { _Pragma("unroll") for (int _i = 0; _i < 2; ++_i) \
;         __builtin_amdgcn_global_load_lds((const unsigned*)((const char*)(gbase) + (voff)[_i]), (PG8_LAS unsigned*)(lds + (bufoff) + ldsw + _i * 8192), 16, 0, 0); } while (0)
; #define PG8_LDA(dst, b, h) do { _Pragma("unroll") for (int m = 0; m < 4; ++m) _Pragma("unroll") for (int k = 0; k < 2; ++k) dst[m][k] = *(const PG8_LAS bf16x8*)(lds + PG8_SA(b, h) + aoff + m * 2048 + k * 1024); } while (0)
; template <class Epi, class Sched, bool ALIGN_EPI = false, bool SP2 = false>
; __device__ __forceinline__ void gemm_phase(PG8_LAS unsigned char* lds, const Gemm g, const Sched& S, const Epi& E) {
;     ...
;             PG8_LDA(At, 1, 1); PG8_STAGE(PG8_SB(1, 0), b3, voffB); PG8_STAGE(PG8_SB(1, 1), b3 + hstep, voffB); PG8_STAGE(PG8_SA(1, 0), a3, voffA);
	s_mov_b32 m0, s62
	ds_read_b128 v[176:179], v215 offset:49152
	ds_read_b128 v[180:183], v215 offset:50176
	ds_read_b128 v[184:187], v215 offset:51200
	ds_read_b128 v[188:191], v215 offset:52224
	ds_read_b128 v[192:195], v215 offset:53248
	ds_read_b128 v[196:199], v215 offset:54272
	ds_read_b128 v[200:203], v215 offset:55296
	ds_read_b128 v[204:207], v215 offset:56320
	global_load_lds_dwordx4 v250, s[96:97]
	s_add_i32 m0, s62, 0x2000
	s_add_u32 s60, s60, 0x200080

; #define PG8_STAGE(bufoff, gbase, voff) do { _Pragma("unroll") for (int _i = 0; _i < 2; ++_i) \
;         __builtin_amdgcn_global_load_lds((const unsigned*)((const char*)(gbase) + (voff)[_i]), (PG8_LAS unsigned*)(lds + (bufoff) + ldsw + _i * 8192), 16, 0, 0); } while (0)
; #define PG8_LDA(dst, b, h) do { _Pragma("unroll") for (int m = 0; m < 4; ++m) _Pragma("unroll") for (int k = 0; k < 2; ++k) dst[m][k] = *(const PG8_LAS bf16x8*)(lds + PG8_SA(b, h) + aoff + m * 2048 + k * 1024); } while (0)
; template <class Epi, class Sched, bool ALIGN_EPI = false, bool SP2 = false>
; __device__ __forceinline__ void gemm_phase(PG8_LAS unsigned char* lds, const Gemm g, const Sched& S, const Epi& E) {
;     ...
;             PG8_LDA(At, 1, 1); PG8_STAGE(PG8_SB(1, 0), b3, voffB); PG8_STAGE(PG8_SB(1, 1), b3 + hstep, voffB); PG8_STAGE(PG8_SA(1, 0), a3, voffA);
	s_addc_u32 s61, s61, 0
	s_add_i32 s62, s83, s64
	global_load_lds_dwordx4 v251, s[96:97]

; #define PG8_STAGE(bufoff, gbase, voff) do { _Pragma("unroll") for (int _i = 0; _i < 2; ++_i) \
;         __builtin_amdgcn_global_load_lds((const unsigned*)((const char*)(gbase) + (voff)[_i]), (PG8_LAS unsigned*)(lds + (bufoff) + ldsw + _i * 8192), 16, 0, 0); } while (0)
; #define PG8_LDA(dst, b, h) do { _Pragma("unroll") for (int m = 0; m < 4; ++m) _Pragma("unroll") for (int k = 0; k < 2; ++k) dst[m][k] = *(const PG8_LAS bf16x8*)(lds + PG8_SA(b, h) + aoff + m * 2048 + k * 1024); } while (0)
; template <class Epi, class Sched, bool ALIGN_EPI = false, bool SP2 = false>
; __device__ __forceinline__ void gemm_phase(PG8_LAS unsigned char* lds, const Gemm g, const Sched& S, const Epi& E) {
;     ...
;             PG8_LDA(At, 1, 1); PG8_STAGE(PG8_SB(1, 0), b3, voffB); PG8_STAGE(PG8_SB(1, 1), b3 + hstep, voffB); PG8_STAGE(PG8_SA(1, 0), a3, voffA);
	s_mov_b32 m0, s62
	s_nop 0
	global_load_lds_dwordx4 v162, s[60:61]

; #define PG8_STAGE(bufoff, gbase, voff) do { _Pragma("unroll") for (int _i = 0; _i < 2; ++_i) \
;         __builtin_amdgcn_global_load_lds((const unsigned*)((const char*)(gbase) + (voff)[_i]), (PG8_LAS unsigned*)(lds + (bufoff) + ldsw + _i * 8192), 16, 0, 0); } while (0)
; #define PG8_LDA(dst, b, h) do { _Pragma("unroll") for (int m = 0; m < 4; ++m) _Pragma("unroll") for (int k = 0; k < 2; ++k) dst[m][k] = *(const PG8_LAS bf16x8*)(lds + PG8_SA(b, h) + aoff + m * 2048 + k * 1024); } while (0)
; template <class Epi, class Sched, bool ALIGN_EPI = false, bool SP2 = false>
; __device__ __forceinline__ void gemm_phase(PG8_LAS unsigned char* lds, const Gemm g, const Sched& S, const Epi& E) {
;     ...
;             PG8_LDA(At, 1, 1); PG8_STAGE(PG8_SB(1, 0), b3, voffB); PG8_STAGE(PG8_SB(1, 1), b3 + hstep, voffB); PG8_STAGE(PG8_SA(1, 0), a3, voffA);
	s_add_i32 m0, s62, 0x2000
	s_nop 0
	global_load_lds_dwordx4 v166, s[60:61]

; #define PG8_STAGE(bufoff, gbase, voff) do { _Pragma("unroll") for (int _i = 0; _i < 2; ++_i) \
;         __builtin_amdgcn_global_load_lds((const unsigned*)((const char*)(gbase) + (voff)[_i]), (PG8_LAS unsigned*)(lds + (bufoff) + ldsw + _i * 8192), 16, 0, 0); } while (0)
; #define PG8_LDA(dst, b, h) do { _Pragma("unroll") for (int m = 0; m < 4; ++m) _Pragma("unroll") for (int k = 0; k < 2; ++k) dst[m][k] = *(const PG8_LAS bf16x8*)(lds + PG8_SA(b, h) + aoff + m * 2048 + k * 1024); } while (0)
; template <class Epi, class Sched, bool ALIGN_EPI = false, bool SP2 = false>
; __device__ __forceinline__ void gemm_phase(PG8_LAS unsigned char* lds, const Gemm g, const Sched& S, const Epi& E) {
;     ...
;             PG8_LDA(At, 1, 1); PG8_STAGE(PG8_SB(1, 0), b3, voffB); PG8_STAGE(PG8_SB(1, 1), b3 + hstep, voffB); PG8_STAGE(PG8_SA(1, 0), a3, voffA);
	s_mov_b32 m0, s70
	s_nop 0
	global_load_lds_dwordx4 v252, s[98:99]

; #define PG8_STAGE(bufoff, gbase, voff) do { _Pragma("unroll") for (int _i = 0; _i < 2; ++_i) \
;         __builtin_amdgcn_global_load_lds((const unsigned*)((const char*)(gbase) + (voff)[_i]), (PG8_LAS unsigned*)(lds + (bufoff) + ldsw + _i * 8192), 16, 0, 0); } while (0)
; #define PG8_LDA(dst, b, h) do { _Pragma("unroll") for (int m = 0; m < 4; ++m) _Pragma("unroll") for (int k = 0; k < 2; ++k) dst[m][k] = *(const PG8_LAS bf16x8*)(lds + PG8_SA(b, h) + aoff + m * 2048 + k * 1024); } while (0)
; #define PG8_MMA(ai, bj, At, Bt) do { __builtin_amdgcn_s_setprio(1); _Pragma("unroll") for (int m = 0; m < 4; ++m) _Pragma("unroll") for (int n = 0; n < 2; ++n) _Pragma("unroll") for (int k = 0; k < 2; ++k) \
;         acc[ai][bj][m][n] = __builtin_amdgcn_mfma_f32_16x16x32_bf16(Bt[n][k], At[m][k], acc[ai][bj][m][n], 0, 0, 0); __builtin_amdgcn_s_setprio(0); } while (0)
; #define PG8_WAIT_V(n) asm volatile("s_waitcnt vmcnt(" #n ")" ::: "memory")
; #define PG8_WAIT_L(n) asm volatile("s_waitcnt lgkmcnt(" #n ")" ::: "memory")
; #define PG8_BAR __builtin_amdgcn_s_barrier()
; #define PG8_SCHED __builtin_amdgcn_sched_barrier(0)
; template <class Epi, class Sched, bool ALIGN_EPI = false, bool SP2 = false>
; __device__ __forceinline__ void gemm_phase(PG8_LAS unsigned char* lds, const Gemm g, const Sched& S, const Epi& E) {
;     ...
;             PG8_LDA(At, 1, 1); PG8_STAGE(PG8_SB(1, 0), b3, voffB); PG8_STAGE(PG8_SB(1, 1), b3 + hstep, voffB); PG8_STAGE(PG8_SA(1, 0), a3, voffA);
;             PG8_WAIT_V(8); PG8_WAIT_L(0); PG8_BAR; PG8_MMA(1, 0, At, B0); PG8_MMA(1, 1, At, B1); PG8_BAR; PG8_SCHED;
	s_mov_b32 m0, s71
	s_nop 0
	global_load_lds_dwordx4 v253, s[98:99]
	s_waitcnt vmcnt(8)
	s_waitcnt lgkmcnt(0)

; #define PG8_MMA(ai, bj, At, Bt) do { __builtin_amdgcn_s_setprio(1); _Pragma("unroll") for (int m = 0; m < 4; ++m) _Pragma("unroll") for (int n = 0; n < 2; ++n) _Pragma("unroll") for (int k = 0; k < 2; ++k) \
;         acc[ai][bj][m][n] = __builtin_amdgcn_mfma_f32_16x16x32_bf16(Bt[n][k], At[m][k], acc[ai][bj][m][n], 0, 0, 0); __builtin_amdgcn_s_setprio(0); } while (0)
; #define PG8_WAIT_V(n) asm volatile("s_waitcnt vmcnt(" #n ")" ::: "memory")
; #define PG8_WAIT_L(n) asm volatile("s_waitcnt lgkmcnt(" #n ")" ::: "memory")
; #define PG8_BAR __builtin_amdgcn_s_barrier()
; #define PG8_SCHED __builtin_amdgcn_sched_barrier(0)
; template <class Epi, class Sched, bool ALIGN_EPI = false, bool SP2 = false>
; __device__ __forceinline__ void gemm_phase(PG8_LAS unsigned char* lds, const Gemm g, const Sched& S, const Epi& E) {
;     ...
;             PG8_WAIT_V(8); PG8_WAIT_L(0); PG8_BAR; PG8_MMA(1, 0, At, B0); PG8_MMA(1, 1, At, B1); PG8_BAR; PG8_SCHED;
	s_barrier

; #define PG8_MMA(ai, bj, At, Bt) do { __builtin_amdgcn_s_setprio(1); _Pragma("unroll") for (int m = 0; m < 4; ++m) _Pragma("unroll") for (int n = 0; n < 2; ++n) _Pragma("unroll") for (int k = 0; k < 2; ++k) \
;         acc[ai][bj][m][n] = __builtin_amdgcn_mfma_f32_16x16x32_bf16(Bt[n][k], At[m][k], acc[ai][bj][m][n], 0, 0, 0); __builtin_amdgcn_s_setprio(0); } while (0)
; #define PG8_WAIT_V(n) asm volatile("s_waitcnt vmcnt(" #n ")" ::: "memory")
; #define PG8_WAIT_L(n) asm volatile("s_waitcnt lgkmcnt(" #n ")" ::: "memory")
; #define PG8_BAR __builtin_amdgcn_s_barrier()
; #define PG8_SCHED __builtin_amdgcn_sched_barrier(0)
; template <class Epi, class Sched, bool ALIGN_EPI = false, bool SP2 = false>
; __device__ __forceinline__ void gemm_phase(PG8_LAS unsigned char* lds, const Gemm g, const Sched& S, const Epi& E) {
;     ...
;             PG8_WAIT_V(8); PG8_WAIT_L(0); PG8_BAR; PG8_MMA(1, 0, At, B0); PG8_MMA(1, 1, At, B1); PG8_BAR; PG8_SCHED;
	v_mfma_f32_16x16x32_bf16 v[60:63], v[64:67], v[176:179], v[60:63]
	v_mfma_f32_16x16x32_bf16 v[56:59], v[72:75], v[176:179], v[56:59]
	v_mfma_f32_16x16x32_bf16 v[44:47], v[64:67], v[184:187], v[44:47]
	v_mfma_f32_16x16x32_bf16 v[40:43], v[72:75], v[184:187], v[40:43]
	v_mfma_f32_16x16x32_bf16 v[28:31], v[64:67], v[192:195], v[28:31]
	v_mfma_f32_16x16x32_bf16 v[24:27], v[72:75], v[192:195], v[24:27]
	v_mfma_f32_16x16x32_bf16 v[12:15], v[64:67], v[200:203], v[12:15]
	v_mfma_f32_16x16x32_bf16 v[8:11], v[72:75], v[200:203], v[8:11]
	v_mfma_f32_16x16x32_bf16 v[60:63], v[68:71], v[180:183], v[60:63]
	v_mfma_f32_16x16x32_bf16 v[56:59], v[76:79], v[180:183], v[56:59]
	v_mfma_f32_16x16x32_bf16 v[44:47], v[68:71], v[188:191], v[44:47]
	v_mfma_f32_16x16x32_bf16 v[40:43], v[76:79], v[188:191], v[40:43]
	v_mfma_f32_16x16x32_bf16 v[28:31], v[68:71], v[196:199], v[28:31]
	v_mfma_f32_16x16x32_bf16 v[24:27], v[76:79], v[196:199], v[24:27]
	v_mfma_f32_16x16x32_bf16 v[12:15], v[68:71], v[204:207], v[12:15]
	v_mfma_f32_16x16x32_bf16 v[8:11], v[76:79], v[204:207], v[8:11]


; #define PG8_MMA(ai, bj, At, Bt) do { __builtin_amdgcn_s_setprio(1); _Pragma("unroll") for (int m = 0; m < 4; ++m) _Pragma("unroll") for (int n = 0; n < 2; ++n) _Pragma("unroll") for (int k = 0; k < 2; ++k) \
;         acc[ai][bj][m][n] = __builtin_amdgcn_mfma_f32_16x16x32_bf16(Bt[n][k], At[m][k], acc[ai][bj][m][n], 0, 0, 0); __builtin_amdgcn_s_setprio(0); } while (0)
; #define PG8_WAIT_V(n) asm volatile("s_waitcnt vmcnt(" #n ")" ::: "memory")
; #define PG8_WAIT_L(n) asm volatile("s_waitcnt lgkmcnt(" #n ")" ::: "memory")
; #define PG8_BAR __builtin_amdgcn_s_barrier()
; #define PG8_SCHED __builtin_amdgcn_sched_barrier(0)
; template <class Epi, class Sched, bool ALIGN_EPI = false, bool SP2 = false>
; __device__ __forceinline__ void gemm_phase(PG8_LAS unsigned char* lds, const Gemm g, const Sched& S, const Epi& E) {
;     ...
;             PG8_WAIT_V(8); PG8_WAIT_L(0); PG8_BAR; PG8_MMA(1, 0, At, B0); PG8_MMA(1, 1, At, B1); PG8_BAR; PG8_SCHED;
	v_mfma_f32_16x16x32_bf16 v[52:55], v[144:147], v[176:179], v[52:55]
	v_mfma_f32_16x16x32_bf16 v[48:51], v[152:155], v[176:179], v[48:51]
	v_mfma_f32_16x16x32_bf16 v[36:39], v[144:147], v[184:187], v[36:39]
	v_mfma_f32_16x16x32_bf16 v[32:35], v[152:155], v[184:187], v[32:35]
	v_mfma_f32_16x16x32_bf16 v[20:23], v[144:147], v[192:195], v[20:23]
	v_mfma_f32_16x16x32_bf16 v[16:19], v[152:155], v[192:195], v[16:19]
	v_mfma_f32_16x16x32_bf16 v[4:7], v[144:147], v[200:203], v[4:7]
	v_mfma_f32_16x16x32_bf16 v[0:3], v[152:155], v[200:203], v[0:3]
	v_mfma_f32_16x16x32_bf16 v[52:55], v[148:151], v[180:183], v[52:55]
	v_mfma_f32_16x16x32_bf16 v[48:51], v[156:159], v[180:183], v[48:51]
	v_mfma_f32_16x16x32_bf16 v[36:39], v[148:151], v[188:191], v[36:39]
	v_mfma_f32_16x16x32_bf16 v[32:35], v[156:159], v[188:191], v[32:35]
	v_mfma_f32_16x16x32_bf16 v[20:23], v[148:151], v[196:199], v[20:23]
	v_mfma_f32_16x16x32_bf16 v[16:19], v[156:159], v[196:199], v[16:19]
	v_mfma_f32_16x16x32_bf16 v[4:7], v[148:151], v[204:207], v[4:7]
	v_mfma_f32_16x16x32_bf16 v[0:3], v[156:159], v[204:207], v[0:3]

; #define PG8_MMA(ai, bj, At, Bt) do { __builtin_amdgcn_s_setprio(1); _Pragma("unroll") for (int m = 0; m < 4; ++m) _Pragma("unroll") for (int n = 0; n < 2; ++n) _Pragma("unroll") for (int k = 0; k < 2; ++k) \
;         acc[ai][bj][m][n] = __builtin_amdgcn_mfma_f32_16x16x32_bf16(Bt[n][k], At[m][k], acc[ai][bj][m][n], 0, 0, 0); __builtin_amdgcn_s_setprio(0); } while (0)
; #define PG8_WAIT_V(n) asm volatile("s_waitcnt vmcnt(" #n ")" ::: "memory")
; #define PG8_WAIT_L(n) asm volatile("s_waitcnt lgkmcnt(" #n ")" ::: "memory")
; #define PG8_BAR __builtin_amdgcn_s_barrier()
; #define PG8_SCHED __builtin_amdgcn_sched_barrier(0)
; template <class Epi, class Sched, bool ALIGN_EPI = false, bool SP2 = false>
; __device__ __forceinline__ void gemm_phase(PG8_LAS unsigned char* lds, const Gemm g, const Sched& S, const Epi& E) {
;     ...
;             PG8_WAIT_V(8); PG8_WAIT_L(0); PG8_BAR; PG8_MMA(1, 0, At, B0); PG8_MMA(1, 1, At, B1); PG8_BAR; PG8_SCHED;
;     ...
;         if constexpr (ALIGN_EPI) { if (wr == 0) PG8_BAR; }
	s_barrier
	s_add_i32 s81, s81, 2
	s_add_u32 s58, s58, 0x100
	s_addc_u32 s59, s59, 0
	s_add_u32 s79, s79, 0x100
	s_addc_u32 s80, s80, 0
	s_cmpk_gt_u32 s81, 0x7d
	s_cbranch_scc0 .LBB0_509
	s_and_b64 vcc, exec, s[42:43]
	s_cbranch_vccz .LBB0_512
	s_barrier

; #define PG8_STAGE(bufoff, gbase, voff) do { _Pragma("unroll") for (int _i = 0; _i < 2; ++_i) \
;         __builtin_amdgcn_global_load_lds((const unsigned*)((const char*)(gbase) + (voff)[_i]), (PG8_LAS unsigned*)(lds + (bufoff) + ldsw + _i * 8192), 16, 0, 0); } while (0)
; #define PG8_LDA(dst, b, h) do { _Pragma("unroll") for (int m = 0; m < 4; ++m) _Pragma("unroll") for (int k = 0; k < 2; ++k) dst[m][k] = *(const PG8_LAS bf16x8*)(lds + PG8_SA(b, h) + aoff + m * 2048 + k * 1024); } while (0)
; #define PG8_LDB(dst, b, h) do { _Pragma("unroll") for (int n = 0; n < 2; ++n) _Pragma("unroll") for (int k = 0; k < 2; ++k) dst[n][k] = *(const PG8_LAS bf16x8*)(lds + PG8_SB(b, h) + boff + n * 2048 + k * 1024); } while (0)
; #define PG8_SCHED __builtin_amdgcn_sched_barrier(0)
; template <class Epi, class Sched, bool ALIGN_EPI = false, bool SP2 = false>
; __device__ __forceinline__ void gemm_phase(PG8_LAS unsigned char* lds, const Gemm g, const Sched& S, const Epi& E) {
;     ...
;             const bool last = (t == nt - 2);
;             const char* a1 = cA + (size_t)(t + 1) * kstep;
;             const char* a2 = last ? nA : cA + (size_t)(t + 2) * kstep; const char* b2 = last ? nB : cB + (size_t)(t + 2) * kstep;
;             const char* a3 = a2 + kstep; const char* b3 = b2 + kstep;
;             if (last && has_next) S.a_ready(nxt);
;             if constexpr (SP2) {
;             PG8_LDB(B0, 0, 0); PG8_LDB(B1, 0, 1); PG8_SCHED; PG8_LDA(At, 0, 0); PG8_STAGE(PG8_SA(1, 1), a1 + hstep, voffA);
.LBB0_679:
	ds_read_b128 v[128:131], v203
	ds_read_b128 v[132:135], v203 offset:1024
	ds_read_b128 v[136:139], v203 offset:2048
	ds_read_b128 v[140:143], v203 offset:3072
	ds_read_b128 v[144:147], v205
	ds_read_b128 v[148:151], v205 offset:1024
	ds_read_b128 v[152:155], v205 offset:2048
	ds_read_b128 v[156:159], v205 offset:3072
	s_add_u32 s12, s10, 0xfff80080
	s_addc_u32 s13, s11, -1
	s_cmp_eq_u32 s78, 28
	s_cselect_b32 s55, s49, s13
	s_cselect_b32 s54, s74, s12
	s_cselect_b32 s13, s47, s77
	s_cselect_b32 s12, s75, s76

; #define PG8_STAGE(bufoff, gbase, voff) do { _Pragma("unroll") for (int _i = 0; _i < 2; ++_i) \
;         __builtin_amdgcn_global_load_lds((const unsigned*)((const char*)(gbase) + (voff)[_i]), (PG8_LAS unsigned*)(lds + (bufoff) + ldsw + _i * 8192), 16, 0, 0); } while (0)
; #define PG8_LDA(dst, b, h) do { _Pragma("unroll") for (int m = 0; m < 4; ++m) _Pragma("unroll") for (int k = 0; k < 2; ++k) dst[m][k] = *(const PG8_LAS bf16x8*)(lds + PG8_SA(b, h) + aoff + m * 2048 + k * 1024); } while (0)
; #define PG8_LDB(dst, b, h) do { _Pragma("unroll") for (int n = 0; n < 2; ++n) _Pragma("unroll") for (int k = 0; k < 2; ++k) dst[n][k] = *(const PG8_LAS bf16x8*)(lds + PG8_SB(b, h) + boff + n * 2048 + k * 1024); } while (0)
; #define PG8_SCHED __builtin_amdgcn_sched_barrier(0)
; template <class Epi, class Sched, bool ALIGN_EPI = false, bool SP2 = false>
; __device__ __forceinline__ void gemm_phase(PG8_LAS unsigned char* lds, const Gemm g, const Sched& S, const Epi& E) {
;     ...
;             PG8_LDB(B0, 0, 0); PG8_LDB(B1, 0, 1); PG8_SCHED; PG8_LDA(At, 0, 0); PG8_STAGE(PG8_SA(1, 1), a1 + hstep, voffA);
	s_add_i32 m0, s60, 0xc000
	ds_read_b128 v[176:179], v207
	ds_read_b128 v[180:183], v207 offset:1024
	ds_read_b128 v[184:187], v207 offset:2048
	ds_read_b128 v[192:195], v207 offset:3072
	ds_read_b128 v[210:213], v207 offset:4096
	ds_read_b128 v[214:217], v207 offset:5120
	ds_read_b128 v[218:221], v207 offset:6144
	ds_read_b128 v[222:225], v207 offset:7168
	global_load_lds_dwordx4 v168, s[10:11]

; #define PG8_STAGE(bufoff, gbase, voff) do { _Pragma("unroll") for (int _i = 0; _i < 2; ++_i) \
;         __builtin_amdgcn_global_load_lds((const unsigned*)((const char*)(gbase) + (voff)[_i]), (PG8_LAS unsigned*)(lds + (bufoff) + ldsw + _i * 8192), 16, 0, 0); } while (0)
; #define PG8_LDA(dst, b, h) do { _Pragma("unroll") for (int m = 0; m < 4; ++m) _Pragma("unroll") for (int k = 0; k < 2; ++k) dst[m][k] = *(const PG8_LAS bf16x8*)(lds + PG8_SA(b, h) + aoff + m * 2048 + k * 1024); } while (0)
; #define PG8_LDB(dst, b, h) do { _Pragma("unroll") for (int n = 0; n < 2; ++n) _Pragma("unroll") for (int k = 0; k < 2; ++k) dst[n][k] = *(const PG8_LAS bf16x8*)(lds + PG8_SB(b, h) + boff + n * 2048 + k * 1024); } while (0)
; #define PG8_MMA(ai, bj, At, Bt) do { __builtin_amdgcn_s_setprio(1); _Pragma("unroll") for (int m = 0; m < 4; ++m) _Pragma("unroll") for (int n = 0; n < 2; ++n) _Pragma("unroll") for (int k = 0; k < 2; ++k) \
;         acc[ai][bj][m][n] = __builtin_amdgcn_mfma_f32_16x16x32_bf16(Bt[n][k], At[m][k], acc[ai][bj][m][n], 0, 0, 0); __builtin_amdgcn_s_setprio(0); } while (0)
; #define PG8_WAIT_V(n) asm volatile("s_waitcnt vmcnt(" #n ")" ::: "memory")
; #define PG8_WAIT_L(n) asm volatile("s_waitcnt lgkmcnt(" #n ")" ::: "memory")
; #define PG8_BAR __builtin_amdgcn_s_barrier()
; #define PG8_SCHED __builtin_amdgcn_sched_barrier(0)
; template <class Epi, class Sched, bool ALIGN_EPI = false, bool SP2 = false>
; __device__ __forceinline__ void gemm_phase(PG8_LAS unsigned char* lds, const Gemm g, const Sched& S, const Epi& E) {
;     ...
;             PG8_LDB(B0, 0, 0); PG8_LDB(B1, 0, 1); PG8_SCHED; PG8_LDA(At, 0, 0); PG8_STAGE(PG8_SA(1, 1), a1 + hstep, voffA);
;             PG8_WAIT_V(8); PG8_WAIT_L(0); PG8_BAR; PG8_MMA(0, 0, At, B0); PG8_MMA(0, 1, At, B1); PG8_BAR; PG8_SCHED;
	s_add_i32 m0, s60, 0xe000
	s_nop 0
	global_load_lds_dwordx4 v170, s[10:11]
	s_waitcnt vmcnt(8)
	s_waitcnt lgkmcnt(0)

; #define PG8_MMA(ai, bj, At, Bt) do { __builtin_amdgcn_s_setprio(1); _Pragma("unroll") for (int m = 0; m < 4; ++m) _Pragma("unroll") for (int n = 0; n < 2; ++n) _Pragma("unroll") for (int k = 0; k < 2; ++k) \
;         acc[ai][bj][m][n] = __builtin_amdgcn_mfma_f32_16x16x32_bf16(Bt[n][k], At[m][k], acc[ai][bj][m][n], 0, 0, 0); __builtin_amdgcn_s_setprio(0); } while (0)
; #define PG8_WAIT_V(n) asm volatile("s_waitcnt vmcnt(" #n ")" ::: "memory")
; #define PG8_WAIT_L(n) asm volatile("s_waitcnt lgkmcnt(" #n ")" ::: "memory")
; #define PG8_BAR __builtin_amdgcn_s_barrier()
; #define PG8_SCHED __builtin_amdgcn_sched_barrier(0)
; template <class Epi, class Sched, bool ALIGN_EPI = false, bool SP2 = false>
; __device__ __forceinline__ void gemm_phase(PG8_LAS unsigned char* lds, const Gemm g, const Sched& S, const Epi& E) {
;     ...
;             PG8_WAIT_V(8); PG8_WAIT_L(0); PG8_BAR; PG8_MMA(0, 0, At, B0); PG8_MMA(0, 1, At, B1); PG8_BAR; PG8_SCHED;
	s_barrier

; #define PG8_MMA(ai, bj, At, Bt) do { __builtin_amdgcn_s_setprio(1); _Pragma("unroll") for (int m = 0; m < 4; ++m) _Pragma("unroll") for (int n = 0; n < 2; ++n) _Pragma("unroll") for (int k = 0; k < 2; ++k) \
;         acc[ai][bj][m][n] = __builtin_amdgcn_mfma_f32_16x16x32_bf16(Bt[n][k], At[m][k], acc[ai][bj][m][n], 0, 0, 0); __builtin_amdgcn_s_setprio(0); } while (0)
; #define PG8_WAIT_V(n) asm volatile("s_waitcnt vmcnt(" #n ")" ::: "memory")
; #define PG8_WAIT_L(n) asm volatile("s_waitcnt lgkmcnt(" #n ")" ::: "memory")
; #define PG8_BAR __builtin_amdgcn_s_barrier()
; #define PG8_SCHED __builtin_amdgcn_sched_barrier(0)
; template <class Epi, class Sched, bool ALIGN_EPI = false, bool SP2 = false>
; __device__ __forceinline__ void gemm_phase(PG8_LAS unsigned char* lds, const Gemm g, const Sched& S, const Epi& E) {
;     ...
;             PG8_WAIT_V(8); PG8_WAIT_L(0); PG8_BAR; PG8_MMA(0, 0, At, B0); PG8_MMA(0, 1, At, B1); PG8_BAR; PG8_SCHED;
	v_mfma_f32_16x16x32_bf16 v[124:127], v[128:131], v[176:179], v[124:127]
	v_mfma_f32_16x16x32_bf16 v[120:123], v[136:139], v[176:179], v[120:123]
	v_mfma_f32_16x16x32_bf16 v[112:115], v[128:131], v[184:187], v[112:115]
	v_mfma_f32_16x16x32_bf16 v[104:107], v[136:139], v[184:187], v[104:107]
	v_mfma_f32_16x16x32_bf16 v[100:103], v[128:131], v[210:213], v[100:103]
	v_mfma_f32_16x16x32_bf16 v[88:91], v[136:139], v[210:213], v[88:91]
	v_mfma_f32_16x16x32_bf16 v[84:87], v[128:131], v[218:221], v[84:87]
	v_mfma_f32_16x16x32_bf16 v[72:75], v[136:139], v[218:221], v[72:75]
	v_mfma_f32_16x16x32_bf16 v[124:127], v[132:135], v[180:183], v[124:127]
	v_mfma_f32_16x16x32_bf16 v[120:123], v[140:143], v[180:183], v[120:123]
	v_mfma_f32_16x16x32_bf16 v[112:115], v[132:135], v[192:195], v[112:115]
	v_mfma_f32_16x16x32_bf16 v[104:107], v[140:143], v[192:195], v[104:107]
	v_mfma_f32_16x16x32_bf16 v[100:103], v[132:135], v[214:217], v[100:103]
	v_mfma_f32_16x16x32_bf16 v[88:91], v[140:143], v[214:217], v[88:91]
	v_mfma_f32_16x16x32_bf16 v[84:87], v[132:135], v[222:225], v[84:87]
	v_mfma_f32_16x16x32_bf16 v[72:75], v[140:143], v[222:225], v[72:75]


; #define PG8_MMA(ai, bj, At, Bt) do { __builtin_amdgcn_s_setprio(1); _Pragma("unroll") for (int m = 0; m < 4; ++m) _Pragma("unroll") for (int n = 0; n < 2; ++n) _Pragma("unroll") for (int k = 0; k < 2; ++k) \
;         acc[ai][bj][m][n] = __builtin_amdgcn_mfma_f32_16x16x32_bf16(Bt[n][k], At[m][k], acc[ai][bj][m][n], 0, 0, 0); __builtin_amdgcn_s_setprio(0); } while (0)
; #define PG8_WAIT_V(n) asm volatile("s_waitcnt vmcnt(" #n ")" ::: "memory")
; #define PG8_WAIT_L(n) asm volatile("s_waitcnt lgkmcnt(" #n ")" ::: "memory")
; #define PG8_BAR __builtin_amdgcn_s_barrier()
; #define PG8_SCHED __builtin_amdgcn_sched_barrier(0)
; template <class Epi, class Sched, bool ALIGN_EPI = false, bool SP2 = false>
; __device__ __forceinline__ void gemm_phase(PG8_LAS unsigned char* lds, const Gemm g, const Sched& S, const Epi& E) {
;     ...
;             PG8_WAIT_V(8); PG8_WAIT_L(0); PG8_BAR; PG8_MMA(0, 0, At, B0); PG8_MMA(0, 1, At, B1); PG8_BAR; PG8_SCHED;
	v_mfma_f32_16x16x32_bf16 v[116:119], v[144:147], v[176:179], v[116:119]
	v_mfma_f32_16x16x32_bf16 v[108:111], v[152:155], v[176:179], v[108:111]
	v_mfma_f32_16x16x32_bf16 v[96:99], v[144:147], v[184:187], v[96:99]
	v_mfma_f32_16x16x32_bf16 v[92:95], v[152:155], v[184:187], v[92:95]
	v_mfma_f32_16x16x32_bf16 v[80:83], v[144:147], v[210:213], v[80:83]
	v_mfma_f32_16x16x32_bf16 v[76:79], v[152:155], v[210:213], v[76:79]
	v_mfma_f32_16x16x32_bf16 v[68:71], v[144:147], v[218:221], v[68:71]
	v_mfma_f32_16x16x32_bf16 v[64:67], v[152:155], v[218:221], v[64:67]
	v_mfma_f32_16x16x32_bf16 v[116:119], v[148:151], v[180:183], v[116:119]
	v_mfma_f32_16x16x32_bf16 v[108:111], v[156:159], v[180:183], v[108:111]
	v_mfma_f32_16x16x32_bf16 v[96:99], v[148:151], v[192:195], v[96:99]
	v_mfma_f32_16x16x32_bf16 v[92:95], v[156:159], v[192:195], v[92:95]
	v_mfma_f32_16x16x32_bf16 v[80:83], v[148:151], v[214:217], v[80:83]
	v_mfma_f32_16x16x32_bf16 v[76:79], v[156:159], v[214:217], v[76:79]
	v_mfma_f32_16x16x32_bf16 v[68:71], v[148:151], v[222:225], v[68:71]
	v_mfma_f32_16x16x32_bf16 v[64:67], v[156:159], v[222:225], v[64:67]

; #define PG8_STAGE(bufoff, gbase, voff) do { _Pragma("unroll") for (int _i = 0; _i < 2; ++_i) \
;         __builtin_amdgcn_global_load_lds((const unsigned*)((const char*)(gbase) + (voff)[_i]), (PG8_LAS unsigned*)(lds + (bufoff) + ldsw + _i * 8192), 16, 0, 0); } while (0)
; #define PG8_LDA(dst, b, h) do { _Pragma("unroll") for (int m = 0; m < 4; ++m) _Pragma("unroll") for (int k = 0; k < 2; ++k) dst[m][k] = *(const PG8_LAS bf16x8*)(lds + PG8_SA(b, h) + aoff + m * 2048 + k * 1024); } while (0)
; #define PG8_MMA(ai, bj, At, Bt) do { __builtin_amdgcn_s_setprio(1); _Pragma("unroll") for (int m = 0; m < 4; ++m) _Pragma("unroll") for (int n = 0; n < 2; ++n) _Pragma("unroll") for (int k = 0; k < 2; ++k) \
;         acc[ai][bj][m][n] = __builtin_amdgcn_mfma_f32_16x16x32_bf16(Bt[n][k], At[m][k], acc[ai][bj][m][n], 0, 0, 0); __builtin_amdgcn_s_setprio(0); } while (0)
; #define PG8_WAIT_V(n) asm volatile("s_waitcnt vmcnt(" #n ")" ::: "memory")
; #define PG8_WAIT_L(n) asm volatile("s_waitcnt lgkmcnt(" #n ")" ::: "memory")
; #define PG8_BAR __builtin_amdgcn_s_barrier()
; #define PG8_SCHED __builtin_amdgcn_sched_barrier(0)
; template <class Epi, class Sched, bool ALIGN_EPI = false, bool SP2 = false>
; __device__ __forceinline__ void gemm_phase(PG8_LAS unsigned char* lds, const Gemm g, const Sched& S, const Epi& E) {
;     ...
;             PG8_WAIT_V(8); PG8_WAIT_L(0); PG8_BAR; PG8_MMA(0, 0, At, B0); PG8_MMA(0, 1, At, B1); PG8_BAR; PG8_SCHED;
;             PG8_LDA(At, 0, 1); PG8_STAGE(PG8_SB(0, 0), b2, voffB); PG8_STAGE(PG8_SB(0, 1), b2 + hstep, voffB); PG8_STAGE(PG8_SA(0, 0), a2, voffA);
	s_barrier
	s_add_i32 s79, s70, s57
	s_mov_b64 s[96:97], s[12:13]

; #define PG8_STAGE(bufoff, gbase, voff) do { _Pragma("unroll") for (int _i = 0; _i < 2; ++_i) \
;         __builtin_amdgcn_global_load_lds((const unsigned*)((const char*)(gbase) + (voff)[_i]), (PG8_LAS unsigned*)(lds + (bufoff) + ldsw + _i * 8192), 16, 0, 0); } while (0)
; #define PG8_LDA(dst, b, h) do { _Pragma("unroll") for (int m = 0; m < 4; ++m) _Pragma("unroll") for (int k = 0; k < 2; ++k) dst[m][k] = *(const PG8_LAS bf16x8*)(lds + PG8_SA(b, h) + aoff + m * 2048 + k * 1024); } while (0)
; template <class Epi, class Sched, bool ALIGN_EPI = false, bool SP2 = false>
; __device__ __forceinline__ void gemm_phase(PG8_LAS unsigned char* lds, const Gemm g, const Sched& S, const Epi& E) {
;     ...
;             PG8_LDA(At, 0, 1); PG8_STAGE(PG8_SB(0, 0), b2, voffB); PG8_STAGE(PG8_SB(0, 1), b2 + hstep, voffB); PG8_STAGE(PG8_SA(0, 0), a2, voffA);
	s_mov_b32 m0, s79
	ds_read_b128 v[176:179], v207 offset:16384
	ds_read_b128 v[180:183], v207 offset:17408
	ds_read_b128 v[184:187], v207 offset:18432
	ds_read_b128 v[192:195], v207 offset:19456
	ds_read_b128 v[210:213], v207 offset:20480
	ds_read_b128 v[214:217], v207 offset:21504
	ds_read_b128 v[218:221], v207 offset:22528
	ds_read_b128 v[222:225], v207 offset:23552
	global_load_lds_dwordx4 v164, s[12:13]
	s_add_i32 m0, s79, 0x2000
	s_add_u32 s80, s12, 0x80000

; #define PG8_STAGE(bufoff, gbase, voff) do { _Pragma("unroll") for (int _i = 0; _i < 2; ++_i) \
;         __builtin_amdgcn_global_load_lds((const unsigned*)((const char*)(gbase) + (voff)[_i]), (PG8_LAS unsigned*)(lds + (bufoff) + ldsw + _i * 8192), 16, 0, 0); } while (0)
; #define PG8_LDA(dst, b, h) do { _Pragma("unroll") for (int m = 0; m < 4; ++m) _Pragma("unroll") for (int k = 0; k < 2; ++k) dst[m][k] = *(const PG8_LAS bf16x8*)(lds + PG8_SA(b, h) + aoff + m * 2048 + k * 1024); } while (0)
; template <class Epi, class Sched, bool ALIGN_EPI = false, bool SP2 = false>
; __device__ __forceinline__ void gemm_phase(PG8_LAS unsigned char* lds, const Gemm g, const Sched& S, const Epi& E) {
;     ...
;             PG8_LDA(At, 0, 1); PG8_STAGE(PG8_SB(0, 0), b2, voffB); PG8_STAGE(PG8_SB(0, 1), b2 + hstep, voffB); PG8_STAGE(PG8_SA(0, 0), a2, voffA);
	s_addc_u32 s81, s13, 0
	s_add_i32 s79, s71, s57
	global_load_lds_dwordx4 v160, s[12:13]

; #define PG8_STAGE(bufoff, gbase, voff) do { _Pragma("unroll") for (int _i = 0; _i < 2; ++_i) \
;         __builtin_amdgcn_global_load_lds((const unsigned*)((const char*)(gbase) + (voff)[_i]), (PG8_LAS unsigned*)(lds + (bufoff) + ldsw + _i * 8192), 16, 0, 0); } while (0)
; #define PG8_LDA(dst, b, h) do { _Pragma("unroll") for (int m = 0; m < 4; ++m) _Pragma("unroll") for (int k = 0; k < 2; ++k) dst[m][k] = *(const PG8_LAS bf16x8*)(lds + PG8_SA(b, h) + aoff + m * 2048 + k * 1024); } while (0)
; template <class Epi, class Sched, bool ALIGN_EPI = false, bool SP2 = false>
; __device__ __forceinline__ void gemm_phase(PG8_LAS unsigned char* lds, const Gemm g, const Sched& S, const Epi& E) {
;     ...
;             PG8_LDA(At, 0, 1); PG8_STAGE(PG8_SB(0, 0), b2, voffB); PG8_STAGE(PG8_SB(0, 1), b2 + hstep, voffB); PG8_STAGE(PG8_SA(0, 0), a2, voffA);
	s_mov_b32 m0, s79
	s_nop 0
	global_load_lds_dwordx4 v164, s[80:81]

; #define PG8_STAGE(bufoff, gbase, voff) do { _Pragma("unroll") for (int _i = 0; _i < 2; ++_i) \
;         __builtin_amdgcn_global_load_lds((const unsigned*)((const char*)(gbase) + (voff)[_i]), (PG8_LAS unsigned*)(lds + (bufoff) + ldsw + _i * 8192), 16, 0, 0); } while (0)
; #define PG8_LDA(dst, b, h) do { _Pragma("unroll") for (int m = 0; m < 4; ++m) _Pragma("unroll") for (int k = 0; k < 2; ++k) dst[m][k] = *(const PG8_LAS bf16x8*)(lds + PG8_SA(b, h) + aoff + m * 2048 + k * 1024); } while (0)
; template <class Epi, class Sched, bool ALIGN_EPI = false, bool SP2 = false>
; __device__ __forceinline__ void gemm_phase(PG8_LAS unsigned char* lds, const Gemm g, const Sched& S, const Epi& E) {
;     ...
;             PG8_LDA(At, 0, 1); PG8_STAGE(PG8_SB(0, 0), b2, voffB); PG8_STAGE(PG8_SB(0, 1), b2 + hstep, voffB); PG8_STAGE(PG8_SA(0, 0), a2, voffA);
	s_add_i32 m0, s79, 0x2000
	s_nop 0
	global_load_lds_dwordx4 v160, s[80:81]
	s_mov_b64 s[98:99], s[54:55]

; #define PG8_STAGE(bufoff, gbase, voff) do { _Pragma("unroll") for (int _i = 0; _i < 2; ++_i) \
;         __builtin_amdgcn_global_load_lds((const unsigned*)((const char*)(gbase) + (voff)[_i]), (PG8_LAS unsigned*)(lds + (bufoff) + ldsw + _i * 8192), 16, 0, 0); } while (0)
; #define PG8_LDA(dst, b, h) do { _Pragma("unroll") for (int m = 0; m < 4; ++m) _Pragma("unroll") for (int k = 0; k < 2; ++k) dst[m][k] = *(const PG8_LAS bf16x8*)(lds + PG8_SA(b, h) + aoff + m * 2048 + k * 1024); } while (0)
; #define PG8_MMA(ai, bj, At, Bt) do { __builtin_amdgcn_s_setprio(1); _Pragma("unroll") for (int m = 0; m < 4; ++m) _Pragma("unroll") for (int n = 0; n < 2; ++n) _Pragma("unroll") for (int k = 0; k < 2; ++k) \
;         acc[ai][bj][m][n] = __builtin_amdgcn_mfma_f32_16x16x32_bf16(Bt[n][k], At[m][k], acc[ai][bj][m][n], 0, 0, 0); __builtin_amdgcn_s_setprio(0); } while (0)
; #define PG8_WAIT_V(n) asm volatile("s_waitcnt vmcnt(" #n ")" ::: "memory")
; #define PG8_WAIT_L(n) asm volatile("s_waitcnt lgkmcnt(" #n ")" ::: "memory")
; #define PG8_BAR __builtin_amdgcn_s_barrier()
; #define PG8_SCHED __builtin_amdgcn_sched_barrier(0)
; template <class Epi, class Sched, bool ALIGN_EPI = false, bool SP2 = false>
; __device__ __forceinline__ void gemm_phase(PG8_LAS unsigned char* lds, const Gemm g, const Sched& S, const Epi& E) {
;     ...
;             PG8_LDA(At, 0, 1); PG8_STAGE(PG8_SB(0, 0), b2, voffB); PG8_STAGE(PG8_SB(0, 1), b2 + hstep, voffB); PG8_STAGE(PG8_SA(0, 0), a2, voffA);
;             PG8_WAIT_V(8); PG8_WAIT_L(0); PG8_BAR; PG8_MMA(1, 0, At, B0); PG8_MMA(1, 1, At, B1); PG8_BAR; PG8_SCHED;
	s_mov_b32 m0, s60
	s_nop 0
	global_load_lds_dwordx4 v166, s[54:55]
	s_mov_b32 m0, s61
	s_nop 0
	global_load_lds_dwordx4 v162, s[54:55]
	s_waitcnt vmcnt(8)
	s_waitcnt lgkmcnt(0)

; #define PG8_MMA(ai, bj, At, Bt) do { __builtin_amdgcn_s_setprio(1); _Pragma("unroll") for (int m = 0; m < 4; ++m) _Pragma("unroll") for (int n = 0; n < 2; ++n) _Pragma("unroll") for (int k = 0; k < 2; ++k) \
;         acc[ai][bj][m][n] = __builtin_amdgcn_mfma_f32_16x16x32_bf16(Bt[n][k], At[m][k], acc[ai][bj][m][n], 0, 0, 0); __builtin_amdgcn_s_setprio(0); } while (0)
; #define PG8_WAIT_V(n) asm volatile("s_waitcnt vmcnt(" #n ")" ::: "memory")
; #define PG8_WAIT_L(n) asm volatile("s_waitcnt lgkmcnt(" #n ")" ::: "memory")
; #define PG8_BAR __builtin_amdgcn_s_barrier()
; #define PG8_SCHED __builtin_amdgcn_sched_barrier(0)
; template <class Epi, class Sched, bool ALIGN_EPI = false, bool SP2 = false>
; __device__ __forceinline__ void gemm_phase(PG8_LAS unsigned char* lds, const Gemm g, const Sched& S, const Epi& E) {
;     ...
;             PG8_WAIT_V(8); PG8_WAIT_L(0); PG8_BAR; PG8_MMA(1, 0, At, B0); PG8_MMA(1, 1, At, B1); PG8_BAR; PG8_SCHED;
	s_barrier

; #define PG8_MMA(ai, bj, At, Bt) do { __builtin_amdgcn_s_setprio(1); _Pragma("unroll") for (int m = 0; m < 4; ++m) _Pragma("unroll") for (int n = 0; n < 2; ++n) _Pragma("unroll") for (int k = 0; k < 2; ++k) \
;         acc[ai][bj][m][n] = __builtin_amdgcn_mfma_f32_16x16x32_bf16(Bt[n][k], At[m][k], acc[ai][bj][m][n], 0, 0, 0); __builtin_amdgcn_s_setprio(0); } while (0)
; #define PG8_WAIT_V(n) asm volatile("s_waitcnt vmcnt(" #n ")" ::: "memory")
; #define PG8_WAIT_L(n) asm volatile("s_waitcnt lgkmcnt(" #n ")" ::: "memory")
; #define PG8_BAR __builtin_amdgcn_s_barrier()
; #define PG8_SCHED __builtin_amdgcn_sched_barrier(0)
; template <class Epi, class Sched, bool ALIGN_EPI = false, bool SP2 = false>
; __device__ __forceinline__ void gemm_phase(PG8_LAS unsigned char* lds, const Gemm g, const Sched& S, const Epi& E) {
;     ...
;             PG8_WAIT_V(8); PG8_WAIT_L(0); PG8_BAR; PG8_MMA(1, 0, At, B0); PG8_MMA(1, 1, At, B1); PG8_BAR; PG8_SCHED;
	v_mfma_f32_16x16x32_bf16 v[60:63], v[128:131], v[176:179], v[60:63]
	v_mfma_f32_16x16x32_bf16 v[56:59], v[136:139], v[176:179], v[56:59]
	v_mfma_f32_16x16x32_bf16 v[52:55], v[128:131], v[184:187], v[52:55]
	v_mfma_f32_16x16x32_bf16 v[40:43], v[136:139], v[184:187], v[40:43]
	v_mfma_f32_16x16x32_bf16 v[36:39], v[128:131], v[210:213], v[36:39]
	v_mfma_f32_16x16x32_bf16 v[24:27], v[136:139], v[210:213], v[24:27]
	v_mfma_f32_16x16x32_bf16 v[20:23], v[128:131], v[218:221], v[20:23]
	v_mfma_f32_16x16x32_bf16 v[8:11], v[136:139], v[218:221], v[8:11]
	v_mfma_f32_16x16x32_bf16 v[60:63], v[132:135], v[180:183], v[60:63]
	v_mfma_f32_16x16x32_bf16 v[56:59], v[140:143], v[180:183], v[56:59]
	v_mfma_f32_16x16x32_bf16 v[52:55], v[132:135], v[192:195], v[52:55]
	v_mfma_f32_16x16x32_bf16 v[40:43], v[140:143], v[192:195], v[40:43]
	v_mfma_f32_16x16x32_bf16 v[36:39], v[132:135], v[214:217], v[36:39]
	v_mfma_f32_16x16x32_bf16 v[24:27], v[140:143], v[214:217], v[24:27]
	v_mfma_f32_16x16x32_bf16 v[20:23], v[132:135], v[222:225], v[20:23]
	v_mfma_f32_16x16x32_bf16 v[8:11], v[140:143], v[222:225], v[8:11]


; #define PG8_MMA(ai, bj, At, Bt) do { __builtin_amdgcn_s_setprio(1); _Pragma("unroll") for (int m = 0; m < 4; ++m) _Pragma("unroll") for (int n = 0; n < 2; ++n) _Pragma("unroll") for (int k = 0; k < 2; ++k) \
;         acc[ai][bj][m][n] = __builtin_amdgcn_mfma_f32_16x16x32_bf16(Bt[n][k], At[m][k], acc[ai][bj][m][n], 0, 0, 0); __builtin_amdgcn_s_setprio(0); } while (0)
; #define PG8_WAIT_V(n) asm volatile("s_waitcnt vmcnt(" #n ")" ::: "memory")
; #define PG8_WAIT_L(n) asm volatile("s_waitcnt lgkmcnt(" #n ")" ::: "memory")
; #define PG8_BAR __builtin_amdgcn_s_barrier()
; #define PG8_SCHED __builtin_amdgcn_sched_barrier(0)
; template <class Epi, class Sched, bool ALIGN_EPI = false, bool SP2 = false>
; __device__ __forceinline__ void gemm_phase(PG8_LAS unsigned char* lds, const Gemm g, const Sched& S, const Epi& E) {
;     ...
;             PG8_WAIT_V(8); PG8_WAIT_L(0); PG8_BAR; PG8_MMA(1, 0, At, B0); PG8_MMA(1, 1, At, B1); PG8_BAR; PG8_SCHED;
	v_mfma_f32_16x16x32_bf16 v[48:51], v[144:147], v[176:179], v[48:51]
	v_mfma_f32_16x16x32_bf16 v[44:47], v[152:155], v[176:179], v[44:47]
	v_mfma_f32_16x16x32_bf16 v[32:35], v[144:147], v[184:187], v[32:35]
	v_mfma_f32_16x16x32_bf16 v[28:31], v[152:155], v[184:187], v[28:31]
	v_mfma_f32_16x16x32_bf16 v[16:19], v[144:147], v[210:213], v[16:19]
	v_mfma_f32_16x16x32_bf16 v[12:15], v[152:155], v[210:213], v[12:15]
	v_mfma_f32_16x16x32_bf16 v[4:7], v[144:147], v[218:221], v[4:7]
	v_mfma_f32_16x16x32_bf16 v[0:3], v[152:155], v[218:221], v[0:3]
	v_mfma_f32_16x16x32_bf16 v[48:51], v[148:151], v[180:183], v[48:51]
	v_mfma_f32_16x16x32_bf16 v[44:47], v[156:159], v[180:183], v[44:47]
	v_mfma_f32_16x16x32_bf16 v[32:35], v[148:151], v[192:195], v[32:35]
	v_mfma_f32_16x16x32_bf16 v[28:31], v[156:159], v[192:195], v[28:31]
	v_mfma_f32_16x16x32_bf16 v[16:19], v[148:151], v[214:217], v[16:19]
	v_mfma_f32_16x16x32_bf16 v[12:15], v[156:159], v[214:217], v[12:15]
	v_mfma_f32_16x16x32_bf16 v[4:7], v[148:151], v[222:225], v[4:7]
	v_mfma_f32_16x16x32_bf16 v[0:3], v[156:159], v[222:225], v[0:3]

; #define PG8_STAGE(bufoff, gbase, voff) do { _Pragma("unroll") for (int _i = 0; _i < 2; ++_i) \
;         __builtin_amdgcn_global_load_lds((const unsigned*)((const char*)(gbase) + (voff)[_i]), (PG8_LAS unsigned*)(lds + (bufoff) + ldsw + _i * 8192), 16, 0, 0); } while (0)
; #define PG8_LDA(dst, b, h) do { _Pragma("unroll") for (int m = 0; m < 4; ++m) _Pragma("unroll") for (int k = 0; k < 2; ++k) dst[m][k] = *(const PG8_LAS bf16x8*)(lds + PG8_SA(b, h) + aoff + m * 2048 + k * 1024); } while (0)
; #define PG8_LDB(dst, b, h) do { _Pragma("unroll") for (int n = 0; n < 2; ++n) _Pragma("unroll") for (int k = 0; k < 2; ++k) dst[n][k] = *(const PG8_LAS bf16x8*)(lds + PG8_SB(b, h) + boff + n * 2048 + k * 1024); } while (0)
; #define PG8_MMA(ai, bj, At, Bt) do { __builtin_amdgcn_s_setprio(1); _Pragma("unroll") for (int m = 0; m < 4; ++m) _Pragma("unroll") for (int n = 0; n < 2; ++n) _Pragma("unroll") for (int k = 0; k < 2; ++k) \
;         acc[ai][bj][m][n] = __builtin_amdgcn_mfma_f32_16x16x32_bf16(Bt[n][k], At[m][k], acc[ai][bj][m][n], 0, 0, 0); __builtin_amdgcn_s_setprio(0); } while (0)
; #define PG8_WAIT_V(n) asm volatile("s_waitcnt vmcnt(" #n ")" ::: "memory")
; #define PG8_WAIT_L(n) asm volatile("s_waitcnt lgkmcnt(" #n ")" ::: "memory")
; #define PG8_BAR __builtin_amdgcn_s_barrier()
; #define PG8_SCHED __builtin_amdgcn_sched_barrier(0)
; template <class Epi, class Sched, bool ALIGN_EPI = false, bool SP2 = false>
; __device__ __forceinline__ void gemm_phase(PG8_LAS unsigned char* lds, const Gemm g, const Sched& S, const Epi& E) {
;     ...
;             PG8_WAIT_V(8); PG8_WAIT_L(0); PG8_BAR; PG8_MMA(1, 0, At, B0); PG8_MMA(1, 1, At, B1); PG8_BAR; PG8_SCHED;
;             PG8_LDB(B0, 1, 0); PG8_LDB(B1, 1, 1); PG8_SCHED; PG8_LDA(At, 1, 0); PG8_STAGE(PG8_SA(0, 1), a2 + hstep, voffA);
	s_barrier
	s_add_i32 s79, 0, 0x18000
	s_add_i32 s80, 0, 0x1c000


; #define PG8_STAGE(bufoff, gbase, voff) do { _Pragma("unroll") for (int _i = 0; _i < 2; ++_i) \
;         __builtin_amdgcn_global_load_lds((const unsigned*)((const char*)(gbase) + (voff)[_i]), (PG8_LAS unsigned*)(lds + (bufoff) + ldsw + _i * 8192), 16, 0, 0); } while (0)
; #define PG8_LDA(dst, b, h) do { _Pragma("unroll") for (int m = 0; m < 4; ++m) _Pragma("unroll") for (int k = 0; k < 2; ++k) dst[m][k] = *(const PG8_LAS bf16x8*)(lds + PG8_SA(b, h) + aoff + m * 2048 + k * 1024); } while (0)
; #define PG8_LDB(dst, b, h) do { _Pragma("unroll") for (int n = 0; n < 2; ++n) _Pragma("unroll") for (int k = 0; k < 2; ++k) dst[n][k] = *(const PG8_LAS bf16x8*)(lds + PG8_SB(b, h) + boff + n * 2048 + k * 1024); } while (0)
; #define PG8_SCHED __builtin_amdgcn_sched_barrier(0)
; template <class Epi, class Sched, bool ALIGN_EPI = false, bool SP2 = false>
; __device__ __forceinline__ void gemm_phase(PG8_LAS unsigned char* lds, const Gemm g, const Sched& S, const Epi& E) {
;     ...
;             PG8_LDB(B0, 1, 0); PG8_LDB(B1, 1, 1); PG8_SCHED; PG8_LDA(At, 1, 0); PG8_STAGE(PG8_SA(0, 1), a2 + hstep, voffA);
	ds_read_b128 v[128:131], v254
	ds_read_b128 v[132:135], v254 offset:1024
	ds_read_b128 v[136:139], v254 offset:2048
	ds_read_b128 v[140:143], v254 offset:3072
	ds_read_b128 v[144:147], v255
	ds_read_b128 v[148:151], v255 offset:1024
	ds_read_b128 v[152:155], v255 offset:2048
	ds_read_b128 v[156:159], v255 offset:3072
	s_add_u32 s54, s54, 0x80000
	s_addc_u32 s55, s55, 0
	s_mov_b32 m0, s62

; #define PG8_STAGE(bufoff, gbase, voff) do { _Pragma("unroll") for (int _i = 0; _i < 2; ++_i) \
;         __builtin_amdgcn_global_load_lds((const unsigned*)((const char*)(gbase) + (voff)[_i]), (PG8_LAS unsigned*)(lds + (bufoff) + ldsw + _i * 8192), 16, 0, 0); } while (0)
; #define PG8_LDA(dst, b, h) do { _Pragma("unroll") for (int m = 0; m < 4; ++m) _Pragma("unroll") for (int k = 0; k < 2; ++k) dst[m][k] = *(const PG8_LAS bf16x8*)(lds + PG8_SA(b, h) + aoff + m * 2048 + k * 1024); } while (0)
; #define PG8_LDB(dst, b, h) do { _Pragma("unroll") for (int n = 0; n < 2; ++n) _Pragma("unroll") for (int k = 0; k < 2; ++k) dst[n][k] = *(const PG8_LAS bf16x8*)(lds + PG8_SB(b, h) + boff + n * 2048 + k * 1024); } while (0)
; #define PG8_SCHED __builtin_amdgcn_sched_barrier(0)
; template <class Epi, class Sched, bool ALIGN_EPI = false, bool SP2 = false>
; __device__ __forceinline__ void gemm_phase(PG8_LAS unsigned char* lds, const Gemm g, const Sched& S, const Epi& E) {
;     ...
;             PG8_LDB(B0, 1, 0); PG8_LDB(B1, 1, 1); PG8_SCHED; PG8_LDA(At, 1, 0); PG8_STAGE(PG8_SA(0, 1), a2 + hstep, voffA);
	ds_read_b128 v[176:179], v207 offset:32768
	ds_read_b128 v[180:183], v207 offset:33792
	ds_read_b128 v[184:187], v207 offset:34816
	ds_read_b128 v[192:195], v207 offset:35840
	ds_read_b128 v[210:213], v207 offset:36864
	ds_read_b128 v[214:217], v207 offset:37888
	ds_read_b128 v[218:221], v207 offset:38912
	ds_read_b128 v[222:225], v207 offset:39936
	global_load_lds_dwordx4 v166, s[54:55]

; #define PG8_STAGE(bufoff, gbase, voff) do { _Pragma("unroll") for (int _i = 0; _i < 2; ++_i) \
;         __builtin_amdgcn_global_load_lds((const unsigned*)((const char*)(gbase) + (voff)[_i]), (PG8_LAS unsigned*)(lds + (bufoff) + ldsw + _i * 8192), 16, 0, 0); } while (0)
; #define PG8_LDA(dst, b, h) do { _Pragma("unroll") for (int m = 0; m < 4; ++m) _Pragma("unroll") for (int k = 0; k < 2; ++k) dst[m][k] = *(const PG8_LAS bf16x8*)(lds + PG8_SA(b, h) + aoff + m * 2048 + k * 1024); } while (0)
; #define PG8_LDB(dst, b, h) do { _Pragma("unroll") for (int n = 0; n < 2; ++n) _Pragma("unroll") for (int k = 0; k < 2; ++k) dst[n][k] = *(const PG8_LAS bf16x8*)(lds + PG8_SB(b, h) + boff + n * 2048 + k * 1024); } while (0)
; #define PG8_MMA(ai, bj, At, Bt) do { __builtin_amdgcn_s_setprio(1); _Pragma("unroll") for (int m = 0; m < 4; ++m) _Pragma("unroll") for (int n = 0; n < 2; ++n) _Pragma("unroll") for (int k = 0; k < 2; ++k) \
;         acc[ai][bj][m][n] = __builtin_amdgcn_mfma_f32_16x16x32_bf16(Bt[n][k], At[m][k], acc[ai][bj][m][n], 0, 0, 0); __builtin_amdgcn_s_setprio(0); } while (0)
; #define PG8_WAIT_V(n) asm volatile("s_waitcnt vmcnt(" #n ")" ::: "memory")
; #define PG8_WAIT_L(n) asm volatile("s_waitcnt lgkmcnt(" #n ")" ::: "memory")
; #define PG8_BAR __builtin_amdgcn_s_barrier()
; #define PG8_SCHED __builtin_amdgcn_sched_barrier(0)
; template <class Epi, class Sched, bool ALIGN_EPI = false, bool SP2 = false>
; __device__ __forceinline__ void gemm_phase(PG8_LAS unsigned char* lds, const Gemm g, const Sched& S, const Epi& E) {
;     ...
;             PG8_LDB(B0, 1, 0); PG8_LDB(B1, 1, 1); PG8_SCHED; PG8_LDA(At, 1, 0); PG8_STAGE(PG8_SA(0, 1), a2 + hstep, voffA);
;             PG8_WAIT_V(8); PG8_WAIT_L(0); PG8_BAR; PG8_MMA(0, 0, At, B0); PG8_MMA(0, 1, At, B1); PG8_BAR; PG8_SCHED;
	s_mov_b32 m0, s63
	s_nop 0
	global_load_lds_dwordx4 v162, s[54:55]
	s_waitcnt vmcnt(8)
	s_waitcnt lgkmcnt(0)

; #define PG8_MMA(ai, bj, At, Bt) do { __builtin_amdgcn_s_setprio(1); _Pragma("unroll") for (int m = 0; m < 4; ++m) _Pragma("unroll") for (int n = 0; n < 2; ++n) _Pragma("unroll") for (int k = 0; k < 2; ++k) \
;         acc[ai][bj][m][n] = __builtin_amdgcn_mfma_f32_16x16x32_bf16(Bt[n][k], At[m][k], acc[ai][bj][m][n], 0, 0, 0); __builtin_amdgcn_s_setprio(0); } while (0)
; #define PG8_WAIT_V(n) asm volatile("s_waitcnt vmcnt(" #n ")" ::: "memory")
; #define PG8_WAIT_L(n) asm volatile("s_waitcnt lgkmcnt(" #n ")" ::: "memory")
; #define PG8_BAR __builtin_amdgcn_s_barrier()
; #define PG8_SCHED __builtin_amdgcn_sched_barrier(0)
; template <class Epi, class Sched, bool ALIGN_EPI = false, bool SP2 = false>
; __device__ __forceinline__ void gemm_phase(PG8_LAS unsigned char* lds, const Gemm g, const Sched& S, const Epi& E) {
;     ...
;             PG8_WAIT_V(8); PG8_WAIT_L(0); PG8_BAR; PG8_MMA(0, 0, At, B0); PG8_MMA(0, 1, At, B1); PG8_BAR; PG8_SCHED;
	s_barrier

; #define PG8_MMA(ai, bj, At, Bt) do { __builtin_amdgcn_s_setprio(1); _Pragma("unroll") for (int m = 0; m < 4; ++m) _Pragma("unroll") for (int n = 0; n < 2; ++n) _Pragma("unroll") for (int k = 0; k < 2; ++k) \
;         acc[ai][bj][m][n] = __builtin_amdgcn_mfma_f32_16x16x32_bf16(Bt[n][k], At[m][k], acc[ai][bj][m][n], 0, 0, 0); __builtin_amdgcn_s_setprio(0); } while (0)
; #define PG8_WAIT_V(n) asm volatile("s_waitcnt vmcnt(" #n ")" ::: "memory")
; #define PG8_WAIT_L(n) asm volatile("s_waitcnt lgkmcnt(" #n ")" ::: "memory")
; #define PG8_BAR __builtin_amdgcn_s_barrier()
; #define PG8_SCHED __builtin_amdgcn_sched_barrier(0)
; template <class Epi, class Sched, bool ALIGN_EPI = false, bool SP2 = false>
; __device__ __forceinline__ void gemm_phase(PG8_LAS unsigned char* lds, const Gemm g, const Sched& S, const Epi& E) {
;     ...
;             PG8_WAIT_V(8); PG8_WAIT_L(0); PG8_BAR; PG8_MMA(0, 0, At, B0); PG8_MMA(0, 1, At, B1); PG8_BAR; PG8_SCHED;
	v_mfma_f32_16x16x32_bf16 v[124:127], v[128:131], v[176:179], v[124:127]
	v_mfma_f32_16x16x32_bf16 v[120:123], v[136:139], v[176:179], v[120:123]
	v_mfma_f32_16x16x32_bf16 v[112:115], v[128:131], v[184:187], v[112:115]
	v_mfma_f32_16x16x32_bf16 v[104:107], v[136:139], v[184:187], v[104:107]
	v_mfma_f32_16x16x32_bf16 v[100:103], v[128:131], v[210:213], v[100:103]
	v_mfma_f32_16x16x32_bf16 v[88:91], v[136:139], v[210:213], v[88:91]
	v_mfma_f32_16x16x32_bf16 v[84:87], v[128:131], v[218:221], v[84:87]
	v_mfma_f32_16x16x32_bf16 v[72:75], v[136:139], v[218:221], v[72:75]
	v_mfma_f32_16x16x32_bf16 v[124:127], v[132:135], v[180:183], v[124:127]
	v_mfma_f32_16x16x32_bf16 v[120:123], v[140:143], v[180:183], v[120:123]
	v_mfma_f32_16x16x32_bf16 v[112:115], v[132:135], v[192:195], v[112:115]
	v_mfma_f32_16x16x32_bf16 v[104:107], v[140:143], v[192:195], v[104:107]
	v_mfma_f32_16x16x32_bf16 v[100:103], v[132:135], v[214:217], v[100:103]
	v_mfma_f32_16x16x32_bf16 v[88:91], v[140:143], v[214:217], v[88:91]
	v_mfma_f32_16x16x32_bf16 v[84:87], v[132:135], v[222:225], v[84:87]
	v_mfma_f32_16x16x32_bf16 v[72:75], v[140:143], v[222:225], v[72:75]


; #define PG8_MMA(ai, bj, At, Bt) do { __builtin_amdgcn_s_setprio(1); _Pragma("unroll") for (int m = 0; m < 4; ++m) _Pragma("unroll") for (int n = 0; n < 2; ++n) _Pragma("unroll") for (int k = 0; k < 2; ++k) \
;         acc[ai][bj][m][n] = __builtin_amdgcn_mfma_f32_16x16x32_bf16(Bt[n][k], At[m][k], acc[ai][bj][m][n], 0, 0, 0); __builtin_amdgcn_s_setprio(0); } while (0)
; #define PG8_WAIT_V(n) asm volatile("s_waitcnt vmcnt(" #n ")" ::: "memory")
; #define PG8_WAIT_L(n) asm volatile("s_waitcnt lgkmcnt(" #n ")" ::: "memory")
; #define PG8_BAR __builtin_amdgcn_s_barrier()
; #define PG8_SCHED __builtin_amdgcn_sched_barrier(0)
; template <class Epi, class Sched, bool ALIGN_EPI = false, bool SP2 = false>
; __device__ __forceinline__ void gemm_phase(PG8_LAS unsigned char* lds, const Gemm g, const Sched& S, const Epi& E) {
;     ...
;             PG8_WAIT_V(8); PG8_WAIT_L(0); PG8_BAR; PG8_MMA(0, 0, At, B0); PG8_MMA(0, 1, At, B1); PG8_BAR; PG8_SCHED;
	v_mfma_f32_16x16x32_bf16 v[116:119], v[144:147], v[176:179], v[116:119]
	v_mfma_f32_16x16x32_bf16 v[108:111], v[152:155], v[176:179], v[108:111]
	v_mfma_f32_16x16x32_bf16 v[96:99], v[144:147], v[184:187], v[96:99]
	v_mfma_f32_16x16x32_bf16 v[92:95], v[152:155], v[184:187], v[92:95]
	v_mfma_f32_16x16x32_bf16 v[80:83], v[144:147], v[210:213], v[80:83]
	v_mfma_f32_16x16x32_bf16 v[76:79], v[152:155], v[210:213], v[76:79]
	v_mfma_f32_16x16x32_bf16 v[68:71], v[144:147], v[218:221], v[68:71]
	v_mfma_f32_16x16x32_bf16 v[64:67], v[152:155], v[218:221], v[64:67]
	v_mfma_f32_16x16x32_bf16 v[116:119], v[148:151], v[180:183], v[116:119]
	v_mfma_f32_16x16x32_bf16 v[108:111], v[156:159], v[180:183], v[108:111]
	v_mfma_f32_16x16x32_bf16 v[96:99], v[148:151], v[192:195], v[96:99]
	v_mfma_f32_16x16x32_bf16 v[92:95], v[156:159], v[192:195], v[92:95]
	v_mfma_f32_16x16x32_bf16 v[80:83], v[148:151], v[214:217], v[80:83]
	v_mfma_f32_16x16x32_bf16 v[76:79], v[156:159], v[214:217], v[76:79]
	v_mfma_f32_16x16x32_bf16 v[68:71], v[148:151], v[222:225], v[68:71]
	v_mfma_f32_16x16x32_bf16 v[64:67], v[156:159], v[222:225], v[64:67]

; #define PG8_STAGE(bufoff, gbase, voff) do { _Pragma("unroll") for (int _i = 0; _i < 2; ++_i) \
;         __builtin_amdgcn_global_load_lds((const unsigned*)((const char*)(gbase) + (voff)[_i]), (PG8_LAS unsigned*)(lds + (bufoff) + ldsw + _i * 8192), 16, 0, 0); } while (0)
; #define PG8_LDA(dst, b, h) do { _Pragma("unroll") for (int m = 0; m < 4; ++m) _Pragma("unroll") for (int k = 0; k < 2; ++k) dst[m][k] = *(const PG8_LAS bf16x8*)(lds + PG8_SA(b, h) + aoff + m * 2048 + k * 1024); } while (0)
; #define PG8_MMA(ai, bj, At, Bt) do { __builtin_amdgcn_s_setprio(1); _Pragma("unroll") for (int m = 0; m < 4; ++m) _Pragma("unroll") for (int n = 0; n < 2; ++n) _Pragma("unroll") for (int k = 0; k < 2; ++k) \
;         acc[ai][bj][m][n] = __builtin_amdgcn_mfma_f32_16x16x32_bf16(Bt[n][k], At[m][k], acc[ai][bj][m][n], 0, 0, 0); __builtin_amdgcn_s_setprio(0); } while (0)
; #define PG8_WAIT_V(n) asm volatile("s_waitcnt vmcnt(" #n ")" ::: "memory")
; #define PG8_WAIT_L(n) asm volatile("s_waitcnt lgkmcnt(" #n ")" ::: "memory")
; #define PG8_BAR __builtin_amdgcn_s_barrier()
; #define PG8_SCHED __builtin_amdgcn_sched_barrier(0)
; template <class Epi, class Sched, bool ALIGN_EPI = false, bool SP2 = false>
; __device__ __forceinline__ void gemm_phase(PG8_LAS unsigned char* lds, const Gemm g, const Sched& S, const Epi& E) {
;     ...
;             PG8_WAIT_V(8); PG8_WAIT_L(0); PG8_BAR; PG8_MMA(0, 0, At, B0); PG8_MMA(0, 1, At, B1); PG8_BAR; PG8_SCHED;
;             PG8_LDA(At, 1, 1); PG8_STAGE(PG8_SB(1, 0), b3, voffB); PG8_STAGE(PG8_SB(1, 1), b3 + hstep, voffB); PG8_STAGE(PG8_SA(1, 0), a3, voffA);
	s_barrier
	s_add_i32 s54, s79, s57

; #define PG8_STAGE(bufoff, gbase, voff) do { _Pragma("unroll") for (int _i = 0; _i < 2; ++_i) \
;         __builtin_amdgcn_global_load_lds((const unsigned*)((const char*)(gbase) + (voff)[_i]), (PG8_LAS unsigned*)(lds + (bufoff) + ldsw + _i * 8192), 16, 0, 0); } while (0)
; #define PG8_LDA(dst, b, h) do { _Pragma("unroll") for (int m = 0; m < 4; ++m) _Pragma("unroll") for (int k = 0; k < 2; ++k) dst[m][k] = *(const PG8_LAS bf16x8*)(lds + PG8_SA(b, h) + aoff + m * 2048 + k * 1024); } while (0)
; template <class Epi, class Sched, bool ALIGN_EPI = false, bool SP2 = false>
; __device__ __forceinline__ void gemm_phase(PG8_LAS unsigned char* lds, const Gemm g, const Sched& S, const Epi& E) {
;     ...
;             PG8_LDA(At, 1, 1); PG8_STAGE(PG8_SB(1, 0), b3, voffB); PG8_STAGE(PG8_SB(1, 1), b3 + hstep, voffB); PG8_STAGE(PG8_SA(1, 0), a3, voffA);
	s_mov_b32 m0, s54
	ds_read_b128 v[176:179], v207 offset:49152
	ds_read_b128 v[180:183], v207 offset:50176
	ds_read_b128 v[184:187], v207 offset:51200
	ds_read_b128 v[192:195], v207 offset:52224
	ds_read_b128 v[210:213], v207 offset:53248
	ds_read_b128 v[214:217], v207 offset:54272
	ds_read_b128 v[218:221], v207 offset:55296
	ds_read_b128 v[222:225], v207 offset:56320
	global_load_lds_dwordx4 v250, s[96:97]
	s_add_i32 m0, s54, 0x2000
	s_add_u32 s12, s12, 0x80080

; #define PG8_STAGE(bufoff, gbase, voff) do { _Pragma("unroll") for (int _i = 0; _i < 2; ++_i) \
;         __builtin_amdgcn_global_load_lds((const unsigned*)((const char*)(gbase) + (voff)[_i]), (PG8_LAS unsigned*)(lds + (bufoff) + ldsw + _i * 8192), 16, 0, 0); } while (0)
; #define PG8_LDA(dst, b, h) do { _Pragma("unroll") for (int m = 0; m < 4; ++m) _Pragma("unroll") for (int k = 0; k < 2; ++k) dst[m][k] = *(const PG8_LAS bf16x8*)(lds + PG8_SA(b, h) + aoff + m * 2048 + k * 1024); } while (0)
; template <class Epi, class Sched, bool ALIGN_EPI = false, bool SP2 = false>
; __device__ __forceinline__ void gemm_phase(PG8_LAS unsigned char* lds, const Gemm g, const Sched& S, const Epi& E) {
;     ...
;             PG8_LDA(At, 1, 1); PG8_STAGE(PG8_SB(1, 0), b3, voffB); PG8_STAGE(PG8_SB(1, 1), b3 + hstep, voffB); PG8_STAGE(PG8_SA(1, 0), a3, voffA);
	s_addc_u32 s13, s13, 0
	s_add_i32 s54, s80, s57
	global_load_lds_dwordx4 v251, s[96:97]

; #define PG8_STAGE(bufoff, gbase, voff) do { _Pragma("unroll") for (int _i = 0; _i < 2; ++_i) \
;         __builtin_amdgcn_global_load_lds((const unsigned*)((const char*)(gbase) + (voff)[_i]), (PG8_LAS unsigned*)(lds + (bufoff) + ldsw + _i * 8192), 16, 0, 0); } while (0)
; #define PG8_LDA(dst, b, h) do { _Pragma("unroll") for (int m = 0; m < 4; ++m) _Pragma("unroll") for (int k = 0; k < 2; ++k) dst[m][k] = *(const PG8_LAS bf16x8*)(lds + PG8_SA(b, h) + aoff + m * 2048 + k * 1024); } while (0)
; template <class Epi, class Sched, bool ALIGN_EPI = false, bool SP2 = false>
; __device__ __forceinline__ void gemm_phase(PG8_LAS unsigned char* lds, const Gemm g, const Sched& S, const Epi& E) {
;     ...
;             PG8_LDA(At, 1, 1); PG8_STAGE(PG8_SB(1, 0), b3, voffB); PG8_STAGE(PG8_SB(1, 1), b3 + hstep, voffB); PG8_STAGE(PG8_SA(1, 0), a3, voffA);
	s_mov_b32 m0, s54
	s_nop 0
	global_load_lds_dwordx4 v164, s[12:13]

; #define PG8_STAGE(bufoff, gbase, voff) do { _Pragma("unroll") for (int _i = 0; _i < 2; ++_i) \
;         __builtin_amdgcn_global_load_lds((const unsigned*)((const char*)(gbase) + (voff)[_i]), (PG8_LAS unsigned*)(lds + (bufoff) + ldsw + _i * 8192), 16, 0, 0); } while (0)
; #define PG8_LDA(dst, b, h) do { _Pragma("unroll") for (int m = 0; m < 4; ++m) _Pragma("unroll") for (int k = 0; k < 2; ++k) dst[m][k] = *(const PG8_LAS bf16x8*)(lds + PG8_SA(b, h) + aoff + m * 2048 + k * 1024); } while (0)
; template <class Epi, class Sched, bool ALIGN_EPI = false, bool SP2 = false>
; __device__ __forceinline__ void gemm_phase(PG8_LAS unsigned char* lds, const Gemm g, const Sched& S, const Epi& E) {
;     ...
;             PG8_LDA(At, 1, 1); PG8_STAGE(PG8_SB(1, 0), b3, voffB); PG8_STAGE(PG8_SB(1, 1), b3 + hstep, voffB); PG8_STAGE(PG8_SA(1, 0), a3, voffA);
	s_add_i32 m0, s54, 0x2000
	s_nop 0
	global_load_lds_dwordx4 v160, s[12:13]

; #define PG8_STAGE(bufoff, gbase, voff) do { _Pragma("unroll") for (int _i = 0; _i < 2; ++_i) \
;         __builtin_amdgcn_global_load_lds((const unsigned*)((const char*)(gbase) + (voff)[_i]), (PG8_LAS unsigned*)(lds + (bufoff) + ldsw + _i * 8192), 16, 0, 0); } while (0)
; #define PG8_LDA(dst, b, h) do { _Pragma("unroll") for (int m = 0; m < 4; ++m) _Pragma("unroll") for (int k = 0; k < 2; ++k) dst[m][k] = *(const PG8_LAS bf16x8*)(lds + PG8_SA(b, h) + aoff + m * 2048 + k * 1024); } while (0)
; template <class Epi, class Sched, bool ALIGN_EPI = false, bool SP2 = false>
; __device__ __forceinline__ void gemm_phase(PG8_LAS unsigned char* lds, const Gemm g, const Sched& S, const Epi& E) {
;     ...
;             PG8_LDA(At, 1, 1); PG8_STAGE(PG8_SB(1, 0), b3, voffB); PG8_STAGE(PG8_SB(1, 1), b3 + hstep, voffB); PG8_STAGE(PG8_SA(1, 0), a3, voffA);
	s_mov_b32 m0, s65
	s_nop 0
	global_load_lds_dwordx4 v252, s[98:99]

; #define PG8_STAGE(bufoff, gbase, voff) do { _Pragma("unroll") for (int _i = 0; _i < 2; ++_i) \
;         __builtin_amdgcn_global_load_lds((const unsigned*)((const char*)(gbase) + (voff)[_i]), (PG8_LAS unsigned*)(lds + (bufoff) + ldsw + _i * 8192), 16, 0, 0); } while (0)
; #define PG8_LDA(dst, b, h) do { _Pragma("unroll") for (int m = 0; m < 4; ++m) _Pragma("unroll") for (int k = 0; k < 2; ++k) dst[m][k] = *(const PG8_LAS bf16x8*)(lds + PG8_SA(b, h) + aoff + m * 2048 + k * 1024); } while (0)
; #define PG8_MMA(ai, bj, At, Bt) do { __builtin_amdgcn_s_setprio(1); _Pragma("unroll") for (int m = 0; m < 4; ++m) _Pragma("unroll") for (int n = 0; n < 2; ++n) _Pragma("unroll") for (int k = 0; k < 2; ++k) \
;         acc[ai][bj][m][n] = __builtin_amdgcn_mfma_f32_16x16x32_bf16(Bt[n][k], At[m][k], acc[ai][bj][m][n], 0, 0, 0); __builtin_amdgcn_s_setprio(0); } while (0)
; #define PG8_WAIT_V(n) asm volatile("s_waitcnt vmcnt(" #n ")" ::: "memory")
; #define PG8_WAIT_L(n) asm volatile("s_waitcnt lgkmcnt(" #n ")" ::: "memory")
; #define PG8_BAR __builtin_amdgcn_s_barrier()
; #define PG8_SCHED __builtin_amdgcn_sched_barrier(0)
; template <class Epi, class Sched, bool ALIGN_EPI = false, bool SP2 = false>
; __device__ __forceinline__ void gemm_phase(PG8_LAS unsigned char* lds, const Gemm g, const Sched& S, const Epi& E) {
;     ...
;             PG8_LDA(At, 1, 1); PG8_STAGE(PG8_SB(1, 0), b3, voffB); PG8_STAGE(PG8_SB(1, 1), b3 + hstep, voffB); PG8_STAGE(PG8_SA(1, 0), a3, voffA);
;             PG8_WAIT_V(8); PG8_WAIT_L(0); PG8_BAR; PG8_MMA(1, 0, At, B0); PG8_MMA(1, 1, At, B1); PG8_BAR; PG8_SCHED;
	s_mov_b32 m0, s67
	s_nop 0
	global_load_lds_dwordx4 v253, s[98:99]
	s_waitcnt vmcnt(8)
	s_waitcnt lgkmcnt(0)

; #define PG8_MMA(ai, bj, At, Bt) do { __builtin_amdgcn_s_setprio(1); _Pragma("unroll") for (int m = 0; m < 4; ++m) _Pragma("unroll") for (int n = 0; n < 2; ++n) _Pragma("unroll") for (int k = 0; k < 2; ++k) \
;         acc[ai][bj][m][n] = __builtin_amdgcn_mfma_f32_16x16x32_bf16(Bt[n][k], At[m][k], acc[ai][bj][m][n], 0, 0, 0); __builtin_amdgcn_s_setprio(0); } while (0)
; #define PG8_WAIT_V(n) asm volatile("s_waitcnt vmcnt(" #n ")" ::: "memory")
; #define PG8_WAIT_L(n) asm volatile("s_waitcnt lgkmcnt(" #n ")" ::: "memory")
; #define PG8_BAR __builtin_amdgcn_s_barrier()
; #define PG8_SCHED __builtin_amdgcn_sched_barrier(0)
; template <class Epi, class Sched, bool ALIGN_EPI = false, bool SP2 = false>
; __device__ __forceinline__ void gemm_phase(PG8_LAS unsigned char* lds, const Gemm g, const Sched& S, const Epi& E) {
;     ...
;             PG8_WAIT_V(8); PG8_WAIT_L(0); PG8_BAR; PG8_MMA(1, 0, At, B0); PG8_MMA(1, 1, At, B1); PG8_BAR; PG8_SCHED;
	s_barrier

; #define PG8_MMA(ai, bj, At, Bt) do { __builtin_amdgcn_s_setprio(1); _Pragma("unroll") for (int m = 0; m < 4; ++m) _Pragma("unroll") for (int n = 0; n < 2; ++n) _Pragma("unroll") for (int k = 0; k < 2; ++k) \
;         acc[ai][bj][m][n] = __builtin_amdgcn_mfma_f32_16x16x32_bf16(Bt[n][k], At[m][k], acc[ai][bj][m][n], 0, 0, 0); __builtin_amdgcn_s_setprio(0); } while (0)
; #define PG8_WAIT_V(n) asm volatile("s_waitcnt vmcnt(" #n ")" ::: "memory")
; #define PG8_WAIT_L(n) asm volatile("s_waitcnt lgkmcnt(" #n ")" ::: "memory")
; #define PG8_BAR __builtin_amdgcn_s_barrier()
; #define PG8_SCHED __builtin_amdgcn_sched_barrier(0)
; template <class Epi, class Sched, bool ALIGN_EPI = false, bool SP2 = false>
; __device__ __forceinline__ void gemm_phase(PG8_LAS unsigned char* lds, const Gemm g, const Sched& S, const Epi& E) {
;     ...
;             PG8_WAIT_V(8); PG8_WAIT_L(0); PG8_BAR; PG8_MMA(1, 0, At, B0); PG8_MMA(1, 1, At, B1); PG8_BAR; PG8_SCHED;
	v_mfma_f32_16x16x32_bf16 v[60:63], v[128:131], v[176:179], v[60:63]
	v_mfma_f32_16x16x32_bf16 v[56:59], v[136:139], v[176:179], v[56:59]
	v_mfma_f32_16x16x32_bf16 v[52:55], v[128:131], v[184:187], v[52:55]
	v_mfma_f32_16x16x32_bf16 v[40:43], v[136:139], v[184:187], v[40:43]
	v_mfma_f32_16x16x32_bf16 v[36:39], v[128:131], v[210:213], v[36:39]
	v_mfma_f32_16x16x32_bf16 v[24:27], v[136:139], v[210:213], v[24:27]
	v_mfma_f32_16x16x32_bf16 v[20:23], v[128:131], v[218:221], v[20:23]
	v_mfma_f32_16x16x32_bf16 v[8:11], v[136:139], v[218:221], v[8:11]
	v_mfma_f32_16x16x32_bf16 v[60:63], v[132:135], v[180:183], v[60:63]
	v_mfma_f32_16x16x32_bf16 v[56:59], v[140:143], v[180:183], v[56:59]
	v_mfma_f32_16x16x32_bf16 v[52:55], v[132:135], v[192:195], v[52:55]
	v_mfma_f32_16x16x32_bf16 v[40:43], v[140:143], v[192:195], v[40:43]
	v_mfma_f32_16x16x32_bf16 v[36:39], v[132:135], v[214:217], v[36:39]
	v_mfma_f32_16x16x32_bf16 v[24:27], v[140:143], v[214:217], v[24:27]
	v_mfma_f32_16x16x32_bf16 v[20:23], v[132:135], v[222:225], v[20:23]
	v_mfma_f32_16x16x32_bf16 v[8:11], v[140:143], v[222:225], v[8:11]


; #define PG8_MMA(ai, bj, At, Bt) do { __builtin_amdgcn_s_setprio(1); _Pragma("unroll") for (int m = 0; m < 4; ++m) _Pragma("unroll") for (int n = 0; n < 2; ++n) _Pragma("unroll") for (int k = 0; k < 2; ++k) \
;         acc[ai][bj][m][n] = __builtin_amdgcn_mfma_f32_16x16x32_bf16(Bt[n][k], At[m][k], acc[ai][bj][m][n], 0, 0, 0); __builtin_amdgcn_s_setprio(0); } while (0)
; #define PG8_WAIT_V(n) asm volatile("s_waitcnt vmcnt(" #n ")" ::: "memory")
; #define PG8_WAIT_L(n) asm volatile("s_waitcnt lgkmcnt(" #n ")" ::: "memory")
; #define PG8_BAR __builtin_amdgcn_s_barrier()
; #define PG8_SCHED __builtin_amdgcn_sched_barrier(0)
; template <class Epi, class Sched, bool ALIGN_EPI = false, bool SP2 = false>
; __device__ __forceinline__ void gemm_phase(PG8_LAS unsigned char* lds, const Gemm g, const Sched& S, const Epi& E) {
;     ...
;             PG8_WAIT_V(8); PG8_WAIT_L(0); PG8_BAR; PG8_MMA(1, 0, At, B0); PG8_MMA(1, 1, At, B1); PG8_BAR; PG8_SCHED;
	v_mfma_f32_16x16x32_bf16 v[48:51], v[144:147], v[176:179], v[48:51]
	v_mfma_f32_16x16x32_bf16 v[44:47], v[152:155], v[176:179], v[44:47]
	v_mfma_f32_16x16x32_bf16 v[32:35], v[144:147], v[184:187], v[32:35]
	v_mfma_f32_16x16x32_bf16 v[28:31], v[152:155], v[184:187], v[28:31]
	v_mfma_f32_16x16x32_bf16 v[16:19], v[144:147], v[210:213], v[16:19]
	v_mfma_f32_16x16x32_bf16 v[12:15], v[152:155], v[210:213], v[12:15]
	v_mfma_f32_16x16x32_bf16 v[4:7], v[144:147], v[218:221], v[4:7]
	v_mfma_f32_16x16x32_bf16 v[0:3], v[152:155], v[218:221], v[0:3]
	v_mfma_f32_16x16x32_bf16 v[48:51], v[148:151], v[180:183], v[48:51]
	v_mfma_f32_16x16x32_bf16 v[44:47], v[156:159], v[180:183], v[44:47]
	v_mfma_f32_16x16x32_bf16 v[32:35], v[148:151], v[192:195], v[32:35]
	v_mfma_f32_16x16x32_bf16 v[28:31], v[156:159], v[192:195], v[28:31]
	v_mfma_f32_16x16x32_bf16 v[16:19], v[148:151], v[214:217], v[16:19]
	v_mfma_f32_16x16x32_bf16 v[12:15], v[156:159], v[214:217], v[12:15]
	v_mfma_f32_16x16x32_bf16 v[4:7], v[148:151], v[222:225], v[4:7]
	v_mfma_f32_16x16x32_bf16 v[0:3], v[156:159], v[222:225], v[0:3]

; #define PG8_MMA(ai, bj, At, Bt) do { __builtin_amdgcn_s_setprio(1); _Pragma("unroll") for (int m = 0; m < 4; ++m) _Pragma("unroll") for (int n = 0; n < 2; ++n) _Pragma("unroll") for (int k = 0; k < 2; ++k) \
;         acc[ai][bj][m][n] = __builtin_amdgcn_mfma_f32_16x16x32_bf16(Bt[n][k], At[m][k], acc[ai][bj][m][n], 0, 0, 0); __builtin_amdgcn_s_setprio(0); } while (0)
; #define PG8_WAIT_V(n) asm volatile("s_waitcnt vmcnt(" #n ")" ::: "memory")
; #define PG8_WAIT_L(n) asm volatile("s_waitcnt lgkmcnt(" #n ")" ::: "memory")
; #define PG8_BAR __builtin_amdgcn_s_barrier()
; #define PG8_SCHED __builtin_amdgcn_sched_barrier(0)
; template <class Epi, class Sched, bool ALIGN_EPI = false, bool SP2 = false>
; __device__ __forceinline__ void gemm_phase(PG8_LAS unsigned char* lds, const Gemm g, const Sched& S, const Epi& E) {
;     ...
;             PG8_WAIT_V(8); PG8_WAIT_L(0); PG8_BAR; PG8_MMA(1, 0, At, B0); PG8_MMA(1, 1, At, B1); PG8_BAR; PG8_SCHED;
;     ...
;         if constexpr (ALIGN_EPI) { if (wr == 0) PG8_BAR; }
	s_barrier
	s_add_i32 s78, s78, 2
	s_add_u32 s10, s10, 0x100
	s_addc_u32 s11, s11, 0
	s_add_u32 s76, s76, 0x100
	s_addc_u32 s77, s77, 0
	s_cmp_gt_u32 s78, 29
	s_cbranch_scc0 .LBB0_679
	s_and_b64 vcc, exec, s[42:43]
	s_cbranch_vccz .LBB0_682
	s_barrier

; #define PG8_STAGE(bufoff, gbase, voff) do { _Pragma("unroll") for (int _i = 0; _i < 2; ++_i) \
;         __builtin_amdgcn_global_load_lds((const unsigned*)((const char*)(gbase) + (voff)[_i]), (PG8_LAS unsigned*)(lds + (bufoff) + ldsw + _i * 8192), 16, 0, 0); } while (0)
; #define PG8_LDA(dst, b, h) do { _Pragma("unroll") for (int m = 0; m < 4; ++m) _Pragma("unroll") for (int k = 0; k < 2; ++k) dst[m][k] = *(const PG8_LAS bf16x8*)(lds + PG8_SA(b, h) + aoff + m * 2048 + k * 1024); } while (0)
; #define PG8_LDB(dst, b, h) do { _Pragma("unroll") for (int n = 0; n < 2; ++n) _Pragma("unroll") for (int k = 0; k < 2; ++k) dst[n][k] = *(const PG8_LAS bf16x8*)(lds + PG8_SB(b, h) + boff + n * 2048 + k * 1024); } while (0)
; #define PG8_SCHED __builtin_amdgcn_sched_barrier(0)
; template <class Epi, class Sched, bool ALIGN_EPI = false, bool SP2 = false>
; __device__ __forceinline__ void gemm_phase(PG8_LAS unsigned char* lds, const Gemm g, const Sched& S, const Epi& E) {
;     ...
;             const bool last = (t == nt - 2);
;             const char* a1 = cA + (size_t)(t + 1) * kstep;
;             const char* a2 = last ? nA : cA + (size_t)(t + 2) * kstep; const char* b2 = last ? nB : cB + (size_t)(t + 2) * kstep;
;             const char* a3 = a2 + kstep; const char* b3 = b2 + kstep;
;             if (last && has_next) S.a_ready(nxt);
;             if constexpr (SP2) {
;             PG8_LDB(B0, 0, 0); PG8_LDB(B1, 0, 1); PG8_SCHED; PG8_LDA(At, 0, 0); PG8_STAGE(PG8_SA(1, 1), a1 + hstep, voffA);
.LBB0_939:
	ds_read_b128 v[64:67], v213
	ds_read_b128 v[68:71], v213 offset:1024
	ds_read_b128 v[72:75], v213 offset:2048
	ds_read_b128 v[76:79], v213 offset:3072
	ds_read_b128 v[144:147], v214
	ds_read_b128 v[148:151], v214 offset:1024
	ds_read_b128 v[152:155], v214 offset:2048
	ds_read_b128 v[156:159], v214 offset:3072
	s_add_u32 s60, s58, 0xfff80080
	s_addc_u32 s61, s59, -1
	s_cmp_eq_u32 s81, 28
	s_cselect_b32 s63, s11, s61
	s_cselect_b32 s62, s51, s60
	s_cselect_b32 s61, s49, s80
	s_cselect_b32 s60, s78, s79

; #define PG8_STAGE(bufoff, gbase, voff) do { _Pragma("unroll") for (int _i = 0; _i < 2; ++_i) \
;         __builtin_amdgcn_global_load_lds((const unsigned*)((const char*)(gbase) + (voff)[_i]), (PG8_LAS unsigned*)(lds + (bufoff) + ldsw + _i * 8192), 16, 0, 0); } while (0)
; #define PG8_LDA(dst, b, h) do { _Pragma("unroll") for (int m = 0; m < 4; ++m) _Pragma("unroll") for (int k = 0; k < 2; ++k) dst[m][k] = *(const PG8_LAS bf16x8*)(lds + PG8_SA(b, h) + aoff + m * 2048 + k * 1024); } while (0)
; #define PG8_LDB(dst, b, h) do { _Pragma("unroll") for (int n = 0; n < 2; ++n) _Pragma("unroll") for (int k = 0; k < 2; ++k) dst[n][k] = *(const PG8_LAS bf16x8*)(lds + PG8_SB(b, h) + boff + n * 2048 + k * 1024); } while (0)
; #define PG8_SCHED __builtin_amdgcn_sched_barrier(0)
; template <class Epi, class Sched, bool ALIGN_EPI = false, bool SP2 = false>
; __device__ __forceinline__ void gemm_phase(PG8_LAS unsigned char* lds, const Gemm g, const Sched& S, const Epi& E) {
;     ...
;             PG8_LDB(B0, 0, 0); PG8_LDB(B1, 0, 1); PG8_SCHED; PG8_LDA(At, 0, 0); PG8_STAGE(PG8_SA(1, 1), a1 + hstep, voffA);
	s_add_i32 m0, s57, 0xc000
	ds_read_b128 v[176:179], v215
	ds_read_b128 v[180:183], v215 offset:1024
	ds_read_b128 v[184:187], v215 offset:2048
	ds_read_b128 v[188:191], v215 offset:3072
	ds_read_b128 v[192:195], v215 offset:4096
	ds_read_b128 v[196:199], v215 offset:5120
	ds_read_b128 v[200:203], v215 offset:6144
	ds_read_b128 v[204:207], v215 offset:7168
	global_load_lds_dwordx4 v168, s[58:59]

; #define PG8_STAGE(bufoff, gbase, voff) do { _Pragma("unroll") for (int _i = 0; _i < 2; ++_i) \
;         __builtin_amdgcn_global_load_lds((const unsigned*)((const char*)(gbase) + (voff)[_i]), (PG8_LAS unsigned*)(lds + (bufoff) + ldsw + _i * 8192), 16, 0, 0); } while (0)
; #define PG8_LDA(dst, b, h) do { _Pragma("unroll") for (int m = 0; m < 4; ++m) _Pragma("unroll") for (int k = 0; k < 2; ++k) dst[m][k] = *(const PG8_LAS bf16x8*)(lds + PG8_SA(b, h) + aoff + m * 2048 + k * 1024); } while (0)
; #define PG8_LDB(dst, b, h) do { _Pragma("unroll") for (int n = 0; n < 2; ++n) _Pragma("unroll") for (int k = 0; k < 2; ++k) dst[n][k] = *(const PG8_LAS bf16x8*)(lds + PG8_SB(b, h) + boff + n * 2048 + k * 1024); } while (0)
; #define PG8_MMA(ai, bj, At, Bt) do { __builtin_amdgcn_s_setprio(1); _Pragma("unroll") for (int m = 0; m < 4; ++m) _Pragma("unroll") for (int n = 0; n < 2; ++n) _Pragma("unroll") for (int k = 0; k < 2; ++k) \
;         acc[ai][bj][m][n] = __builtin_amdgcn_mfma_f32_16x16x32_bf16(Bt[n][k], At[m][k], acc[ai][bj][m][n], 0, 0, 0); __builtin_amdgcn_s_setprio(0); } while (0)
; #define PG8_WAIT_V(n) asm volatile("s_waitcnt vmcnt(" #n ")" ::: "memory")
; #define PG8_WAIT_L(n) asm volatile("s_waitcnt lgkmcnt(" #n ")" ::: "memory")
; #define PG8_BAR __builtin_amdgcn_s_barrier()
; #define PG8_SCHED __builtin_amdgcn_sched_barrier(0)
; template <class Epi, class Sched, bool ALIGN_EPI = false, bool SP2 = false>
; __device__ __forceinline__ void gemm_phase(PG8_LAS unsigned char* lds, const Gemm g, const Sched& S, const Epi& E) {
;     ...
;             PG8_LDB(B0, 0, 0); PG8_LDB(B1, 0, 1); PG8_SCHED; PG8_LDA(At, 0, 0); PG8_STAGE(PG8_SA(1, 1), a1 + hstep, voffA);
;             PG8_WAIT_V(8); PG8_WAIT_L(0); PG8_BAR; PG8_MMA(0, 0, At, B0); PG8_MMA(0, 1, At, B1); PG8_BAR; PG8_SCHED;
	s_add_i32 m0, s57, 0xe000
	s_nop 0
	global_load_lds_dwordx4 v170, s[58:59]
	s_waitcnt vmcnt(8)
	s_waitcnt lgkmcnt(0)

; #define PG8_MMA(ai, bj, At, Bt) do { __builtin_amdgcn_s_setprio(1); _Pragma("unroll") for (int m = 0; m < 4; ++m) _Pragma("unroll") for (int n = 0; n < 2; ++n) _Pragma("unroll") for (int k = 0; k < 2; ++k) \
;         acc[ai][bj][m][n] = __builtin_amdgcn_mfma_f32_16x16x32_bf16(Bt[n][k], At[m][k], acc[ai][bj][m][n], 0, 0, 0); __builtin_amdgcn_s_setprio(0); } while (0)
; #define PG8_WAIT_V(n) asm volatile("s_waitcnt vmcnt(" #n ")" ::: "memory")
; #define PG8_WAIT_L(n) asm volatile("s_waitcnt lgkmcnt(" #n ")" ::: "memory")
; #define PG8_BAR __builtin_amdgcn_s_barrier()
; #define PG8_SCHED __builtin_amdgcn_sched_barrier(0)
; template <class Epi, class Sched, bool ALIGN_EPI = false, bool SP2 = false>
; __device__ __forceinline__ void gemm_phase(PG8_LAS unsigned char* lds, const Gemm g, const Sched& S, const Epi& E) {
;     ...
;             PG8_WAIT_V(8); PG8_WAIT_L(0); PG8_BAR; PG8_MMA(0, 0, At, B0); PG8_MMA(0, 1, At, B1); PG8_BAR; PG8_SCHED;
	s_barrier

; #define PG8_MMA(ai, bj, At, Bt) do { __builtin_amdgcn_s_setprio(1); _Pragma("unroll") for (int m = 0; m < 4; ++m) _Pragma("unroll") for (int n = 0; n < 2; ++n) _Pragma("unroll") for (int k = 0; k < 2; ++k) \
;         acc[ai][bj][m][n] = __builtin_amdgcn_mfma_f32_16x16x32_bf16(Bt[n][k], At[m][k], acc[ai][bj][m][n], 0, 0, 0); __builtin_amdgcn_s_setprio(0); } while (0)
; #define PG8_WAIT_V(n) asm volatile("s_waitcnt vmcnt(" #n ")" ::: "memory")
; #define PG8_WAIT_L(n) asm volatile("s_waitcnt lgkmcnt(" #n ")" ::: "memory")
; #define PG8_BAR __builtin_amdgcn_s_barrier()
; #define PG8_SCHED __builtin_amdgcn_sched_barrier(0)
; template <class Epi, class Sched, bool ALIGN_EPI = false, bool SP2 = false>
; __device__ __forceinline__ void gemm_phase(PG8_LAS unsigned char* lds, const Gemm g, const Sched& S, const Epi& E) {
;     ...
;             PG8_WAIT_V(8); PG8_WAIT_L(0); PG8_BAR; PG8_MMA(0, 0, At, B0); PG8_MMA(0, 1, At, B1); PG8_BAR; PG8_SCHED;
	v_mfma_f32_16x16x32_bf16 v[140:143], v[64:67], v[176:179], v[140:143]
	v_mfma_f32_16x16x32_bf16 v[136:139], v[72:75], v[176:179], v[136:139]
	v_mfma_f32_16x16x32_bf16 v[124:127], v[64:67], v[184:187], v[124:127]
	v_mfma_f32_16x16x32_bf16 v[120:123], v[72:75], v[184:187], v[120:123]
	v_mfma_f32_16x16x32_bf16 v[108:111], v[64:67], v[192:195], v[108:111]
	v_mfma_f32_16x16x32_bf16 v[104:107], v[72:75], v[192:195], v[104:107]
	v_mfma_f32_16x16x32_bf16 v[92:95], v[64:67], v[200:203], v[92:95]
	v_mfma_f32_16x16x32_bf16 v[88:91], v[72:75], v[200:203], v[88:91]
	v_mfma_f32_16x16x32_bf16 v[140:143], v[68:71], v[180:183], v[140:143]
	v_mfma_f32_16x16x32_bf16 v[136:139], v[76:79], v[180:183], v[136:139]
	v_mfma_f32_16x16x32_bf16 v[124:127], v[68:71], v[188:191], v[124:127]
	v_mfma_f32_16x16x32_bf16 v[120:123], v[76:79], v[188:191], v[120:123]
	v_mfma_f32_16x16x32_bf16 v[108:111], v[68:71], v[196:199], v[108:111]
	v_mfma_f32_16x16x32_bf16 v[104:107], v[76:79], v[196:199], v[104:107]
	v_mfma_f32_16x16x32_bf16 v[92:95], v[68:71], v[204:207], v[92:95]
	v_mfma_f32_16x16x32_bf16 v[88:91], v[76:79], v[204:207], v[88:91]


; #define PG8_MMA(ai, bj, At, Bt) do { __builtin_amdgcn_s_setprio(1); _Pragma("unroll") for (int m = 0; m < 4; ++m) _Pragma("unroll") for (int n = 0; n < 2; ++n) _Pragma("unroll") for (int k = 0; k < 2; ++k) \
;         acc[ai][bj][m][n] = __builtin_amdgcn_mfma_f32_16x16x32_bf16(Bt[n][k], At[m][k], acc[ai][bj][m][n], 0, 0, 0); __builtin_amdgcn_s_setprio(0); } while (0)
; #define PG8_WAIT_V(n) asm volatile("s_waitcnt vmcnt(" #n ")" ::: "memory")
; #define PG8_WAIT_L(n) asm volatile("s_waitcnt lgkmcnt(" #n ")" ::: "memory")
; #define PG8_BAR __builtin_amdgcn_s_barrier()
; #define PG8_SCHED __builtin_amdgcn_sched_barrier(0)
; template <class Epi, class Sched, bool ALIGN_EPI = false, bool SP2 = false>
; __device__ __forceinline__ void gemm_phase(PG8_LAS unsigned char* lds, const Gemm g, const Sched& S, const Epi& E) {
;     ...
;             PG8_WAIT_V(8); PG8_WAIT_L(0); PG8_BAR; PG8_MMA(0, 0, At, B0); PG8_MMA(0, 1, At, B1); PG8_BAR; PG8_SCHED;
	v_mfma_f32_16x16x32_bf16 v[132:135], v[144:147], v[176:179], v[132:135]
	v_mfma_f32_16x16x32_bf16 v[128:131], v[152:155], v[176:179], v[128:131]
	v_mfma_f32_16x16x32_bf16 v[116:119], v[144:147], v[184:187], v[116:119]
	v_mfma_f32_16x16x32_bf16 v[112:115], v[152:155], v[184:187], v[112:115]
	v_mfma_f32_16x16x32_bf16 v[100:103], v[144:147], v[192:195], v[100:103]
	v_mfma_f32_16x16x32_bf16 v[96:99], v[152:155], v[192:195], v[96:99]
	v_mfma_f32_16x16x32_bf16 v[84:87], v[144:147], v[200:203], v[84:87]
	v_mfma_f32_16x16x32_bf16 v[80:83], v[152:155], v[200:203], v[80:83]
	v_mfma_f32_16x16x32_bf16 v[132:135], v[148:151], v[180:183], v[132:135]
	v_mfma_f32_16x16x32_bf16 v[128:131], v[156:159], v[180:183], v[128:131]
	v_mfma_f32_16x16x32_bf16 v[116:119], v[148:151], v[188:191], v[116:119]
	v_mfma_f32_16x16x32_bf16 v[112:115], v[156:159], v[188:191], v[112:115]
	v_mfma_f32_16x16x32_bf16 v[100:103], v[148:151], v[196:199], v[100:103]
	v_mfma_f32_16x16x32_bf16 v[96:99], v[156:159], v[196:199], v[96:99]
	v_mfma_f32_16x16x32_bf16 v[84:87], v[148:151], v[204:207], v[84:87]
	v_mfma_f32_16x16x32_bf16 v[80:83], v[156:159], v[204:207], v[80:83]

; #define PG8_STAGE(bufoff, gbase, voff) do { _Pragma("unroll") for (int _i = 0; _i < 2; ++_i) \
;         __builtin_amdgcn_global_load_lds((const unsigned*)((const char*)(gbase) + (voff)[_i]), (PG8_LAS unsigned*)(lds + (bufoff) + ldsw + _i * 8192), 16, 0, 0); } while (0)
; #define PG8_LDA(dst, b, h) do { _Pragma("unroll") for (int m = 0; m < 4; ++m) _Pragma("unroll") for (int k = 0; k < 2; ++k) dst[m][k] = *(const PG8_LAS bf16x8*)(lds + PG8_SA(b, h) + aoff + m * 2048 + k * 1024); } while (0)
; #define PG8_MMA(ai, bj, At, Bt) do { __builtin_amdgcn_s_setprio(1); _Pragma("unroll") for (int m = 0; m < 4; ++m) _Pragma("unroll") for (int n = 0; n < 2; ++n) _Pragma("unroll") for (int k = 0; k < 2; ++k) \
;         acc[ai][bj][m][n] = __builtin_amdgcn_mfma_f32_16x16x32_bf16(Bt[n][k], At[m][k], acc[ai][bj][m][n], 0, 0, 0); __builtin_amdgcn_s_setprio(0); } while (0)
; #define PG8_WAIT_V(n) asm volatile("s_waitcnt vmcnt(" #n ")" ::: "memory")
; #define PG8_WAIT_L(n) asm volatile("s_waitcnt lgkmcnt(" #n ")" ::: "memory")
; #define PG8_BAR __builtin_amdgcn_s_barrier()
; #define PG8_SCHED __builtin_amdgcn_sched_barrier(0)
; template <class Epi, class Sched, bool ALIGN_EPI = false, bool SP2 = false>
; __device__ __forceinline__ void gemm_phase(PG8_LAS unsigned char* lds, const Gemm g, const Sched& S, const Epi& E) {
;     ...
;             PG8_WAIT_V(8); PG8_WAIT_L(0); PG8_BAR; PG8_MMA(0, 0, At, B0); PG8_MMA(0, 1, At, B1); PG8_BAR; PG8_SCHED;
;             PG8_LDA(At, 0, 1); PG8_STAGE(PG8_SB(0, 0), b2, voffB); PG8_STAGE(PG8_SB(0, 1), b2 + hstep, voffB); PG8_STAGE(PG8_SA(0, 0), a2, voffA);
	s_barrier
	s_add_i32 s82, s75, s64
	s_mov_b64 s[96:97], s[60:61]

; #define PG8_STAGE(bufoff, gbase, voff) do { _Pragma("unroll") for (int _i = 0; _i < 2; ++_i) \
;         __builtin_amdgcn_global_load_lds((const unsigned*)((const char*)(gbase) + (voff)[_i]), (PG8_LAS unsigned*)(lds + (bufoff) + ldsw + _i * 8192), 16, 0, 0); } while (0)
; #define PG8_LDA(dst, b, h) do { _Pragma("unroll") for (int m = 0; m < 4; ++m) _Pragma("unroll") for (int k = 0; k < 2; ++k) dst[m][k] = *(const PG8_LAS bf16x8*)(lds + PG8_SA(b, h) + aoff + m * 2048 + k * 1024); } while (0)
; template <class Epi, class Sched, bool ALIGN_EPI = false, bool SP2 = false>
; __device__ __forceinline__ void gemm_phase(PG8_LAS unsigned char* lds, const Gemm g, const Sched& S, const Epi& E) {
;     ...
;             PG8_LDA(At, 0, 1); PG8_STAGE(PG8_SB(0, 0), b2, voffB); PG8_STAGE(PG8_SB(0, 1), b2 + hstep, voffB); PG8_STAGE(PG8_SA(0, 0), a2, voffA);
	s_mov_b32 m0, s82
	ds_read_b128 v[176:179], v215 offset:16384
	ds_read_b128 v[180:183], v215 offset:17408
	ds_read_b128 v[184:187], v215 offset:18432
	ds_read_b128 v[188:191], v215 offset:19456
	ds_read_b128 v[192:195], v215 offset:20480
	ds_read_b128 v[196:199], v215 offset:21504
	ds_read_b128 v[200:203], v215 offset:22528
	ds_read_b128 v[204:207], v215 offset:23552
	global_load_lds_dwordx4 v162, s[60:61]
	s_add_i32 m0, s82, 0x2000
	s_add_u32 s82, s60, 0x80000

; #define PG8_STAGE(bufoff, gbase, voff) do { _Pragma("unroll") for (int _i = 0; _i < 2; ++_i) \
;         __builtin_amdgcn_global_load_lds((const unsigned*)((const char*)(gbase) + (voff)[_i]), (PG8_LAS unsigned*)(lds + (bufoff) + ldsw + _i * 8192), 16, 0, 0); } while (0)
; #define PG8_LDA(dst, b, h) do { _Pragma("unroll") for (int m = 0; m < 4; ++m) _Pragma("unroll") for (int k = 0; k < 2; ++k) dst[m][k] = *(const PG8_LAS bf16x8*)(lds + PG8_SA(b, h) + aoff + m * 2048 + k * 1024); } while (0)
; template <class Epi, class Sched, bool ALIGN_EPI = false, bool SP2 = false>
; __device__ __forceinline__ void gemm_phase(PG8_LAS unsigned char* lds, const Gemm g, const Sched& S, const Epi& E) {
;     ...
;             PG8_LDA(At, 0, 1); PG8_STAGE(PG8_SB(0, 0), b2, voffB); PG8_STAGE(PG8_SB(0, 1), b2 + hstep, voffB); PG8_STAGE(PG8_SA(0, 0), a2, voffA);
	s_addc_u32 s83, s61, 0
	s_add_i32 s84, s76, s64
	global_load_lds_dwordx4 v166, s[60:61]

; #define PG8_STAGE(bufoff, gbase, voff) do { _Pragma("unroll") for (int _i = 0; _i < 2; ++_i) \
;         __builtin_amdgcn_global_load_lds((const unsigned*)((const char*)(gbase) + (voff)[_i]), (PG8_LAS unsigned*)(lds + (bufoff) + ldsw + _i * 8192), 16, 0, 0); } while (0)
; #define PG8_LDA(dst, b, h) do { _Pragma("unroll") for (int m = 0; m < 4; ++m) _Pragma("unroll") for (int k = 0; k < 2; ++k) dst[m][k] = *(const PG8_LAS bf16x8*)(lds + PG8_SA(b, h) + aoff + m * 2048 + k * 1024); } while (0)
; template <class Epi, class Sched, bool ALIGN_EPI = false, bool SP2 = false>
; __device__ __forceinline__ void gemm_phase(PG8_LAS unsigned char* lds, const Gemm g, const Sched& S, const Epi& E) {
;     ...
;             PG8_LDA(At, 0, 1); PG8_STAGE(PG8_SB(0, 0), b2, voffB); PG8_STAGE(PG8_SB(0, 1), b2 + hstep, voffB); PG8_STAGE(PG8_SA(0, 0), a2, voffA);
	s_mov_b32 m0, s84
	s_nop 0
	global_load_lds_dwordx4 v162, s[82:83]

; #define PG8_STAGE(bufoff, gbase, voff) do { _Pragma("unroll") for (int _i = 0; _i < 2; ++_i) \
;         __builtin_amdgcn_global_load_lds((const unsigned*)((const char*)(gbase) + (voff)[_i]), (PG8_LAS unsigned*)(lds + (bufoff) + ldsw + _i * 8192), 16, 0, 0); } while (0)
; #define PG8_LDA(dst, b, h) do { _Pragma("unroll") for (int m = 0; m < 4; ++m) _Pragma("unroll") for (int k = 0; k < 2; ++k) dst[m][k] = *(const PG8_LAS bf16x8*)(lds + PG8_SA(b, h) + aoff + m * 2048 + k * 1024); } while (0)
; template <class Epi, class Sched, bool ALIGN_EPI = false, bool SP2 = false>
; __device__ __forceinline__ void gemm_phase(PG8_LAS unsigned char* lds, const Gemm g, const Sched& S, const Epi& E) {
;     ...
;             PG8_LDA(At, 0, 1); PG8_STAGE(PG8_SB(0, 0), b2, voffB); PG8_STAGE(PG8_SB(0, 1), b2 + hstep, voffB); PG8_STAGE(PG8_SA(0, 0), a2, voffA);
	s_add_i32 m0, s84, 0x2000
	s_nop 0
	global_load_lds_dwordx4 v166, s[82:83]
	s_mov_b64 s[98:99], s[62:63]

; #define PG8_STAGE(bufoff, gbase, voff) do { _Pragma("unroll") for (int _i = 0; _i < 2; ++_i) \
;         __builtin_amdgcn_global_load_lds((const unsigned*)((const char*)(gbase) + (voff)[_i]), (PG8_LAS unsigned*)(lds + (bufoff) + ldsw + _i * 8192), 16, 0, 0); } while (0)
; #define PG8_LDA(dst, b, h) do { _Pragma("unroll") for (int m = 0; m < 4; ++m) _Pragma("unroll") for (int k = 0; k < 2; ++k) dst[m][k] = *(const PG8_LAS bf16x8*)(lds + PG8_SA(b, h) + aoff + m * 2048 + k * 1024); } while (0)
; #define PG8_MMA(ai, bj, At, Bt) do { __builtin_amdgcn_s_setprio(1); _Pragma("unroll") for (int m = 0; m < 4; ++m) _Pragma("unroll") for (int n = 0; n < 2; ++n) _Pragma("unroll") for (int k = 0; k < 2; ++k) \
;         acc[ai][bj][m][n] = __builtin_amdgcn_mfma_f32_16x16x32_bf16(Bt[n][k], At[m][k], acc[ai][bj][m][n], 0, 0, 0); __builtin_amdgcn_s_setprio(0); } while (0)
; #define PG8_WAIT_V(n) asm volatile("s_waitcnt vmcnt(" #n ")" ::: "memory")
; #define PG8_WAIT_L(n) asm volatile("s_waitcnt lgkmcnt(" #n ")" ::: "memory")
; #define PG8_BAR __builtin_amdgcn_s_barrier()
; #define PG8_SCHED __builtin_amdgcn_sched_barrier(0)
; template <class Epi, class Sched, bool ALIGN_EPI = false, bool SP2 = false>
; __device__ __forceinline__ void gemm_phase(PG8_LAS unsigned char* lds, const Gemm g, const Sched& S, const Epi& E) {
;     ...
;             PG8_LDA(At, 0, 1); PG8_STAGE(PG8_SB(0, 0), b2, voffB); PG8_STAGE(PG8_SB(0, 1), b2 + hstep, voffB); PG8_STAGE(PG8_SA(0, 0), a2, voffA);
;             PG8_WAIT_V(8); PG8_WAIT_L(0); PG8_BAR; PG8_MMA(1, 0, At, B0); PG8_MMA(1, 1, At, B1); PG8_BAR; PG8_SCHED;
	s_mov_b32 m0, s57
	s_nop 0
	global_load_lds_dwordx4 v160, s[62:63]
	s_mov_b32 m0, s65
	s_nop 0
	global_load_lds_dwordx4 v164, s[62:63]
	s_waitcnt vmcnt(8)
	s_waitcnt lgkmcnt(0)

; #define PG8_MMA(ai, bj, At, Bt) do { __builtin_amdgcn_s_setprio(1); _Pragma("unroll") for (int m = 0; m < 4; ++m) _Pragma("unroll") for (int n = 0; n < 2; ++n) _Pragma("unroll") for (int k = 0; k < 2; ++k) \
;         acc[ai][bj][m][n] = __builtin_amdgcn_mfma_f32_16x16x32_bf16(Bt[n][k], At[m][k], acc[ai][bj][m][n], 0, 0, 0); __builtin_amdgcn_s_setprio(0); } while (0)
; #define PG8_WAIT_V(n) asm volatile("s_waitcnt vmcnt(" #n ")" ::: "memory")
; #define PG8_WAIT_L(n) asm volatile("s_waitcnt lgkmcnt(" #n ")" ::: "memory")
; #define PG8_BAR __builtin_amdgcn_s_barrier()
; #define PG8_SCHED __builtin_amdgcn_sched_barrier(0)
; template <class Epi, class Sched, bool ALIGN_EPI = false, bool SP2 = false>
; __device__ __forceinline__ void gemm_phase(PG8_LAS unsigned char* lds, const Gemm g, const Sched& S, const Epi& E) {
;     ...
;             PG8_WAIT_V(8); PG8_WAIT_L(0); PG8_BAR; PG8_MMA(1, 0, At, B0); PG8_MMA(1, 1, At, B1); PG8_BAR; PG8_SCHED;
	s_barrier

; #define PG8_MMA(ai, bj, At, Bt) do { __builtin_amdgcn_s_setprio(1); _Pragma("unroll") for (int m = 0; m < 4; ++m) _Pragma("unroll") for (int n = 0; n < 2; ++n) _Pragma("unroll") for (int k = 0; k < 2; ++k) \
;         acc[ai][bj][m][n] = __builtin_amdgcn_mfma_f32_16x16x32_bf16(Bt[n][k], At[m][k], acc[ai][bj][m][n], 0, 0, 0); __builtin_amdgcn_s_setprio(0); } while (0)
; #define PG8_WAIT_V(n) asm volatile("s_waitcnt vmcnt(" #n ")" ::: "memory")
; #define PG8_WAIT_L(n) asm volatile("s_waitcnt lgkmcnt(" #n ")" ::: "memory")
; #define PG8_BAR __builtin_amdgcn_s_barrier()
; #define PG8_SCHED __builtin_amdgcn_sched_barrier(0)
; template <class Epi, class Sched, bool ALIGN_EPI = false, bool SP2 = false>
; __device__ __forceinline__ void gemm_phase(PG8_LAS unsigned char* lds, const Gemm g, const Sched& S, const Epi& E) {
;     ...
;             PG8_WAIT_V(8); PG8_WAIT_L(0); PG8_BAR; PG8_MMA(1, 0, At, B0); PG8_MMA(1, 1, At, B1); PG8_BAR; PG8_SCHED;
	v_mfma_f32_16x16x32_bf16 v[60:63], v[64:67], v[176:179], v[60:63]
	v_mfma_f32_16x16x32_bf16 v[56:59], v[72:75], v[176:179], v[56:59]
	v_mfma_f32_16x16x32_bf16 v[44:47], v[64:67], v[184:187], v[44:47]
	v_mfma_f32_16x16x32_bf16 v[40:43], v[72:75], v[184:187], v[40:43]
	v_mfma_f32_16x16x32_bf16 v[28:31], v[64:67], v[192:195], v[28:31]
	v_mfma_f32_16x16x32_bf16 v[24:27], v[72:75], v[192:195], v[24:27]
	v_mfma_f32_16x16x32_bf16 v[12:15], v[64:67], v[200:203], v[12:15]
	v_mfma_f32_16x16x32_bf16 v[8:11], v[72:75], v[200:203], v[8:11]
	v_mfma_f32_16x16x32_bf16 v[60:63], v[68:71], v[180:183], v[60:63]
	v_mfma_f32_16x16x32_bf16 v[56:59], v[76:79], v[180:183], v[56:59]
	v_mfma_f32_16x16x32_bf16 v[44:47], v[68:71], v[188:191], v[44:47]
	v_mfma_f32_16x16x32_bf16 v[40:43], v[76:79], v[188:191], v[40:43]
	v_mfma_f32_16x16x32_bf16 v[28:31], v[68:71], v[196:199], v[28:31]
	v_mfma_f32_16x16x32_bf16 v[24:27], v[76:79], v[196:199], v[24:27]
	v_mfma_f32_16x16x32_bf16 v[12:15], v[68:71], v[204:207], v[12:15]
	v_mfma_f32_16x16x32_bf16 v[8:11], v[76:79], v[204:207], v[8:11]


; #define PG8_MMA(ai, bj, At, Bt) do { __builtin_amdgcn_s_setprio(1); _Pragma("unroll") for (int m = 0; m < 4; ++m) _Pragma("unroll") for (int n = 0; n < 2; ++n) _Pragma("unroll") for (int k = 0; k < 2; ++k) \
;         acc[ai][bj][m][n] = __builtin_amdgcn_mfma_f32_16x16x32_bf16(Bt[n][k], At[m][k], acc[ai][bj][m][n], 0, 0, 0); __builtin_amdgcn_s_setprio(0); } while (0)
; #define PG8_WAIT_V(n) asm volatile("s_waitcnt vmcnt(" #n ")" ::: "memory")
; #define PG8_WAIT_L(n) asm volatile("s_waitcnt lgkmcnt(" #n ")" ::: "memory")
; #define PG8_BAR __builtin_amdgcn_s_barrier()
; #define PG8_SCHED __builtin_amdgcn_sched_barrier(0)
; template <class Epi, class Sched, bool ALIGN_EPI = false, bool SP2 = false>
; __device__ __forceinline__ void gemm_phase(PG8_LAS unsigned char* lds, const Gemm g, const Sched& S, const Epi& E) {
;     ...
;             PG8_WAIT_V(8); PG8_WAIT_L(0); PG8_BAR; PG8_MMA(1, 0, At, B0); PG8_MMA(1, 1, At, B1); PG8_BAR; PG8_SCHED;
	v_mfma_f32_16x16x32_bf16 v[52:55], v[144:147], v[176:179], v[52:55]
	v_mfma_f32_16x16x32_bf16 v[48:51], v[152:155], v[176:179], v[48:51]
	v_mfma_f32_16x16x32_bf16 v[36:39], v[144:147], v[184:187], v[36:39]
	v_mfma_f32_16x16x32_bf16 v[32:35], v[152:155], v[184:187], v[32:35]
	v_mfma_f32_16x16x32_bf16 v[20:23], v[144:147], v[192:195], v[20:23]
	v_mfma_f32_16x16x32_bf16 v[16:19], v[152:155], v[192:195], v[16:19]
	v_mfma_f32_16x16x32_bf16 v[4:7], v[144:147], v[200:203], v[4:7]
	v_mfma_f32_16x16x32_bf16 v[0:3], v[152:155], v[200:203], v[0:3]
	v_mfma_f32_16x16x32_bf16 v[52:55], v[148:151], v[180:183], v[52:55]
	v_mfma_f32_16x16x32_bf16 v[48:51], v[156:159], v[180:183], v[48:51]
	v_mfma_f32_16x16x32_bf16 v[36:39], v[148:151], v[188:191], v[36:39]
	v_mfma_f32_16x16x32_bf16 v[32:35], v[156:159], v[188:191], v[32:35]
	v_mfma_f32_16x16x32_bf16 v[20:23], v[148:151], v[196:199], v[20:23]
	v_mfma_f32_16x16x32_bf16 v[16:19], v[156:159], v[196:199], v[16:19]
	v_mfma_f32_16x16x32_bf16 v[4:7], v[148:151], v[204:207], v[4:7]
	v_mfma_f32_16x16x32_bf16 v[0:3], v[156:159], v[204:207], v[0:3]

; #define PG8_STAGE(bufoff, gbase, voff) do { _Pragma("unroll") for (int _i = 0; _i < 2; ++_i) \
;         __builtin_amdgcn_global_load_lds((const unsigned*)((const char*)(gbase) + (voff)[_i]), (PG8_LAS unsigned*)(lds + (bufoff) + ldsw + _i * 8192), 16, 0, 0); } while (0)
; #define PG8_LDA(dst, b, h) do { _Pragma("unroll") for (int m = 0; m < 4; ++m) _Pragma("unroll") for (int k = 0; k < 2; ++k) dst[m][k] = *(const PG8_LAS bf16x8*)(lds + PG8_SA(b, h) + aoff + m * 2048 + k * 1024); } while (0)
; #define PG8_LDB(dst, b, h) do { _Pragma("unroll") for (int n = 0; n < 2; ++n) _Pragma("unroll") for (int k = 0; k < 2; ++k) dst[n][k] = *(const PG8_LAS bf16x8*)(lds + PG8_SB(b, h) + boff + n * 2048 + k * 1024); } while (0)
; #define PG8_MMA(ai, bj, At, Bt) do { __builtin_amdgcn_s_setprio(1); _Pragma("unroll") for (int m = 0; m < 4; ++m) _Pragma("unroll") for (int n = 0; n < 2; ++n) _Pragma("unroll") for (int k = 0; k < 2; ++k) \
;         acc[ai][bj][m][n] = __builtin_amdgcn_mfma_f32_16x16x32_bf16(Bt[n][k], At[m][k], acc[ai][bj][m][n], 0, 0, 0); __builtin_amdgcn_s_setprio(0); } while (0)
; #define PG8_WAIT_V(n) asm volatile("s_waitcnt vmcnt(" #n ")" ::: "memory")
; #define PG8_WAIT_L(n) asm volatile("s_waitcnt lgkmcnt(" #n ")" ::: "memory")
; #define PG8_BAR __builtin_amdgcn_s_barrier()
; #define PG8_SCHED __builtin_amdgcn_sched_barrier(0)
; template <class Epi, class Sched, bool ALIGN_EPI = false, bool SP2 = false>
; __device__ __forceinline__ void gemm_phase(PG8_LAS unsigned char* lds, const Gemm g, const Sched& S, const Epi& E) {
;     ...
;             PG8_WAIT_V(8); PG8_WAIT_L(0); PG8_BAR; PG8_MMA(1, 0, At, B0); PG8_MMA(1, 1, At, B1); PG8_BAR; PG8_SCHED;
;             PG8_LDB(B0, 1, 0); PG8_LDB(B1, 1, 1); PG8_SCHED; PG8_LDA(At, 1, 0); PG8_STAGE(PG8_SA(0, 1), a2 + hstep, voffA);
	s_barrier
	s_add_i32 s82, 0, 0x18000
	s_add_i32 s83, 0, 0x1c000


; #define PG8_STAGE(bufoff, gbase, voff) do { _Pragma("unroll") for (int _i = 0; _i < 2; ++_i) \
;         __builtin_amdgcn_global_load_lds((const unsigned*)((const char*)(gbase) + (voff)[_i]), (PG8_LAS unsigned*)(lds + (bufoff) + ldsw + _i * 8192), 16, 0, 0); } while (0)
; #define PG8_LDA(dst, b, h) do { _Pragma("unroll") for (int m = 0; m < 4; ++m) _Pragma("unroll") for (int k = 0; k < 2; ++k) dst[m][k] = *(const PG8_LAS bf16x8*)(lds + PG8_SA(b, h) + aoff + m * 2048 + k * 1024); } while (0)
; #define PG8_LDB(dst, b, h) do { _Pragma("unroll") for (int n = 0; n < 2; ++n) _Pragma("unroll") for (int k = 0; k < 2; ++k) dst[n][k] = *(const PG8_LAS bf16x8*)(lds + PG8_SB(b, h) + boff + n * 2048 + k * 1024); } while (0)
; #define PG8_SCHED __builtin_amdgcn_sched_barrier(0)
; template <class Epi, class Sched, bool ALIGN_EPI = false, bool SP2 = false>
; __device__ __forceinline__ void gemm_phase(PG8_LAS unsigned char* lds, const Gemm g, const Sched& S, const Epi& E) {
;     ...
;             PG8_LDB(B0, 1, 0); PG8_LDB(B1, 1, 1); PG8_SCHED; PG8_LDA(At, 1, 0); PG8_STAGE(PG8_SA(0, 1), a2 + hstep, voffA);
	ds_read_b128 v[64:67], v254
	ds_read_b128 v[68:71], v254 offset:1024
	ds_read_b128 v[72:75], v254 offset:2048
	ds_read_b128 v[76:79], v254 offset:3072
	ds_read_b128 v[144:147], v255
	ds_read_b128 v[148:151], v255 offset:1024
	ds_read_b128 v[152:155], v255 offset:2048
	ds_read_b128 v[156:159], v255 offset:3072
	s_add_u32 s62, s62, 0x80000
	s_addc_u32 s63, s63, 0
	s_mov_b32 m0, s67

; #define PG8_STAGE(bufoff, gbase, voff) do { _Pragma("unroll") for (int _i = 0; _i < 2; ++_i) \
;         __builtin_amdgcn_global_load_lds((const unsigned*)((const char*)(gbase) + (voff)[_i]), (PG8_LAS unsigned*)(lds + (bufoff) + ldsw + _i * 8192), 16, 0, 0); } while (0)
; #define PG8_LDA(dst, b, h) do { _Pragma("unroll") for (int m = 0; m < 4; ++m) _Pragma("unroll") for (int k = 0; k < 2; ++k) dst[m][k] = *(const PG8_LAS bf16x8*)(lds + PG8_SA(b, h) + aoff + m * 2048 + k * 1024); } while (0)
; #define PG8_LDB(dst, b, h) do { _Pragma("unroll") for (int n = 0; n < 2; ++n) _Pragma("unroll") for (int k = 0; k < 2; ++k) dst[n][k] = *(const PG8_LAS bf16x8*)(lds + PG8_SB(b, h) + boff + n * 2048 + k * 1024); } while (0)
; #define PG8_SCHED __builtin_amdgcn_sched_barrier(0)
; template <class Epi, class Sched, bool ALIGN_EPI = false, bool SP2 = false>
; __device__ __forceinline__ void gemm_phase(PG8_LAS unsigned char* lds, const Gemm g, const Sched& S, const Epi& E) {
;     ...
;             PG8_LDB(B0, 1, 0); PG8_LDB(B1, 1, 1); PG8_SCHED; PG8_LDA(At, 1, 0); PG8_STAGE(PG8_SA(0, 1), a2 + hstep, voffA);
	ds_read_b128 v[176:179], v215 offset:32768
	ds_read_b128 v[180:183], v215 offset:33792
	ds_read_b128 v[184:187], v215 offset:34816
	ds_read_b128 v[188:191], v215 offset:35840
	ds_read_b128 v[192:195], v215 offset:36864
	ds_read_b128 v[196:199], v215 offset:37888
	ds_read_b128 v[200:203], v215 offset:38912
	ds_read_b128 v[204:207], v215 offset:39936
	global_load_lds_dwordx4 v160, s[62:63]

; #define PG8_STAGE(bufoff, gbase, voff) do { _Pragma("unroll") for (int _i = 0; _i < 2; ++_i) \
;         __builtin_amdgcn_global_load_lds((const unsigned*)((const char*)(gbase) + (voff)[_i]), (PG8_LAS unsigned*)(lds + (bufoff) + ldsw + _i * 8192), 16, 0, 0); } while (0)
; #define PG8_LDA(dst, b, h) do { _Pragma("unroll") for (int m = 0; m < 4; ++m) _Pragma("unroll") for (int k = 0; k < 2; ++k) dst[m][k] = *(const PG8_LAS bf16x8*)(lds + PG8_SA(b, h) + aoff + m * 2048 + k * 1024); } while (0)
; #define PG8_LDB(dst, b, h) do { _Pragma("unroll") for (int n = 0; n < 2; ++n) _Pragma("unroll") for (int k = 0; k < 2; ++k) dst[n][k] = *(const PG8_LAS bf16x8*)(lds + PG8_SB(b, h) + boff + n * 2048 + k * 1024); } while (0)
; #define PG8_MMA(ai, bj, At, Bt) do { __builtin_amdgcn_s_setprio(1); _Pragma("unroll") for (int m = 0; m < 4; ++m) _Pragma("unroll") for (int n = 0; n < 2; ++n) _Pragma("unroll") for (int k = 0; k < 2; ++k) \
;         acc[ai][bj][m][n] = __builtin_amdgcn_mfma_f32_16x16x32_bf16(Bt[n][k], At[m][k], acc[ai][bj][m][n], 0, 0, 0); __builtin_amdgcn_s_setprio(0); } while (0)
; #define PG8_WAIT_V(n) asm volatile("s_waitcnt vmcnt(" #n ")" ::: "memory")
; #define PG8_WAIT_L(n) asm volatile("s_waitcnt lgkmcnt(" #n ")" ::: "memory")
; #define PG8_BAR __builtin_amdgcn_s_barrier()
; #define PG8_SCHED __builtin_amdgcn_sched_barrier(0)
; template <class Epi, class Sched, bool ALIGN_EPI = false, bool SP2 = false>
; __device__ __forceinline__ void gemm_phase(PG8_LAS unsigned char* lds, const Gemm g, const Sched& S, const Epi& E) {
;     ...
;             PG8_LDB(B0, 1, 0); PG8_LDB(B1, 1, 1); PG8_SCHED; PG8_LDA(At, 1, 0); PG8_STAGE(PG8_SA(0, 1), a2 + hstep, voffA);
;             PG8_WAIT_V(8); PG8_WAIT_L(0); PG8_BAR; PG8_MMA(0, 0, At, B0); PG8_MMA(0, 1, At, B1); PG8_BAR; PG8_SCHED;
	s_mov_b32 m0, s68
	s_nop 0
	global_load_lds_dwordx4 v164, s[62:63]
	s_waitcnt vmcnt(8)
	s_waitcnt lgkmcnt(0)

; #define PG8_MMA(ai, bj, At, Bt) do { __builtin_amdgcn_s_setprio(1); _Pragma("unroll") for (int m = 0; m < 4; ++m) _Pragma("unroll") for (int n = 0; n < 2; ++n) _Pragma("unroll") for (int k = 0; k < 2; ++k) \
;         acc[ai][bj][m][n] = __builtin_amdgcn_mfma_f32_16x16x32_bf16(Bt[n][k], At[m][k], acc[ai][bj][m][n], 0, 0, 0); __builtin_amdgcn_s_setprio(0); } while (0)
; #define PG8_WAIT_V(n) asm volatile("s_waitcnt vmcnt(" #n ")" ::: "memory")
; #define PG8_WAIT_L(n) asm volatile("s_waitcnt lgkmcnt(" #n ")" ::: "memory")
; #define PG8_BAR __builtin_amdgcn_s_barrier()
; #define PG8_SCHED __builtin_amdgcn_sched_barrier(0)
; template <class Epi, class Sched, bool ALIGN_EPI = false, bool SP2 = false>
; __device__ __forceinline__ void gemm_phase(PG8_LAS unsigned char* lds, const Gemm g, const Sched& S, const Epi& E) {
;     ...
;             PG8_WAIT_V(8); PG8_WAIT_L(0); PG8_BAR; PG8_MMA(0, 0, At, B0); PG8_MMA(0, 1, At, B1); PG8_BAR; PG8_SCHED;
	s_barrier

; #define PG8_MMA(ai, bj, At, Bt) do { __builtin_amdgcn_s_setprio(1); _Pragma("unroll") for (int m = 0; m < 4; ++m) _Pragma("unroll") for (int n = 0; n < 2; ++n) _Pragma("unroll") for (int k = 0; k < 2; ++k) \
;         acc[ai][bj][m][n] = __builtin_amdgcn_mfma_f32_16x16x32_bf16(Bt[n][k], At[m][k], acc[ai][bj][m][n], 0, 0, 0); __builtin_amdgcn_s_setprio(0); } while (0)
; #define PG8_WAIT_V(n) asm volatile("s_waitcnt vmcnt(" #n ")" ::: "memory")
; #define PG8_WAIT_L(n) asm volatile("s_waitcnt lgkmcnt(" #n ")" ::: "memory")
; #define PG8_BAR __builtin_amdgcn_s_barrier()
; #define PG8_SCHED __builtin_amdgcn_sched_barrier(0)
; template <class Epi, class Sched, bool ALIGN_EPI = false, bool SP2 = false>
; __device__ __forceinline__ void gemm_phase(PG8_LAS unsigned char* lds, const Gemm g, const Sched& S, const Epi& E) {
;     ...
;             PG8_WAIT_V(8); PG8_WAIT_L(0); PG8_BAR; PG8_MMA(0, 0, At, B0); PG8_MMA(0, 1, At, B1); PG8_BAR; PG8_SCHED;
	v_mfma_f32_16x16x32_bf16 v[140:143], v[64:67], v[176:179], v[140:143]
	v_mfma_f32_16x16x32_bf16 v[136:139], v[72:75], v[176:179], v[136:139]
	v_mfma_f32_16x16x32_bf16 v[124:127], v[64:67], v[184:187], v[124:127]
	v_mfma_f32_16x16x32_bf16 v[120:123], v[72:75], v[184:187], v[120:123]
	v_mfma_f32_16x16x32_bf16 v[108:111], v[64:67], v[192:195], v[108:111]
	v_mfma_f32_16x16x32_bf16 v[104:107], v[72:75], v[192:195], v[104:107]
	v_mfma_f32_16x16x32_bf16 v[92:95], v[64:67], v[200:203], v[92:95]
	v_mfma_f32_16x16x32_bf16 v[88:91], v[72:75], v[200:203], v[88:91]
	v_mfma_f32_16x16x32_bf16 v[140:143], v[68:71], v[180:183], v[140:143]
	v_mfma_f32_16x16x32_bf16 v[136:139], v[76:79], v[180:183], v[136:139]
	v_mfma_f32_16x16x32_bf16 v[124:127], v[68:71], v[188:191], v[124:127]
	v_mfma_f32_16x16x32_bf16 v[120:123], v[76:79], v[188:191], v[120:123]
	v_mfma_f32_16x16x32_bf16 v[108:111], v[68:71], v[196:199], v[108:111]
	v_mfma_f32_16x16x32_bf16 v[104:107], v[76:79], v[196:199], v[104:107]
	v_mfma_f32_16x16x32_bf16 v[92:95], v[68:71], v[204:207], v[92:95]
	v_mfma_f32_16x16x32_bf16 v[88:91], v[76:79], v[204:207], v[88:91]


; #define PG8_MMA(ai, bj, At, Bt) do { __builtin_amdgcn_s_setprio(1); _Pragma("unroll") for (int m = 0; m < 4; ++m) _Pragma("unroll") for (int n = 0; n < 2; ++n) _Pragma("unroll") for (int k = 0; k < 2; ++k) \
;         acc[ai][bj][m][n] = __builtin_amdgcn_mfma_f32_16x16x32_bf16(Bt[n][k], At[m][k], acc[ai][bj][m][n], 0, 0, 0); __builtin_amdgcn_s_setprio(0); } while (0)
; #define PG8_WAIT_V(n) asm volatile("s_waitcnt vmcnt(" #n ")" ::: "memory")
; #define PG8_WAIT_L(n) asm volatile("s_waitcnt lgkmcnt(" #n ")" ::: "memory")
; #define PG8_BAR __builtin_amdgcn_s_barrier()
; #define PG8_SCHED __builtin_amdgcn_sched_barrier(0)
; template <class Epi, class Sched, bool ALIGN_EPI = false, bool SP2 = false>
; __device__ __forceinline__ void gemm_phase(PG8_LAS unsigned char* lds, const Gemm g, const Sched& S, const Epi& E) {
;     ...
;             PG8_WAIT_V(8); PG8_WAIT_L(0); PG8_BAR; PG8_MMA(0, 0, At, B0); PG8_MMA(0, 1, At, B1); PG8_BAR; PG8_SCHED;
	v_mfma_f32_16x16x32_bf16 v[132:135], v[144:147], v[176:179], v[132:135]
	v_mfma_f32_16x16x32_bf16 v[128:131], v[152:155], v[176:179], v[128:131]
	v_mfma_f32_16x16x32_bf16 v[116:119], v[144:147], v[184:187], v[116:119]
	v_mfma_f32_16x16x32_bf16 v[112:115], v[152:155], v[184:187], v[112:115]
	v_mfma_f32_16x16x32_bf16 v[100:103], v[144:147], v[192:195], v[100:103]
	v_mfma_f32_16x16x32_bf16 v[96:99], v[152:155], v[192:195], v[96:99]
	v_mfma_f32_16x16x32_bf16 v[84:87], v[144:147], v[200:203], v[84:87]
	v_mfma_f32_16x16x32_bf16 v[80:83], v[152:155], v[200:203], v[80:83]
	v_mfma_f32_16x16x32_bf16 v[132:135], v[148:151], v[180:183], v[132:135]
	v_mfma_f32_16x16x32_bf16 v[128:131], v[156:159], v[180:183], v[128:131]
	v_mfma_f32_16x16x32_bf16 v[116:119], v[148:151], v[188:191], v[116:119]
	v_mfma_f32_16x16x32_bf16 v[112:115], v[156:159], v[188:191], v[112:115]
	v_mfma_f32_16x16x32_bf16 v[100:103], v[148:151], v[196:199], v[100:103]
	v_mfma_f32_16x16x32_bf16 v[96:99], v[156:159], v[196:199], v[96:99]
	v_mfma_f32_16x16x32_bf16 v[84:87], v[148:151], v[204:207], v[84:87]
	v_mfma_f32_16x16x32_bf16 v[80:83], v[156:159], v[204:207], v[80:83]

; #define PG8_STAGE(bufoff, gbase, voff) do { _Pragma("unroll") for (int _i = 0; _i < 2; ++_i) \
;         __builtin_amdgcn_global_load_lds((const unsigned*)((const char*)(gbase) + (voff)[_i]), (PG8_LAS unsigned*)(lds + (bufoff) + ldsw + _i * 8192), 16, 0, 0); } while (0)
; #define PG8_LDA(dst, b, h) do { _Pragma("unroll") for (int m = 0; m < 4; ++m) _Pragma("unroll") for (int k = 0; k < 2; ++k) dst[m][k] = *(const PG8_LAS bf16x8*)(lds + PG8_SA(b, h) + aoff + m * 2048 + k * 1024); } while (0)
; #define PG8_MMA(ai, bj, At, Bt) do { __builtin_amdgcn_s_setprio(1); _Pragma("unroll") for (int m = 0; m < 4; ++m) _Pragma("unroll") for (int n = 0; n < 2; ++n) _Pragma("unroll") for (int k = 0; k < 2; ++k) \
;         acc[ai][bj][m][n] = __builtin_amdgcn_mfma_f32_16x16x32_bf16(Bt[n][k], At[m][k], acc[ai][bj][m][n], 0, 0, 0); __builtin_amdgcn_s_setprio(0); } while (0)
; #define PG8_WAIT_V(n) asm volatile("s_waitcnt vmcnt(" #n ")" ::: "memory")
; #define PG8_WAIT_L(n) asm volatile("s_waitcnt lgkmcnt(" #n ")" ::: "memory")
; #define PG8_BAR __builtin_amdgcn_s_barrier()
; #define PG8_SCHED __builtin_amdgcn_sched_barrier(0)
; template <class Epi, class Sched, bool ALIGN_EPI = false, bool SP2 = false>
; __device__ __forceinline__ void gemm_phase(PG8_LAS unsigned char* lds, const Gemm g, const Sched& S, const Epi& E) {
;     ...
;             PG8_WAIT_V(8); PG8_WAIT_L(0); PG8_BAR; PG8_MMA(0, 0, At, B0); PG8_MMA(0, 1, At, B1); PG8_BAR; PG8_SCHED;
;             PG8_LDA(At, 1, 1); PG8_STAGE(PG8_SB(1, 0), b3, voffB); PG8_STAGE(PG8_SB(1, 1), b3 + hstep, voffB); PG8_STAGE(PG8_SA(1, 0), a3, voffA);
	s_barrier
	s_add_i32 s62, s82, s64

; #define PG8_STAGE(bufoff, gbase, voff) do { _Pragma("unroll") for (int _i = 0; _i < 2; ++_i) \
;         __builtin_amdgcn_global_load_lds((const unsigned*)((const char*)(gbase) + (voff)[_i]), (PG8_LAS unsigned*)(lds + (bufoff) + ldsw + _i * 8192), 16, 0, 0); } while (0)
; #define PG8_LDA(dst, b, h) do { _Pragma("unroll") for (int m = 0; m < 4; ++m) _Pragma("unroll") for (int k = 0; k < 2; ++k) dst[m][k] = *(const PG8_LAS bf16x8*)(lds + PG8_SA(b, h) + aoff + m * 2048 + k * 1024); } while (0)
; template <class Epi, class Sched, bool ALIGN_EPI = false, bool SP2 = false>
; __device__ __forceinline__ void gemm_phase(PG8_LAS unsigned char* lds, const Gemm g, const Sched& S, const Epi& E) {
;     ...
;             PG8_LDA(At, 1, 1); PG8_STAGE(PG8_SB(1, 0), b3, voffB); PG8_STAGE(PG8_SB(1, 1), b3 + hstep, voffB); PG8_STAGE(PG8_SA(1, 0), a3, voffA);
	s_mov_b32 m0, s62
	ds_read_b128 v[176:179], v215 offset:49152
	ds_read_b128 v[180:183], v215 offset:50176
	ds_read_b128 v[184:187], v215 offset:51200
	ds_read_b128 v[188:191], v215 offset:52224
	ds_read_b128 v[192:195], v215 offset:53248
	ds_read_b128 v[196:199], v215 offset:54272
	ds_read_b128 v[200:203], v215 offset:55296
	ds_read_b128 v[204:207], v215 offset:56320
	global_load_lds_dwordx4 v250, s[96:97]
	s_add_i32 m0, s62, 0x2000
	s_add_u32 s60, s60, 0x80080

; #define PG8_STAGE(bufoff, gbase, voff) do { _Pragma("unroll") for (int _i = 0; _i < 2; ++_i) \
;         __builtin_amdgcn_global_load_lds((const unsigned*)((const char*)(gbase) + (voff)[_i]), (PG8_LAS unsigned*)(lds + (bufoff) + ldsw + _i * 8192), 16, 0, 0); } while (0)
; #define PG8_LDA(dst, b, h) do { _Pragma("unroll") for (int m = 0; m < 4; ++m) _Pragma("unroll") for (int k = 0; k < 2; ++k) dst[m][k] = *(const PG8_LAS bf16x8*)(lds + PG8_SA(b, h) + aoff + m * 2048 + k * 1024); } while (0)
; template <class Epi, class Sched, bool ALIGN_EPI = false, bool SP2 = false>
; __device__ __forceinline__ void gemm_phase(PG8_LAS unsigned char* lds, const Gemm g, const Sched& S, const Epi& E) {
;     ...
;             PG8_LDA(At, 1, 1); PG8_STAGE(PG8_SB(1, 0), b3, voffB); PG8_STAGE(PG8_SB(1, 1), b3 + hstep, voffB); PG8_STAGE(PG8_SA(1, 0), a3, voffA);
	s_addc_u32 s61, s61, 0
	s_add_i32 s62, s83, s64
	global_load_lds_dwordx4 v251, s[96:97]

; #define PG8_STAGE(bufoff, gbase, voff) do { _Pragma("unroll") for (int _i = 0; _i < 2; ++_i) \
;         __builtin_amdgcn_global_load_lds((const unsigned*)((const char*)(gbase) + (voff)[_i]), (PG8_LAS unsigned*)(lds + (bufoff) + ldsw + _i * 8192), 16, 0, 0); } while (0)
; #define PG8_LDA(dst, b, h) do { _Pragma("unroll") for (int m = 0; m < 4; ++m) _Pragma("unroll") for (int k = 0; k < 2; ++k) dst[m][k] = *(const PG8_LAS bf16x8*)(lds + PG8_SA(b, h) + aoff + m * 2048 + k * 1024); } while (0)
; template <class Epi, class Sched, bool ALIGN_EPI = false, bool SP2 = false>
; __device__ __forceinline__ void gemm_phase(PG8_LAS unsigned char* lds, const Gemm g, const Sched& S, const Epi& E) {
;     ...
;             PG8_LDA(At, 1, 1); PG8_STAGE(PG8_SB(1, 0), b3, voffB); PG8_STAGE(PG8_SB(1, 1), b3 + hstep, voffB); PG8_STAGE(PG8_SA(1, 0), a3, voffA);
	s_mov_b32 m0, s62
	s_nop 0
	global_load_lds_dwordx4 v162, s[60:61]

; #define PG8_STAGE(bufoff, gbase, voff) do { _Pragma("unroll") for (int _i = 0; _i < 2; ++_i) \
;         __builtin_amdgcn_global_load_lds((const unsigned*)((const char*)(gbase) + (voff)[_i]), (PG8_LAS unsigned*)(lds + (bufoff) + ldsw + _i * 8192), 16, 0, 0); } while (0)
; #define PG8_LDA(dst, b, h) do { _Pragma("unroll") for (int m = 0; m < 4; ++m) _Pragma("unroll") for (int k = 0; k < 2; ++k) dst[m][k] = *(const PG8_LAS bf16x8*)(lds + PG8_SA(b, h) + aoff + m * 2048 + k * 1024); } while (0)
; template <class Epi, class Sched, bool ALIGN_EPI = false, bool SP2 = false>
; __device__ __forceinline__ void gemm_phase(PG8_LAS unsigned char* lds, const Gemm g, const Sched& S, const Epi& E) {
;     ...
;             PG8_LDA(At, 1, 1); PG8_STAGE(PG8_SB(1, 0), b3, voffB); PG8_STAGE(PG8_SB(1, 1), b3 + hstep, voffB); PG8_STAGE(PG8_SA(1, 0), a3, voffA);
	s_add_i32 m0, s62, 0x2000
	s_nop 0
	global_load_lds_dwordx4 v166, s[60:61]

; #define PG8_STAGE(bufoff, gbase, voff) do { _Pragma("unroll") for (int _i = 0; _i < 2; ++_i) \
;         __builtin_amdgcn_global_load_lds((const unsigned*)((const char*)(gbase) + (voff)[_i]), (PG8_LAS unsigned*)(lds + (bufoff) + ldsw + _i * 8192), 16, 0, 0); } while (0)
; #define PG8_LDA(dst, b, h) do { _Pragma("unroll") for (int m = 0; m < 4; ++m) _Pragma("unroll") for (int k = 0; k < 2; ++k) dst[m][k] = *(const PG8_LAS bf16x8*)(lds + PG8_SA(b, h) + aoff + m * 2048 + k * 1024); } while (0)
; template <class Epi, class Sched, bool ALIGN_EPI = false, bool SP2 = false>
; __device__ __forceinline__ void gemm_phase(PG8_LAS unsigned char* lds, const Gemm g, const Sched& S, const Epi& E) {
;     ...
;             PG8_LDA(At, 1, 1); PG8_STAGE(PG8_SB(1, 0), b3, voffB); PG8_STAGE(PG8_SB(1, 1), b3 + hstep, voffB); PG8_STAGE(PG8_SA(1, 0), a3, voffA);
	s_mov_b32 m0, s70
	s_nop 0
	global_load_lds_dwordx4 v252, s[98:99]

; #define PG8_STAGE(bufoff, gbase, voff) do { _Pragma("unroll") for (int _i = 0; _i < 2; ++_i) \
;         __builtin_amdgcn_global_load_lds((const unsigned*)((const char*)(gbase) + (voff)[_i]), (PG8_LAS unsigned*)(lds + (bufoff) + ldsw + _i * 8192), 16, 0, 0); } while (0)
; #define PG8_LDA(dst, b, h) do { _Pragma("unroll") for (int m = 0; m < 4; ++m) _Pragma("unroll") for (int k = 0; k < 2; ++k) dst[m][k] = *(const PG8_LAS bf16x8*)(lds + PG8_SA(b, h) + aoff + m * 2048 + k * 1024); } while (0)
; #define PG8_MMA(ai, bj, At, Bt) do { __builtin_amdgcn_s_setprio(1); _Pragma("unroll") for (int m = 0; m < 4; ++m) _Pragma("unroll") for (int n = 0; n < 2; ++n) _Pragma("unroll") for (int k = 0; k < 2; ++k) \
;         acc[ai][bj][m][n] = __builtin_amdgcn_mfma_f32_16x16x32_bf16(Bt[n][k], At[m][k], acc[ai][bj][m][n], 0, 0, 0); __builtin_amdgcn_s_setprio(0); } while (0)
; #define PG8_WAIT_V(n) asm volatile("s_waitcnt vmcnt(" #n ")" ::: "memory")
; #define PG8_WAIT_L(n) asm volatile("s_waitcnt lgkmcnt(" #n ")" ::: "memory")
; #define PG8_BAR __builtin_amdgcn_s_barrier()
; #define PG8_SCHED __builtin_amdgcn_sched_barrier(0)
; template <class Epi, class Sched, bool ALIGN_EPI = false, bool SP2 = false>
; __device__ __forceinline__ void gemm_phase(PG8_LAS unsigned char* lds, const Gemm g, const Sched& S, const Epi& E) {
;     ...
;             PG8_LDA(At, 1, 1); PG8_STAGE(PG8_SB(1, 0), b3, voffB); PG8_STAGE(PG8_SB(1, 1), b3 + hstep, voffB); PG8_STAGE(PG8_SA(1, 0), a3, voffA);
;             PG8_WAIT_V(8); PG8_WAIT_L(0); PG8_BAR; PG8_MMA(1, 0, At, B0); PG8_MMA(1, 1, At, B1); PG8_BAR; PG8_SCHED;
	s_mov_b32 m0, s71
	s_nop 0
	global_load_lds_dwordx4 v253, s[98:99]
	s_waitcnt vmcnt(8)
	s_waitcnt lgkmcnt(0)

; #define PG8_MMA(ai, bj, At, Bt) do { __builtin_amdgcn_s_setprio(1); _Pragma("unroll") for (int m = 0; m < 4; ++m) _Pragma("unroll") for (int n = 0; n < 2; ++n) _Pragma("unroll") for (int k = 0; k < 2; ++k) \
;         acc[ai][bj][m][n] = __builtin_amdgcn_mfma_f32_16x16x32_bf16(Bt[n][k], At[m][k], acc[ai][bj][m][n], 0, 0, 0); __builtin_amdgcn_s_setprio(0); } while (0)
; #define PG8_WAIT_V(n) asm volatile("s_waitcnt vmcnt(" #n ")" ::: "memory")
; #define PG8_WAIT_L(n) asm volatile("s_waitcnt lgkmcnt(" #n ")" ::: "memory")
; #define PG8_BAR __builtin_amdgcn_s_barrier()
; #define PG8_SCHED __builtin_amdgcn_sched_barrier(0)
; template <class Epi, class Sched, bool ALIGN_EPI = false, bool SP2 = false>
; __device__ __forceinline__ void gemm_phase(PG8_LAS unsigned char* lds, const Gemm g, const Sched& S, const Epi& E) {
;     ...
;             PG8_WAIT_V(8); PG8_WAIT_L(0); PG8_BAR; PG8_MMA(1, 0, At, B0); PG8_MMA(1, 1, At, B1); PG8_BAR; PG8_SCHED;
	s_barrier

; #define PG8_MMA(ai, bj, At, Bt) do { __builtin_amdgcn_s_setprio(1); _Pragma("unroll") for (int m = 0; m < 4; ++m) _Pragma("unroll") for (int n = 0; n < 2; ++n) _Pragma("unroll") for (int k = 0; k < 2; ++k) \
;         acc[ai][bj][m][n] = __builtin_amdgcn_mfma_f32_16x16x32_bf16(Bt[n][k], At[m][k], acc[ai][bj][m][n], 0, 0, 0); __builtin_amdgcn_s_setprio(0); } while (0)
; #define PG8_WAIT_V(n) asm volatile("s_waitcnt vmcnt(" #n ")" ::: "memory")
; #define PG8_WAIT_L(n) asm volatile("s_waitcnt lgkmcnt(" #n ")" ::: "memory")
; #define PG8_BAR __builtin_amdgcn_s_barrier()
; #define PG8_SCHED __builtin_amdgcn_sched_barrier(0)
; template <class Epi, class Sched, bool ALIGN_EPI = false, bool SP2 = false>
; __device__ __forceinline__ void gemm_phase(PG8_LAS unsigned char* lds, const Gemm g, const Sched& S, const Epi& E) {
;     ...
;             PG8_WAIT_V(8); PG8_WAIT_L(0); PG8_BAR; PG8_MMA(1, 0, At, B0); PG8_MMA(1, 1, At, B1); PG8_BAR; PG8_SCHED;
	v_mfma_f32_16x16x32_bf16 v[60:63], v[64:67], v[176:179], v[60:63]
	v_mfma_f32_16x16x32_bf16 v[56:59], v[72:75], v[176:179], v[56:59]
	v_mfma_f32_16x16x32_bf16 v[44:47], v[64:67], v[184:187], v[44:47]
	v_mfma_f32_16x16x32_bf16 v[40:43], v[72:75], v[184:187], v[40:43]
	v_mfma_f32_16x16x32_bf16 v[28:31], v[64:67], v[192:195], v[28:31]
	v_mfma_f32_16x16x32_bf16 v[24:27], v[72:75], v[192:195], v[24:27]
	v_mfma_f32_16x16x32_bf16 v[12:15], v[64:67], v[200:203], v[12:15]
	v_mfma_f32_16x16x32_bf16 v[8:11], v[72:75], v[200:203], v[8:11]
	v_mfma_f32_16x16x32_bf16 v[60:63], v[68:71], v[180:183], v[60:63]
	v_mfma_f32_16x16x32_bf16 v[56:59], v[76:79], v[180:183], v[56:59]
	v_mfma_f32_16x16x32_bf16 v[44:47], v[68:71], v[188:191], v[44:47]
	v_mfma_f32_16x16x32_bf16 v[40:43], v[76:79], v[188:191], v[40:43]
	v_mfma_f32_16x16x32_bf16 v[28:31], v[68:71], v[196:199], v[28:31]
	v_mfma_f32_16x16x32_bf16 v[24:27], v[76:79], v[196:199], v[24:27]
	v_mfma_f32_16x16x32_bf16 v[12:15], v[68:71], v[204:207], v[12:15]
	v_mfma_f32_16x16x32_bf16 v[8:11], v[76:79], v[204:207], v[8:11]


; #define PG8_MMA(ai, bj, At, Bt) do { __builtin_amdgcn_s_setprio(1); _Pragma("unroll") for (int m = 0; m < 4; ++m) _Pragma("unroll") for (int n = 0; n < 2; ++n) _Pragma("unroll") for (int k = 0; k < 2; ++k) \
;         acc[ai][bj][m][n] = __builtin_amdgcn_mfma_f32_16x16x32_bf16(Bt[n][k], At[m][k], acc[ai][bj][m][n], 0, 0, 0); __builtin_amdgcn_s_setprio(0); } while (0)
; #define PG8_WAIT_V(n) asm volatile("s_waitcnt vmcnt(" #n ")" ::: "memory")
; #define PG8_WAIT_L(n) asm volatile("s_waitcnt lgkmcnt(" #n ")" ::: "memory")
; #define PG8_BAR __builtin_amdgcn_s_barrier()
; #define PG8_SCHED __builtin_amdgcn_sched_barrier(0)
; template <class Epi, class Sched, bool ALIGN_EPI = false, bool SP2 = false>
; __device__ __forceinline__ void gemm_phase(PG8_LAS unsigned char* lds, const Gemm g, const Sched& S, const Epi& E) {
;     ...
;             PG8_WAIT_V(8); PG8_WAIT_L(0); PG8_BAR; PG8_MMA(1, 0, At, B0); PG8_MMA(1, 1, At, B1); PG8_BAR; PG8_SCHED;
	v_mfma_f32_16x16x32_bf16 v[52:55], v[144:147], v[176:179], v[52:55]
	v_mfma_f32_16x16x32_bf16 v[48:51], v[152:155], v[176:179], v[48:51]
	v_mfma_f32_16x16x32_bf16 v[36:39], v[144:147], v[184:187], v[36:39]
	v_mfma_f32_16x16x32_bf16 v[32:35], v[152:155], v[184:187], v[32:35]
	v_mfma_f32_16x16x32_bf16 v[20:23], v[144:147], v[192:195], v[20:23]
	v_mfma_f32_16x16x32_bf16 v[16:19], v[152:155], v[192:195], v[16:19]
	v_mfma_f32_16x16x32_bf16 v[4:7], v[144:147], v[200:203], v[4:7]
	v_mfma_f32_16x16x32_bf16 v[0:3], v[152:155], v[200:203], v[0:3]
	v_mfma_f32_16x16x32_bf16 v[52:55], v[148:151], v[180:183], v[52:55]
	v_mfma_f32_16x16x32_bf16 v[48:51], v[156:159], v[180:183], v[48:51]
	v_mfma_f32_16x16x32_bf16 v[36:39], v[148:151], v[188:191], v[36:39]
	v_mfma_f32_16x16x32_bf16 v[32:35], v[156:159], v[188:191], v[32:35]
	v_mfma_f32_16x16x32_bf16 v[20:23], v[148:151], v[196:199], v[20:23]
	v_mfma_f32_16x16x32_bf16 v[16:19], v[156:159], v[196:199], v[16:19]
	v_mfma_f32_16x16x32_bf16 v[4:7], v[148:151], v[204:207], v[4:7]
	v_mfma_f32_16x16x32_bf16 v[0:3], v[156:159], v[204:207], v[0:3]

; #define PG8_STAGE(bufoff, gbase, voff) do { _Pragma("unroll") for (int _i = 0; _i < 2; ++_i) \
;         __builtin_amdgcn_global_load_lds((const unsigned*)((const char*)(gbase) + (voff)[_i]), (PG8_LAS unsigned*)(lds + (bufoff) + ldsw + _i * 8192), 16, 0, 0); } while (0)
; #define PG8_LDA(dst, b, h) do { _Pragma("unroll") for (int m = 0; m < 4; ++m) _Pragma("unroll") for (int k = 0; k < 2; ++k) dst[m][k] = *(const PG8_LAS bf16x8*)(lds + PG8_SA(b, h) + aoff + m * 2048 + k * 1024); } while (0)
; #define PG8_WAIT_V(n) asm volatile("s_waitcnt vmcnt(" #n ")" ::: "memory")
; #define PG8_WAIT_L(n) asm volatile("s_waitcnt lgkmcnt(" #n ")" ::: "memory")
; template <class Epi, class Sched, bool ALIGN_EPI = false, bool SP2 = false>
; __device__ __forceinline__ void gemm_phase(PG8_LAS unsigned char* lds, const Gemm g, const Sched& S, const Epi& E) {
;     ...
;         for (int t = 0; t < nt; t += 2) {
;             const bool last = (t == nt - 2);
;             const char* a1 = cA + (size_t)(t + 1) * kstep;
;             const char* a2 = last ? nA : cA + (size_t)(t + 2) * kstep; const char* b2 = last ? nB : cB + (size_t)(t + 2) * kstep;
;             const char* a3 = a2 + kstep; const char* b3 = b2 + kstep;
;             if (last && has_next) S.a_ready(nxt);
;             if constexpr (SP2) {
;             PG8_LDB(B0, 0, 0); PG8_LDB(B1, 0, 1); PG8_SCHED; PG8_LDA(At, 0, 0); PG8_STAGE(PG8_SA(1, 1), a1 + hstep, voffA);
;             PG8_WAIT_V(8); PG8_WAIT_L(0); PG8_BAR; PG8_MMA(0, 0, At, B0); PG8_MMA(0, 1, At, B1); PG8_BAR; PG8_SCHED;
;             PG8_LDA(At, 0, 1); PG8_STAGE(PG8_SB(0, 0), b2, voffB); PG8_STAGE(PG8_SB(0, 1), b2 + hstep, voffB); PG8_STAGE(PG8_SA(0, 0), a2, voffA);
;             PG8_WAIT_V(8); PG8_WAIT_L(0); PG8_BAR; PG8_MMA(1, 0, At, B0); PG8_MMA(1, 1, At, B1); PG8_BAR; PG8_SCHED;
;             PG8_LDB(B0, 1, 0); PG8_LDB(B1, 1, 1); PG8_SCHED; PG8_LDA(At, 1, 0); PG8_STAGE(PG8_SA(0, 1), a2 + hstep, voffA);
;             PG8_WAIT_V(8); PG8_WAIT_L(0); PG8_BAR; PG8_MMA(0, 0, At, B0); PG8_MMA(0, 1, At, B1); PG8_BAR; PG8_SCHED;
;             PG8_LDA(At, 1, 1); PG8_STAGE(PG8_SB(1, 0), b3, voffB); PG8_STAGE(PG8_SB(1, 1), b3 + hstep, voffB); PG8_STAGE(PG8_SA(1, 0), a3, voffA);
;             PG8_WAIT_V(8); PG8_WAIT_L(0); PG8_BAR; PG8_MMA(1, 0, At, B0); PG8_MMA(1, 1, At, B1); PG8_BAR; PG8_SCHED;
;     ...
;         if constexpr (ALIGN_EPI) { if (wr == 0) PG8_BAR; }
	s_barrier
	s_add_i32 s81, s81, 2
	s_add_u32 s58, s58, 0x100
	s_addc_u32 s59, s59, 0
	s_add_u32 s79, s79, 0x100
	s_addc_u32 s80, s80, 0
	s_cmp_gt_u32 s81, 29
	s_cbranch_scc0 .LBB0_939
	s_and_b64 vcc, exec, s[42:43]
	s_cbranch_vccz .LBB0_942
	s_barrier

; #define PG8_STAGE(bufoff, gbase, voff) do { _Pragma("unroll") for (int _i = 0; _i < 2; ++_i) \
;         __builtin_amdgcn_global_load_lds((const unsigned*)((const char*)(gbase) + (voff)[_i]), (PG8_LAS unsigned*)(lds + (bufoff) + ldsw + _i * 8192), 16, 0, 0); } while (0)
; #define PG8_LDA(dst, b, h) do { _Pragma("unroll") for (int m = 0; m < 4; ++m) _Pragma("unroll") for (int k = 0; k < 2; ++k) dst[m][k] = *(const PG8_LAS bf16x8*)(lds + PG8_SA(b, h) + aoff + m * 2048 + k * 1024); } while (0)
; #define PG8_LDB(dst, b, h) do { _Pragma("unroll") for (int n = 0; n < 2; ++n) _Pragma("unroll") for (int k = 0; k < 2; ++k) dst[n][k] = *(const PG8_LAS bf16x8*)(lds + PG8_SB(b, h) + boff + n * 2048 + k * 1024); } while (0)
; #define PG8_SCHED __builtin_amdgcn_sched_barrier(0)
; template <class Epi, class Sched, bool ALIGN_EPI = false, bool SP2 = false>
; __device__ __forceinline__ void gemm_phase(PG8_LAS unsigned char* lds, const Gemm g, const Sched& S, const Epi& E) {
;     ...
;         for (int t = 0; t < nt; t += 2) {
;             const bool last = (t == nt - 2);
;             const char* a1 = cA + (size_t)(t + 1) * kstep;
;             const char* a2 = last ? nA : cA + (size_t)(t + 2) * kstep; const char* b2 = last ? nB : cB + (size_t)(t + 2) * kstep;
;             const char* a3 = a2 + kstep; const char* b3 = b2 + kstep;
;             if (last && has_next) S.a_ready(nxt);
;             if constexpr (SP2) {
;             PG8_LDB(B0, 0, 0); PG8_LDB(B1, 0, 1); PG8_SCHED; PG8_LDA(At, 0, 0); PG8_STAGE(PG8_SA(1, 1), a1 + hstep, voffA);
.LBB0_1034:
	ds_read_b128 v[128:131], v201
	ds_read_b128 v[132:135], v201 offset:1024
	ds_read_b128 v[136:139], v201 offset:2048
	ds_read_b128 v[140:143], v201 offset:3072
	ds_read_b128 v[144:147], v205
	ds_read_b128 v[148:151], v205 offset:1024
	ds_read_b128 v[152:155], v205 offset:2048
	ds_read_b128 v[156:159], v205 offset:3072
	s_add_u32 s12, s10, 0xfff80080
	s_addc_u32 s13, s11, -1
	s_cmp_eq_u32 s83, 28
	s_cselect_b32 s59, s53, s13
	s_cselect_b32 s58, s79, s12
	s_cselect_b32 s13, s51, s82
	s_cselect_b32 s12, s80, s81

; #define PG8_STAGE(bufoff, gbase, voff) do { _Pragma("unroll") for (int _i = 0; _i < 2; ++_i) \
;         __builtin_amdgcn_global_load_lds((const unsigned*)((const char*)(gbase) + (voff)[_i]), (PG8_LAS unsigned*)(lds + (bufoff) + ldsw + _i * 8192), 16, 0, 0); } while (0)
; #define PG8_LDA(dst, b, h) do { _Pragma("unroll") for (int m = 0; m < 4; ++m) _Pragma("unroll") for (int k = 0; k < 2; ++k) dst[m][k] = *(const PG8_LAS bf16x8*)(lds + PG8_SA(b, h) + aoff + m * 2048 + k * 1024); } while (0)
; #define PG8_LDB(dst, b, h) do { _Pragma("unroll") for (int n = 0; n < 2; ++n) _Pragma("unroll") for (int k = 0; k < 2; ++k) dst[n][k] = *(const PG8_LAS bf16x8*)(lds + PG8_SB(b, h) + boff + n * 2048 + k * 1024); } while (0)
; #define PG8_SCHED __builtin_amdgcn_sched_barrier(0)
; template <class Epi, class Sched, bool ALIGN_EPI = false, bool SP2 = false>
; __device__ __forceinline__ void gemm_phase(PG8_LAS unsigned char* lds, const Gemm g, const Sched& S, const Epi& E) {
;     ...
;             PG8_LDB(B0, 0, 0); PG8_LDB(B1, 0, 1); PG8_SCHED; PG8_LDA(At, 0, 0); PG8_STAGE(PG8_SA(1, 1), a1 + hstep, voffA);
	s_add_i32 m0, s63, 0xc000
	ds_read_b128 v[176:179], v207
	ds_read_b128 v[184:187], v207 offset:1024
	ds_read_b128 v[190:193], v207 offset:2048
	ds_read_b128 v[210:213], v207 offset:3072
	ds_read_b128 v[214:217], v207 offset:4096
	ds_read_b128 v[218:221], v207 offset:5120
	ds_read_b128 v[222:225], v207 offset:6144
	ds_read_b128 v[226:229], v207 offset:7168
	global_load_lds_dwordx4 v168, s[10:11]

; #define PG8_STAGE(bufoff, gbase, voff) do { _Pragma("unroll") for (int _i = 0; _i < 2; ++_i) \
;         __builtin_amdgcn_global_load_lds((const unsigned*)((const char*)(gbase) + (voff)[_i]), (PG8_LAS unsigned*)(lds + (bufoff) + ldsw + _i * 8192), 16, 0, 0); } while (0)
; #define PG8_LDA(dst, b, h) do { _Pragma("unroll") for (int m = 0; m < 4; ++m) _Pragma("unroll") for (int k = 0; k < 2; ++k) dst[m][k] = *(const PG8_LAS bf16x8*)(lds + PG8_SA(b, h) + aoff + m * 2048 + k * 1024); } while (0)
; #define PG8_LDB(dst, b, h) do { _Pragma("unroll") for (int n = 0; n < 2; ++n) _Pragma("unroll") for (int k = 0; k < 2; ++k) dst[n][k] = *(const PG8_LAS bf16x8*)(lds + PG8_SB(b, h) + boff + n * 2048 + k * 1024); } while (0)
; #define PG8_MMA(ai, bj, At, Bt) do { __builtin_amdgcn_s_setprio(1); _Pragma("unroll") for (int m = 0; m < 4; ++m) _Pragma("unroll") for (int n = 0; n < 2; ++n) _Pragma("unroll") for (int k = 0; k < 2; ++k) \
;         acc[ai][bj][m][n] = __builtin_amdgcn_mfma_f32_16x16x32_bf16(Bt[n][k], At[m][k], acc[ai][bj][m][n], 0, 0, 0); __builtin_amdgcn_s_setprio(0); } while (0)
; #define PG8_WAIT_V(n) asm volatile("s_waitcnt vmcnt(" #n ")" ::: "memory")
; #define PG8_WAIT_L(n) asm volatile("s_waitcnt lgkmcnt(" #n ")" ::: "memory")
; #define PG8_BAR __builtin_amdgcn_s_barrier()
; #define PG8_SCHED __builtin_amdgcn_sched_barrier(0)
; template <class Epi, class Sched, bool ALIGN_EPI = false, bool SP2 = false>
; __device__ __forceinline__ void gemm_phase(PG8_LAS unsigned char* lds, const Gemm g, const Sched& S, const Epi& E) {
;     ...
;             PG8_LDB(B0, 0, 0); PG8_LDB(B1, 0, 1); PG8_SCHED; PG8_LDA(At, 0, 0); PG8_STAGE(PG8_SA(1, 1), a1 + hstep, voffA);
;             PG8_WAIT_V(8); PG8_WAIT_L(0); PG8_BAR; PG8_MMA(0, 0, At, B0); PG8_MMA(0, 1, At, B1); PG8_BAR; PG8_SCHED;
	s_add_i32 m0, s63, 0xe000
	s_nop 0
	global_load_lds_dwordx4 v170, s[10:11]
	s_waitcnt vmcnt(8)
	s_waitcnt lgkmcnt(0)

; #define PG8_MMA(ai, bj, At, Bt) do { __builtin_amdgcn_s_setprio(1); _Pragma("unroll") for (int m = 0; m < 4; ++m) _Pragma("unroll") for (int n = 0; n < 2; ++n) _Pragma("unroll") for (int k = 0; k < 2; ++k) \
;         acc[ai][bj][m][n] = __builtin_amdgcn_mfma_f32_16x16x32_bf16(Bt[n][k], At[m][k], acc[ai][bj][m][n], 0, 0, 0); __builtin_amdgcn_s_setprio(0); } while (0)
; #define PG8_WAIT_V(n) asm volatile("s_waitcnt vmcnt(" #n ")" ::: "memory")
; #define PG8_WAIT_L(n) asm volatile("s_waitcnt lgkmcnt(" #n ")" ::: "memory")
; #define PG8_BAR __builtin_amdgcn_s_barrier()
; #define PG8_SCHED __builtin_amdgcn_sched_barrier(0)
; template <class Epi, class Sched, bool ALIGN_EPI = false, bool SP2 = false>
; __device__ __forceinline__ void gemm_phase(PG8_LAS unsigned char* lds, const Gemm g, const Sched& S, const Epi& E) {
;     ...
;             PG8_WAIT_V(8); PG8_WAIT_L(0); PG8_BAR; PG8_MMA(0, 0, At, B0); PG8_MMA(0, 1, At, B1); PG8_BAR; PG8_SCHED;
	s_barrier

; #define PG8_MMA(ai, bj, At, Bt) do { __builtin_amdgcn_s_setprio(1); _Pragma("unroll") for (int m = 0; m < 4; ++m) _Pragma("unroll") for (int n = 0; n < 2; ++n) _Pragma("unroll") for (int k = 0; k < 2; ++k) \
;         acc[ai][bj][m][n] = __builtin_amdgcn_mfma_f32_16x16x32_bf16(Bt[n][k], At[m][k], acc[ai][bj][m][n], 0, 0, 0); __builtin_amdgcn_s_setprio(0); } while (0)
; #define PG8_WAIT_V(n) asm volatile("s_waitcnt vmcnt(" #n ")" ::: "memory")
; #define PG8_WAIT_L(n) asm volatile("s_waitcnt lgkmcnt(" #n ")" ::: "memory")
; #define PG8_BAR __builtin_amdgcn_s_barrier()
; #define PG8_SCHED __builtin_amdgcn_sched_barrier(0)
; template <class Epi, class Sched, bool ALIGN_EPI = false, bool SP2 = false>
; __device__ __forceinline__ void gemm_phase(PG8_LAS unsigned char* lds, const Gemm g, const Sched& S, const Epi& E) {
;     ...
;             PG8_WAIT_V(8); PG8_WAIT_L(0); PG8_BAR; PG8_MMA(0, 0, At, B0); PG8_MMA(0, 1, At, B1); PG8_BAR; PG8_SCHED;
	v_mfma_f32_16x16x32_bf16 v[124:127], v[128:131], v[176:179], v[124:127]
	v_mfma_f32_16x16x32_bf16 v[120:123], v[136:139], v[176:179], v[120:123]
	v_mfma_f32_16x16x32_bf16 v[108:111], v[128:131], v[190:193], v[108:111]
	v_mfma_f32_16x16x32_bf16 v[104:107], v[136:139], v[190:193], v[104:107]
	v_mfma_f32_16x16x32_bf16 v[92:95], v[128:131], v[214:217], v[92:95]
	v_mfma_f32_16x16x32_bf16 v[88:91], v[136:139], v[214:217], v[88:91]
	v_mfma_f32_16x16x32_bf16 v[76:79], v[128:131], v[222:225], v[76:79]
	v_mfma_f32_16x16x32_bf16 v[72:75], v[136:139], v[222:225], v[72:75]
	v_mfma_f32_16x16x32_bf16 v[124:127], v[132:135], v[184:187], v[124:127]
	v_mfma_f32_16x16x32_bf16 v[120:123], v[140:143], v[184:187], v[120:123]
	v_mfma_f32_16x16x32_bf16 v[108:111], v[132:135], v[210:213], v[108:111]
	v_mfma_f32_16x16x32_bf16 v[104:107], v[140:143], v[210:213], v[104:107]
	v_mfma_f32_16x16x32_bf16 v[92:95], v[132:135], v[218:221], v[92:95]
	v_mfma_f32_16x16x32_bf16 v[88:91], v[140:143], v[218:221], v[88:91]
	v_mfma_f32_16x16x32_bf16 v[76:79], v[132:135], v[226:229], v[76:79]
	v_mfma_f32_16x16x32_bf16 v[72:75], v[140:143], v[226:229], v[72:75]


; #define PG8_MMA(ai, bj, At, Bt) do { __builtin_amdgcn_s_setprio(1); _Pragma("unroll") for (int m = 0; m < 4; ++m) _Pragma("unroll") for (int n = 0; n < 2; ++n) _Pragma("unroll") for (int k = 0; k < 2; ++k) \
;         acc[ai][bj][m][n] = __builtin_amdgcn_mfma_f32_16x16x32_bf16(Bt[n][k], At[m][k], acc[ai][bj][m][n], 0, 0, 0); __builtin_amdgcn_s_setprio(0); } while (0)
; #define PG8_WAIT_V(n) asm volatile("s_waitcnt vmcnt(" #n ")" ::: "memory")
; #define PG8_WAIT_L(n) asm volatile("s_waitcnt lgkmcnt(" #n ")" ::: "memory")
; #define PG8_BAR __builtin_amdgcn_s_barrier()
; #define PG8_SCHED __builtin_amdgcn_sched_barrier(0)
; template <class Epi, class Sched, bool ALIGN_EPI = false, bool SP2 = false>
; __device__ __forceinline__ void gemm_phase(PG8_LAS unsigned char* lds, const Gemm g, const Sched& S, const Epi& E) {
;     ...
;             PG8_WAIT_V(8); PG8_WAIT_L(0); PG8_BAR; PG8_MMA(0, 0, At, B0); PG8_MMA(0, 1, At, B1); PG8_BAR; PG8_SCHED;
	v_mfma_f32_16x16x32_bf16 v[116:119], v[144:147], v[176:179], v[116:119]
	v_mfma_f32_16x16x32_bf16 v[112:115], v[152:155], v[176:179], v[112:115]
	v_mfma_f32_16x16x32_bf16 v[100:103], v[144:147], v[190:193], v[100:103]
	v_mfma_f32_16x16x32_bf16 v[96:99], v[152:155], v[190:193], v[96:99]
	v_mfma_f32_16x16x32_bf16 v[84:87], v[144:147], v[214:217], v[84:87]
	v_mfma_f32_16x16x32_bf16 v[80:83], v[152:155], v[214:217], v[80:83]
	v_mfma_f32_16x16x32_bf16 v[68:71], v[144:147], v[222:225], v[68:71]
	v_mfma_f32_16x16x32_bf16 v[64:67], v[152:155], v[222:225], v[64:67]
	v_mfma_f32_16x16x32_bf16 v[116:119], v[148:151], v[184:187], v[116:119]
	v_mfma_f32_16x16x32_bf16 v[112:115], v[156:159], v[184:187], v[112:115]
	v_mfma_f32_16x16x32_bf16 v[100:103], v[148:151], v[210:213], v[100:103]
	v_mfma_f32_16x16x32_bf16 v[96:99], v[156:159], v[210:213], v[96:99]
	v_mfma_f32_16x16x32_bf16 v[84:87], v[148:151], v[218:221], v[84:87]
	v_mfma_f32_16x16x32_bf16 v[80:83], v[156:159], v[218:221], v[80:83]
	v_mfma_f32_16x16x32_bf16 v[68:71], v[148:151], v[226:229], v[68:71]
	v_mfma_f32_16x16x32_bf16 v[64:67], v[156:159], v[226:229], v[64:67]

; #define PG8_STAGE(bufoff, gbase, voff) do { _Pragma("unroll") for (int _i = 0; _i < 2; ++_i) \
;         __builtin_amdgcn_global_load_lds((const unsigned*)((const char*)(gbase) + (voff)[_i]), (PG8_LAS unsigned*)(lds + (bufoff) + ldsw + _i * 8192), 16, 0, 0); } while (0)
; #define PG8_LDA(dst, b, h) do { _Pragma("unroll") for (int m = 0; m < 4; ++m) _Pragma("unroll") for (int k = 0; k < 2; ++k) dst[m][k] = *(const PG8_LAS bf16x8*)(lds + PG8_SA(b, h) + aoff + m * 2048 + k * 1024); } while (0)
; #define PG8_MMA(ai, bj, At, Bt) do { __builtin_amdgcn_s_setprio(1); _Pragma("unroll") for (int m = 0; m < 4; ++m) _Pragma("unroll") for (int n = 0; n < 2; ++n) _Pragma("unroll") for (int k = 0; k < 2; ++k) \
;         acc[ai][bj][m][n] = __builtin_amdgcn_mfma_f32_16x16x32_bf16(Bt[n][k], At[m][k], acc[ai][bj][m][n], 0, 0, 0); __builtin_amdgcn_s_setprio(0); } while (0)
; #define PG8_WAIT_V(n) asm volatile("s_waitcnt vmcnt(" #n ")" ::: "memory")
; #define PG8_WAIT_L(n) asm volatile("s_waitcnt lgkmcnt(" #n ")" ::: "memory")
; #define PG8_BAR __builtin_amdgcn_s_barrier()
; #define PG8_SCHED __builtin_amdgcn_sched_barrier(0)
; template <class Epi, class Sched, bool ALIGN_EPI = false, bool SP2 = false>
; __device__ __forceinline__ void gemm_phase(PG8_LAS unsigned char* lds, const Gemm g, const Sched& S, const Epi& E) {
;     ...
;             PG8_WAIT_V(8); PG8_WAIT_L(0); PG8_BAR; PG8_MMA(0, 0, At, B0); PG8_MMA(0, 1, At, B1); PG8_BAR; PG8_SCHED;
;             PG8_LDA(At, 0, 1); PG8_STAGE(PG8_SB(0, 0), b2, voffB); PG8_STAGE(PG8_SB(0, 1), b2 + hstep, voffB); PG8_STAGE(PG8_SA(0, 0), a2, voffA);
	s_barrier
	s_add_i32 s84, s73, s62
	s_mov_b64 s[96:97], s[12:13]

; #define PG8_STAGE(bufoff, gbase, voff) do { _Pragma("unroll") for (int _i = 0; _i < 2; ++_i) \
;         __builtin_amdgcn_global_load_lds((const unsigned*)((const char*)(gbase) + (voff)[_i]), (PG8_LAS unsigned*)(lds + (bufoff) + ldsw + _i * 8192), 16, 0, 0); } while (0)
; #define PG8_LDA(dst, b, h) do { _Pragma("unroll") for (int m = 0; m < 4; ++m) _Pragma("unroll") for (int k = 0; k < 2; ++k) dst[m][k] = *(const PG8_LAS bf16x8*)(lds + PG8_SA(b, h) + aoff + m * 2048 + k * 1024); } while (0)
; template <class Epi, class Sched, bool ALIGN_EPI = false, bool SP2 = false>
; __device__ __forceinline__ void gemm_phase(PG8_LAS unsigned char* lds, const Gemm g, const Sched& S, const Epi& E) {
;     ...
;             PG8_LDA(At, 0, 1); PG8_STAGE(PG8_SB(0, 0), b2, voffB); PG8_STAGE(PG8_SB(0, 1), b2 + hstep, voffB); PG8_STAGE(PG8_SA(0, 0), a2, voffA);
	s_mov_b32 m0, s84
	ds_read_b128 v[176:179], v207 offset:16384
	ds_read_b128 v[184:187], v207 offset:17408
	ds_read_b128 v[190:193], v207 offset:18432
	ds_read_b128 v[210:213], v207 offset:19456
	ds_read_b128 v[214:217], v207 offset:20480
	ds_read_b128 v[218:221], v207 offset:21504
	ds_read_b128 v[222:225], v207 offset:22528
	ds_read_b128 v[226:229], v207 offset:23552
	global_load_lds_dwordx4 v162, s[12:13]
	s_add_i32 m0, s84, 0x2000
	s_add_u32 s84, s12, 0x80000

; #define PG8_STAGE(bufoff, gbase, voff) do { _Pragma("unroll") for (int _i = 0; _i < 2; ++_i) \
;         __builtin_amdgcn_global_load_lds((const unsigned*)((const char*)(gbase) + (voff)[_i]), (PG8_LAS unsigned*)(lds + (bufoff) + ldsw + _i * 8192), 16, 0, 0); } while (0)
; #define PG8_LDA(dst, b, h) do { _Pragma("unroll") for (int m = 0; m < 4; ++m) _Pragma("unroll") for (int k = 0; k < 2; ++k) dst[m][k] = *(const PG8_LAS bf16x8*)(lds + PG8_SA(b, h) + aoff + m * 2048 + k * 1024); } while (0)
; template <class Epi, class Sched, bool ALIGN_EPI = false, bool SP2 = false>
; __device__ __forceinline__ void gemm_phase(PG8_LAS unsigned char* lds, const Gemm g, const Sched& S, const Epi& E) {
;     ...
;             PG8_LDA(At, 0, 1); PG8_STAGE(PG8_SB(0, 0), b2, voffB); PG8_STAGE(PG8_SB(0, 1), b2 + hstep, voffB); PG8_STAGE(PG8_SA(0, 0), a2, voffA);
	s_addc_u32 s85, s13, 0
	s_add_i32 s86, s74, s62
	global_load_lds_dwordx4 v166, s[12:13]

; #define PG8_STAGE(bufoff, gbase, voff) do { _Pragma("unroll") for (int _i = 0; _i < 2; ++_i) \
;         __builtin_amdgcn_global_load_lds((const unsigned*)((const char*)(gbase) + (voff)[_i]), (PG8_LAS unsigned*)(lds + (bufoff) + ldsw + _i * 8192), 16, 0, 0); } while (0)
; #define PG8_LDA(dst, b, h) do { _Pragma("unroll") for (int m = 0; m < 4; ++m) _Pragma("unroll") for (int k = 0; k < 2; ++k) dst[m][k] = *(const PG8_LAS bf16x8*)(lds + PG8_SA(b, h) + aoff + m * 2048 + k * 1024); } while (0)
; template <class Epi, class Sched, bool ALIGN_EPI = false, bool SP2 = false>
; __device__ __forceinline__ void gemm_phase(PG8_LAS unsigned char* lds, const Gemm g, const Sched& S, const Epi& E) {
;     ...
;             PG8_LDA(At, 0, 1); PG8_STAGE(PG8_SB(0, 0), b2, voffB); PG8_STAGE(PG8_SB(0, 1), b2 + hstep, voffB); PG8_STAGE(PG8_SA(0, 0), a2, voffA);
	s_mov_b32 m0, s86
	s_nop 0
	global_load_lds_dwordx4 v162, s[84:85]

; #define PG8_STAGE(bufoff, gbase, voff) do { _Pragma("unroll") for (int _i = 0; _i < 2; ++_i) \
;         __builtin_amdgcn_global_load_lds((const unsigned*)((const char*)(gbase) + (voff)[_i]), (PG8_LAS unsigned*)(lds + (bufoff) + ldsw + _i * 8192), 16, 0, 0); } while (0)
; #define PG8_LDA(dst, b, h) do { _Pragma("unroll") for (int m = 0; m < 4; ++m) _Pragma("unroll") for (int k = 0; k < 2; ++k) dst[m][k] = *(const PG8_LAS bf16x8*)(lds + PG8_SA(b, h) + aoff + m * 2048 + k * 1024); } while (0)
; template <class Epi, class Sched, bool ALIGN_EPI = false, bool SP2 = false>
; __device__ __forceinline__ void gemm_phase(PG8_LAS unsigned char* lds, const Gemm g, const Sched& S, const Epi& E) {
;     ...
;             PG8_LDA(At, 0, 1); PG8_STAGE(PG8_SB(0, 0), b2, voffB); PG8_STAGE(PG8_SB(0, 1), b2 + hstep, voffB); PG8_STAGE(PG8_SA(0, 0), a2, voffA);
	s_add_i32 m0, s86, 0x2000
	s_nop 0
	global_load_lds_dwordx4 v166, s[84:85]
	s_mov_b64 s[98:99], s[58:59]

; #define PG8_STAGE(bufoff, gbase, voff) do { _Pragma("unroll") for (int _i = 0; _i < 2; ++_i) \
;         __builtin_amdgcn_global_load_lds((const unsigned*)((const char*)(gbase) + (voff)[_i]), (PG8_LAS unsigned*)(lds + (bufoff) + ldsw + _i * 8192), 16, 0, 0); } while (0)
; #define PG8_LDA(dst, b, h) do { _Pragma("unroll") for (int m = 0; m < 4; ++m) _Pragma("unroll") for (int k = 0; k < 2; ++k) dst[m][k] = *(const PG8_LAS bf16x8*)(lds + PG8_SA(b, h) + aoff + m * 2048 + k * 1024); } while (0)
; #define PG8_MMA(ai, bj, At, Bt) do { __builtin_amdgcn_s_setprio(1); _Pragma("unroll") for (int m = 0; m < 4; ++m) _Pragma("unroll") for (int n = 0; n < 2; ++n) _Pragma("unroll") for (int k = 0; k < 2; ++k) \
;         acc[ai][bj][m][n] = __builtin_amdgcn_mfma_f32_16x16x32_bf16(Bt[n][k], At[m][k], acc[ai][bj][m][n], 0, 0, 0); __builtin_amdgcn_s_setprio(0); } while (0)
; #define PG8_WAIT_V(n) asm volatile("s_waitcnt vmcnt(" #n ")" ::: "memory")
; #define PG8_WAIT_L(n) asm volatile("s_waitcnt lgkmcnt(" #n ")" ::: "memory")
; #define PG8_BAR __builtin_amdgcn_s_barrier()
; #define PG8_SCHED __builtin_amdgcn_sched_barrier(0)
; template <class Epi, class Sched, bool ALIGN_EPI = false, bool SP2 = false>
; __device__ __forceinline__ void gemm_phase(PG8_LAS unsigned char* lds, const Gemm g, const Sched& S, const Epi& E) {
;     ...
;             PG8_LDA(At, 0, 1); PG8_STAGE(PG8_SB(0, 0), b2, voffB); PG8_STAGE(PG8_SB(0, 1), b2 + hstep, voffB); PG8_STAGE(PG8_SA(0, 0), a2, voffA);
;             PG8_WAIT_V(8); PG8_WAIT_L(0); PG8_BAR; PG8_MMA(1, 0, At, B0); PG8_MMA(1, 1, At, B1); PG8_BAR; PG8_SCHED;
	s_mov_b32 m0, s63
	s_nop 0
	global_load_lds_dwordx4 v160, s[58:59]
	s_mov_b32 m0, s64
	s_nop 0
	global_load_lds_dwordx4 v164, s[58:59]
	s_waitcnt vmcnt(8)
	s_waitcnt lgkmcnt(0)

; #define PG8_MMA(ai, bj, At, Bt) do { __builtin_amdgcn_s_setprio(1); _Pragma("unroll") for (int m = 0; m < 4; ++m) _Pragma("unroll") for (int n = 0; n < 2; ++n) _Pragma("unroll") for (int k = 0; k < 2; ++k) \
;         acc[ai][bj][m][n] = __builtin_amdgcn_mfma_f32_16x16x32_bf16(Bt[n][k], At[m][k], acc[ai][bj][m][n], 0, 0, 0); __builtin_amdgcn_s_setprio(0); } while (0)
; #define PG8_WAIT_V(n) asm volatile("s_waitcnt vmcnt(" #n ")" ::: "memory")
; #define PG8_WAIT_L(n) asm volatile("s_waitcnt lgkmcnt(" #n ")" ::: "memory")
; #define PG8_BAR __builtin_amdgcn_s_barrier()
; #define PG8_SCHED __builtin_amdgcn_sched_barrier(0)
; template <class Epi, class Sched, bool ALIGN_EPI = false, bool SP2 = false>
; __device__ __forceinline__ void gemm_phase(PG8_LAS unsigned char* lds, const Gemm g, const Sched& S, const Epi& E) {
;     ...
;             PG8_WAIT_V(8); PG8_WAIT_L(0); PG8_BAR; PG8_MMA(1, 0, At, B0); PG8_MMA(1, 1, At, B1); PG8_BAR; PG8_SCHED;
	s_barrier

; #define PG8_MMA(ai, bj, At, Bt) do { __builtin_amdgcn_s_setprio(1); _Pragma("unroll") for (int m = 0; m < 4; ++m) _Pragma("unroll") for (int n = 0; n < 2; ++n) _Pragma("unroll") for (int k = 0; k < 2; ++k) \
;         acc[ai][bj][m][n] = __builtin_amdgcn_mfma_f32_16x16x32_bf16(Bt[n][k], At[m][k], acc[ai][bj][m][n], 0, 0, 0); __builtin_amdgcn_s_setprio(0); } while (0)
; #define PG8_WAIT_V(n) asm volatile("s_waitcnt vmcnt(" #n ")" ::: "memory")
; #define PG8_WAIT_L(n) asm volatile("s_waitcnt lgkmcnt(" #n ")" ::: "memory")
; #define PG8_BAR __builtin_amdgcn_s_barrier()
; #define PG8_SCHED __builtin_amdgcn_sched_barrier(0)
; template <class Epi, class Sched, bool ALIGN_EPI = false, bool SP2 = false>
; __device__ __forceinline__ void gemm_phase(PG8_LAS unsigned char* lds, const Gemm g, const Sched& S, const Epi& E) {
;     ...
;             PG8_WAIT_V(8); PG8_WAIT_L(0); PG8_BAR; PG8_MMA(1, 0, At, B0); PG8_MMA(1, 1, At, B1); PG8_BAR; PG8_SCHED;
	v_mfma_f32_16x16x32_bf16 v[60:63], v[128:131], v[176:179], v[60:63]
	v_mfma_f32_16x16x32_bf16 v[56:59], v[136:139], v[176:179], v[56:59]
	v_mfma_f32_16x16x32_bf16 v[44:47], v[128:131], v[190:193], v[44:47]
	v_mfma_f32_16x16x32_bf16 v[40:43], v[136:139], v[190:193], v[40:43]
	v_mfma_f32_16x16x32_bf16 v[28:31], v[128:131], v[214:217], v[28:31]
	v_mfma_f32_16x16x32_bf16 v[24:27], v[136:139], v[214:217], v[24:27]
	v_mfma_f32_16x16x32_bf16 v[12:15], v[128:131], v[222:225], v[12:15]
	v_mfma_f32_16x16x32_bf16 v[8:11], v[136:139], v[222:225], v[8:11]
	v_mfma_f32_16x16x32_bf16 v[60:63], v[132:135], v[184:187], v[60:63]
	v_mfma_f32_16x16x32_bf16 v[56:59], v[140:143], v[184:187], v[56:59]
	v_mfma_f32_16x16x32_bf16 v[44:47], v[132:135], v[210:213], v[44:47]
	v_mfma_f32_16x16x32_bf16 v[40:43], v[140:143], v[210:213], v[40:43]
	v_mfma_f32_16x16x32_bf16 v[28:31], v[132:135], v[218:221], v[28:31]
	v_mfma_f32_16x16x32_bf16 v[24:27], v[140:143], v[218:221], v[24:27]
	v_mfma_f32_16x16x32_bf16 v[12:15], v[132:135], v[226:229], v[12:15]
	v_mfma_f32_16x16x32_bf16 v[8:11], v[140:143], v[226:229], v[8:11]


; #define PG8_MMA(ai, bj, At, Bt) do { __builtin_amdgcn_s_setprio(1); _Pragma("unroll") for (int m = 0; m < 4; ++m) _Pragma("unroll") for (int n = 0; n < 2; ++n) _Pragma("unroll") for (int k = 0; k < 2; ++k) \
;         acc[ai][bj][m][n] = __builtin_amdgcn_mfma_f32_16x16x32_bf16(Bt[n][k], At[m][k], acc[ai][bj][m][n], 0, 0, 0); __builtin_amdgcn_s_setprio(0); } while (0)
; #define PG8_WAIT_V(n) asm volatile("s_waitcnt vmcnt(" #n ")" ::: "memory")
; #define PG8_WAIT_L(n) asm volatile("s_waitcnt lgkmcnt(" #n ")" ::: "memory")
; #define PG8_BAR __builtin_amdgcn_s_barrier()
; #define PG8_SCHED __builtin_amdgcn_sched_barrier(0)
; template <class Epi, class Sched, bool ALIGN_EPI = false, bool SP2 = false>
; __device__ __forceinline__ void gemm_phase(PG8_LAS unsigned char* lds, const Gemm g, const Sched& S, const Epi& E) {
;     ...
;             PG8_WAIT_V(8); PG8_WAIT_L(0); PG8_BAR; PG8_MMA(1, 0, At, B0); PG8_MMA(1, 1, At, B1); PG8_BAR; PG8_SCHED;
	v_mfma_f32_16x16x32_bf16 v[52:55], v[144:147], v[176:179], v[52:55]
	v_mfma_f32_16x16x32_bf16 v[48:51], v[152:155], v[176:179], v[48:51]
	v_mfma_f32_16x16x32_bf16 v[36:39], v[144:147], v[190:193], v[36:39]
	v_mfma_f32_16x16x32_bf16 v[32:35], v[152:155], v[190:193], v[32:35]
	v_mfma_f32_16x16x32_bf16 v[20:23], v[144:147], v[214:217], v[20:23]
	v_mfma_f32_16x16x32_bf16 v[16:19], v[152:155], v[214:217], v[16:19]
	v_mfma_f32_16x16x32_bf16 v[4:7], v[144:147], v[222:225], v[4:7]
	v_mfma_f32_16x16x32_bf16 v[0:3], v[152:155], v[222:225], v[0:3]
	v_mfma_f32_16x16x32_bf16 v[52:55], v[148:151], v[184:187], v[52:55]
	v_mfma_f32_16x16x32_bf16 v[48:51], v[156:159], v[184:187], v[48:51]
	v_mfma_f32_16x16x32_bf16 v[36:39], v[148:151], v[210:213], v[36:39]
	v_mfma_f32_16x16x32_bf16 v[32:35], v[156:159], v[210:213], v[32:35]
	v_mfma_f32_16x16x32_bf16 v[20:23], v[148:151], v[218:221], v[20:23]
	v_mfma_f32_16x16x32_bf16 v[16:19], v[156:159], v[218:221], v[16:19]
	v_mfma_f32_16x16x32_bf16 v[4:7], v[148:151], v[226:229], v[4:7]
	v_mfma_f32_16x16x32_bf16 v[0:3], v[156:159], v[226:229], v[0:3]

; #define PG8_STAGE(bufoff, gbase, voff) do { _Pragma("unroll") for (int _i = 0; _i < 2; ++_i) \
;         __builtin_amdgcn_global_load_lds((const unsigned*)((const char*)(gbase) + (voff)[_i]), (PG8_LAS unsigned*)(lds + (bufoff) + ldsw + _i * 8192), 16, 0, 0); } while (0)
; #define PG8_LDA(dst, b, h) do { _Pragma("unroll") for (int m = 0; m < 4; ++m) _Pragma("unroll") for (int k = 0; k < 2; ++k) dst[m][k] = *(const PG8_LAS bf16x8*)(lds + PG8_SA(b, h) + aoff + m * 2048 + k * 1024); } while (0)
; #define PG8_LDB(dst, b, h) do { _Pragma("unroll") for (int n = 0; n < 2; ++n) _Pragma("unroll") for (int k = 0; k < 2; ++k) dst[n][k] = *(const PG8_LAS bf16x8*)(lds + PG8_SB(b, h) + boff + n * 2048 + k * 1024); } while (0)
; #define PG8_MMA(ai, bj, At, Bt) do { __builtin_amdgcn_s_setprio(1); _Pragma("unroll") for (int m = 0; m < 4; ++m) _Pragma("unroll") for (int n = 0; n < 2; ++n) _Pragma("unroll") for (int k = 0; k < 2; ++k) \
;         acc[ai][bj][m][n] = __builtin_amdgcn_mfma_f32_16x16x32_bf16(Bt[n][k], At[m][k], acc[ai][bj][m][n], 0, 0, 0); __builtin_amdgcn_s_setprio(0); } while (0)
; #define PG8_WAIT_V(n) asm volatile("s_waitcnt vmcnt(" #n ")" ::: "memory")
; #define PG8_WAIT_L(n) asm volatile("s_waitcnt lgkmcnt(" #n ")" ::: "memory")
; #define PG8_BAR __builtin_amdgcn_s_barrier()
; #define PG8_SCHED __builtin_amdgcn_sched_barrier(0)
; template <class Epi, class Sched, bool ALIGN_EPI = false, bool SP2 = false>
; __device__ __forceinline__ void gemm_phase(PG8_LAS unsigned char* lds, const Gemm g, const Sched& S, const Epi& E) {
;     ...
;             PG8_WAIT_V(8); PG8_WAIT_L(0); PG8_BAR; PG8_MMA(1, 0, At, B0); PG8_MMA(1, 1, At, B1); PG8_BAR; PG8_SCHED;
;             PG8_LDB(B0, 1, 0); PG8_LDB(B1, 1, 1); PG8_SCHED; PG8_LDA(At, 1, 0); PG8_STAGE(PG8_SA(0, 1), a2 + hstep, voffA);
	s_barrier
	s_add_i32 s84, 0, 0x18000
	s_add_i32 s85, 0, 0x1c000


; #define PG8_STAGE(bufoff, gbase, voff) do { _Pragma("unroll") for (int _i = 0; _i < 2; ++_i) \
;         __builtin_amdgcn_global_load_lds((const unsigned*)((const char*)(gbase) + (voff)[_i]), (PG8_LAS unsigned*)(lds + (bufoff) + ldsw + _i * 8192), 16, 0, 0); } while (0)
; #define PG8_LDA(dst, b, h) do { _Pragma("unroll") for (int m = 0; m < 4; ++m) _Pragma("unroll") for (int k = 0; k < 2; ++k) dst[m][k] = *(const PG8_LAS bf16x8*)(lds + PG8_SA(b, h) + aoff + m * 2048 + k * 1024); } while (0)
; #define PG8_LDB(dst, b, h) do { _Pragma("unroll") for (int n = 0; n < 2; ++n) _Pragma("unroll") for (int k = 0; k < 2; ++k) dst[n][k] = *(const PG8_LAS bf16x8*)(lds + PG8_SB(b, h) + boff + n * 2048 + k * 1024); } while (0)
; #define PG8_SCHED __builtin_amdgcn_sched_barrier(0)
; template <class Epi, class Sched, bool ALIGN_EPI = false, bool SP2 = false>
; __device__ __forceinline__ void gemm_phase(PG8_LAS unsigned char* lds, const Gemm g, const Sched& S, const Epi& E) {
;     ...
;             PG8_LDB(B0, 1, 0); PG8_LDB(B1, 1, 1); PG8_SCHED; PG8_LDA(At, 1, 0); PG8_STAGE(PG8_SA(0, 1), a2 + hstep, voffA);
	ds_read_b128 v[128:131], v254
	ds_read_b128 v[132:135], v254 offset:1024
	ds_read_b128 v[136:139], v254 offset:2048
	ds_read_b128 v[140:143], v254 offset:3072
	ds_read_b128 v[144:147], v255
	ds_read_b128 v[148:151], v255 offset:1024
	ds_read_b128 v[152:155], v255 offset:2048
	ds_read_b128 v[156:159], v255 offset:3072
	s_add_u32 s58, s58, 0x80000
	s_addc_u32 s59, s59, 0
	s_mov_b32 m0, s65

; #define PG8_STAGE(bufoff, gbase, voff) do { _Pragma("unroll") for (int _i = 0; _i < 2; ++_i) \
;         __builtin_amdgcn_global_load_lds((const unsigned*)((const char*)(gbase) + (voff)[_i]), (PG8_LAS unsigned*)(lds + (bufoff) + ldsw + _i * 8192), 16, 0, 0); } while (0)
; #define PG8_LDA(dst, b, h) do { _Pragma("unroll") for (int m = 0; m < 4; ++m) _Pragma("unroll") for (int k = 0; k < 2; ++k) dst[m][k] = *(const PG8_LAS bf16x8*)(lds + PG8_SA(b, h) + aoff + m * 2048 + k * 1024); } while (0)
; #define PG8_LDB(dst, b, h) do { _Pragma("unroll") for (int n = 0; n < 2; ++n) _Pragma("unroll") for (int k = 0; k < 2; ++k) dst[n][k] = *(const PG8_LAS bf16x8*)(lds + PG8_SB(b, h) + boff + n * 2048 + k * 1024); } while (0)
; #define PG8_SCHED __builtin_amdgcn_sched_barrier(0)
; template <class Epi, class Sched, bool ALIGN_EPI = false, bool SP2 = false>
; __device__ __forceinline__ void gemm_phase(PG8_LAS unsigned char* lds, const Gemm g, const Sched& S, const Epi& E) {
;     ...
;             PG8_LDB(B0, 1, 0); PG8_LDB(B1, 1, 1); PG8_SCHED; PG8_LDA(At, 1, 0); PG8_STAGE(PG8_SA(0, 1), a2 + hstep, voffA);
	ds_read_b128 v[176:179], v207 offset:32768
	ds_read_b128 v[184:187], v207 offset:33792
	ds_read_b128 v[190:193], v207 offset:34816
	ds_read_b128 v[210:213], v207 offset:35840
	ds_read_b128 v[214:217], v207 offset:36864
	ds_read_b128 v[218:221], v207 offset:37888
	ds_read_b128 v[222:225], v207 offset:38912
	ds_read_b128 v[226:229], v207 offset:39936
	global_load_lds_dwordx4 v160, s[58:59]

; #define PG8_STAGE(bufoff, gbase, voff) do { _Pragma("unroll") for (int _i = 0; _i < 2; ++_i) \
;         __builtin_amdgcn_global_load_lds((const unsigned*)((const char*)(gbase) + (voff)[_i]), (PG8_LAS unsigned*)(lds + (bufoff) + ldsw + _i * 8192), 16, 0, 0); } while (0)
; #define PG8_LDA(dst, b, h) do { _Pragma("unroll") for (int m = 0; m < 4; ++m) _Pragma("unroll") for (int k = 0; k < 2; ++k) dst[m][k] = *(const PG8_LAS bf16x8*)(lds + PG8_SA(b, h) + aoff + m * 2048 + k * 1024); } while (0)
; #define PG8_LDB(dst, b, h) do { _Pragma("unroll") for (int n = 0; n < 2; ++n) _Pragma("unroll") for (int k = 0; k < 2; ++k) dst[n][k] = *(const PG8_LAS bf16x8*)(lds + PG8_SB(b, h) + boff + n * 2048 + k * 1024); } while (0)
; #define PG8_MMA(ai, bj, At, Bt) do { __builtin_amdgcn_s_setprio(1); _Pragma("unroll") for (int m = 0; m < 4; ++m) _Pragma("unroll") for (int n = 0; n < 2; ++n) _Pragma("unroll") for (int k = 0; k < 2; ++k) \
;         acc[ai][bj][m][n] = __builtin_amdgcn_mfma_f32_16x16x32_bf16(Bt[n][k], At[m][k], acc[ai][bj][m][n], 0, 0, 0); __builtin_amdgcn_s_setprio(0); } while (0)
; #define PG8_WAIT_V(n) asm volatile("s_waitcnt vmcnt(" #n ")" ::: "memory")
; #define PG8_WAIT_L(n) asm volatile("s_waitcnt lgkmcnt(" #n ")" ::: "memory")
; #define PG8_BAR __builtin_amdgcn_s_barrier()
; #define PG8_SCHED __builtin_amdgcn_sched_barrier(0)
; template <class Epi, class Sched, bool ALIGN_EPI = false, bool SP2 = false>
; __device__ __forceinline__ void gemm_phase(PG8_LAS unsigned char* lds, const Gemm g, const Sched& S, const Epi& E) {
;     ...
;             PG8_LDB(B0, 1, 0); PG8_LDB(B1, 1, 1); PG8_SCHED; PG8_LDA(At, 1, 0); PG8_STAGE(PG8_SA(0, 1), a2 + hstep, voffA);
;             PG8_WAIT_V(8); PG8_WAIT_L(0); PG8_BAR; PG8_MMA(0, 0, At, B0); PG8_MMA(0, 1, At, B1); PG8_BAR; PG8_SCHED;
	s_mov_b32 m0, s67
	s_nop 0
	global_load_lds_dwordx4 v164, s[58:59]
	s_waitcnt vmcnt(8)
	s_waitcnt lgkmcnt(0)

; #define PG8_MMA(ai, bj, At, Bt) do { __builtin_amdgcn_s_setprio(1); _Pragma("unroll") for (int m = 0; m < 4; ++m) _Pragma("unroll") for (int n = 0; n < 2; ++n) _Pragma("unroll") for (int k = 0; k < 2; ++k) \
;         acc[ai][bj][m][n] = __builtin_amdgcn_mfma_f32_16x16x32_bf16(Bt[n][k], At[m][k], acc[ai][bj][m][n], 0, 0, 0); __builtin_amdgcn_s_setprio(0); } while (0)
; #define PG8_WAIT_V(n) asm volatile("s_waitcnt vmcnt(" #n ")" ::: "memory")
; #define PG8_WAIT_L(n) asm volatile("s_waitcnt lgkmcnt(" #n ")" ::: "memory")
; #define PG8_BAR __builtin_amdgcn_s_barrier()
; #define PG8_SCHED __builtin_amdgcn_sched_barrier(0)
; template <class Epi, class Sched, bool ALIGN_EPI = false, bool SP2 = false>
; __device__ __forceinline__ void gemm_phase(PG8_LAS unsigned char* lds, const Gemm g, const Sched& S, const Epi& E) {
;     ...
;             PG8_WAIT_V(8); PG8_WAIT_L(0); PG8_BAR; PG8_MMA(0, 0, At, B0); PG8_MMA(0, 1, At, B1); PG8_BAR; PG8_SCHED;
	s_barrier

; #define PG8_MMA(ai, bj, At, Bt) do { __builtin_amdgcn_s_setprio(1); _Pragma("unroll") for (int m = 0; m < 4; ++m) _Pragma("unroll") for (int n = 0; n < 2; ++n) _Pragma("unroll") for (int k = 0; k < 2; ++k) \
;         acc[ai][bj][m][n] = __builtin_amdgcn_mfma_f32_16x16x32_bf16(Bt[n][k], At[m][k], acc[ai][bj][m][n], 0, 0, 0); __builtin_amdgcn_s_setprio(0); } while (0)
; #define PG8_WAIT_V(n) asm volatile("s_waitcnt vmcnt(" #n ")" ::: "memory")
; #define PG8_WAIT_L(n) asm volatile("s_waitcnt lgkmcnt(" #n ")" ::: "memory")
; #define PG8_BAR __builtin_amdgcn_s_barrier()
; #define PG8_SCHED __builtin_amdgcn_sched_barrier(0)
; template <class Epi, class Sched, bool ALIGN_EPI = false, bool SP2 = false>
; __device__ __forceinline__ void gemm_phase(PG8_LAS unsigned char* lds, const Gemm g, const Sched& S, const Epi& E) {
;     ...
;             PG8_WAIT_V(8); PG8_WAIT_L(0); PG8_BAR; PG8_MMA(0, 0, At, B0); PG8_MMA(0, 1, At, B1); PG8_BAR; PG8_SCHED;
	v_mfma_f32_16x16x32_bf16 v[124:127], v[128:131], v[176:179], v[124:127]
	v_mfma_f32_16x16x32_bf16 v[120:123], v[136:139], v[176:179], v[120:123]
	v_mfma_f32_16x16x32_bf16 v[108:111], v[128:131], v[190:193], v[108:111]
	v_mfma_f32_16x16x32_bf16 v[104:107], v[136:139], v[190:193], v[104:107]
	v_mfma_f32_16x16x32_bf16 v[92:95], v[128:131], v[214:217], v[92:95]
	v_mfma_f32_16x16x32_bf16 v[88:91], v[136:139], v[214:217], v[88:91]
	v_mfma_f32_16x16x32_bf16 v[76:79], v[128:131], v[222:225], v[76:79]
	v_mfma_f32_16x16x32_bf16 v[72:75], v[136:139], v[222:225], v[72:75]
	v_mfma_f32_16x16x32_bf16 v[124:127], v[132:135], v[184:187], v[124:127]
	v_mfma_f32_16x16x32_bf16 v[120:123], v[140:143], v[184:187], v[120:123]
	v_mfma_f32_16x16x32_bf16 v[108:111], v[132:135], v[210:213], v[108:111]
	v_mfma_f32_16x16x32_bf16 v[104:107], v[140:143], v[210:213], v[104:107]
	v_mfma_f32_16x16x32_bf16 v[92:95], v[132:135], v[218:221], v[92:95]
	v_mfma_f32_16x16x32_bf16 v[88:91], v[140:143], v[218:221], v[88:91]
	v_mfma_f32_16x16x32_bf16 v[76:79], v[132:135], v[226:229], v[76:79]
	v_mfma_f32_16x16x32_bf16 v[72:75], v[140:143], v[226:229], v[72:75]


; #define PG8_MMA(ai, bj, At, Bt) do { __builtin_amdgcn_s_setprio(1); _Pragma("unroll") for (int m = 0; m < 4; ++m) _Pragma("unroll") for (int n = 0; n < 2; ++n) _Pragma("unroll") for (int k = 0; k < 2; ++k) \
;         acc[ai][bj][m][n] = __builtin_amdgcn_mfma_f32_16x16x32_bf16(Bt[n][k], At[m][k], acc[ai][bj][m][n], 0, 0, 0); __builtin_amdgcn_s_setprio(0); } while (0)
; #define PG8_WAIT_V(n) asm volatile("s_waitcnt vmcnt(" #n ")" ::: "memory")
; #define PG8_WAIT_L(n) asm volatile("s_waitcnt lgkmcnt(" #n ")" ::: "memory")
; #define PG8_BAR __builtin_amdgcn_s_barrier()
; #define PG8_SCHED __builtin_amdgcn_sched_barrier(0)
; template <class Epi, class Sched, bool ALIGN_EPI = false, bool SP2 = false>
; __device__ __forceinline__ void gemm_phase(PG8_LAS unsigned char* lds, const Gemm g, const Sched& S, const Epi& E) {
;     ...
;             PG8_WAIT_V(8); PG8_WAIT_L(0); PG8_BAR; PG8_MMA(0, 0, At, B0); PG8_MMA(0, 1, At, B1); PG8_BAR; PG8_SCHED;
	v_mfma_f32_16x16x32_bf16 v[116:119], v[144:147], v[176:179], v[116:119]
	v_mfma_f32_16x16x32_bf16 v[112:115], v[152:155], v[176:179], v[112:115]
	v_mfma_f32_16x16x32_bf16 v[100:103], v[144:147], v[190:193], v[100:103]
	v_mfma_f32_16x16x32_bf16 v[96:99], v[152:155], v[190:193], v[96:99]
	v_mfma_f32_16x16x32_bf16 v[84:87], v[144:147], v[214:217], v[84:87]
	v_mfma_f32_16x16x32_bf16 v[80:83], v[152:155], v[214:217], v[80:83]
	v_mfma_f32_16x16x32_bf16 v[68:71], v[144:147], v[222:225], v[68:71]
	v_mfma_f32_16x16x32_bf16 v[64:67], v[152:155], v[222:225], v[64:67]
	v_mfma_f32_16x16x32_bf16 v[116:119], v[148:151], v[184:187], v[116:119]
	v_mfma_f32_16x16x32_bf16 v[112:115], v[156:159], v[184:187], v[112:115]
	v_mfma_f32_16x16x32_bf16 v[100:103], v[148:151], v[210:213], v[100:103]
	v_mfma_f32_16x16x32_bf16 v[96:99], v[156:159], v[210:213], v[96:99]
	v_mfma_f32_16x16x32_bf16 v[84:87], v[148:151], v[218:221], v[84:87]
	v_mfma_f32_16x16x32_bf16 v[80:83], v[156:159], v[218:221], v[80:83]
	v_mfma_f32_16x16x32_bf16 v[68:71], v[148:151], v[226:229], v[68:71]
	v_mfma_f32_16x16x32_bf16 v[64:67], v[156:159], v[226:229], v[64:67]

; #define PG8_STAGE(bufoff, gbase, voff) do { _Pragma("unroll") for (int _i = 0; _i < 2; ++_i) \
;         __builtin_amdgcn_global_load_lds((const unsigned*)((const char*)(gbase) + (voff)[_i]), (PG8_LAS unsigned*)(lds + (bufoff) + ldsw + _i * 8192), 16, 0, 0); } while (0)
; #define PG8_LDA(dst, b, h) do { _Pragma("unroll") for (int m = 0; m < 4; ++m) _Pragma("unroll") for (int k = 0; k < 2; ++k) dst[m][k] = *(const PG8_LAS bf16x8*)(lds + PG8_SA(b, h) + aoff + m * 2048 + k * 1024); } while (0)
; #define PG8_MMA(ai, bj, At, Bt) do { __builtin_amdgcn_s_setprio(1); _Pragma("unroll") for (int m = 0; m < 4; ++m) _Pragma("unroll") for (int n = 0; n < 2; ++n) _Pragma("unroll") for (int k = 0; k < 2; ++k) \
;         acc[ai][bj][m][n] = __builtin_amdgcn_mfma_f32_16x16x32_bf16(Bt[n][k], At[m][k], acc[ai][bj][m][n], 0, 0, 0); __builtin_amdgcn_s_setprio(0); } while (0)
; #define PG8_WAIT_V(n) asm volatile("s_waitcnt vmcnt(" #n ")" ::: "memory")
; #define PG8_WAIT_L(n) asm volatile("s_waitcnt lgkmcnt(" #n ")" ::: "memory")
; #define PG8_BAR __builtin_amdgcn_s_barrier()
; #define PG8_SCHED __builtin_amdgcn_sched_barrier(0)
; template <class Epi, class Sched, bool ALIGN_EPI = false, bool SP2 = false>
; __device__ __forceinline__ void gemm_phase(PG8_LAS unsigned char* lds, const Gemm g, const Sched& S, const Epi& E) {
;     ...
;             PG8_WAIT_V(8); PG8_WAIT_L(0); PG8_BAR; PG8_MMA(0, 0, At, B0); PG8_MMA(0, 1, At, B1); PG8_BAR; PG8_SCHED;
;             PG8_LDA(At, 1, 1); PG8_STAGE(PG8_SB(1, 0), b3, voffB); PG8_STAGE(PG8_SB(1, 1), b3 + hstep, voffB); PG8_STAGE(PG8_SA(1, 0), a3, voffA);
	s_barrier
	s_add_i32 s58, s84, s62

; #define PG8_STAGE(bufoff, gbase, voff) do { _Pragma("unroll") for (int _i = 0; _i < 2; ++_i) \
;         __builtin_amdgcn_global_load_lds((const unsigned*)((const char*)(gbase) + (voff)[_i]), (PG8_LAS unsigned*)(lds + (bufoff) + ldsw + _i * 8192), 16, 0, 0); } while (0)
; #define PG8_LDA(dst, b, h) do { _Pragma("unroll") for (int m = 0; m < 4; ++m) _Pragma("unroll") for (int k = 0; k < 2; ++k) dst[m][k] = *(const PG8_LAS bf16x8*)(lds + PG8_SA(b, h) + aoff + m * 2048 + k * 1024); } while (0)
; template <class Epi, class Sched, bool ALIGN_EPI = false, bool SP2 = false>
; __device__ __forceinline__ void gemm_phase(PG8_LAS unsigned char* lds, const Gemm g, const Sched& S, const Epi& E) {
;     ...
;             PG8_LDA(At, 1, 1); PG8_STAGE(PG8_SB(1, 0), b3, voffB); PG8_STAGE(PG8_SB(1, 1), b3 + hstep, voffB); PG8_STAGE(PG8_SA(1, 0), a3, voffA);
	s_mov_b32 m0, s58
	ds_read_b128 v[176:179], v207 offset:49152
	ds_read_b128 v[184:187], v207 offset:50176
	ds_read_b128 v[190:193], v207 offset:51200
	ds_read_b128 v[210:213], v207 offset:52224
	ds_read_b128 v[214:217], v207 offset:53248
	ds_read_b128 v[218:221], v207 offset:54272
	ds_read_b128 v[222:225], v207 offset:55296
	ds_read_b128 v[226:229], v207 offset:56320
	global_load_lds_dwordx4 v250, s[96:97]
	s_add_i32 m0, s58, 0x2000
	s_add_u32 s12, s12, 0x80080

; #define PG8_STAGE(bufoff, gbase, voff) do { _Pragma("unroll") for (int _i = 0; _i < 2; ++_i) \
;         __builtin_amdgcn_global_load_lds((const unsigned*)((const char*)(gbase) + (voff)[_i]), (PG8_LAS unsigned*)(lds + (bufoff) + ldsw + _i * 8192), 16, 0, 0); } while (0)
; #define PG8_LDA(dst, b, h) do { _Pragma("unroll") for (int m = 0; m < 4; ++m) _Pragma("unroll") for (int k = 0; k < 2; ++k) dst[m][k] = *(const PG8_LAS bf16x8*)(lds + PG8_SA(b, h) + aoff + m * 2048 + k * 1024); } while (0)
; template <class Epi, class Sched, bool ALIGN_EPI = false, bool SP2 = false>
; __device__ __forceinline__ void gemm_phase(PG8_LAS unsigned char* lds, const Gemm g, const Sched& S, const Epi& E) {
;     ...
;             PG8_LDA(At, 1, 1); PG8_STAGE(PG8_SB(1, 0), b3, voffB); PG8_STAGE(PG8_SB(1, 1), b3 + hstep, voffB); PG8_STAGE(PG8_SA(1, 0), a3, voffA);
	s_addc_u32 s13, s13, 0
	s_add_i32 s58, s85, s62
	global_load_lds_dwordx4 v251, s[96:97]

; #define PG8_STAGE(bufoff, gbase, voff) do { _Pragma("unroll") for (int _i = 0; _i < 2; ++_i) \
;         __builtin_amdgcn_global_load_lds((const unsigned*)((const char*)(gbase) + (voff)[_i]), (PG8_LAS unsigned*)(lds + (bufoff) + ldsw + _i * 8192), 16, 0, 0); } while (0)
; #define PG8_LDA(dst, b, h) do { _Pragma("unroll") for (int m = 0; m < 4; ++m) _Pragma("unroll") for (int k = 0; k < 2; ++k) dst[m][k] = *(const PG8_LAS bf16x8*)(lds + PG8_SA(b, h) + aoff + m * 2048 + k * 1024); } while (0)
; template <class Epi, class Sched, bool ALIGN_EPI = false, bool SP2 = false>
; __device__ __forceinline__ void gemm_phase(PG8_LAS unsigned char* lds, const Gemm g, const Sched& S, const Epi& E) {
;     ...
;             PG8_LDA(At, 1, 1); PG8_STAGE(PG8_SB(1, 0), b3, voffB); PG8_STAGE(PG8_SB(1, 1), b3 + hstep, voffB); PG8_STAGE(PG8_SA(1, 0), a3, voffA);
	s_mov_b32 m0, s58
	s_nop 0
	global_load_lds_dwordx4 v162, s[12:13]

; #define PG8_STAGE(bufoff, gbase, voff) do { _Pragma("unroll") for (int _i = 0; _i < 2; ++_i) \
;         __builtin_amdgcn_global_load_lds((const unsigned*)((const char*)(gbase) + (voff)[_i]), (PG8_LAS unsigned*)(lds + (bufoff) + ldsw + _i * 8192), 16, 0, 0); } while (0)
; #define PG8_LDA(dst, b, h) do { _Pragma("unroll") for (int m = 0; m < 4; ++m) _Pragma("unroll") for (int k = 0; k < 2; ++k) dst[m][k] = *(const PG8_LAS bf16x8*)(lds + PG8_SA(b, h) + aoff + m * 2048 + k * 1024); } while (0)
; template <class Epi, class Sched, bool ALIGN_EPI = false, bool SP2 = false>
; __device__ __forceinline__ void gemm_phase(PG8_LAS unsigned char* lds, const Gemm g, const Sched& S, const Epi& E) {
;     ...
;             PG8_LDA(At, 1, 1); PG8_STAGE(PG8_SB(1, 0), b3, voffB); PG8_STAGE(PG8_SB(1, 1), b3 + hstep, voffB); PG8_STAGE(PG8_SA(1, 0), a3, voffA);
	s_add_i32 m0, s58, 0x2000
	s_nop 0
	global_load_lds_dwordx4 v166, s[12:13]

; #define PG8_STAGE(bufoff, gbase, voff) do { _Pragma("unroll") for (int _i = 0; _i < 2; ++_i) \
;         __builtin_amdgcn_global_load_lds((const unsigned*)((const char*)(gbase) + (voff)[_i]), (PG8_LAS unsigned*)(lds + (bufoff) + ldsw + _i * 8192), 16, 0, 0); } while (0)
; #define PG8_LDA(dst, b, h) do { _Pragma("unroll") for (int m = 0; m < 4; ++m) _Pragma("unroll") for (int k = 0; k < 2; ++k) dst[m][k] = *(const PG8_LAS bf16x8*)(lds + PG8_SA(b, h) + aoff + m * 2048 + k * 1024); } while (0)
; template <class Epi, class Sched, bool ALIGN_EPI = false, bool SP2 = false>
; __device__ __forceinline__ void gemm_phase(PG8_LAS unsigned char* lds, const Gemm g, const Sched& S, const Epi& E) {
;     ...
;             PG8_LDA(At, 1, 1); PG8_STAGE(PG8_SB(1, 0), b3, voffB); PG8_STAGE(PG8_SB(1, 1), b3 + hstep, voffB); PG8_STAGE(PG8_SA(1, 0), a3, voffA);
	s_mov_b32 m0, s69
	s_nop 0
	global_load_lds_dwordx4 v252, s[98:99]

; #define PG8_STAGE(bufoff, gbase, voff) do { _Pragma("unroll") for (int _i = 0; _i < 2; ++_i) \
;         __builtin_amdgcn_global_load_lds((const unsigned*)((const char*)(gbase) + (voff)[_i]), (PG8_LAS unsigned*)(lds + (bufoff) + ldsw + _i * 8192), 16, 0, 0); } while (0)
; #define PG8_LDA(dst, b, h) do { _Pragma("unroll") for (int m = 0; m < 4; ++m) _Pragma("unroll") for (int k = 0; k < 2; ++k) dst[m][k] = *(const PG8_LAS bf16x8*)(lds + PG8_SA(b, h) + aoff + m * 2048 + k * 1024); } while (0)
; #define PG8_MMA(ai, bj, At, Bt) do { __builtin_amdgcn_s_setprio(1); _Pragma("unroll") for (int m = 0; m < 4; ++m) _Pragma("unroll") for (int n = 0; n < 2; ++n) _Pragma("unroll") for (int k = 0; k < 2; ++k) \
;         acc[ai][bj][m][n] = __builtin_amdgcn_mfma_f32_16x16x32_bf16(Bt[n][k], At[m][k], acc[ai][bj][m][n], 0, 0, 0); __builtin_amdgcn_s_setprio(0); } while (0)
; #define PG8_WAIT_V(n) asm volatile("s_waitcnt vmcnt(" #n ")" ::: "memory")
; #define PG8_WAIT_L(n) asm volatile("s_waitcnt lgkmcnt(" #n ")" ::: "memory")
; #define PG8_BAR __builtin_amdgcn_s_barrier()
; #define PG8_SCHED __builtin_amdgcn_sched_barrier(0)
; template <class Epi, class Sched, bool ALIGN_EPI = false, bool SP2 = false>
; __device__ __forceinline__ void gemm_phase(PG8_LAS unsigned char* lds, const Gemm g, const Sched& S, const Epi& E) {
;     ...
;             PG8_LDA(At, 1, 1); PG8_STAGE(PG8_SB(1, 0), b3, voffB); PG8_STAGE(PG8_SB(1, 1), b3 + hstep, voffB); PG8_STAGE(PG8_SA(1, 0), a3, voffA);
;             PG8_WAIT_V(8); PG8_WAIT_L(0); PG8_BAR; PG8_MMA(1, 0, At, B0); PG8_MMA(1, 1, At, B1); PG8_BAR; PG8_SCHED;
	s_mov_b32 m0, s70
	s_nop 0
	global_load_lds_dwordx4 v253, s[98:99]
	s_waitcnt vmcnt(8)
	s_waitcnt lgkmcnt(0)

; #define PG8_MMA(ai, bj, At, Bt) do { __builtin_amdgcn_s_setprio(1); _Pragma("unroll") for (int m = 0; m < 4; ++m) _Pragma("unroll") for (int n = 0; n < 2; ++n) _Pragma("unroll") for (int k = 0; k < 2; ++k) \
;         acc[ai][bj][m][n] = __builtin_amdgcn_mfma_f32_16x16x32_bf16(Bt[n][k], At[m][k], acc[ai][bj][m][n], 0, 0, 0); __builtin_amdgcn_s_setprio(0); } while (0)
; #define PG8_WAIT_V(n) asm volatile("s_waitcnt vmcnt(" #n ")" ::: "memory")
; #define PG8_WAIT_L(n) asm volatile("s_waitcnt lgkmcnt(" #n ")" ::: "memory")
; #define PG8_BAR __builtin_amdgcn_s_barrier()
; #define PG8_SCHED __builtin_amdgcn_sched_barrier(0)
; template <class Epi, class Sched, bool ALIGN_EPI = false, bool SP2 = false>
; __device__ __forceinline__ void gemm_phase(PG8_LAS unsigned char* lds, const Gemm g, const Sched& S, const Epi& E) {
;     ...
;             PG8_WAIT_V(8); PG8_WAIT_L(0); PG8_BAR; PG8_MMA(1, 0, At, B0); PG8_MMA(1, 1, At, B1); PG8_BAR; PG8_SCHED;
	s_barrier

; #define PG8_MMA(ai, bj, At, Bt) do { __builtin_amdgcn_s_setprio(1); _Pragma("unroll") for (int m = 0; m < 4; ++m) _Pragma("unroll") for (int n = 0; n < 2; ++n) _Pragma("unroll") for (int k = 0; k < 2; ++k) \
;         acc[ai][bj][m][n] = __builtin_amdgcn_mfma_f32_16x16x32_bf16(Bt[n][k], At[m][k], acc[ai][bj][m][n], 0, 0, 0); __builtin_amdgcn_s_setprio(0); } while (0)
; #define PG8_WAIT_V(n) asm volatile("s_waitcnt vmcnt(" #n ")" ::: "memory")
; #define PG8_WAIT_L(n) asm volatile("s_waitcnt lgkmcnt(" #n ")" ::: "memory")
; #define PG8_BAR __builtin_amdgcn_s_barrier()
; #define PG8_SCHED __builtin_amdgcn_sched_barrier(0)
; template <class Epi, class Sched, bool ALIGN_EPI = false, bool SP2 = false>
; __device__ __forceinline__ void gemm_phase(PG8_LAS unsigned char* lds, const Gemm g, const Sched& S, const Epi& E) {
;     ...
;             PG8_WAIT_V(8); PG8_WAIT_L(0); PG8_BAR; PG8_MMA(1, 0, At, B0); PG8_MMA(1, 1, At, B1); PG8_BAR; PG8_SCHED;
	v_mfma_f32_16x16x32_bf16 v[60:63], v[128:131], v[176:179], v[60:63]
	v_mfma_f32_16x16x32_bf16 v[56:59], v[136:139], v[176:179], v[56:59]
	v_mfma_f32_16x16x32_bf16 v[44:47], v[128:131], v[190:193], v[44:47]
	v_mfma_f32_16x16x32_bf16 v[40:43], v[136:139], v[190:193], v[40:43]
	v_mfma_f32_16x16x32_bf16 v[28:31], v[128:131], v[214:217], v[28:31]
	v_mfma_f32_16x16x32_bf16 v[24:27], v[136:139], v[214:217], v[24:27]
	v_mfma_f32_16x16x32_bf16 v[12:15], v[128:131], v[222:225], v[12:15]
	v_mfma_f32_16x16x32_bf16 v[8:11], v[136:139], v[222:225], v[8:11]
	v_mfma_f32_16x16x32_bf16 v[60:63], v[132:135], v[184:187], v[60:63]
	v_mfma_f32_16x16x32_bf16 v[56:59], v[140:143], v[184:187], v[56:59]
	v_mfma_f32_16x16x32_bf16 v[44:47], v[132:135], v[210:213], v[44:47]
	v_mfma_f32_16x16x32_bf16 v[40:43], v[140:143], v[210:213], v[40:43]
	v_mfma_f32_16x16x32_bf16 v[28:31], v[132:135], v[218:221], v[28:31]
	v_mfma_f32_16x16x32_bf16 v[24:27], v[140:143], v[218:221], v[24:27]
	v_mfma_f32_16x16x32_bf16 v[12:15], v[132:135], v[226:229], v[12:15]
	v_mfma_f32_16x16x32_bf16 v[8:11], v[140:143], v[226:229], v[8:11]


; #define PG8_MMA(ai, bj, At, Bt) do { __builtin_amdgcn_s_setprio(1); _Pragma("unroll") for (int m = 0; m < 4; ++m) _Pragma("unroll") for (int n = 0; n < 2; ++n) _Pragma("unroll") for (int k = 0; k < 2; ++k) \
;         acc[ai][bj][m][n] = __builtin_amdgcn_mfma_f32_16x16x32_bf16(Bt[n][k], At[m][k], acc[ai][bj][m][n], 0, 0, 0); __builtin_amdgcn_s_setprio(0); } while (0)
; #define PG8_WAIT_V(n) asm volatile("s_waitcnt vmcnt(" #n ")" ::: "memory")
; #define PG8_WAIT_L(n) asm volatile("s_waitcnt lgkmcnt(" #n ")" ::: "memory")
; #define PG8_BAR __builtin_amdgcn_s_barrier()
; #define PG8_SCHED __builtin_amdgcn_sched_barrier(0)
; template <class Epi, class Sched, bool ALIGN_EPI = false, bool SP2 = false>
; __device__ __forceinline__ void gemm_phase(PG8_LAS unsigned char* lds, const Gemm g, const Sched& S, const Epi& E) {
;     ...
;             PG8_WAIT_V(8); PG8_WAIT_L(0); PG8_BAR; PG8_MMA(1, 0, At, B0); PG8_MMA(1, 1, At, B1); PG8_BAR; PG8_SCHED;
	v_mfma_f32_16x16x32_bf16 v[52:55], v[144:147], v[176:179], v[52:55]
	v_mfma_f32_16x16x32_bf16 v[48:51], v[152:155], v[176:179], v[48:51]
	v_mfma_f32_16x16x32_bf16 v[36:39], v[144:147], v[190:193], v[36:39]
	v_mfma_f32_16x16x32_bf16 v[32:35], v[152:155], v[190:193], v[32:35]
	v_mfma_f32_16x16x32_bf16 v[20:23], v[144:147], v[214:217], v[20:23]
	v_mfma_f32_16x16x32_bf16 v[16:19], v[152:155], v[214:217], v[16:19]
	v_mfma_f32_16x16x32_bf16 v[4:7], v[144:147], v[222:225], v[4:7]
	v_mfma_f32_16x16x32_bf16 v[0:3], v[152:155], v[222:225], v[0:3]
	v_mfma_f32_16x16x32_bf16 v[52:55], v[148:151], v[184:187], v[52:55]
	v_mfma_f32_16x16x32_bf16 v[48:51], v[156:159], v[184:187], v[48:51]
	v_mfma_f32_16x16x32_bf16 v[36:39], v[148:151], v[210:213], v[36:39]
	v_mfma_f32_16x16x32_bf16 v[32:35], v[156:159], v[210:213], v[32:35]
	v_mfma_f32_16x16x32_bf16 v[20:23], v[148:151], v[218:221], v[20:23]
	v_mfma_f32_16x16x32_bf16 v[16:19], v[156:159], v[218:221], v[16:19]
	v_mfma_f32_16x16x32_bf16 v[4:7], v[148:151], v[226:229], v[4:7]
	v_mfma_f32_16x16x32_bf16 v[0:3], v[156:159], v[226:229], v[0:3]

; #define PG8_STAGE(bufoff, gbase, voff) do { _Pragma("unroll") for (int _i = 0; _i < 2; ++_i) \
;         __builtin_amdgcn_global_load_lds((const unsigned*)((const char*)(gbase) + (voff)[_i]), (PG8_LAS unsigned*)(lds + (bufoff) + ldsw + _i * 8192), 16, 0, 0); } while (0)
; #define PG8_LDA(dst, b, h) do { _Pragma("unroll") for (int m = 0; m < 4; ++m) _Pragma("unroll") for (int k = 0; k < 2; ++k) dst[m][k] = *(const PG8_LAS bf16x8*)(lds + PG8_SA(b, h) + aoff + m * 2048 + k * 1024); } while (0)
; #define PG8_WAIT_V(n) asm volatile("s_waitcnt vmcnt(" #n ")" ::: "memory")
; #define PG8_WAIT_L(n) asm volatile("s_waitcnt lgkmcnt(" #n ")" ::: "memory")
; template <class Epi, class Sched, bool ALIGN_EPI = false, bool SP2 = false>
; __device__ __forceinline__ void gemm_phase(PG8_LAS unsigned char* lds, const Gemm g, const Sched& S, const Epi& E) {
;     ...
;         for (int t = 0; t < nt; t += 2) {
;             const bool last = (t == nt - 2);
;             const char* a1 = cA + (size_t)(t + 1) * kstep;
;             const char* a2 = last ? nA : cA + (size_t)(t + 2) * kstep; const char* b2 = last ? nB : cB + (size_t)(t + 2) * kstep;
;             const char* a3 = a2 + kstep; const char* b3 = b2 + kstep;
;             if (last && has_next) S.a_ready(nxt);
;             if constexpr (SP2) {
;             PG8_LDB(B0, 0, 0); PG8_LDB(B1, 0, 1); PG8_SCHED; PG8_LDA(At, 0, 0); PG8_STAGE(PG8_SA(1, 1), a1 + hstep, voffA);
;             PG8_WAIT_V(8); PG8_WAIT_L(0); PG8_BAR; PG8_MMA(0, 0, At, B0); PG8_MMA(0, 1, At, B1); PG8_BAR; PG8_SCHED;
;             PG8_LDA(At, 0, 1); PG8_STAGE(PG8_SB(0, 0), b2, voffB); PG8_STAGE(PG8_SB(0, 1), b2 + hstep, voffB); PG8_STAGE(PG8_SA(0, 0), a2, voffA);
;             PG8_WAIT_V(8); PG8_WAIT_L(0); PG8_BAR; PG8_MMA(1, 0, At, B0); PG8_MMA(1, 1, At, B1); PG8_BAR; PG8_SCHED;
;             PG8_LDB(B0, 1, 0); PG8_LDB(B1, 1, 1); PG8_SCHED; PG8_LDA(At, 1, 0); PG8_STAGE(PG8_SA(0, 1), a2 + hstep, voffA);
;             PG8_WAIT_V(8); PG8_WAIT_L(0); PG8_BAR; PG8_MMA(0, 0, At, B0); PG8_MMA(0, 1, At, B1); PG8_BAR; PG8_SCHED;
;             PG8_LDA(At, 1, 1); PG8_STAGE(PG8_SB(1, 0), b3, voffB); PG8_STAGE(PG8_SB(1, 1), b3 + hstep, voffB); PG8_STAGE(PG8_SA(1, 0), a3, voffA);
;             PG8_WAIT_V(8); PG8_WAIT_L(0); PG8_BAR; PG8_MMA(1, 0, At, B0); PG8_MMA(1, 1, At, B1); PG8_BAR; PG8_SCHED;
;     ...
;         if constexpr (ALIGN_EPI) { if (wr == 0) PG8_BAR; }
	s_barrier
	s_add_i32 s83, s83, 2
	s_add_u32 s10, s10, 0x100
	s_addc_u32 s11, s11, 0
	s_add_u32 s81, s81, 0x100
	s_addc_u32 s82, s82, 0
	s_cmp_gt_u32 s83, 29
	s_cbranch_scc0 .LBB0_1034
	s_and_b64 vcc, exec, s[40:41]
	s_cbranch_vccz .LBB0_1037
	s_barrier

; #define PG8_STAGE(bufoff, gbase, voff) do { _Pragma("unroll") for (int _i = 0; _i < 2; ++_i) \
;         __builtin_amdgcn_global_load_lds((const unsigned*)((const char*)(gbase) + (voff)[_i]), (PG8_LAS unsigned*)(lds + (bufoff) + ldsw + _i * 8192), 16, 0, 0); } while (0)
; #define PG8_LDA(dst, b, h) do { _Pragma("unroll") for (int m = 0; m < 4; ++m) _Pragma("unroll") for (int k = 0; k < 2; ++k) dst[m][k] = *(const PG8_LAS bf16x8*)(lds + PG8_SA(b, h) + aoff + m * 2048 + k * 1024); } while (0)
; #define PG8_LDB(dst, b, h) do { _Pragma("unroll") for (int n = 0; n < 2; ++n) _Pragma("unroll") for (int k = 0; k < 2; ++k) dst[n][k] = *(const PG8_LAS bf16x8*)(lds + PG8_SB(b, h) + boff + n * 2048 + k * 1024); } while (0)
; #define PG8_SCHED __builtin_amdgcn_sched_barrier(0)
; template <class Epi, class Sched, bool ALIGN_EPI = false, bool SP2 = false>
; __device__ __forceinline__ void gemm_phase(PG8_LAS unsigned char* lds, const Gemm g, const Sched& S, const Epi& E) {
;     ...
;         for (int t = 0; t < nt; t += 2) {
;             const bool last = (t == nt - 2);
;             const char* a1 = cA + (size_t)(t + 1) * kstep;
;             const char* a2 = last ? nA : cA + (size_t)(t + 2) * kstep; const char* b2 = last ? nB : cB + (size_t)(t + 2) * kstep;
;             const char* a3 = a2 + kstep; const char* b3 = b2 + kstep;
;             if (last && has_next) S.a_ready(nxt);
;             if constexpr (SP2) {
;             PG8_LDB(B0, 0, 0); PG8_LDB(B1, 0, 1); PG8_SCHED; PG8_LDA(At, 0, 0); PG8_STAGE(PG8_SA(1, 1), a1 + hstep, voffA);
.LBB0_1114:
	ds_read_b128 v[96:99], v197
	ds_read_b128 v[100:103], v197 offset:1024
	ds_read_b128 v[104:107], v197 offset:2048
	ds_read_b128 v[112:115], v197 offset:3072
	ds_read_b128 v[144:147], v198
	ds_read_b128 v[148:151], v198 offset:1024
	ds_read_b128 v[152:155], v198 offset:2048
	ds_read_b128 v[172:175], v198 offset:3072
	s_add_u32 s50, s48, 0xffe00080
	s_addc_u32 s51, s49, -1
	s_cmpk_eq_i32 s73, 0x7c
	s_cselect_b32 s53, s43, s51
	s_cselect_b32 s52, s69, s50
	s_cselect_b32 s51, s41, s72
	s_cselect_b32 s50, s70, s71

; #define PG8_STAGE(bufoff, gbase, voff) do { _Pragma("unroll") for (int _i = 0; _i < 2; ++_i) \
;         __builtin_amdgcn_global_load_lds((const unsigned*)((const char*)(gbase) + (voff)[_i]), (PG8_LAS unsigned*)(lds + (bufoff) + ldsw + _i * 8192), 16, 0, 0); } while (0)
; #define PG8_LDA(dst, b, h) do { _Pragma("unroll") for (int m = 0; m < 4; ++m) _Pragma("unroll") for (int k = 0; k < 2; ++k) dst[m][k] = *(const PG8_LAS bf16x8*)(lds + PG8_SA(b, h) + aoff + m * 2048 + k * 1024); } while (0)
; #define PG8_LDB(dst, b, h) do { _Pragma("unroll") for (int n = 0; n < 2; ++n) _Pragma("unroll") for (int k = 0; k < 2; ++k) dst[n][k] = *(const PG8_LAS bf16x8*)(lds + PG8_SB(b, h) + boff + n * 2048 + k * 1024); } while (0)
; #define PG8_SCHED __builtin_amdgcn_sched_barrier(0)
; template <class Epi, class Sched, bool ALIGN_EPI = false, bool SP2 = false>
; __device__ __forceinline__ void gemm_phase(PG8_LAS unsigned char* lds, const Gemm g, const Sched& S, const Epi& E) {
;     ...
;             PG8_LDB(B0, 0, 0); PG8_LDB(B1, 0, 1); PG8_SCHED; PG8_LDA(At, 0, 0); PG8_STAGE(PG8_SA(1, 1), a1 + hstep, voffA);
	s_add_i32 m0, s56, 0xc000
	ds_read_b128 v[176:179], v199
	ds_read_b128 v[180:183], v199 offset:1024
	ds_read_b128 v[184:187], v199 offset:2048
	ds_read_b128 v[188:191], v199 offset:3072
	ds_read_b128 v[202:205], v199 offset:4096
	ds_read_b128 v[206:209], v199 offset:5120
	ds_read_b128 v[210:213], v199 offset:6144
	ds_read_b128 v[214:217], v199 offset:7168
	global_load_lds_dwordx4 v164, s[48:49]

; #define PG8_STAGE(bufoff, gbase, voff) do { _Pragma("unroll") for (int _i = 0; _i < 2; ++_i) \
;         __builtin_amdgcn_global_load_lds((const unsigned*)((const char*)(gbase) + (voff)[_i]), (PG8_LAS unsigned*)(lds + (bufoff) + ldsw + _i * 8192), 16, 0, 0); } while (0)
; #define PG8_LDA(dst, b, h) do { _Pragma("unroll") for (int m = 0; m < 4; ++m) _Pragma("unroll") for (int k = 0; k < 2; ++k) dst[m][k] = *(const PG8_LAS bf16x8*)(lds + PG8_SA(b, h) + aoff + m * 2048 + k * 1024); } while (0)
; #define PG8_LDB(dst, b, h) do { _Pragma("unroll") for (int n = 0; n < 2; ++n) _Pragma("unroll") for (int k = 0; k < 2; ++k) dst[n][k] = *(const PG8_LAS bf16x8*)(lds + PG8_SB(b, h) + boff + n * 2048 + k * 1024); } while (0)
; #define PG8_MMA(ai, bj, At, Bt) do { __builtin_amdgcn_s_setprio(1); _Pragma("unroll") for (int m = 0; m < 4; ++m) _Pragma("unroll") for (int n = 0; n < 2; ++n) _Pragma("unroll") for (int k = 0; k < 2; ++k) \
;         acc[ai][bj][m][n] = __builtin_amdgcn_mfma_f32_16x16x32_bf16(Bt[n][k], At[m][k], acc[ai][bj][m][n], 0, 0, 0); __builtin_amdgcn_s_setprio(0); } while (0)
; #define PG8_WAIT_V(n) asm volatile("s_waitcnt vmcnt(" #n ")" ::: "memory")
; #define PG8_WAIT_L(n) asm volatile("s_waitcnt lgkmcnt(" #n ")" ::: "memory")
; #define PG8_BAR __builtin_amdgcn_s_barrier()
; #define PG8_SCHED __builtin_amdgcn_sched_barrier(0)
; template <class Epi, class Sched, bool ALIGN_EPI = false, bool SP2 = false>
; __device__ __forceinline__ void gemm_phase(PG8_LAS unsigned char* lds, const Gemm g, const Sched& S, const Epi& E) {
;     ...
;             PG8_LDB(B0, 0, 0); PG8_LDB(B1, 0, 1); PG8_SCHED; PG8_LDA(At, 0, 0); PG8_STAGE(PG8_SA(1, 1), a1 + hstep, voffA);
;             PG8_WAIT_V(8); PG8_WAIT_L(0); PG8_BAR; PG8_MMA(0, 0, At, B0); PG8_MMA(0, 1, At, B1); PG8_BAR; PG8_SCHED;
	s_add_i32 m0, s56, 0xe000
	s_nop 0
	global_load_lds_dwordx4 v166, s[48:49]
	s_waitcnt vmcnt(8)
	s_waitcnt lgkmcnt(0)

; #define PG8_MMA(ai, bj, At, Bt) do { __builtin_amdgcn_s_setprio(1); _Pragma("unroll") for (int m = 0; m < 4; ++m) _Pragma("unroll") for (int n = 0; n < 2; ++n) _Pragma("unroll") for (int k = 0; k < 2; ++k) \
;         acc[ai][bj][m][n] = __builtin_amdgcn_mfma_f32_16x16x32_bf16(Bt[n][k], At[m][k], acc[ai][bj][m][n], 0, 0, 0); __builtin_amdgcn_s_setprio(0); } while (0)
; #define PG8_WAIT_V(n) asm volatile("s_waitcnt vmcnt(" #n ")" ::: "memory")
; #define PG8_WAIT_L(n) asm volatile("s_waitcnt lgkmcnt(" #n ")" ::: "memory")
; #define PG8_BAR __builtin_amdgcn_s_barrier()
; #define PG8_SCHED __builtin_amdgcn_sched_barrier(0)
; template <class Epi, class Sched, bool ALIGN_EPI = false, bool SP2 = false>
; __device__ __forceinline__ void gemm_phase(PG8_LAS unsigned char* lds, const Gemm g, const Sched& S, const Epi& E) {
;     ...
;             PG8_WAIT_V(8); PG8_WAIT_L(0); PG8_BAR; PG8_MMA(0, 0, At, B0); PG8_MMA(0, 1, At, B1); PG8_BAR; PG8_SCHED;
	s_barrier

; #define PG8_MMA(ai, bj, At, Bt) do { __builtin_amdgcn_s_setprio(1); _Pragma("unroll") for (int m = 0; m < 4; ++m) _Pragma("unroll") for (int n = 0; n < 2; ++n) _Pragma("unroll") for (int k = 0; k < 2; ++k) \
;         acc[ai][bj][m][n] = __builtin_amdgcn_mfma_f32_16x16x32_bf16(Bt[n][k], At[m][k], acc[ai][bj][m][n], 0, 0, 0); __builtin_amdgcn_s_setprio(0); } while (0)
; #define PG8_WAIT_V(n) asm volatile("s_waitcnt vmcnt(" #n ")" ::: "memory")
; #define PG8_WAIT_L(n) asm volatile("s_waitcnt lgkmcnt(" #n ")" ::: "memory")
; #define PG8_BAR __builtin_amdgcn_s_barrier()
; #define PG8_SCHED __builtin_amdgcn_sched_barrier(0)
; template <class Epi, class Sched, bool ALIGN_EPI = false, bool SP2 = false>
; __device__ __forceinline__ void gemm_phase(PG8_LAS unsigned char* lds, const Gemm g, const Sched& S, const Epi& E) {
;     ...
;             PG8_WAIT_V(8); PG8_WAIT_L(0); PG8_BAR; PG8_MMA(0, 0, At, B0); PG8_MMA(0, 1, At, B1); PG8_BAR; PG8_SCHED;
	v_mfma_f32_16x16x32_bf16 v[140:143], v[96:99], v[176:179], v[140:143]
	v_mfma_f32_16x16x32_bf16 v[136:139], v[104:107], v[176:179], v[136:139]
	v_mfma_f32_16x16x32_bf16 v[124:127], v[96:99], v[184:187], v[124:127]
	v_mfma_f32_16x16x32_bf16 v[120:123], v[104:107], v[184:187], v[120:123]
	v_mfma_f32_16x16x32_bf16 v[92:95], v[96:99], v[202:205], v[92:95]
	v_mfma_f32_16x16x32_bf16 v[88:91], v[104:107], v[202:205], v[88:91]
	v_mfma_f32_16x16x32_bf16 v[76:79], v[96:99], v[210:213], v[76:79]
	v_mfma_f32_16x16x32_bf16 v[72:75], v[104:107], v[210:213], v[72:75]
	v_mfma_f32_16x16x32_bf16 v[140:143], v[100:103], v[180:183], v[140:143]
	v_mfma_f32_16x16x32_bf16 v[136:139], v[112:115], v[180:183], v[136:139]
	v_mfma_f32_16x16x32_bf16 v[124:127], v[100:103], v[188:191], v[124:127]
	v_mfma_f32_16x16x32_bf16 v[120:123], v[112:115], v[188:191], v[120:123]
	v_mfma_f32_16x16x32_bf16 v[92:95], v[100:103], v[206:209], v[92:95]
	v_mfma_f32_16x16x32_bf16 v[88:91], v[112:115], v[206:209], v[88:91]
	v_mfma_f32_16x16x32_bf16 v[76:79], v[100:103], v[214:217], v[76:79]
	v_mfma_f32_16x16x32_bf16 v[72:75], v[112:115], v[214:217], v[72:75]


; #define PG8_MMA(ai, bj, At, Bt) do { __builtin_amdgcn_s_setprio(1); _Pragma("unroll") for (int m = 0; m < 4; ++m) _Pragma("unroll") for (int n = 0; n < 2; ++n) _Pragma("unroll") for (int k = 0; k < 2; ++k) \
;         acc[ai][bj][m][n] = __builtin_amdgcn_mfma_f32_16x16x32_bf16(Bt[n][k], At[m][k], acc[ai][bj][m][n], 0, 0, 0); __builtin_amdgcn_s_setprio(0); } while (0)
; #define PG8_WAIT_V(n) asm volatile("s_waitcnt vmcnt(" #n ")" ::: "memory")
; #define PG8_WAIT_L(n) asm volatile("s_waitcnt lgkmcnt(" #n ")" ::: "memory")
; #define PG8_BAR __builtin_amdgcn_s_barrier()
; #define PG8_SCHED __builtin_amdgcn_sched_barrier(0)
; template <class Epi, class Sched, bool ALIGN_EPI = false, bool SP2 = false>
; __device__ __forceinline__ void gemm_phase(PG8_LAS unsigned char* lds, const Gemm g, const Sched& S, const Epi& E) {
;     ...
;             PG8_WAIT_V(8); PG8_WAIT_L(0); PG8_BAR; PG8_MMA(0, 0, At, B0); PG8_MMA(0, 1, At, B1); PG8_BAR; PG8_SCHED;
	v_mfma_f32_16x16x32_bf16 v[132:135], v[144:147], v[176:179], v[132:135]
	v_mfma_f32_16x16x32_bf16 v[128:131], v[152:155], v[176:179], v[128:131]
	v_mfma_f32_16x16x32_bf16 v[116:119], v[144:147], v[184:187], v[116:119]
	v_mfma_f32_16x16x32_bf16 v[108:111], v[152:155], v[184:187], v[108:111]
	v_mfma_f32_16x16x32_bf16 v[84:87], v[144:147], v[202:205], v[84:87]
	v_mfma_f32_16x16x32_bf16 v[80:83], v[152:155], v[202:205], v[80:83]
	v_mfma_f32_16x16x32_bf16 v[68:71], v[144:147], v[210:213], v[68:71]
	v_mfma_f32_16x16x32_bf16 v[64:67], v[152:155], v[210:213], v[64:67]
	v_mfma_f32_16x16x32_bf16 v[132:135], v[148:151], v[180:183], v[132:135]
	v_mfma_f32_16x16x32_bf16 v[128:131], v[172:175], v[180:183], v[128:131]
	v_mfma_f32_16x16x32_bf16 v[116:119], v[148:151], v[188:191], v[116:119]
	v_mfma_f32_16x16x32_bf16 v[108:111], v[172:175], v[188:191], v[108:111]
	v_mfma_f32_16x16x32_bf16 v[84:87], v[148:151], v[206:209], v[84:87]
	v_mfma_f32_16x16x32_bf16 v[80:83], v[172:175], v[206:209], v[80:83]
	v_mfma_f32_16x16x32_bf16 v[68:71], v[148:151], v[214:217], v[68:71]
	v_mfma_f32_16x16x32_bf16 v[64:67], v[172:175], v[214:217], v[64:67]

; #define PG8_STAGE(bufoff, gbase, voff) do { _Pragma("unroll") for (int _i = 0; _i < 2; ++_i) \
;         __builtin_amdgcn_global_load_lds((const unsigned*)((const char*)(gbase) + (voff)[_i]), (PG8_LAS unsigned*)(lds + (bufoff) + ldsw + _i * 8192), 16, 0, 0); } while (0)
; #define PG8_LDA(dst, b, h) do { _Pragma("unroll") for (int m = 0; m < 4; ++m) _Pragma("unroll") for (int k = 0; k < 2; ++k) dst[m][k] = *(const PG8_LAS bf16x8*)(lds + PG8_SA(b, h) + aoff + m * 2048 + k * 1024); } while (0)
; #define PG8_MMA(ai, bj, At, Bt) do { __builtin_amdgcn_s_setprio(1); _Pragma("unroll") for (int m = 0; m < 4; ++m) _Pragma("unroll") for (int n = 0; n < 2; ++n) _Pragma("unroll") for (int k = 0; k < 2; ++k) \
;         acc[ai][bj][m][n] = __builtin_amdgcn_mfma_f32_16x16x32_bf16(Bt[n][k], At[m][k], acc[ai][bj][m][n], 0, 0, 0); __builtin_amdgcn_s_setprio(0); } while (0)
; #define PG8_WAIT_V(n) asm volatile("s_waitcnt vmcnt(" #n ")" ::: "memory")
; #define PG8_WAIT_L(n) asm volatile("s_waitcnt lgkmcnt(" #n ")" ::: "memory")
; #define PG8_BAR __builtin_amdgcn_s_barrier()
; #define PG8_SCHED __builtin_amdgcn_sched_barrier(0)
; template <class Epi, class Sched, bool ALIGN_EPI = false, bool SP2 = false>
; __device__ __forceinline__ void gemm_phase(PG8_LAS unsigned char* lds, const Gemm g, const Sched& S, const Epi& E) {
;     ...
;             PG8_WAIT_V(8); PG8_WAIT_L(0); PG8_BAR; PG8_MMA(0, 0, At, B0); PG8_MMA(0, 1, At, B1); PG8_BAR; PG8_SCHED;
;             PG8_LDA(At, 0, 1); PG8_STAGE(PG8_SB(0, 0), b2, voffB); PG8_STAGE(PG8_SB(0, 1), b2 + hstep, voffB); PG8_STAGE(PG8_SA(0, 0), a2, voffA);
	s_barrier
	s_add_i32 s74, s65, s55
	s_mov_b64 s[96:97], s[50:51]

; #define PG8_STAGE(bufoff, gbase, voff) do { _Pragma("unroll") for (int _i = 0; _i < 2; ++_i) \
;         __builtin_amdgcn_global_load_lds((const unsigned*)((const char*)(gbase) + (voff)[_i]), (PG8_LAS unsigned*)(lds + (bufoff) + ldsw + _i * 8192), 16, 0, 0); } while (0)
; #define PG8_LDA(dst, b, h) do { _Pragma("unroll") for (int m = 0; m < 4; ++m) _Pragma("unroll") for (int k = 0; k < 2; ++k) dst[m][k] = *(const PG8_LAS bf16x8*)(lds + PG8_SA(b, h) + aoff + m * 2048 + k * 1024); } while (0)
; template <class Epi, class Sched, bool ALIGN_EPI = false, bool SP2 = false>
; __device__ __forceinline__ void gemm_phase(PG8_LAS unsigned char* lds, const Gemm g, const Sched& S, const Epi& E) {
;     ...
;             PG8_LDA(At, 0, 1); PG8_STAGE(PG8_SB(0, 0), b2, voffB); PG8_STAGE(PG8_SB(0, 1), b2 + hstep, voffB); PG8_STAGE(PG8_SA(0, 0), a2, voffA);
	s_mov_b32 m0, s74
	ds_read_b128 v[176:179], v199 offset:16384
	ds_read_b128 v[180:183], v199 offset:17408
	ds_read_b128 v[184:187], v199 offset:18432
	ds_read_b128 v[188:191], v199 offset:19456
	ds_read_b128 v[202:205], v199 offset:20480
	ds_read_b128 v[206:209], v199 offset:21504
	ds_read_b128 v[210:213], v199 offset:22528
	ds_read_b128 v[214:217], v199 offset:23552
	global_load_lds_dwordx4 v158, s[50:51]
	s_add_i32 m0, s74, 0x2000
	s_add_u32 s74, s50, 0x200000

; #define PG8_STAGE(bufoff, gbase, voff) do { _Pragma("unroll") for (int _i = 0; _i < 2; ++_i) \
;         __builtin_amdgcn_global_load_lds((const unsigned*)((const char*)(gbase) + (voff)[_i]), (PG8_LAS unsigned*)(lds + (bufoff) + ldsw + _i * 8192), 16, 0, 0); } while (0)
; #define PG8_LDA(dst, b, h) do { _Pragma("unroll") for (int m = 0; m < 4; ++m) _Pragma("unroll") for (int k = 0; k < 2; ++k) dst[m][k] = *(const PG8_LAS bf16x8*)(lds + PG8_SA(b, h) + aoff + m * 2048 + k * 1024); } while (0)
; template <class Epi, class Sched, bool ALIGN_EPI = false, bool SP2 = false>
; __device__ __forceinline__ void gemm_phase(PG8_LAS unsigned char* lds, const Gemm g, const Sched& S, const Epi& E) {
;     ...
;             PG8_LDA(At, 0, 1); PG8_STAGE(PG8_SB(0, 0), b2, voffB); PG8_STAGE(PG8_SB(0, 1), b2 + hstep, voffB); PG8_STAGE(PG8_SA(0, 0), a2, voffA);
	s_addc_u32 s75, s51, 0
	s_add_i32 s76, s67, s55
	global_load_lds_dwordx4 v162, s[50:51]

; #define PG8_STAGE(bufoff, gbase, voff) do { _Pragma("unroll") for (int _i = 0; _i < 2; ++_i) \
;         __builtin_amdgcn_global_load_lds((const unsigned*)((const char*)(gbase) + (voff)[_i]), (PG8_LAS unsigned*)(lds + (bufoff) + ldsw + _i * 8192), 16, 0, 0); } while (0)
; #define PG8_LDA(dst, b, h) do { _Pragma("unroll") for (int m = 0; m < 4; ++m) _Pragma("unroll") for (int k = 0; k < 2; ++k) dst[m][k] = *(const PG8_LAS bf16x8*)(lds + PG8_SA(b, h) + aoff + m * 2048 + k * 1024); } while (0)
; template <class Epi, class Sched, bool ALIGN_EPI = false, bool SP2 = false>
; __device__ __forceinline__ void gemm_phase(PG8_LAS unsigned char* lds, const Gemm g, const Sched& S, const Epi& E) {
;     ...
;             PG8_LDA(At, 0, 1); PG8_STAGE(PG8_SB(0, 0), b2, voffB); PG8_STAGE(PG8_SB(0, 1), b2 + hstep, voffB); PG8_STAGE(PG8_SA(0, 0), a2, voffA);
	s_mov_b32 m0, s76
	s_nop 0
	global_load_lds_dwordx4 v158, s[74:75]

; #define PG8_STAGE(bufoff, gbase, voff) do { _Pragma("unroll") for (int _i = 0; _i < 2; ++_i) \
;         __builtin_amdgcn_global_load_lds((const unsigned*)((const char*)(gbase) + (voff)[_i]), (PG8_LAS unsigned*)(lds + (bufoff) + ldsw + _i * 8192), 16, 0, 0); } while (0)
; #define PG8_LDA(dst, b, h) do { _Pragma("unroll") for (int m = 0; m < 4; ++m) _Pragma("unroll") for (int k = 0; k < 2; ++k) dst[m][k] = *(const PG8_LAS bf16x8*)(lds + PG8_SA(b, h) + aoff + m * 2048 + k * 1024); } while (0)
; template <class Epi, class Sched, bool ALIGN_EPI = false, bool SP2 = false>
; __device__ __forceinline__ void gemm_phase(PG8_LAS unsigned char* lds, const Gemm g, const Sched& S, const Epi& E) {
;     ...
;             PG8_LDA(At, 0, 1); PG8_STAGE(PG8_SB(0, 0), b2, voffB); PG8_STAGE(PG8_SB(0, 1), b2 + hstep, voffB); PG8_STAGE(PG8_SA(0, 0), a2, voffA);
	s_add_i32 m0, s76, 0x2000
	s_nop 0
	global_load_lds_dwordx4 v162, s[74:75]
	s_mov_b64 s[98:99], s[52:53]

; #define PG8_STAGE(bufoff, gbase, voff) do { _Pragma("unroll") for (int _i = 0; _i < 2; ++_i) \
;         __builtin_amdgcn_global_load_lds((const unsigned*)((const char*)(gbase) + (voff)[_i]), (PG8_LAS unsigned*)(lds + (bufoff) + ldsw + _i * 8192), 16, 0, 0); } while (0)
; #define PG8_LDA(dst, b, h) do { _Pragma("unroll") for (int m = 0; m < 4; ++m) _Pragma("unroll") for (int k = 0; k < 2; ++k) dst[m][k] = *(const PG8_LAS bf16x8*)(lds + PG8_SA(b, h) + aoff + m * 2048 + k * 1024); } while (0)
; #define PG8_MMA(ai, bj, At, Bt) do { __builtin_amdgcn_s_setprio(1); _Pragma("unroll") for (int m = 0; m < 4; ++m) _Pragma("unroll") for (int n = 0; n < 2; ++n) _Pragma("unroll") for (int k = 0; k < 2; ++k) \
;         acc[ai][bj][m][n] = __builtin_amdgcn_mfma_f32_16x16x32_bf16(Bt[n][k], At[m][k], acc[ai][bj][m][n], 0, 0, 0); __builtin_amdgcn_s_setprio(0); } while (0)
; #define PG8_WAIT_V(n) asm volatile("s_waitcnt vmcnt(" #n ")" ::: "memory")
; #define PG8_WAIT_L(n) asm volatile("s_waitcnt lgkmcnt(" #n ")" ::: "memory")
; #define PG8_BAR __builtin_amdgcn_s_barrier()
; #define PG8_SCHED __builtin_amdgcn_sched_barrier(0)
; template <class Epi, class Sched, bool ALIGN_EPI = false, bool SP2 = false>
; __device__ __forceinline__ void gemm_phase(PG8_LAS unsigned char* lds, const Gemm g, const Sched& S, const Epi& E) {
;     ...
;             PG8_LDA(At, 0, 1); PG8_STAGE(PG8_SB(0, 0), b2, voffB); PG8_STAGE(PG8_SB(0, 1), b2 + hstep, voffB); PG8_STAGE(PG8_SA(0, 0), a2, voffA);
;             PG8_WAIT_V(8); PG8_WAIT_L(0); PG8_BAR; PG8_MMA(1, 0, At, B0); PG8_MMA(1, 1, At, B1); PG8_BAR; PG8_SCHED;
	s_mov_b32 m0, s56
	s_nop 0
	global_load_lds_dwordx4 v156, s[52:53]
	s_mov_b32 m0, s57
	s_nop 0
	global_load_lds_dwordx4 v160, s[52:53]
	s_waitcnt vmcnt(8)
	s_waitcnt lgkmcnt(0)

; #define PG8_MMA(ai, bj, At, Bt) do { __builtin_amdgcn_s_setprio(1); _Pragma("unroll") for (int m = 0; m < 4; ++m) _Pragma("unroll") for (int n = 0; n < 2; ++n) _Pragma("unroll") for (int k = 0; k < 2; ++k) \
;         acc[ai][bj][m][n] = __builtin_amdgcn_mfma_f32_16x16x32_bf16(Bt[n][k], At[m][k], acc[ai][bj][m][n], 0, 0, 0); __builtin_amdgcn_s_setprio(0); } while (0)
; #define PG8_WAIT_V(n) asm volatile("s_waitcnt vmcnt(" #n ")" ::: "memory")
; #define PG8_WAIT_L(n) asm volatile("s_waitcnt lgkmcnt(" #n ")" ::: "memory")
; #define PG8_BAR __builtin_amdgcn_s_barrier()
; #define PG8_SCHED __builtin_amdgcn_sched_barrier(0)
; template <class Epi, class Sched, bool ALIGN_EPI = false, bool SP2 = false>
; __device__ __forceinline__ void gemm_phase(PG8_LAS unsigned char* lds, const Gemm g, const Sched& S, const Epi& E) {
;     ...
;             PG8_WAIT_V(8); PG8_WAIT_L(0); PG8_BAR; PG8_MMA(1, 0, At, B0); PG8_MMA(1, 1, At, B1); PG8_BAR; PG8_SCHED;
	s_barrier

; #define PG8_MMA(ai, bj, At, Bt) do { __builtin_amdgcn_s_setprio(1); _Pragma("unroll") for (int m = 0; m < 4; ++m) _Pragma("unroll") for (int n = 0; n < 2; ++n) _Pragma("unroll") for (int k = 0; k < 2; ++k) \
;         acc[ai][bj][m][n] = __builtin_amdgcn_mfma_f32_16x16x32_bf16(Bt[n][k], At[m][k], acc[ai][bj][m][n], 0, 0, 0); __builtin_amdgcn_s_setprio(0); } while (0)
; #define PG8_WAIT_V(n) asm volatile("s_waitcnt vmcnt(" #n ")" ::: "memory")
; #define PG8_WAIT_L(n) asm volatile("s_waitcnt lgkmcnt(" #n ")" ::: "memory")
; #define PG8_BAR __builtin_amdgcn_s_barrier()
; #define PG8_SCHED __builtin_amdgcn_sched_barrier(0)
; template <class Epi, class Sched, bool ALIGN_EPI = false, bool SP2 = false>
; __device__ __forceinline__ void gemm_phase(PG8_LAS unsigned char* lds, const Gemm g, const Sched& S, const Epi& E) {
;     ...
;             PG8_WAIT_V(8); PG8_WAIT_L(0); PG8_BAR; PG8_MMA(1, 0, At, B0); PG8_MMA(1, 1, At, B1); PG8_BAR; PG8_SCHED;
	v_mfma_f32_16x16x32_bf16 v[60:63], v[96:99], v[176:179], v[60:63]
	v_mfma_f32_16x16x32_bf16 v[56:59], v[104:107], v[176:179], v[56:59]
	v_mfma_f32_16x16x32_bf16 v[44:47], v[96:99], v[184:187], v[44:47]
	v_mfma_f32_16x16x32_bf16 v[40:43], v[104:107], v[184:187], v[40:43]
	v_mfma_f32_16x16x32_bf16 v[28:31], v[96:99], v[202:205], v[28:31]
	v_mfma_f32_16x16x32_bf16 v[24:27], v[104:107], v[202:205], v[24:27]
	v_mfma_f32_16x16x32_bf16 v[12:15], v[96:99], v[210:213], v[12:15]
	v_mfma_f32_16x16x32_bf16 v[8:11], v[104:107], v[210:213], v[8:11]
	v_mfma_f32_16x16x32_bf16 v[60:63], v[100:103], v[180:183], v[60:63]
	v_mfma_f32_16x16x32_bf16 v[56:59], v[112:115], v[180:183], v[56:59]
	v_mfma_f32_16x16x32_bf16 v[44:47], v[100:103], v[188:191], v[44:47]
	v_mfma_f32_16x16x32_bf16 v[40:43], v[112:115], v[188:191], v[40:43]
	v_mfma_f32_16x16x32_bf16 v[28:31], v[100:103], v[206:209], v[28:31]
	v_mfma_f32_16x16x32_bf16 v[24:27], v[112:115], v[206:209], v[24:27]
	v_mfma_f32_16x16x32_bf16 v[12:15], v[100:103], v[214:217], v[12:15]
	v_mfma_f32_16x16x32_bf16 v[8:11], v[112:115], v[214:217], v[8:11]


; #define PG8_MMA(ai, bj, At, Bt) do { __builtin_amdgcn_s_setprio(1); _Pragma("unroll") for (int m = 0; m < 4; ++m) _Pragma("unroll") for (int n = 0; n < 2; ++n) _Pragma("unroll") for (int k = 0; k < 2; ++k) \
;         acc[ai][bj][m][n] = __builtin_amdgcn_mfma_f32_16x16x32_bf16(Bt[n][k], At[m][k], acc[ai][bj][m][n], 0, 0, 0); __builtin_amdgcn_s_setprio(0); } while (0)
; #define PG8_WAIT_V(n) asm volatile("s_waitcnt vmcnt(" #n ")" ::: "memory")
; #define PG8_WAIT_L(n) asm volatile("s_waitcnt lgkmcnt(" #n ")" ::: "memory")
; #define PG8_BAR __builtin_amdgcn_s_barrier()
; #define PG8_SCHED __builtin_amdgcn_sched_barrier(0)
; template <class Epi, class Sched, bool ALIGN_EPI = false, bool SP2 = false>
; __device__ __forceinline__ void gemm_phase(PG8_LAS unsigned char* lds, const Gemm g, const Sched& S, const Epi& E) {
;     ...
;             PG8_WAIT_V(8); PG8_WAIT_L(0); PG8_BAR; PG8_MMA(1, 0, At, B0); PG8_MMA(1, 1, At, B1); PG8_BAR; PG8_SCHED;
	v_mfma_f32_16x16x32_bf16 v[52:55], v[144:147], v[176:179], v[52:55]
	v_mfma_f32_16x16x32_bf16 v[48:51], v[152:155], v[176:179], v[48:51]
	v_mfma_f32_16x16x32_bf16 v[36:39], v[144:147], v[184:187], v[36:39]
	v_mfma_f32_16x16x32_bf16 v[32:35], v[152:155], v[184:187], v[32:35]
	v_mfma_f32_16x16x32_bf16 v[20:23], v[144:147], v[202:205], v[20:23]
	v_mfma_f32_16x16x32_bf16 v[16:19], v[152:155], v[202:205], v[16:19]
	v_mfma_f32_16x16x32_bf16 v[4:7], v[144:147], v[210:213], v[4:7]
	v_mfma_f32_16x16x32_bf16 v[0:3], v[152:155], v[210:213], v[0:3]
	v_mfma_f32_16x16x32_bf16 v[52:55], v[148:151], v[180:183], v[52:55]
	v_mfma_f32_16x16x32_bf16 v[48:51], v[172:175], v[180:183], v[48:51]
	v_mfma_f32_16x16x32_bf16 v[36:39], v[148:151], v[188:191], v[36:39]
	v_mfma_f32_16x16x32_bf16 v[32:35], v[172:175], v[188:191], v[32:35]
	v_mfma_f32_16x16x32_bf16 v[20:23], v[148:151], v[206:209], v[20:23]
	v_mfma_f32_16x16x32_bf16 v[16:19], v[172:175], v[206:209], v[16:19]
	v_mfma_f32_16x16x32_bf16 v[4:7], v[148:151], v[214:217], v[4:7]
	v_mfma_f32_16x16x32_bf16 v[0:3], v[172:175], v[214:217], v[0:3]

; #define PG8_STAGE(bufoff, gbase, voff) do { _Pragma("unroll") for (int _i = 0; _i < 2; ++_i) \
;         __builtin_amdgcn_global_load_lds((const unsigned*)((const char*)(gbase) + (voff)[_i]), (PG8_LAS unsigned*)(lds + (bufoff) + ldsw + _i * 8192), 16, 0, 0); } while (0)
; #define PG8_LDA(dst, b, h) do { _Pragma("unroll") for (int m = 0; m < 4; ++m) _Pragma("unroll") for (int k = 0; k < 2; ++k) dst[m][k] = *(const PG8_LAS bf16x8*)(lds + PG8_SA(b, h) + aoff + m * 2048 + k * 1024); } while (0)
; #define PG8_LDB(dst, b, h) do { _Pragma("unroll") for (int n = 0; n < 2; ++n) _Pragma("unroll") for (int k = 0; k < 2; ++k) dst[n][k] = *(const PG8_LAS bf16x8*)(lds + PG8_SB(b, h) + boff + n * 2048 + k * 1024); } while (0)
; #define PG8_MMA(ai, bj, At, Bt) do { __builtin_amdgcn_s_setprio(1); _Pragma("unroll") for (int m = 0; m < 4; ++m) _Pragma("unroll") for (int n = 0; n < 2; ++n) _Pragma("unroll") for (int k = 0; k < 2; ++k) \
;         acc[ai][bj][m][n] = __builtin_amdgcn_mfma_f32_16x16x32_bf16(Bt[n][k], At[m][k], acc[ai][bj][m][n], 0, 0, 0); __builtin_amdgcn_s_setprio(0); } while (0)
; #define PG8_WAIT_V(n) asm volatile("s_waitcnt vmcnt(" #n ")" ::: "memory")
; #define PG8_WAIT_L(n) asm volatile("s_waitcnt lgkmcnt(" #n ")" ::: "memory")
; #define PG8_BAR __builtin_amdgcn_s_barrier()
; #define PG8_SCHED __builtin_amdgcn_sched_barrier(0)
; template <class Epi, class Sched, bool ALIGN_EPI = false, bool SP2 = false>
; __device__ __forceinline__ void gemm_phase(PG8_LAS unsigned char* lds, const Gemm g, const Sched& S, const Epi& E) {
;     ...
;             PG8_WAIT_V(8); PG8_WAIT_L(0); PG8_BAR; PG8_MMA(1, 0, At, B0); PG8_MMA(1, 1, At, B1); PG8_BAR; PG8_SCHED;
;             PG8_LDB(B0, 1, 0); PG8_LDB(B1, 1, 1); PG8_SCHED; PG8_LDA(At, 1, 0); PG8_STAGE(PG8_SA(0, 1), a2 + hstep, voffA);
	s_barrier
	s_add_i32 s74, 0, 0x18000
	s_add_i32 s75, 0, 0x1c000


; #define PG8_STAGE(bufoff, gbase, voff) do { _Pragma("unroll") for (int _i = 0; _i < 2; ++_i) \
;         __builtin_amdgcn_global_load_lds((const unsigned*)((const char*)(gbase) + (voff)[_i]), (PG8_LAS unsigned*)(lds + (bufoff) + ldsw + _i * 8192), 16, 0, 0); } while (0)
; #define PG8_LDA(dst, b, h) do { _Pragma("unroll") for (int m = 0; m < 4; ++m) _Pragma("unroll") for (int k = 0; k < 2; ++k) dst[m][k] = *(const PG8_LAS bf16x8*)(lds + PG8_SA(b, h) + aoff + m * 2048 + k * 1024); } while (0)
; #define PG8_LDB(dst, b, h) do { _Pragma("unroll") for (int n = 0; n < 2; ++n) _Pragma("unroll") for (int k = 0; k < 2; ++k) dst[n][k] = *(const PG8_LAS bf16x8*)(lds + PG8_SB(b, h) + boff + n * 2048 + k * 1024); } while (0)
; #define PG8_SCHED __builtin_amdgcn_sched_barrier(0)
; template <class Epi, class Sched, bool ALIGN_EPI = false, bool SP2 = false>
; __device__ __forceinline__ void gemm_phase(PG8_LAS unsigned char* lds, const Gemm g, const Sched& S, const Epi& E) {
;     ...
;             PG8_LDB(B0, 1, 0); PG8_LDB(B1, 1, 1); PG8_SCHED; PG8_LDA(At, 1, 0); PG8_STAGE(PG8_SA(0, 1), a2 + hstep, voffA);
	ds_read_b128 v[96:99], v254
	ds_read_b128 v[100:103], v254 offset:1024
	ds_read_b128 v[104:107], v254 offset:2048
	ds_read_b128 v[112:115], v254 offset:3072
	ds_read_b128 v[144:147], v255
	ds_read_b128 v[148:151], v255 offset:1024
	ds_read_b128 v[152:155], v255 offset:2048
	ds_read_b128 v[172:175], v255 offset:3072
	s_add_u32 s52, s52, 0x200000
	s_addc_u32 s53, s53, 0
	s_mov_b32 m0, s58

; #define PG8_STAGE(bufoff, gbase, voff) do { _Pragma("unroll") for (int _i = 0; _i < 2; ++_i) \
;         __builtin_amdgcn_global_load_lds((const unsigned*)((const char*)(gbase) + (voff)[_i]), (PG8_LAS unsigned*)(lds + (bufoff) + ldsw + _i * 8192), 16, 0, 0); } while (0)
; #define PG8_LDA(dst, b, h) do { _Pragma("unroll") for (int m = 0; m < 4; ++m) _Pragma("unroll") for (int k = 0; k < 2; ++k) dst[m][k] = *(const PG8_LAS bf16x8*)(lds + PG8_SA(b, h) + aoff + m * 2048 + k * 1024); } while (0)
; #define PG8_LDB(dst, b, h) do { _Pragma("unroll") for (int n = 0; n < 2; ++n) _Pragma("unroll") for (int k = 0; k < 2; ++k) dst[n][k] = *(const PG8_LAS bf16x8*)(lds + PG8_SB(b, h) + boff + n * 2048 + k * 1024); } while (0)
; #define PG8_SCHED __builtin_amdgcn_sched_barrier(0)
; template <class Epi, class Sched, bool ALIGN_EPI = false, bool SP2 = false>
; __device__ __forceinline__ void gemm_phase(PG8_LAS unsigned char* lds, const Gemm g, const Sched& S, const Epi& E) {
;     ...
;             PG8_LDB(B0, 1, 0); PG8_LDB(B1, 1, 1); PG8_SCHED; PG8_LDA(At, 1, 0); PG8_STAGE(PG8_SA(0, 1), a2 + hstep, voffA);
	ds_read_b128 v[176:179], v199 offset:32768
	ds_read_b128 v[180:183], v199 offset:33792
	ds_read_b128 v[184:187], v199 offset:34816
	ds_read_b128 v[188:191], v199 offset:35840
	ds_read_b128 v[202:205], v199 offset:36864
	ds_read_b128 v[206:209], v199 offset:37888
	ds_read_b128 v[210:213], v199 offset:38912
	ds_read_b128 v[214:217], v199 offset:39936
	global_load_lds_dwordx4 v156, s[52:53]

; #define PG8_STAGE(bufoff, gbase, voff) do { _Pragma("unroll") for (int _i = 0; _i < 2; ++_i) \
;         __builtin_amdgcn_global_load_lds((const unsigned*)((const char*)(gbase) + (voff)[_i]), (PG8_LAS unsigned*)(lds + (bufoff) + ldsw + _i * 8192), 16, 0, 0); } while (0)
; #define PG8_LDA(dst, b, h) do { _Pragma("unroll") for (int m = 0; m < 4; ++m) _Pragma("unroll") for (int k = 0; k < 2; ++k) dst[m][k] = *(const PG8_LAS bf16x8*)(lds + PG8_SA(b, h) + aoff + m * 2048 + k * 1024); } while (0)
; #define PG8_LDB(dst, b, h) do { _Pragma("unroll") for (int n = 0; n < 2; ++n) _Pragma("unroll") for (int k = 0; k < 2; ++k) dst[n][k] = *(const PG8_LAS bf16x8*)(lds + PG8_SB(b, h) + boff + n * 2048 + k * 1024); } while (0)
; #define PG8_MMA(ai, bj, At, Bt) do { __builtin_amdgcn_s_setprio(1); _Pragma("unroll") for (int m = 0; m < 4; ++m) _Pragma("unroll") for (int n = 0; n < 2; ++n) _Pragma("unroll") for (int k = 0; k < 2; ++k) \
;         acc[ai][bj][m][n] = __builtin_amdgcn_mfma_f32_16x16x32_bf16(Bt[n][k], At[m][k], acc[ai][bj][m][n], 0, 0, 0); __builtin_amdgcn_s_setprio(0); } while (0)
; #define PG8_WAIT_V(n) asm volatile("s_waitcnt vmcnt(" #n ")" ::: "memory")
; #define PG8_WAIT_L(n) asm volatile("s_waitcnt lgkmcnt(" #n ")" ::: "memory")
; #define PG8_BAR __builtin_amdgcn_s_barrier()
; #define PG8_SCHED __builtin_amdgcn_sched_barrier(0)
; template <class Epi, class Sched, bool ALIGN_EPI = false, bool SP2 = false>
; __device__ __forceinline__ void gemm_phase(PG8_LAS unsigned char* lds, const Gemm g, const Sched& S, const Epi& E) {
;     ...
;             PG8_LDB(B0, 1, 0); PG8_LDB(B1, 1, 1); PG8_SCHED; PG8_LDA(At, 1, 0); PG8_STAGE(PG8_SA(0, 1), a2 + hstep, voffA);
;             PG8_WAIT_V(8); PG8_WAIT_L(0); PG8_BAR; PG8_MMA(0, 0, At, B0); PG8_MMA(0, 1, At, B1); PG8_BAR; PG8_SCHED;
	s_mov_b32 m0, s59
	s_nop 0
	global_load_lds_dwordx4 v160, s[52:53]
	s_waitcnt vmcnt(8)
	s_waitcnt lgkmcnt(0)

; #define PG8_MMA(ai, bj, At, Bt) do { __builtin_amdgcn_s_setprio(1); _Pragma("unroll") for (int m = 0; m < 4; ++m) _Pragma("unroll") for (int n = 0; n < 2; ++n) _Pragma("unroll") for (int k = 0; k < 2; ++k) \
;         acc[ai][bj][m][n] = __builtin_amdgcn_mfma_f32_16x16x32_bf16(Bt[n][k], At[m][k], acc[ai][bj][m][n], 0, 0, 0); __builtin_amdgcn_s_setprio(0); } while (0)
; #define PG8_WAIT_V(n) asm volatile("s_waitcnt vmcnt(" #n ")" ::: "memory")
; #define PG8_WAIT_L(n) asm volatile("s_waitcnt lgkmcnt(" #n ")" ::: "memory")
; #define PG8_BAR __builtin_amdgcn_s_barrier()
; #define PG8_SCHED __builtin_amdgcn_sched_barrier(0)
; template <class Epi, class Sched, bool ALIGN_EPI = false, bool SP2 = false>
; __device__ __forceinline__ void gemm_phase(PG8_LAS unsigned char* lds, const Gemm g, const Sched& S, const Epi& E) {
;     ...
;             PG8_WAIT_V(8); PG8_WAIT_L(0); PG8_BAR; PG8_MMA(0, 0, At, B0); PG8_MMA(0, 1, At, B1); PG8_BAR; PG8_SCHED;
	s_barrier

; #define PG8_MMA(ai, bj, At, Bt) do { __builtin_amdgcn_s_setprio(1); _Pragma("unroll") for (int m = 0; m < 4; ++m) _Pragma("unroll") for (int n = 0; n < 2; ++n) _Pragma("unroll") for (int k = 0; k < 2; ++k) \
;         acc[ai][bj][m][n] = __builtin_amdgcn_mfma_f32_16x16x32_bf16(Bt[n][k], At[m][k], acc[ai][bj][m][n], 0, 0, 0); __builtin_amdgcn_s_setprio(0); } while (0)
; #define PG8_WAIT_V(n) asm volatile("s_waitcnt vmcnt(" #n ")" ::: "memory")
; #define PG8_WAIT_L(n) asm volatile("s_waitcnt lgkmcnt(" #n ")" ::: "memory")
; #define PG8_BAR __builtin_amdgcn_s_barrier()
; #define PG8_SCHED __builtin_amdgcn_sched_barrier(0)
; template <class Epi, class Sched, bool ALIGN_EPI = false, bool SP2 = false>
; __device__ __forceinline__ void gemm_phase(PG8_LAS unsigned char* lds, const Gemm g, const Sched& S, const Epi& E) {
;     ...
;             PG8_WAIT_V(8); PG8_WAIT_L(0); PG8_BAR; PG8_MMA(0, 0, At, B0); PG8_MMA(0, 1, At, B1); PG8_BAR; PG8_SCHED;
	v_mfma_f32_16x16x32_bf16 v[140:143], v[96:99], v[176:179], v[140:143]
	v_mfma_f32_16x16x32_bf16 v[136:139], v[104:107], v[176:179], v[136:139]
	v_mfma_f32_16x16x32_bf16 v[124:127], v[96:99], v[184:187], v[124:127]
	v_mfma_f32_16x16x32_bf16 v[120:123], v[104:107], v[184:187], v[120:123]
	v_mfma_f32_16x16x32_bf16 v[92:95], v[96:99], v[202:205], v[92:95]
	v_mfma_f32_16x16x32_bf16 v[88:91], v[104:107], v[202:205], v[88:91]
	v_mfma_f32_16x16x32_bf16 v[76:79], v[96:99], v[210:213], v[76:79]
	v_mfma_f32_16x16x32_bf16 v[72:75], v[104:107], v[210:213], v[72:75]
	v_mfma_f32_16x16x32_bf16 v[140:143], v[100:103], v[180:183], v[140:143]
	v_mfma_f32_16x16x32_bf16 v[136:139], v[112:115], v[180:183], v[136:139]
	v_mfma_f32_16x16x32_bf16 v[124:127], v[100:103], v[188:191], v[124:127]
	v_mfma_f32_16x16x32_bf16 v[120:123], v[112:115], v[188:191], v[120:123]
	v_mfma_f32_16x16x32_bf16 v[92:95], v[100:103], v[206:209], v[92:95]
	v_mfma_f32_16x16x32_bf16 v[88:91], v[112:115], v[206:209], v[88:91]
	v_mfma_f32_16x16x32_bf16 v[76:79], v[100:103], v[214:217], v[76:79]
	v_mfma_f32_16x16x32_bf16 v[72:75], v[112:115], v[214:217], v[72:75]


; #define PG8_MMA(ai, bj, At, Bt) do { __builtin_amdgcn_s_setprio(1); _Pragma("unroll") for (int m = 0; m < 4; ++m) _Pragma("unroll") for (int n = 0; n < 2; ++n) _Pragma("unroll") for (int k = 0; k < 2; ++k) \
;         acc[ai][bj][m][n] = __builtin_amdgcn_mfma_f32_16x16x32_bf16(Bt[n][k], At[m][k], acc[ai][bj][m][n], 0, 0, 0); __builtin_amdgcn_s_setprio(0); } while (0)
; #define PG8_WAIT_V(n) asm volatile("s_waitcnt vmcnt(" #n ")" ::: "memory")
; #define PG8_WAIT_L(n) asm volatile("s_waitcnt lgkmcnt(" #n ")" ::: "memory")
; #define PG8_BAR __builtin_amdgcn_s_barrier()
; #define PG8_SCHED __builtin_amdgcn_sched_barrier(0)
; template <class Epi, class Sched, bool ALIGN_EPI = false, bool SP2 = false>
; __device__ __forceinline__ void gemm_phase(PG8_LAS unsigned char* lds, const Gemm g, const Sched& S, const Epi& E) {
;     ...
;             PG8_WAIT_V(8); PG8_WAIT_L(0); PG8_BAR; PG8_MMA(0, 0, At, B0); PG8_MMA(0, 1, At, B1); PG8_BAR; PG8_SCHED;
	v_mfma_f32_16x16x32_bf16 v[132:135], v[144:147], v[176:179], v[132:135]
	v_mfma_f32_16x16x32_bf16 v[128:131], v[152:155], v[176:179], v[128:131]
	v_mfma_f32_16x16x32_bf16 v[116:119], v[144:147], v[184:187], v[116:119]
	v_mfma_f32_16x16x32_bf16 v[108:111], v[152:155], v[184:187], v[108:111]
	v_mfma_f32_16x16x32_bf16 v[84:87], v[144:147], v[202:205], v[84:87]
	v_mfma_f32_16x16x32_bf16 v[80:83], v[152:155], v[202:205], v[80:83]
	v_mfma_f32_16x16x32_bf16 v[68:71], v[144:147], v[210:213], v[68:71]
	v_mfma_f32_16x16x32_bf16 v[64:67], v[152:155], v[210:213], v[64:67]
	v_mfma_f32_16x16x32_bf16 v[132:135], v[148:151], v[180:183], v[132:135]
	v_mfma_f32_16x16x32_bf16 v[128:131], v[172:175], v[180:183], v[128:131]
	v_mfma_f32_16x16x32_bf16 v[116:119], v[148:151], v[188:191], v[116:119]
	v_mfma_f32_16x16x32_bf16 v[108:111], v[172:175], v[188:191], v[108:111]
	v_mfma_f32_16x16x32_bf16 v[84:87], v[148:151], v[206:209], v[84:87]
	v_mfma_f32_16x16x32_bf16 v[80:83], v[172:175], v[206:209], v[80:83]
	v_mfma_f32_16x16x32_bf16 v[68:71], v[148:151], v[214:217], v[68:71]
	v_mfma_f32_16x16x32_bf16 v[64:67], v[172:175], v[214:217], v[64:67]

; #define PG8_STAGE(bufoff, gbase, voff) do { _Pragma("unroll") for (int _i = 0; _i < 2; ++_i) \
;         __builtin_amdgcn_global_load_lds((const unsigned*)((const char*)(gbase) + (voff)[_i]), (PG8_LAS unsigned*)(lds + (bufoff) + ldsw + _i * 8192), 16, 0, 0); } while (0)
; #define PG8_LDA(dst, b, h) do { _Pragma("unroll") for (int m = 0; m < 4; ++m) _Pragma("unroll") for (int k = 0; k < 2; ++k) dst[m][k] = *(const PG8_LAS bf16x8*)(lds + PG8_SA(b, h) + aoff + m * 2048 + k * 1024); } while (0)
; #define PG8_MMA(ai, bj, At, Bt) do { __builtin_amdgcn_s_setprio(1); _Pragma("unroll") for (int m = 0; m < 4; ++m) _Pragma("unroll") for (int n = 0; n < 2; ++n) _Pragma("unroll") for (int k = 0; k < 2; ++k) \
;         acc[ai][bj][m][n] = __builtin_amdgcn_mfma_f32_16x16x32_bf16(Bt[n][k], At[m][k], acc[ai][bj][m][n], 0, 0, 0); __builtin_amdgcn_s_setprio(0); } while (0)
; #define PG8_WAIT_V(n) asm volatile("s_waitcnt vmcnt(" #n ")" ::: "memory")
; #define PG8_WAIT_L(n) asm volatile("s_waitcnt lgkmcnt(" #n ")" ::: "memory")
; #define PG8_BAR __builtin_amdgcn_s_barrier()
; #define PG8_SCHED __builtin_amdgcn_sched_barrier(0)
; template <class Epi, class Sched, bool ALIGN_EPI = false, bool SP2 = false>
; __device__ __forceinline__ void gemm_phase(PG8_LAS unsigned char* lds, const Gemm g, const Sched& S, const Epi& E) {
;     ...
;             PG8_WAIT_V(8); PG8_WAIT_L(0); PG8_BAR; PG8_MMA(0, 0, At, B0); PG8_MMA(0, 1, At, B1); PG8_BAR; PG8_SCHED;
;             PG8_LDA(At, 1, 1); PG8_STAGE(PG8_SB(1, 0), b3, voffB); PG8_STAGE(PG8_SB(1, 1), b3 + hstep, voffB); PG8_STAGE(PG8_SA(1, 0), a3, voffA);
	s_barrier
	s_add_i32 s52, s74, s55

; #define PG8_STAGE(bufoff, gbase, voff) do { _Pragma("unroll") for (int _i = 0; _i < 2; ++_i) \
;         __builtin_amdgcn_global_load_lds((const unsigned*)((const char*)(gbase) + (voff)[_i]), (PG8_LAS unsigned*)(lds + (bufoff) + ldsw + _i * 8192), 16, 0, 0); } while (0)
; #define PG8_LDA(dst, b, h) do { _Pragma("unroll") for (int m = 0; m < 4; ++m) _Pragma("unroll") for (int k = 0; k < 2; ++k) dst[m][k] = *(const PG8_LAS bf16x8*)(lds + PG8_SA(b, h) + aoff + m * 2048 + k * 1024); } while (0)
; template <class Epi, class Sched, bool ALIGN_EPI = false, bool SP2 = false>
; __device__ __forceinline__ void gemm_phase(PG8_LAS unsigned char* lds, const Gemm g, const Sched& S, const Epi& E) {
;     ...
;             PG8_LDA(At, 1, 1); PG8_STAGE(PG8_SB(1, 0), b3, voffB); PG8_STAGE(PG8_SB(1, 1), b3 + hstep, voffB); PG8_STAGE(PG8_SA(1, 0), a3, voffA);
	s_mov_b32 m0, s52
	ds_read_b128 v[176:179], v199 offset:49152
	ds_read_b128 v[180:183], v199 offset:50176
	ds_read_b128 v[184:187], v199 offset:51200
	ds_read_b128 v[188:191], v199 offset:52224
	ds_read_b128 v[202:205], v199 offset:53248
	ds_read_b128 v[206:209], v199 offset:54272
	ds_read_b128 v[210:213], v199 offset:55296
	ds_read_b128 v[214:217], v199 offset:56320
	global_load_lds_dwordx4 v250, s[96:97]
	s_add_i32 m0, s52, 0x2000
	s_add_u32 s50, s50, 0x200080

; #define PG8_STAGE(bufoff, gbase, voff) do { _Pragma("unroll") for (int _i = 0; _i < 2; ++_i) \
;         __builtin_amdgcn_global_load_lds((const unsigned*)((const char*)(gbase) + (voff)[_i]), (PG8_LAS unsigned*)(lds + (bufoff) + ldsw + _i * 8192), 16, 0, 0); } while (0)
; #define PG8_LDA(dst, b, h) do { _Pragma("unroll") for (int m = 0; m < 4; ++m) _Pragma("unroll") for (int k = 0; k < 2; ++k) dst[m][k] = *(const PG8_LAS bf16x8*)(lds + PG8_SA(b, h) + aoff + m * 2048 + k * 1024); } while (0)
; template <class Epi, class Sched, bool ALIGN_EPI = false, bool SP2 = false>
; __device__ __forceinline__ void gemm_phase(PG8_LAS unsigned char* lds, const Gemm g, const Sched& S, const Epi& E) {
;     ...
;             PG8_LDA(At, 1, 1); PG8_STAGE(PG8_SB(1, 0), b3, voffB); PG8_STAGE(PG8_SB(1, 1), b3 + hstep, voffB); PG8_STAGE(PG8_SA(1, 0), a3, voffA);
	s_addc_u32 s51, s51, 0
	s_add_i32 s52, s75, s55
	global_load_lds_dwordx4 v251, s[96:97]

; #define PG8_STAGE(bufoff, gbase, voff) do { _Pragma("unroll") for (int _i = 0; _i < 2; ++_i) \
;         __builtin_amdgcn_global_load_lds((const unsigned*)((const char*)(gbase) + (voff)[_i]), (PG8_LAS unsigned*)(lds + (bufoff) + ldsw + _i * 8192), 16, 0, 0); } while (0)
; #define PG8_LDA(dst, b, h) do { _Pragma("unroll") for (int m = 0; m < 4; ++m) _Pragma("unroll") for (int k = 0; k < 2; ++k) dst[m][k] = *(const PG8_LAS bf16x8*)(lds + PG8_SA(b, h) + aoff + m * 2048 + k * 1024); } while (0)
; template <class Epi, class Sched, bool ALIGN_EPI = false, bool SP2 = false>
; __device__ __forceinline__ void gemm_phase(PG8_LAS unsigned char* lds, const Gemm g, const Sched& S, const Epi& E) {
;     ...
;             PG8_LDA(At, 1, 1); PG8_STAGE(PG8_SB(1, 0), b3, voffB); PG8_STAGE(PG8_SB(1, 1), b3 + hstep, voffB); PG8_STAGE(PG8_SA(1, 0), a3, voffA);
	s_mov_b32 m0, s52
	s_nop 0
	global_load_lds_dwordx4 v158, s[50:51]

; #define PG8_STAGE(bufoff, gbase, voff) do { _Pragma("unroll") for (int _i = 0; _i < 2; ++_i) \
;         __builtin_amdgcn_global_load_lds((const unsigned*)((const char*)(gbase) + (voff)[_i]), (PG8_LAS unsigned*)(lds + (bufoff) + ldsw + _i * 8192), 16, 0, 0); } while (0)
; #define PG8_LDA(dst, b, h) do { _Pragma("unroll") for (int m = 0; m < 4; ++m) _Pragma("unroll") for (int k = 0; k < 2; ++k) dst[m][k] = *(const PG8_LAS bf16x8*)(lds + PG8_SA(b, h) + aoff + m * 2048 + k * 1024); } while (0)
; template <class Epi, class Sched, bool ALIGN_EPI = false, bool SP2 = false>
; __device__ __forceinline__ void gemm_phase(PG8_LAS unsigned char* lds, const Gemm g, const Sched& S, const Epi& E) {
;     ...
;             PG8_LDA(At, 1, 1); PG8_STAGE(PG8_SB(1, 0), b3, voffB); PG8_STAGE(PG8_SB(1, 1), b3 + hstep, voffB); PG8_STAGE(PG8_SA(1, 0), a3, voffA);
	s_add_i32 m0, s52, 0x2000
	s_nop 0
	global_load_lds_dwordx4 v162, s[50:51]

; #define PG8_STAGE(bufoff, gbase, voff) do { _Pragma("unroll") for (int _i = 0; _i < 2; ++_i) \
;         __builtin_amdgcn_global_load_lds((const unsigned*)((const char*)(gbase) + (voff)[_i]), (PG8_LAS unsigned*)(lds + (bufoff) + ldsw + _i * 8192), 16, 0, 0); } while (0)
; #define PG8_LDA(dst, b, h) do { _Pragma("unroll") for (int m = 0; m < 4; ++m) _Pragma("unroll") for (int k = 0; k < 2; ++k) dst[m][k] = *(const PG8_LAS bf16x8*)(lds + PG8_SA(b, h) + aoff + m * 2048 + k * 1024); } while (0)
; template <class Epi, class Sched, bool ALIGN_EPI = false, bool SP2 = false>
; __device__ __forceinline__ void gemm_phase(PG8_LAS unsigned char* lds, const Gemm g, const Sched& S, const Epi& E) {
;     ...
;             PG8_LDA(At, 1, 1); PG8_STAGE(PG8_SB(1, 0), b3, voffB); PG8_STAGE(PG8_SB(1, 1), b3 + hstep, voffB); PG8_STAGE(PG8_SA(1, 0), a3, voffA);
	s_mov_b32 m0, s61
	s_nop 0
	global_load_lds_dwordx4 v252, s[98:99]

; #define PG8_STAGE(bufoff, gbase, voff) do { _Pragma("unroll") for (int _i = 0; _i < 2; ++_i) \
;         __builtin_amdgcn_global_load_lds((const unsigned*)((const char*)(gbase) + (voff)[_i]), (PG8_LAS unsigned*)(lds + (bufoff) + ldsw + _i * 8192), 16, 0, 0); } while (0)
; #define PG8_LDA(dst, b, h) do { _Pragma("unroll") for (int m = 0; m < 4; ++m) _Pragma("unroll") for (int k = 0; k < 2; ++k) dst[m][k] = *(const PG8_LAS bf16x8*)(lds + PG8_SA(b, h) + aoff + m * 2048 + k * 1024); } while (0)
; #define PG8_MMA(ai, bj, At, Bt) do { __builtin_amdgcn_s_setprio(1); _Pragma("unroll") for (int m = 0; m < 4; ++m) _Pragma("unroll") for (int n = 0; n < 2; ++n) _Pragma("unroll") for (int k = 0; k < 2; ++k) \
;         acc[ai][bj][m][n] = __builtin_amdgcn_mfma_f32_16x16x32_bf16(Bt[n][k], At[m][k], acc[ai][bj][m][n], 0, 0, 0); __builtin_amdgcn_s_setprio(0); } while (0)
; #define PG8_WAIT_V(n) asm volatile("s_waitcnt vmcnt(" #n ")" ::: "memory")
; #define PG8_WAIT_L(n) asm volatile("s_waitcnt lgkmcnt(" #n ")" ::: "memory")
; #define PG8_BAR __builtin_amdgcn_s_barrier()
; #define PG8_SCHED __builtin_amdgcn_sched_barrier(0)
; template <class Epi, class Sched, bool ALIGN_EPI = false, bool SP2 = false>
; __device__ __forceinline__ void gemm_phase(PG8_LAS unsigned char* lds, const Gemm g, const Sched& S, const Epi& E) {
;     ...
;             PG8_LDA(At, 1, 1); PG8_STAGE(PG8_SB(1, 0), b3, voffB); PG8_STAGE(PG8_SB(1, 1), b3 + hstep, voffB); PG8_STAGE(PG8_SA(1, 0), a3, voffA);
;             PG8_WAIT_V(8); PG8_WAIT_L(0); PG8_BAR; PG8_MMA(1, 0, At, B0); PG8_MMA(1, 1, At, B1); PG8_BAR; PG8_SCHED;
	s_mov_b32 m0, s62
	s_nop 0
	global_load_lds_dwordx4 v253, s[98:99]
	s_waitcnt vmcnt(8)
	s_waitcnt lgkmcnt(0)

; #define PG8_MMA(ai, bj, At, Bt) do { __builtin_amdgcn_s_setprio(1); _Pragma("unroll") for (int m = 0; m < 4; ++m) _Pragma("unroll") for (int n = 0; n < 2; ++n) _Pragma("unroll") for (int k = 0; k < 2; ++k) \
;         acc[ai][bj][m][n] = __builtin_amdgcn_mfma_f32_16x16x32_bf16(Bt[n][k], At[m][k], acc[ai][bj][m][n], 0, 0, 0); __builtin_amdgcn_s_setprio(0); } while (0)
; #define PG8_WAIT_V(n) asm volatile("s_waitcnt vmcnt(" #n ")" ::: "memory")
; #define PG8_WAIT_L(n) asm volatile("s_waitcnt lgkmcnt(" #n ")" ::: "memory")
; #define PG8_BAR __builtin_amdgcn_s_barrier()
; #define PG8_SCHED __builtin_amdgcn_sched_barrier(0)
; template <class Epi, class Sched, bool ALIGN_EPI = false, bool SP2 = false>
; __device__ __forceinline__ void gemm_phase(PG8_LAS unsigned char* lds, const Gemm g, const Sched& S, const Epi& E) {
;     ...
;             PG8_WAIT_V(8); PG8_WAIT_L(0); PG8_BAR; PG8_MMA(1, 0, At, B0); PG8_MMA(1, 1, At, B1); PG8_BAR; PG8_SCHED;
	s_barrier

; #define PG8_MMA(ai, bj, At, Bt) do { __builtin_amdgcn_s_setprio(1); _Pragma("unroll") for (int m = 0; m < 4; ++m) _Pragma("unroll") for (int n = 0; n < 2; ++n) _Pragma("unroll") for (int k = 0; k < 2; ++k) \
;         acc[ai][bj][m][n] = __builtin_amdgcn_mfma_f32_16x16x32_bf16(Bt[n][k], At[m][k], acc[ai][bj][m][n], 0, 0, 0); __builtin_amdgcn_s_setprio(0); } while (0)
; #define PG8_WAIT_V(n) asm volatile("s_waitcnt vmcnt(" #n ")" ::: "memory")
; #define PG8_WAIT_L(n) asm volatile("s_waitcnt lgkmcnt(" #n ")" ::: "memory")
; #define PG8_BAR __builtin_amdgcn_s_barrier()
; #define PG8_SCHED __builtin_amdgcn_sched_barrier(0)
; template <class Epi, class Sched, bool ALIGN_EPI = false, bool SP2 = false>
; __device__ __forceinline__ void gemm_phase(PG8_LAS unsigned char* lds, const Gemm g, const Sched& S, const Epi& E) {
;     ...
;             PG8_WAIT_V(8); PG8_WAIT_L(0); PG8_BAR; PG8_MMA(1, 0, At, B0); PG8_MMA(1, 1, At, B1); PG8_BAR; PG8_SCHED;
	v_mfma_f32_16x16x32_bf16 v[60:63], v[96:99], v[176:179], v[60:63]
	v_mfma_f32_16x16x32_bf16 v[56:59], v[104:107], v[176:179], v[56:59]
	v_mfma_f32_16x16x32_bf16 v[44:47], v[96:99], v[184:187], v[44:47]
	v_mfma_f32_16x16x32_bf16 v[40:43], v[104:107], v[184:187], v[40:43]
	v_mfma_f32_16x16x32_bf16 v[28:31], v[96:99], v[202:205], v[28:31]
	v_mfma_f32_16x16x32_bf16 v[24:27], v[104:107], v[202:205], v[24:27]
	v_mfma_f32_16x16x32_bf16 v[12:15], v[96:99], v[210:213], v[12:15]
	v_mfma_f32_16x16x32_bf16 v[8:11], v[104:107], v[210:213], v[8:11]
	v_mfma_f32_16x16x32_bf16 v[60:63], v[100:103], v[180:183], v[60:63]
	v_mfma_f32_16x16x32_bf16 v[56:59], v[112:115], v[180:183], v[56:59]
	v_mfma_f32_16x16x32_bf16 v[44:47], v[100:103], v[188:191], v[44:47]
	v_mfma_f32_16x16x32_bf16 v[40:43], v[112:115], v[188:191], v[40:43]
	v_mfma_f32_16x16x32_bf16 v[28:31], v[100:103], v[206:209], v[28:31]
	v_mfma_f32_16x16x32_bf16 v[24:27], v[112:115], v[206:209], v[24:27]
	v_mfma_f32_16x16x32_bf16 v[12:15], v[100:103], v[214:217], v[12:15]
	v_mfma_f32_16x16x32_bf16 v[8:11], v[112:115], v[214:217], v[8:11]


; #define PG8_MMA(ai, bj, At, Bt) do { __builtin_amdgcn_s_setprio(1); _Pragma("unroll") for (int m = 0; m < 4; ++m) _Pragma("unroll") for (int n = 0; n < 2; ++n) _Pragma("unroll") for (int k = 0; k < 2; ++k) \
;         acc[ai][bj][m][n] = __builtin_amdgcn_mfma_f32_16x16x32_bf16(Bt[n][k], At[m][k], acc[ai][bj][m][n], 0, 0, 0); __builtin_amdgcn_s_setprio(0); } while (0)
; #define PG8_WAIT_V(n) asm volatile("s_waitcnt vmcnt(" #n ")" ::: "memory")
; #define PG8_WAIT_L(n) asm volatile("s_waitcnt lgkmcnt(" #n ")" ::: "memory")
; #define PG8_BAR __builtin_amdgcn_s_barrier()
; #define PG8_SCHED __builtin_amdgcn_sched_barrier(0)
; template <class Epi, class Sched, bool ALIGN_EPI = false, bool SP2 = false>
; __device__ __forceinline__ void gemm_phase(PG8_LAS unsigned char* lds, const Gemm g, const Sched& S, const Epi& E) {
;     ...
;             PG8_WAIT_V(8); PG8_WAIT_L(0); PG8_BAR; PG8_MMA(1, 0, At, B0); PG8_MMA(1, 1, At, B1); PG8_BAR; PG8_SCHED;
	v_mfma_f32_16x16x32_bf16 v[52:55], v[144:147], v[176:179], v[52:55]
	v_mfma_f32_16x16x32_bf16 v[48:51], v[152:155], v[176:179], v[48:51]
	v_mfma_f32_16x16x32_bf16 v[36:39], v[144:147], v[184:187], v[36:39]
	v_mfma_f32_16x16x32_bf16 v[32:35], v[152:155], v[184:187], v[32:35]
	v_mfma_f32_16x16x32_bf16 v[20:23], v[144:147], v[202:205], v[20:23]
	v_mfma_f32_16x16x32_bf16 v[16:19], v[152:155], v[202:205], v[16:19]
	v_mfma_f32_16x16x32_bf16 v[4:7], v[144:147], v[210:213], v[4:7]
	v_mfma_f32_16x16x32_bf16 v[0:3], v[152:155], v[210:213], v[0:3]
	v_mfma_f32_16x16x32_bf16 v[52:55], v[148:151], v[180:183], v[52:55]
	v_mfma_f32_16x16x32_bf16 v[48:51], v[172:175], v[180:183], v[48:51]
	v_mfma_f32_16x16x32_bf16 v[36:39], v[148:151], v[188:191], v[36:39]
	v_mfma_f32_16x16x32_bf16 v[32:35], v[172:175], v[188:191], v[32:35]
	v_mfma_f32_16x16x32_bf16 v[20:23], v[148:151], v[206:209], v[20:23]
	v_mfma_f32_16x16x32_bf16 v[16:19], v[172:175], v[206:209], v[16:19]
	v_mfma_f32_16x16x32_bf16 v[4:7], v[148:151], v[214:217], v[4:7]
	v_mfma_f32_16x16x32_bf16 v[0:3], v[172:175], v[214:217], v[0:3]

; #define PG8_MMA(ai, bj, At, Bt) do { __builtin_amdgcn_s_setprio(1); _Pragma("unroll") for (int m = 0; m < 4; ++m) _Pragma("unroll") for (int n = 0; n < 2; ++n) _Pragma("unroll") for (int k = 0; k < 2; ++k) \
;         acc[ai][bj][m][n] = __builtin_amdgcn_mfma_f32_16x16x32_bf16(Bt[n][k], At[m][k], acc[ai][bj][m][n], 0, 0, 0); __builtin_amdgcn_s_setprio(0); } while (0)
; #define PG8_WAIT_V(n) asm volatile("s_waitcnt vmcnt(" #n ")" ::: "memory")
; #define PG8_WAIT_L(n) asm volatile("s_waitcnt lgkmcnt(" #n ")" ::: "memory")
; #define PG8_BAR __builtin_amdgcn_s_barrier()
; #define PG8_SCHED __builtin_amdgcn_sched_barrier(0)
; template <class Epi, class Sched, bool ALIGN_EPI = false, bool SP2 = false>
; __device__ __forceinline__ void gemm_phase(PG8_LAS unsigned char* lds, const Gemm g, const Sched& S, const Epi& E) {
;     ...
;         for (int t = 0; t < nt; t += 2) {
;     ...
;             PG8_WAIT_V(8); PG8_WAIT_L(0); PG8_BAR; PG8_MMA(1, 0, At, B0); PG8_MMA(1, 1, At, B1); PG8_BAR; PG8_SCHED;
	s_barrier
	s_add_i32 s73, s73, 2
	s_add_u32 s48, s48, 0x100
	s_addc_u32 s49, s49, 0
	s_add_u32 s71, s71, 0x100
	s_addc_u32 s72, s72, 0
	s_cmpk_gt_u32 s73, 0x7d
	s_cbranch_scc0 .LBB0_1114
	s_and_b64 vcc, exec, s[34:35]
	s_cbranch_vccz .LBB0_1117
	s_barrier
